# GEMM K-loops: ks=1 fragment ds_reads issued right after ks=0 reads into a second register set (v204-v235), counted lgkmcnt 11/10/9/8 then 3/2/1/0
# speedup vs baseline: 1.0488x; 1.0153x over previous
.LBB0_259:
	s_and_b32 s8, s7, 0x4000
	s_xor_b32 s9, s8, 0x4000
	s_lshl_b32 s9, s9, 1
	s_add_i32 s9, s9, 32
	s_add_u32 s90, s52, s4
	s_addc_u32 s91, s53, s5
	s_add_i32 m0, s9, s82
	s_lshl_b32 s8, s8, 1
	global_load_lds_dwordx4 v184, s[90:91]
	s_add_i32 m0, s9, s83
	s_add_i32 s8, s8, 32
	global_load_lds_dwordx4 v185, s[90:91]
	s_add_i32 m0, s9, s84
	v_lshl_add_u32 v64, v120, 1, s8
	global_load_lds_dwordx4 v186, s[90:91]
	s_add_i32 m0, s9, s85
	v_lshl_add_u32 v95, v121, 1, s8
	global_load_lds_dwordx4 v187, s[90:91]
	s_add_i32 m0, s9, s86
	v_add_u32_e32 v166, v64, v142
	global_load_lds_dwordx4 v188, s[90:91]
	s_add_i32 m0, s9, s87
	v_add_u32_e32 v174, v95, v142
	global_load_lds_dwordx4 v189, s[90:91]
	s_add_i32 m0, s9, s88
	s_addk_i32 s7, 0x4000
	global_load_lds_dwordx4 v190, s[90:91]
	s_add_i32 m0, s9, s89
	s_add_u32 s4, s4, 0x80
	s_addc_u32 s5, s5, 0
	global_load_lds_dwordx4 v191, s[90:91]
	ds_read_b128 v[146:149], v166
	ds_read_b128 v[154:157], v174 offset:16384
	ds_read_b128 v[158:161], v174 offset:18432
	ds_read_b128 v[170:173], v174 offset:20480
	ds_read_b128 v[174:177], v174 offset:22528
	ds_read_b128 v[150:153], v166 offset:2048
	ds_read_b128 v[162:165], v166 offset:4096
	ds_read_b128 v[166:169], v166 offset:6144
	v_add_u32_e32 v64, v64, v143
	v_add_u32_e32 v95, v95, v143
	ds_read_b128 v[204:207], v64
	ds_read_b128 v[208:211], v95 offset:16384
	ds_read_b128 v[212:215], v95 offset:18432
	ds_read_b128 v[216:219], v95 offset:20480
	ds_read_b128 v[220:223], v95 offset:22528
	ds_read_b128 v[224:227], v64 offset:2048
	ds_read_b128 v[228:231], v64 offset:4096
	ds_read_b128 v[232:235], v64 offset:6144
	s_setprio 1
	s_waitcnt lgkmcnt(11)
	v_mfma_f32_16x16x32_bf16 v[60:63], v[146:149], v[154:157], v[60:63]
	v_mfma_f32_16x16x32_bf16 v[56:59], v[146:149], v[158:161], v[56:59]
	v_mfma_f32_16x16x32_bf16 v[52:55], v[146:149], v[170:173], v[52:55]
	v_mfma_f32_16x16x32_bf16 v[48:51], v[146:149], v[174:177], v[48:51]
	s_waitcnt lgkmcnt(10)
	v_mfma_f32_16x16x32_bf16 v[44:47], v[150:153], v[154:157], v[44:47]
	v_mfma_f32_16x16x32_bf16 v[40:43], v[150:153], v[158:161], v[40:43]
	v_mfma_f32_16x16x32_bf16 v[36:39], v[150:153], v[170:173], v[36:39]
	v_mfma_f32_16x16x32_bf16 v[32:35], v[150:153], v[174:177], v[32:35]
	s_waitcnt lgkmcnt(9)
	v_mfma_f32_16x16x32_bf16 v[28:31], v[162:165], v[154:157], v[28:31]
	v_mfma_f32_16x16x32_bf16 v[24:27], v[162:165], v[158:161], v[24:27]
	v_mfma_f32_16x16x32_bf16 v[20:23], v[162:165], v[170:173], v[20:23]
	v_mfma_f32_16x16x32_bf16 v[16:19], v[162:165], v[174:177], v[16:19]
	s_waitcnt lgkmcnt(8)
	v_mfma_f32_16x16x32_bf16 v[12:15], v[166:169], v[154:157], v[12:15]
	v_mfma_f32_16x16x32_bf16 v[8:11], v[166:169], v[158:161], v[8:11]
	v_mfma_f32_16x16x32_bf16 v[4:7], v[166:169], v[170:173], v[4:7]
	v_mfma_f32_16x16x32_bf16 v[0:3], v[166:169], v[174:177], v[0:3]
	s_waitcnt lgkmcnt(3)
	v_mfma_f32_16x16x32_bf16 v[60:63], v[204:207], v[208:211], v[60:63]
	v_mfma_f32_16x16x32_bf16 v[56:59], v[204:207], v[212:215], v[56:59]
	v_mfma_f32_16x16x32_bf16 v[52:55], v[204:207], v[216:219], v[52:55]
	v_mfma_f32_16x16x32_bf16 v[48:51], v[204:207], v[220:223], v[48:51]
	s_waitcnt lgkmcnt(2)
	v_mfma_f32_16x16x32_bf16 v[44:47], v[224:227], v[208:211], v[44:47]
	v_mfma_f32_16x16x32_bf16 v[40:43], v[224:227], v[212:215], v[40:43]
	v_mfma_f32_16x16x32_bf16 v[36:39], v[224:227], v[216:219], v[36:39]
	v_mfma_f32_16x16x32_bf16 v[32:35], v[224:227], v[220:223], v[32:35]
	s_waitcnt lgkmcnt(1)
	v_mfma_f32_16x16x32_bf16 v[28:31], v[228:231], v[208:211], v[28:31]
	v_mfma_f32_16x16x32_bf16 v[24:27], v[228:231], v[212:215], v[24:27]
	v_mfma_f32_16x16x32_bf16 v[20:23], v[228:231], v[216:219], v[20:23]
	v_mfma_f32_16x16x32_bf16 v[16:19], v[228:231], v[220:223], v[16:19]
	s_waitcnt lgkmcnt(0)
	v_mfma_f32_16x16x32_bf16 v[12:15], v[232:235], v[208:211], v[12:15]
	v_mfma_f32_16x16x32_bf16 v[8:11], v[232:235], v[212:215], v[8:11]
	v_mfma_f32_16x16x32_bf16 v[4:7], v[232:235], v[216:219], v[4:7]
	v_mfma_f32_16x16x32_bf16 v[0:3], v[232:235], v[220:223], v[0:3]
	s_setprio 0
	s_cmpk_eq_i32 s4, 0x780
	s_waitcnt vmcnt(0)
	s_barrier
	s_cbranch_scc0 .LBB0_259
	ds_read_b128 v[96:99], v122 offset:55296
	ds_read_b128 v[100:103], v122 offset:53248
	ds_read_b128 v[104:107], v123 offset:38912
	ds_read_b128 v[108:111], v123 offset:36864
	ds_read_b128 v[146:149], v122 offset:51200
	ds_read_b128 v[150:153], v122 offset:49152
	ds_read_b128 v[154:157], v123 offset:34816
	ds_read_b128 v[158:161], v123 offset:32768
	s_setprio 1
	s_waitcnt lgkmcnt(3)
	v_mfma_f32_16x16x32_bf16 v[24:27], v[108:111], v[146:149], v[24:27]
	v_mfma_f32_16x16x32_bf16 v[20:23], v[108:111], v[100:103], v[20:23]
	v_mfma_f32_16x16x32_bf16 v[16:19], v[108:111], v[96:99], v[16:19]
	s_waitcnt lgkmcnt(0)
	v_mfma_f32_16x16x32_bf16 v[60:63], v[158:161], v[150:153], v[60:63]
	v_mfma_f32_16x16x32_bf16 v[56:59], v[158:161], v[146:149], v[56:59]
	v_mfma_f32_16x16x32_bf16 v[52:55], v[158:161], v[100:103], v[52:55]
	v_mfma_f32_16x16x32_bf16 v[48:51], v[158:161], v[96:99], v[48:51]
	v_mfma_f32_16x16x32_bf16 v[44:47], v[154:157], v[150:153], v[44:47]
	v_mfma_f32_16x16x32_bf16 v[40:43], v[154:157], v[146:149], v[40:43]
	v_mfma_f32_16x16x32_bf16 v[36:39], v[154:157], v[100:103], v[36:39]
	v_mfma_f32_16x16x32_bf16 v[32:35], v[154:157], v[96:99], v[32:35]
	v_mfma_f32_16x16x32_bf16 v[28:31], v[108:111], v[150:153], v[28:31]
	v_mfma_f32_16x16x32_bf16 v[12:15], v[104:107], v[150:153], v[12:15]
	v_mfma_f32_16x16x32_bf16 v[8:11], v[104:107], v[146:149], v[8:11]
	v_mfma_f32_16x16x32_bf16 v[4:7], v[104:107], v[100:103], v[4:7]
	v_mfma_f32_16x16x32_bf16 v[0:3], v[104:107], v[96:99], v[0:3]
	s_setprio 0
	ds_read_b128 v[96:99], v124 offset:32768
	ds_read_b128 v[100:103], v124 offset:34816
	ds_read_b128 v[104:107], v125 offset:49152
	ds_read_b128 v[108:111], v125 offset:51200
	ds_read_b128 v[146:149], v124 offset:36864
	ds_read_b128 v[150:153], v124 offset:38912
	ds_read_b128 v[154:157], v125 offset:53248
	ds_read_b128 v[158:161], v125 offset:55296
	s_setprio 1
	s_waitcnt lgkmcnt(3)
	v_mfma_f32_16x16x32_bf16 v[24:27], v[146:149], v[108:111], v[24:27]
	s_waitcnt lgkmcnt(1)
	v_mfma_f32_16x16x32_bf16 v[20:23], v[146:149], v[154:157], v[20:23]
	s_waitcnt lgkmcnt(0)
	v_mfma_f32_16x16x32_bf16 v[16:19], v[146:149], v[158:161], v[16:19]
	v_mfma_f32_16x16x32_bf16 v[60:63], v[96:99], v[104:107], v[60:63]
	v_mfma_f32_16x16x32_bf16 v[56:59], v[96:99], v[108:111], v[56:59]
	v_mfma_f32_16x16x32_bf16 v[52:55], v[96:99], v[154:157], v[52:55]
	v_mfma_f32_16x16x32_bf16 v[48:51], v[96:99], v[158:161], v[48:51]
	v_mfma_f32_16x16x32_bf16 v[44:47], v[100:103], v[104:107], v[44:47]
	v_mfma_f32_16x16x32_bf16 v[40:43], v[100:103], v[108:111], v[40:43]
	v_mfma_f32_16x16x32_bf16 v[36:39], v[100:103], v[154:157], v[36:39]
	v_mfma_f32_16x16x32_bf16 v[32:35], v[100:103], v[158:161], v[32:35]
	v_mfma_f32_16x16x32_bf16 v[28:31], v[146:149], v[104:107], v[28:31]
	v_mfma_f32_16x16x32_bf16 v[12:15], v[150:153], v[104:107], v[12:15]
	v_mfma_f32_16x16x32_bf16 v[8:11], v[150:153], v[108:111], v[8:11]
	v_mfma_f32_16x16x32_bf16 v[4:7], v[150:153], v[154:157], v[4:7]
	v_mfma_f32_16x16x32_bf16 v[0:3], v[150:153], v[158:161], v[0:3]
	s_setprio 0
	s_barrier
	ds_write2_b32 v126, v60, v56 offset1:16
	ds_write2_b32 v126, v61, v57 offset0:132 offset1:148
	v_add_u32_e32 v56, 0x400, v126
	ds_write2_b32 v56, v62, v58 offset0:8 offset1:24
	ds_write2_b32 v56, v63, v59 offset0:140 offset1:156
	ds_write2_b32 v126, v52, v48 offset0:32 offset1:48
	ds_write2_b32 v126, v53, v49 offset0:164 offset1:180
	ds_write2_b32 v56, v54, v50 offset0:40 offset1:56
	ds_write2_b32 v56, v55, v51 offset0:172 offset1:188
	v_add_u32_e32 v48, 0x2000, v126
	ds_write2_b32 v48, v44, v40 offset0:64 offset1:80
	ds_write2_b32 v48, v45, v41 offset0:196 offset1:212
	v_add_u32_e32 v40, 0x2400, v126
	ds_write2_b32 v40, v46, v42 offset0:72 offset1:88
	ds_write2_b32 v40, v47, v43 offset0:204 offset1:220
	ds_write2_b32 v48, v36, v32 offset0:96 offset1:112
	ds_write2_b32 v48, v37, v33 offset0:228 offset1:244
	ds_write2_b32 v40, v38, v34 offset0:104 offset1:120
	ds_write2_b32 v40, v39, v35 offset0:236 offset1:252
	v_add_u32_e32 v32, 0x4000, v126
	ds_write2_b32 v32, v28, v24 offset0:128 offset1:144
	v_add_u32_e32 v24, 0x4400, v126
	ds_write2_b32 v24, v29, v25 offset0:4 offset1:20
	ds_write2_b32 v24, v30, v26 offset0:136 offset1:152
	v_add_u32_e32 v25, 0x4800, v126
	ds_write2_b32 v25, v31, v27 offset0:12 offset1:28
	ds_write2_b32 v32, v20, v16 offset0:160 offset1:176
	ds_write2_b32 v24, v21, v17 offset0:36 offset1:52
	ds_write2_b32 v24, v22, v18 offset0:168 offset1:184
	ds_write2_b32 v25, v23, v19 offset0:44 offset1:60
	v_add_u32_e32 v16, 0x6000, v126
	ds_write2_b32 v16, v12, v8 offset0:192 offset1:208
	v_add_u32_e32 v8, 0x6400, v126
	ds_write2_b32 v8, v13, v9 offset0:68 offset1:84
	ds_write2_b32 v8, v14, v10 offset0:200 offset1:216
	v_add_u32_e32 v9, 0x6800, v126
	v_or_b32_e32 v64, s6, v127
	ds_write2_b32 v9, v15, v11 offset0:76 offset1:92
	ds_write2_b32 v16, v4, v0 offset0:224 offset1:240
	ds_write2_b32 v8, v5, v1 offset0:100 offset1:116
	ds_write2_b32 v8, v6, v2 offset0:232 offset1:248
	ds_write2_b32 v9, v7, v3 offset0:108 offset1:124
	v_ashrrev_i32_e32 v1, 31, v64
	v_mov_b32_e32 v0, v64
	v_lshlrev_b64 v[2:3], 1, v[64:65]
	v_lshl_add_u64 v[20:21], v[0:1], 1, s[10:11]
	v_mov_b32_e32 v0, s15
	v_mov_b32_e32 v1, s13
	v_cmp_gt_i32_e64 s[8:9], s38, v64
	v_lshl_add_u64 v[16:17], s[18:19], 0, v[2:3]
	v_lshl_add_u64 v[18:19], s[16:17], 0, v[2:3]
	v_cndmask_b32_e64 v1, v0, v1, s[8:9]
	v_mov_b32_e32 v0, s14
	v_mov_b32_e32 v2, s12
	v_cndmask_b32_e64 v0, v0, v2, s[8:9]
	v_mov_b32_e32 v95, v65
	v_cmp_lt_i32_e64 s[4:5], s39, v64
	v_cmp_lt_i32_e64 s[6:7], s40, v64
	v_lshl_add_u64 v[22:23], v[0:1], 0, v[94:95]
	v_add_u32_e32 v24, s30, v135
	s_mov_b32 s45, 0
	s_waitcnt lgkmcnt(0)
	s_barrier
	s_branch .LBB0_263

.LBB0_278:
	s_and_b32 s8, s7, 0x4000
	s_xor_b32 s9, s8, 0x4000
	s_lshl_b32 s9, s9, 1
	s_add_i32 s9, s9, 32
	s_add_u32 s90, s52, s4
	s_addc_u32 s91, s53, s5
	s_add_i32 m0, s9, s82
	s_lshl_b32 s8, s8, 1
	global_load_lds_dwordx4 v184, s[90:91]
	s_add_i32 m0, s9, s83
	s_add_i32 s8, s8, 32
	global_load_lds_dwordx4 v185, s[90:91]
	s_add_i32 m0, s9, s84
	v_lshl_add_u32 v64, v121, 1, s8
	global_load_lds_dwordx4 v186, s[90:91]
	s_add_i32 m0, s9, s85
	v_lshl_add_u32 v95, v122, 1, s8
	global_load_lds_dwordx4 v187, s[90:91]
	s_add_i32 m0, s9, s86
	v_add_u32_e32 v164, v64, v139
	global_load_lds_dwordx4 v188, s[90:91]
	s_add_i32 m0, s9, s87
	v_add_u32_e32 v172, v95, v139
	global_load_lds_dwordx4 v189, s[90:91]
	s_add_i32 m0, s9, s88
	s_addk_i32 s7, 0x4000
	global_load_lds_dwordx4 v190, s[90:91]
	s_add_i32 m0, s9, s89
	s_add_u32 s4, s4, 0x80
	s_addc_u32 s5, s5, 0
	global_load_lds_dwordx4 v191, s[90:91]
	ds_read_b128 v[144:147], v164
	ds_read_b128 v[152:155], v172 offset:16384
	ds_read_b128 v[156:159], v172 offset:18432
	ds_read_b128 v[168:171], v172 offset:20480
	ds_read_b128 v[172:175], v172 offset:22528
	ds_read_b128 v[148:151], v164 offset:2048
	ds_read_b128 v[160:163], v164 offset:4096
	ds_read_b128 v[164:167], v164 offset:6144
	v_add_u32_e32 v64, v64, v140
	v_add_u32_e32 v95, v95, v140
	ds_read_b128 v[204:207], v64
	ds_read_b128 v[208:211], v95 offset:16384
	ds_read_b128 v[212:215], v95 offset:18432
	ds_read_b128 v[216:219], v95 offset:20480
	ds_read_b128 v[220:223], v95 offset:22528
	ds_read_b128 v[224:227], v64 offset:2048
	ds_read_b128 v[228:231], v64 offset:4096
	ds_read_b128 v[232:235], v64 offset:6144
	s_setprio 1
	s_waitcnt lgkmcnt(11)
	v_mfma_f32_16x16x32_bf16 v[60:63], v[144:147], v[152:155], v[60:63]
	v_mfma_f32_16x16x32_bf16 v[56:59], v[144:147], v[156:159], v[56:59]
	v_mfma_f32_16x16x32_bf16 v[52:55], v[144:147], v[168:171], v[52:55]
	v_mfma_f32_16x16x32_bf16 v[48:51], v[144:147], v[172:175], v[48:51]
	s_waitcnt lgkmcnt(10)
	v_mfma_f32_16x16x32_bf16 v[44:47], v[148:151], v[152:155], v[44:47]
	v_mfma_f32_16x16x32_bf16 v[40:43], v[148:151], v[156:159], v[40:43]
	v_mfma_f32_16x16x32_bf16 v[36:39], v[148:151], v[168:171], v[36:39]
	v_mfma_f32_16x16x32_bf16 v[32:35], v[148:151], v[172:175], v[32:35]
	s_waitcnt lgkmcnt(9)
	v_mfma_f32_16x16x32_bf16 v[28:31], v[160:163], v[152:155], v[28:31]
	v_mfma_f32_16x16x32_bf16 v[24:27], v[160:163], v[156:159], v[24:27]
	v_mfma_f32_16x16x32_bf16 v[20:23], v[160:163], v[168:171], v[20:23]
	v_mfma_f32_16x16x32_bf16 v[16:19], v[160:163], v[172:175], v[16:19]
	s_waitcnt lgkmcnt(8)
	v_mfma_f32_16x16x32_bf16 v[12:15], v[164:167], v[152:155], v[12:15]
	v_mfma_f32_16x16x32_bf16 v[8:11], v[164:167], v[156:159], v[8:11]
	v_mfma_f32_16x16x32_bf16 v[4:7], v[164:167], v[168:171], v[4:7]
	v_mfma_f32_16x16x32_bf16 v[0:3], v[164:167], v[172:175], v[0:3]
	s_waitcnt lgkmcnt(3)
	v_mfma_f32_16x16x32_bf16 v[60:63], v[204:207], v[208:211], v[60:63]
	v_mfma_f32_16x16x32_bf16 v[56:59], v[204:207], v[212:215], v[56:59]
	v_mfma_f32_16x16x32_bf16 v[52:55], v[204:207], v[216:219], v[52:55]
	v_mfma_f32_16x16x32_bf16 v[48:51], v[204:207], v[220:223], v[48:51]
	s_waitcnt lgkmcnt(2)
	v_mfma_f32_16x16x32_bf16 v[44:47], v[224:227], v[208:211], v[44:47]
	v_mfma_f32_16x16x32_bf16 v[40:43], v[224:227], v[212:215], v[40:43]
	v_mfma_f32_16x16x32_bf16 v[36:39], v[224:227], v[216:219], v[36:39]
	v_mfma_f32_16x16x32_bf16 v[32:35], v[224:227], v[220:223], v[32:35]
	s_waitcnt lgkmcnt(1)
	v_mfma_f32_16x16x32_bf16 v[28:31], v[228:231], v[208:211], v[28:31]
	v_mfma_f32_16x16x32_bf16 v[24:27], v[228:231], v[212:215], v[24:27]
	v_mfma_f32_16x16x32_bf16 v[20:23], v[228:231], v[216:219], v[20:23]
	v_mfma_f32_16x16x32_bf16 v[16:19], v[228:231], v[220:223], v[16:19]
	s_waitcnt lgkmcnt(0)
	v_mfma_f32_16x16x32_bf16 v[12:15], v[232:235], v[208:211], v[12:15]
	v_mfma_f32_16x16x32_bf16 v[8:11], v[232:235], v[212:215], v[8:11]
	v_mfma_f32_16x16x32_bf16 v[4:7], v[232:235], v[216:219], v[4:7]
	v_mfma_f32_16x16x32_bf16 v[0:3], v[232:235], v[220:223], v[0:3]
	s_setprio 0
	s_cmpk_eq_i32 s4, 0x780
	s_waitcnt vmcnt(0)
	s_barrier
	s_cbranch_scc0 .LBB0_278
	ds_read_b128 v[96:99], v123 offset:55296
	ds_read_b128 v[100:103], v123 offset:53248
	ds_read_b128 v[104:107], v124 offset:38912
	ds_read_b128 v[108:111], v124 offset:36864
	ds_read_b128 v[144:147], v123 offset:51200
	ds_read_b128 v[148:151], v123 offset:49152
	ds_read_b128 v[152:155], v124 offset:34816
	ds_read_b128 v[156:159], v124 offset:32768
	s_setprio 1
	s_waitcnt lgkmcnt(3)
	v_mfma_f32_16x16x32_bf16 v[24:27], v[108:111], v[144:147], v[24:27]
	v_mfma_f32_16x16x32_bf16 v[20:23], v[108:111], v[100:103], v[20:23]
	v_mfma_f32_16x16x32_bf16 v[16:19], v[108:111], v[96:99], v[16:19]
	s_waitcnt lgkmcnt(0)
	v_mfma_f32_16x16x32_bf16 v[60:63], v[156:159], v[148:151], v[60:63]
	v_mfma_f32_16x16x32_bf16 v[56:59], v[156:159], v[144:147], v[56:59]
	v_mfma_f32_16x16x32_bf16 v[52:55], v[156:159], v[100:103], v[52:55]
	v_mfma_f32_16x16x32_bf16 v[48:51], v[156:159], v[96:99], v[48:51]
	v_mfma_f32_16x16x32_bf16 v[44:47], v[152:155], v[148:151], v[44:47]
	v_mfma_f32_16x16x32_bf16 v[40:43], v[152:155], v[144:147], v[40:43]
	v_mfma_f32_16x16x32_bf16 v[36:39], v[152:155], v[100:103], v[36:39]
	v_mfma_f32_16x16x32_bf16 v[32:35], v[152:155], v[96:99], v[32:35]
	v_mfma_f32_16x16x32_bf16 v[28:31], v[108:111], v[148:151], v[28:31]
	v_mfma_f32_16x16x32_bf16 v[12:15], v[104:107], v[148:151], v[12:15]
	v_mfma_f32_16x16x32_bf16 v[8:11], v[104:107], v[144:147], v[8:11]
	v_mfma_f32_16x16x32_bf16 v[4:7], v[104:107], v[100:103], v[4:7]
	v_mfma_f32_16x16x32_bf16 v[0:3], v[104:107], v[96:99], v[0:3]
	s_setprio 0
	ds_read_b128 v[96:99], v125 offset:32768
	ds_read_b128 v[100:103], v125 offset:34816
	ds_read_b128 v[104:107], v126 offset:49152
	ds_read_b128 v[108:111], v126 offset:51200
	ds_read_b128 v[144:147], v125 offset:36864
	ds_read_b128 v[148:151], v125 offset:38912
	ds_read_b128 v[152:155], v126 offset:53248
	ds_read_b128 v[156:159], v126 offset:55296
	s_setprio 1
	s_waitcnt lgkmcnt(3)
	v_mfma_f32_16x16x32_bf16 v[24:27], v[144:147], v[108:111], v[24:27]
	s_waitcnt lgkmcnt(1)
	v_mfma_f32_16x16x32_bf16 v[20:23], v[144:147], v[152:155], v[20:23]
	s_waitcnt lgkmcnt(0)
	v_mfma_f32_16x16x32_bf16 v[16:19], v[144:147], v[156:159], v[16:19]
	v_mfma_f32_16x16x32_bf16 v[60:63], v[96:99], v[104:107], v[60:63]
	v_mfma_f32_16x16x32_bf16 v[56:59], v[96:99], v[108:111], v[56:59]
	v_mfma_f32_16x16x32_bf16 v[52:55], v[96:99], v[152:155], v[52:55]
	v_mfma_f32_16x16x32_bf16 v[48:51], v[96:99], v[156:159], v[48:51]
	v_mfma_f32_16x16x32_bf16 v[44:47], v[100:103], v[104:107], v[44:47]
	v_mfma_f32_16x16x32_bf16 v[40:43], v[100:103], v[108:111], v[40:43]
	v_mfma_f32_16x16x32_bf16 v[36:39], v[100:103], v[152:155], v[36:39]
	v_mfma_f32_16x16x32_bf16 v[32:35], v[100:103], v[156:159], v[32:35]
	v_mfma_f32_16x16x32_bf16 v[28:31], v[144:147], v[104:107], v[28:31]
	v_mfma_f32_16x16x32_bf16 v[12:15], v[148:151], v[104:107], v[12:15]
	v_mfma_f32_16x16x32_bf16 v[8:11], v[148:151], v[108:111], v[8:11]
	v_mfma_f32_16x16x32_bf16 v[4:7], v[148:151], v[152:155], v[4:7]
	v_mfma_f32_16x16x32_bf16 v[0:3], v[148:151], v[156:159], v[0:3]
	s_setprio 0
	s_barrier
	ds_write2_b32 v127, v60, v56 offset1:16
	ds_write2_b32 v127, v61, v57 offset0:132 offset1:148
	v_add_u32_e32 v56, 0x400, v127
	ds_write2_b32 v56, v62, v58 offset0:8 offset1:24
	ds_write2_b32 v56, v63, v59 offset0:140 offset1:156
	ds_write2_b32 v127, v52, v48 offset0:32 offset1:48
	ds_write2_b32 v127, v53, v49 offset0:164 offset1:180
	ds_write2_b32 v56, v54, v50 offset0:40 offset1:56
	ds_write2_b32 v56, v55, v51 offset0:172 offset1:188
	v_add_u32_e32 v48, 0x2000, v127
	ds_write2_b32 v48, v44, v40 offset0:64 offset1:80
	ds_write2_b32 v48, v45, v41 offset0:196 offset1:212
	v_add_u32_e32 v40, 0x2400, v127
	ds_write2_b32 v40, v46, v42 offset0:72 offset1:88
	ds_write2_b32 v40, v47, v43 offset0:204 offset1:220
	ds_write2_b32 v48, v36, v32 offset0:96 offset1:112
	ds_write2_b32 v48, v37, v33 offset0:228 offset1:244
	ds_write2_b32 v40, v38, v34 offset0:104 offset1:120
	ds_write2_b32 v40, v39, v35 offset0:236 offset1:252
	v_add_u32_e32 v32, 0x4000, v127
	ds_write2_b32 v32, v28, v24 offset0:128 offset1:144
	v_add_u32_e32 v24, 0x4400, v127
	ds_write2_b32 v24, v29, v25 offset0:4 offset1:20
	ds_write2_b32 v24, v30, v26 offset0:136 offset1:152
	v_add_u32_e32 v25, 0x4800, v127
	ds_write2_b32 v25, v31, v27 offset0:12 offset1:28
	ds_write2_b32 v32, v20, v16 offset0:160 offset1:176
	ds_write2_b32 v24, v21, v17 offset0:36 offset1:52
	ds_write2_b32 v24, v22, v18 offset0:168 offset1:184
	ds_write2_b32 v25, v23, v19 offset0:44 offset1:60
	v_add_u32_e32 v16, 0x6000, v127
	ds_write2_b32 v16, v12, v8 offset0:192 offset1:208
	v_add_u32_e32 v8, 0x6400, v127
	ds_write2_b32 v8, v13, v9 offset0:68 offset1:84
	ds_write2_b32 v8, v14, v10 offset0:200 offset1:216
	v_add_u32_e32 v9, 0x6800, v127
	v_or_b32_e32 v64, s6, v128
	ds_write2_b32 v9, v15, v11 offset0:76 offset1:92
	ds_write2_b32 v16, v4, v0 offset0:224 offset1:240
	ds_write2_b32 v8, v5, v1 offset0:100 offset1:116
	ds_write2_b32 v8, v6, v2 offset0:232 offset1:248
	ds_write2_b32 v9, v7, v3 offset0:108 offset1:124
	v_ashrrev_i32_e32 v1, 31, v64
	v_mov_b32_e32 v0, v64
	v_lshlrev_b64 v[2:3], 1, v[64:65]
	v_lshl_add_u64 v[20:21], v[0:1], 1, s[10:11]
	v_mov_b32_e32 v0, s15
	v_mov_b32_e32 v1, s13
	v_cmp_gt_i32_e64 s[8:9], s24, v64
	v_lshl_add_u64 v[16:17], s[18:19], 0, v[2:3]
	v_lshl_add_u64 v[18:19], s[16:17], 0, v[2:3]
	v_cndmask_b32_e64 v1, v0, v1, s[8:9]
	v_mov_b32_e32 v0, s14
	v_mov_b32_e32 v2, s12
	v_cndmask_b32_e64 v0, v0, v2, s[8:9]
	v_mov_b32_e32 v95, v65
	v_cmp_lt_i32_e64 s[4:5], s26, v64
	v_cmp_lt_i32_e64 s[6:7], s27, v64
	v_lshl_add_u64 v[22:23], v[0:1], 0, v[94:95]
	v_add_u32_e32 v24, v132, v143
	s_mov_b32 s35, 0
	s_waitcnt lgkmcnt(0)
	s_barrier
	s_branch .LBB0_282

.LBB0_423:
	s_and_b32 s25, s24, 0x4000
	s_xor_b32 s26, s25, 0x4000
	s_lshl_b32 s26, s26, 1
	s_add_i32 s26, s26, 32
	s_add_u32 s90, s52, s14
	s_addc_u32 s91, s53, s15
	s_add_i32 m0, s26, s82
	s_lshl_b32 s25, s25, 1
	global_load_lds_dwordx4 v188, s[90:91]
	s_add_i32 m0, s26, s83
	s_add_i32 s25, s25, 32
	global_load_lds_dwordx4 v189, s[90:91]
	s_add_i32 m0, s26, s84
	v_add3_u32 v170, s25, v114, v135
	global_load_lds_dwordx4 v190, s[90:91]
	s_add_i32 m0, s26, s85
	v_add3_u32 v171, s25, v115, v135
	global_load_lds_dwordx4 v191, s[90:91]
	s_add_i32 m0, s26, s86
	v_add_u32_e32 v158, v170, v136
	global_load_lds_dwordx4 v192, s[90:91]
	s_add_i32 m0, s26, s87
	v_add_u32_e32 v166, v171, v136
	global_load_lds_dwordx4 v193, s[90:91]
	s_add_i32 m0, s26, s88
	s_addk_i32 s24, 0x4000
	global_load_lds_dwordx4 v194, s[90:91]
	s_add_i32 m0, s26, s89
	s_add_u32 s14, s14, 0x80
	s_addc_u32 s15, s15, 0
	global_load_lds_dwordx4 v195, s[90:91]
	ds_read_b128 v[138:141], v158
	ds_read_b128 v[146:149], v166 offset:16384
	ds_read_b128 v[150:153], v166 offset:18432
	ds_read_b128 v[162:165], v166 offset:20480
	ds_read_b128 v[166:169], v166 offset:22528
	ds_read_b128 v[142:145], v158 offset:2048
	ds_read_b128 v[154:157], v158 offset:4096
	ds_read_b128 v[158:161], v158 offset:6144
	v_add_u32_e32 v236, v170, v137
	v_add_u32_e32 v237, v171, v137
	ds_read_b128 v[204:207], v236
	ds_read_b128 v[208:211], v237 offset:16384
	ds_read_b128 v[212:215], v237 offset:18432
	ds_read_b128 v[216:219], v237 offset:20480
	ds_read_b128 v[220:223], v237 offset:22528
	ds_read_b128 v[224:227], v236 offset:2048
	ds_read_b128 v[228:231], v236 offset:4096
	ds_read_b128 v[232:235], v236 offset:6144
	s_setprio 1
	s_waitcnt lgkmcnt(11)
	v_mfma_f32_16x16x32_bf16 v[60:63], v[138:141], v[146:149], v[60:63]
	v_mfma_f32_16x16x32_bf16 v[56:59], v[138:141], v[150:153], v[56:59]
	v_mfma_f32_16x16x32_bf16 v[52:55], v[138:141], v[162:165], v[52:55]
	v_mfma_f32_16x16x32_bf16 v[48:51], v[138:141], v[166:169], v[48:51]
	s_waitcnt lgkmcnt(10)
	v_mfma_f32_16x16x32_bf16 v[44:47], v[142:145], v[146:149], v[44:47]
	v_mfma_f32_16x16x32_bf16 v[40:43], v[142:145], v[150:153], v[40:43]
	v_mfma_f32_16x16x32_bf16 v[36:39], v[142:145], v[162:165], v[36:39]
	v_mfma_f32_16x16x32_bf16 v[32:35], v[142:145], v[166:169], v[32:35]
	s_waitcnt lgkmcnt(9)
	v_mfma_f32_16x16x32_bf16 v[28:31], v[154:157], v[146:149], v[28:31]
	v_mfma_f32_16x16x32_bf16 v[24:27], v[154:157], v[150:153], v[24:27]
	v_mfma_f32_16x16x32_bf16 v[20:23], v[154:157], v[162:165], v[20:23]
	v_mfma_f32_16x16x32_bf16 v[16:19], v[154:157], v[166:169], v[16:19]
	s_waitcnt lgkmcnt(8)
	v_mfma_f32_16x16x32_bf16 v[12:15], v[158:161], v[146:149], v[12:15]
	v_mfma_f32_16x16x32_bf16 v[8:11], v[158:161], v[150:153], v[8:11]
	v_mfma_f32_16x16x32_bf16 v[4:7], v[158:161], v[162:165], v[4:7]
	v_mfma_f32_16x16x32_bf16 v[0:3], v[158:161], v[166:169], v[0:3]
	s_waitcnt lgkmcnt(3)
	v_mfma_f32_16x16x32_bf16 v[60:63], v[204:207], v[208:211], v[60:63]
	v_mfma_f32_16x16x32_bf16 v[56:59], v[204:207], v[212:215], v[56:59]
	v_mfma_f32_16x16x32_bf16 v[52:55], v[204:207], v[216:219], v[52:55]
	v_mfma_f32_16x16x32_bf16 v[48:51], v[204:207], v[220:223], v[48:51]
	s_waitcnt lgkmcnt(2)
	v_mfma_f32_16x16x32_bf16 v[44:47], v[224:227], v[208:211], v[44:47]
	v_mfma_f32_16x16x32_bf16 v[40:43], v[224:227], v[212:215], v[40:43]
	v_mfma_f32_16x16x32_bf16 v[36:39], v[224:227], v[216:219], v[36:39]
	v_mfma_f32_16x16x32_bf16 v[32:35], v[224:227], v[220:223], v[32:35]
	s_waitcnt lgkmcnt(1)
	v_mfma_f32_16x16x32_bf16 v[28:31], v[228:231], v[208:211], v[28:31]
	v_mfma_f32_16x16x32_bf16 v[24:27], v[228:231], v[212:215], v[24:27]
	v_mfma_f32_16x16x32_bf16 v[20:23], v[228:231], v[216:219], v[20:23]
	v_mfma_f32_16x16x32_bf16 v[16:19], v[228:231], v[220:223], v[16:19]
	s_waitcnt lgkmcnt(0)
	v_mfma_f32_16x16x32_bf16 v[12:15], v[232:235], v[208:211], v[12:15]
	v_mfma_f32_16x16x32_bf16 v[8:11], v[232:235], v[212:215], v[8:11]
	v_mfma_f32_16x16x32_bf16 v[4:7], v[232:235], v[216:219], v[4:7]
	v_mfma_f32_16x16x32_bf16 v[0:3], v[232:235], v[220:223], v[0:3]
	s_setprio 0
	s_cmpk_eq_i32 s14, 0x780
	s_waitcnt vmcnt(0)
	s_barrier
	s_cbranch_scc0 .LBB0_423
	ds_read_b128 v[90:93], v118 offset:55296
	ds_read_b128 v[94:97], v118 offset:53248
	ds_read_b128 v[98:101], v119 offset:38912
	ds_read_b128 v[102:105], v119 offset:36864
	ds_read_b128 v[138:141], v118 offset:51200
	ds_read_b128 v[142:145], v118 offset:49152
	ds_read_b128 v[146:149], v119 offset:34816
	ds_read_b128 v[150:153], v119 offset:32768
	s_setprio 1
	s_waitcnt lgkmcnt(5)
	v_mfma_f32_16x16x32_bf16 v[4:7], v[98:101], v[94:97], v[4:7]
	v_mfma_f32_16x16x32_bf16 v[0:3], v[98:101], v[90:93], v[0:3]
	s_waitcnt lgkmcnt(0)
	v_mfma_f32_16x16x32_bf16 v[60:63], v[150:153], v[142:145], v[60:63]
	v_mfma_f32_16x16x32_bf16 v[56:59], v[150:153], v[138:141], v[56:59]
	v_mfma_f32_16x16x32_bf16 v[52:55], v[150:153], v[94:97], v[52:55]
	v_mfma_f32_16x16x32_bf16 v[48:51], v[150:153], v[90:93], v[48:51]
	v_mfma_f32_16x16x32_bf16 v[44:47], v[146:149], v[142:145], v[44:47]
	v_mfma_f32_16x16x32_bf16 v[40:43], v[146:149], v[138:141], v[40:43]
	v_mfma_f32_16x16x32_bf16 v[36:39], v[146:149], v[94:97], v[36:39]
	v_mfma_f32_16x16x32_bf16 v[32:35], v[146:149], v[90:93], v[32:35]
	v_mfma_f32_16x16x32_bf16 v[28:31], v[102:105], v[142:145], v[28:31]
	v_mfma_f32_16x16x32_bf16 v[24:27], v[102:105], v[138:141], v[24:27]
	v_mfma_f32_16x16x32_bf16 v[20:23], v[102:105], v[94:97], v[20:23]
	v_mfma_f32_16x16x32_bf16 v[16:19], v[102:105], v[90:93], v[16:19]
	v_mfma_f32_16x16x32_bf16 v[12:15], v[98:101], v[142:145], v[12:15]
	v_mfma_f32_16x16x32_bf16 v[8:11], v[98:101], v[138:141], v[8:11]
	s_setprio 0
	ds_read_b128 v[90:93], v120 offset:32768
	ds_read_b128 v[94:97], v120 offset:34816
	ds_read_b128 v[98:101], v121 offset:49152
	ds_read_b128 v[102:105], v121 offset:51200
	ds_read_b128 v[138:141], v120 offset:36864
	ds_read_b128 v[142:145], v120 offset:38912
	ds_read_b128 v[146:149], v121 offset:53248
	ds_read_b128 v[150:153], v121 offset:55296
	s_setprio 1
	s_waitcnt lgkmcnt(1)
	v_mfma_f32_16x16x32_bf16 v[4:7], v[142:145], v[146:149], v[4:7]
	s_waitcnt lgkmcnt(0)
	v_mfma_f32_16x16x32_bf16 v[0:3], v[142:145], v[150:153], v[0:3]
	v_mfma_f32_16x16x32_bf16 v[60:63], v[90:93], v[98:101], v[60:63]
	v_mfma_f32_16x16x32_bf16 v[56:59], v[90:93], v[102:105], v[56:59]
	v_mfma_f32_16x16x32_bf16 v[52:55], v[90:93], v[146:149], v[52:55]
	v_mfma_f32_16x16x32_bf16 v[48:51], v[90:93], v[150:153], v[48:51]
	v_mfma_f32_16x16x32_bf16 v[44:47], v[94:97], v[98:101], v[44:47]
	v_mfma_f32_16x16x32_bf16 v[40:43], v[94:97], v[102:105], v[40:43]
	v_mfma_f32_16x16x32_bf16 v[36:39], v[94:97], v[146:149], v[36:39]
	v_mfma_f32_16x16x32_bf16 v[32:35], v[94:97], v[150:153], v[32:35]
	v_mfma_f32_16x16x32_bf16 v[28:31], v[138:141], v[98:101], v[28:31]
	v_mfma_f32_16x16x32_bf16 v[24:27], v[138:141], v[102:105], v[24:27]
	v_mfma_f32_16x16x32_bf16 v[20:23], v[138:141], v[146:149], v[20:23]
	v_mfma_f32_16x16x32_bf16 v[16:19], v[138:141], v[150:153], v[16:19]
	v_mfma_f32_16x16x32_bf16 v[12:15], v[142:145], v[98:101], v[12:15]
	v_mfma_f32_16x16x32_bf16 v[8:11], v[142:145], v[102:105], v[8:11]
	s_setprio 0
	s_barrier
	ds_write2_b32 v116, v60, v56 offset1:16
	ds_write2_b32 v116, v61, v57 offset0:132 offset1:148
	v_add_u32_e32 v56, 0x400, v116
	ds_write2_b32 v56, v62, v58 offset0:8 offset1:24
	ds_write2_b32 v56, v63, v59 offset0:140 offset1:156
	ds_write2_b32 v116, v52, v48 offset0:32 offset1:48
	ds_write2_b32 v116, v53, v49 offset0:164 offset1:180
	ds_write2_b32 v56, v54, v50 offset0:40 offset1:56
	ds_write2_b32 v56, v55, v51 offset0:172 offset1:188
	v_add_u32_e32 v48, 0x2000, v116
	ds_write2_b32 v48, v44, v40 offset0:64 offset1:80
	ds_write2_b32 v48, v45, v41 offset0:196 offset1:212
	v_add_u32_e32 v40, 0x2400, v116
	ds_write2_b32 v40, v46, v42 offset0:72 offset1:88
	ds_write2_b32 v40, v47, v43 offset0:204 offset1:220
	ds_write2_b32 v48, v36, v32 offset0:96 offset1:112
	ds_write2_b32 v48, v37, v33 offset0:228 offset1:244
	ds_write2_b32 v40, v38, v34 offset0:104 offset1:120
	ds_write2_b32 v40, v39, v35 offset0:236 offset1:252
	v_add_u32_e32 v32, 0x4000, v116
	ds_write2_b32 v32, v28, v24 offset0:128 offset1:144
	v_add_u32_e32 v24, 0x4400, v116
	ds_write2_b32 v24, v29, v25 offset0:4 offset1:20
	ds_write2_b32 v24, v30, v26 offset0:136 offset1:152
	v_add_u32_e32 v25, 0x4800, v116
	ds_write2_b32 v25, v31, v27 offset0:12 offset1:28
	ds_write2_b32 v32, v20, v16 offset0:160 offset1:176
	ds_write2_b32 v24, v21, v17 offset0:36 offset1:52
	ds_write2_b32 v24, v22, v18 offset0:168 offset1:184
	ds_write2_b32 v25, v23, v19 offset0:44 offset1:60
	v_add_u32_e32 v16, 0x6000, v116
	ds_write2_b32 v16, v12, v8 offset0:192 offset1:208
	v_add_u32_e32 v8, 0x6400, v116
	ds_write2_b32 v8, v13, v9 offset0:68 offset1:84
	ds_write2_b32 v8, v14, v10 offset0:200 offset1:216
	v_add_u32_e32 v9, 0x6800, v116
	ds_write2_b32 v9, v15, v11 offset0:76 offset1:92
	ds_write2_b32 v16, v4, v0 offset0:224 offset1:240
	ds_write2_b32 v8, v5, v1 offset0:100 offset1:116
	ds_write2_b32 v8, v6, v2 offset0:232 offset1:248
	ds_write2_b32 v9, v7, v3 offset0:108 offset1:124
	v_or_b32_e32 v0, s23, v117
	v_ashrrev_i32_e32 v1, 31, v0
	v_lshlrev_b64 v[2:3], 2, v[0:1]
	v_lshl_add_u64 v[0:1], s[12:13], 0, v[2:3]
	v_lshl_add_u64 v[2:3], s[8:9], 0, v[2:3]
	v_add_u32_e32 v4, s22, v128
	s_mov_b32 s14, 0
	s_waitcnt lgkmcnt(0)
	s_barrier

.LBB0_432:
	s_and_b32 s26, s25, 0x4000
	s_xor_b32 s27, s26, 0x4000
	s_lshl_b32 s27, s27, 1
	s_add_i32 s27, s27, 32
	s_add_u32 s90, s52, s14
	s_addc_u32 s91, s53, s15
	s_add_i32 m0, s27, s82
	s_lshl_b32 s26, s26, 1
	global_load_lds_dwordx4 v188, s[90:91]
	s_add_i32 m0, s27, s83
	s_add_i32 s26, s26, 32
	global_load_lds_dwordx4 v189, s[90:91]
	s_add_i32 m0, s27, s84
	v_add3_u32 v139, s26, v113, v136
	global_load_lds_dwordx4 v190, s[90:91]
	s_add_i32 m0, s27, s85
	v_add3_u32 v172, s26, v114, v136
	global_load_lds_dwordx4 v191, s[90:91]
	s_add_i32 m0, s27, s86
	v_add_u32_e32 v160, v139, v137
	global_load_lds_dwordx4 v192, s[90:91]
	s_add_i32 m0, s27, s87
	v_add_u32_e32 v168, v172, v137
	global_load_lds_dwordx4 v193, s[90:91]
	s_add_i32 m0, s27, s88
	s_addk_i32 s25, 0x4000
	global_load_lds_dwordx4 v194, s[90:91]
	s_add_i32 m0, s27, s89
	s_add_u32 s14, s14, 0x80
	s_addc_u32 s15, s15, 0
	global_load_lds_dwordx4 v195, s[90:91]
	ds_read_b128 v[140:143], v160
	ds_read_b128 v[148:151], v168 offset:16384
	ds_read_b128 v[152:155], v168 offset:18432
	ds_read_b128 v[164:167], v168 offset:20480
	ds_read_b128 v[168:171], v168 offset:22528
	ds_read_b128 v[144:147], v160 offset:2048
	ds_read_b128 v[156:159], v160 offset:4096
	ds_read_b128 v[160:163], v160 offset:6144
	v_add_u32_e32 v139, v139, v138
	v_add_u32_e32 v236, v172, v138
	ds_read_b128 v[204:207], v139
	ds_read_b128 v[208:211], v236 offset:16384
	ds_read_b128 v[212:215], v236 offset:18432
	ds_read_b128 v[216:219], v236 offset:20480
	ds_read_b128 v[220:223], v236 offset:22528
	ds_read_b128 v[224:227], v139 offset:2048
	ds_read_b128 v[228:231], v139 offset:4096
	ds_read_b128 v[232:235], v139 offset:6144
	s_setprio 1
	s_waitcnt lgkmcnt(11)
	v_mfma_f32_16x16x32_bf16 v[60:63], v[140:143], v[148:151], v[60:63]
	v_mfma_f32_16x16x32_bf16 v[56:59], v[140:143], v[152:155], v[56:59]
	v_mfma_f32_16x16x32_bf16 v[52:55], v[140:143], v[164:167], v[52:55]
	v_mfma_f32_16x16x32_bf16 v[48:51], v[140:143], v[168:171], v[48:51]
	s_waitcnt lgkmcnt(10)
	v_mfma_f32_16x16x32_bf16 v[44:47], v[144:147], v[148:151], v[44:47]
	v_mfma_f32_16x16x32_bf16 v[40:43], v[144:147], v[152:155], v[40:43]
	v_mfma_f32_16x16x32_bf16 v[36:39], v[144:147], v[164:167], v[36:39]
	v_mfma_f32_16x16x32_bf16 v[32:35], v[144:147], v[168:171], v[32:35]
	s_waitcnt lgkmcnt(9)
	v_mfma_f32_16x16x32_bf16 v[28:31], v[156:159], v[148:151], v[28:31]
	v_mfma_f32_16x16x32_bf16 v[24:27], v[156:159], v[152:155], v[24:27]
	v_mfma_f32_16x16x32_bf16 v[20:23], v[156:159], v[164:167], v[20:23]
	v_mfma_f32_16x16x32_bf16 v[16:19], v[156:159], v[168:171], v[16:19]
	s_waitcnt lgkmcnt(8)
	v_mfma_f32_16x16x32_bf16 v[12:15], v[160:163], v[148:151], v[12:15]
	v_mfma_f32_16x16x32_bf16 v[8:11], v[160:163], v[152:155], v[8:11]
	v_mfma_f32_16x16x32_bf16 v[4:7], v[160:163], v[164:167], v[4:7]
	v_mfma_f32_16x16x32_bf16 v[0:3], v[160:163], v[168:171], v[0:3]
	s_waitcnt lgkmcnt(3)
	v_mfma_f32_16x16x32_bf16 v[60:63], v[204:207], v[208:211], v[60:63]
	v_mfma_f32_16x16x32_bf16 v[56:59], v[204:207], v[212:215], v[56:59]
	v_mfma_f32_16x16x32_bf16 v[52:55], v[204:207], v[216:219], v[52:55]
	v_mfma_f32_16x16x32_bf16 v[48:51], v[204:207], v[220:223], v[48:51]
	s_waitcnt lgkmcnt(2)
	v_mfma_f32_16x16x32_bf16 v[44:47], v[224:227], v[208:211], v[44:47]
	v_mfma_f32_16x16x32_bf16 v[40:43], v[224:227], v[212:215], v[40:43]
	v_mfma_f32_16x16x32_bf16 v[36:39], v[224:227], v[216:219], v[36:39]
	v_mfma_f32_16x16x32_bf16 v[32:35], v[224:227], v[220:223], v[32:35]
	s_waitcnt lgkmcnt(1)
	v_mfma_f32_16x16x32_bf16 v[28:31], v[228:231], v[208:211], v[28:31]
	v_mfma_f32_16x16x32_bf16 v[24:27], v[228:231], v[212:215], v[24:27]
	v_mfma_f32_16x16x32_bf16 v[20:23], v[228:231], v[216:219], v[20:23]
	v_mfma_f32_16x16x32_bf16 v[16:19], v[228:231], v[220:223], v[16:19]
	s_waitcnt lgkmcnt(0)
	v_mfma_f32_16x16x32_bf16 v[12:15], v[232:235], v[208:211], v[12:15]
	v_mfma_f32_16x16x32_bf16 v[8:11], v[232:235], v[212:215], v[8:11]
	v_mfma_f32_16x16x32_bf16 v[4:7], v[232:235], v[216:219], v[4:7]
	v_mfma_f32_16x16x32_bf16 v[0:3], v[232:235], v[220:223], v[0:3]
	s_setprio 0
	s_cmpk_eq_i32 s14, 0x780
	s_waitcnt vmcnt(0)
	s_barrier
	s_cbranch_scc0 .LBB0_432
	ds_read_b128 v[88:91], v117 offset:55296
	ds_read_b128 v[92:95], v117 offset:53248
	ds_read_b128 v[96:99], v118 offset:38912
	ds_read_b128 v[100:103], v118 offset:36864
	ds_read_b128 v[140:143], v117 offset:51200
	ds_read_b128 v[144:147], v117 offset:49152
	ds_read_b128 v[148:151], v118 offset:34816
	ds_read_b128 v[152:155], v118 offset:32768
	s_setprio 1
	s_waitcnt lgkmcnt(5)
	v_mfma_f32_16x16x32_bf16 v[4:7], v[96:99], v[92:95], v[4:7]
	v_mfma_f32_16x16x32_bf16 v[0:3], v[96:99], v[88:91], v[0:3]
	s_waitcnt lgkmcnt(0)
	v_mfma_f32_16x16x32_bf16 v[60:63], v[152:155], v[144:147], v[60:63]
	v_mfma_f32_16x16x32_bf16 v[56:59], v[152:155], v[140:143], v[56:59]
	v_mfma_f32_16x16x32_bf16 v[52:55], v[152:155], v[92:95], v[52:55]
	v_mfma_f32_16x16x32_bf16 v[48:51], v[152:155], v[88:91], v[48:51]
	v_mfma_f32_16x16x32_bf16 v[44:47], v[148:151], v[144:147], v[44:47]
	v_mfma_f32_16x16x32_bf16 v[40:43], v[148:151], v[140:143], v[40:43]
	v_mfma_f32_16x16x32_bf16 v[36:39], v[148:151], v[92:95], v[36:39]
	v_mfma_f32_16x16x32_bf16 v[32:35], v[148:151], v[88:91], v[32:35]
	v_mfma_f32_16x16x32_bf16 v[28:31], v[100:103], v[144:147], v[28:31]
	v_mfma_f32_16x16x32_bf16 v[24:27], v[100:103], v[140:143], v[24:27]
	v_mfma_f32_16x16x32_bf16 v[20:23], v[100:103], v[92:95], v[20:23]
	v_mfma_f32_16x16x32_bf16 v[16:19], v[100:103], v[88:91], v[16:19]
	v_mfma_f32_16x16x32_bf16 v[12:15], v[96:99], v[144:147], v[12:15]
	v_mfma_f32_16x16x32_bf16 v[8:11], v[96:99], v[140:143], v[8:11]
	s_setprio 0
	ds_read_b128 v[88:91], v119 offset:32768
	ds_read_b128 v[92:95], v119 offset:34816
	ds_read_b128 v[96:99], v120 offset:49152
	ds_read_b128 v[100:103], v120 offset:51200
	ds_read_b128 v[140:143], v119 offset:36864
	ds_read_b128 v[144:147], v119 offset:38912
	ds_read_b128 v[148:151], v120 offset:53248
	ds_read_b128 v[152:155], v120 offset:55296
	s_setprio 1
	s_waitcnt lgkmcnt(1)
	v_mfma_f32_16x16x32_bf16 v[4:7], v[144:147], v[148:151], v[4:7]
	s_waitcnt lgkmcnt(0)
	v_mfma_f32_16x16x32_bf16 v[0:3], v[144:147], v[152:155], v[0:3]
	v_mfma_f32_16x16x32_bf16 v[60:63], v[88:91], v[96:99], v[60:63]
	v_mfma_f32_16x16x32_bf16 v[56:59], v[88:91], v[100:103], v[56:59]
	v_mfma_f32_16x16x32_bf16 v[52:55], v[88:91], v[148:151], v[52:55]
	v_mfma_f32_16x16x32_bf16 v[48:51], v[88:91], v[152:155], v[48:51]
	v_mfma_f32_16x16x32_bf16 v[44:47], v[92:95], v[96:99], v[44:47]
	v_mfma_f32_16x16x32_bf16 v[40:43], v[92:95], v[100:103], v[40:43]
	v_mfma_f32_16x16x32_bf16 v[36:39], v[92:95], v[148:151], v[36:39]
	v_mfma_f32_16x16x32_bf16 v[32:35], v[92:95], v[152:155], v[32:35]
	v_mfma_f32_16x16x32_bf16 v[28:31], v[140:143], v[96:99], v[28:31]
	v_mfma_f32_16x16x32_bf16 v[24:27], v[140:143], v[100:103], v[24:27]
	v_mfma_f32_16x16x32_bf16 v[20:23], v[140:143], v[148:151], v[20:23]
	v_mfma_f32_16x16x32_bf16 v[16:19], v[140:143], v[152:155], v[16:19]
	v_mfma_f32_16x16x32_bf16 v[12:15], v[144:147], v[96:99], v[12:15]
	v_mfma_f32_16x16x32_bf16 v[8:11], v[144:147], v[100:103], v[8:11]
	s_setprio 0
	s_barrier
	ds_write2_b32 v115, v60, v56 offset1:16
	ds_write2_b32 v115, v61, v57 offset0:132 offset1:148
	v_add_u32_e32 v56, 0x400, v115
	ds_write2_b32 v56, v62, v58 offset0:8 offset1:24
	ds_write2_b32 v56, v63, v59 offset0:140 offset1:156
	ds_write2_b32 v115, v52, v48 offset0:32 offset1:48
	ds_write2_b32 v115, v53, v49 offset0:164 offset1:180
	ds_write2_b32 v56, v54, v50 offset0:40 offset1:56
	ds_write2_b32 v56, v55, v51 offset0:172 offset1:188
	v_add_u32_e32 v48, 0x2000, v115
	ds_write2_b32 v48, v44, v40 offset0:64 offset1:80
	ds_write2_b32 v48, v45, v41 offset0:196 offset1:212
	v_add_u32_e32 v40, 0x2400, v115
	ds_write2_b32 v40, v46, v42 offset0:72 offset1:88
	ds_write2_b32 v40, v47, v43 offset0:204 offset1:220
	ds_write2_b32 v48, v36, v32 offset0:96 offset1:112
	ds_write2_b32 v48, v37, v33 offset0:228 offset1:244
	ds_write2_b32 v40, v38, v34 offset0:104 offset1:120
	ds_write2_b32 v40, v39, v35 offset0:236 offset1:252
	v_add_u32_e32 v32, 0x4000, v115
	ds_write2_b32 v32, v28, v24 offset0:128 offset1:144
	v_add_u32_e32 v24, 0x4400, v115
	ds_write2_b32 v24, v29, v25 offset0:4 offset1:20
	ds_write2_b32 v24, v30, v26 offset0:136 offset1:152
	v_add_u32_e32 v25, 0x4800, v115
	ds_write2_b32 v25, v31, v27 offset0:12 offset1:28
	ds_write2_b32 v32, v20, v16 offset0:160 offset1:176
	ds_write2_b32 v24, v21, v17 offset0:36 offset1:52
	ds_write2_b32 v24, v22, v18 offset0:168 offset1:184
	ds_write2_b32 v25, v23, v19 offset0:44 offset1:60
	v_add_u32_e32 v16, 0x6000, v115
	ds_write2_b32 v16, v12, v8 offset0:192 offset1:208
	v_add_u32_e32 v8, 0x6400, v115
	ds_write2_b32 v8, v13, v9 offset0:68 offset1:84
	ds_write2_b32 v8, v14, v10 offset0:200 offset1:216
	v_add_u32_e32 v9, 0x6800, v115
	ds_write2_b32 v9, v15, v11 offset0:76 offset1:92
	ds_write2_b32 v16, v4, v0 offset0:224 offset1:240
	ds_write2_b32 v8, v5, v1 offset0:100 offset1:116
	ds_write2_b32 v8, v6, v2 offset0:232 offset1:248
	ds_write2_b32 v9, v7, v3 offset0:108 offset1:124
	v_or_b32_e32 v0, s23, v116
	v_ashrrev_i32_e32 v1, 31, v0
	v_lshlrev_b64 v[2:3], 2, v[0:1]
	v_lshl_add_u64 v[0:1], s[12:13], 0, v[2:3]
	v_lshl_add_u64 v[2:3], s[8:9], 0, v[2:3]
	v_add_u32_e32 v4, s24, v129
	s_mov_b32 s14, 0
	s_waitcnt lgkmcnt(0)
	s_barrier

.LBB0_443:
	s_and_b32 s25, s24, 0x4000
	s_xor_b32 s26, s25, 0x4000
	s_lshl_b32 s26, s26, 1
	s_add_i32 s26, s26, 32
	s_add_u32 s90, s52, s10
	s_addc_u32 s91, s53, s11
	s_add_i32 m0, s26, s82
	s_lshl_b32 s25, s25, 1
	global_load_lds_dwordx4 v189, s[90:91]
	s_add_i32 m0, s26, s83
	s_add_i32 s25, s25, 32
	global_load_lds_dwordx4 v190, s[90:91]
	s_add_i32 m0, s26, s84
	v_lshlrev_b32_e32 v70, 1, v129
	global_load_lds_dwordx4 v191, s[90:91]
	s_add_i32 m0, s26, s85
	v_add3_u32 v151, s25, v124, v70
	global_load_lds_dwordx4 v192, s[90:91]
	s_add_i32 m0, s26, s86
	v_lshlrev_b32_e32 v152, 1, v117
	global_load_lds_dwordx4 v193, s[90:91]
	s_add_i32 m0, s26, s87
	v_add3_u32 v70, s25, v125, v70
	global_load_lds_dwordx4 v194, s[90:91]
	s_add_i32 m0, s26, s88
	v_add_u32_e32 v172, v151, v152
	global_load_lds_dwordx4 v195, s[90:91]
	s_add_i32 m0, s26, s89
	v_add_u32_e32 v181, v70, v152
	global_load_lds_dwordx4 v196, s[90:91]
	ds_read_b128 v[152:155], v172
	ds_read_b128 v[160:163], v181 offset:16384
	ds_read_b128 v[164:167], v181 offset:18432
	ds_read_b128 v[176:179], v181 offset:20480
	ds_read_b128 v[182:185], v181 offset:22528
	ds_read_b128 v[156:159], v172 offset:2048
	ds_read_b128 v[168:171], v172 offset:4096
	ds_read_b128 v[172:175], v172 offset:6144
	v_lshlrev_b32_e32 v236, 1, v116
	v_add_u32_e32 v151, v151, v236
	v_add_u32_e32 v70, v70, v236
	ds_read_b128 v[204:207], v151
	ds_read_b128 v[208:211], v70 offset:16384
	ds_read_b128 v[212:215], v70 offset:18432
	ds_read_b128 v[216:219], v70 offset:20480
	ds_read_b128 v[220:223], v70 offset:22528
	ds_read_b128 v[224:227], v151 offset:2048
	ds_read_b128 v[228:231], v151 offset:4096
	ds_read_b128 v[232:235], v151 offset:6144
	s_setprio 1
	s_waitcnt lgkmcnt(11)
	v_mfma_f32_16x16x32_bf16 v[60:63], v[152:155], v[160:163], v[60:63]
	v_mfma_f32_16x16x32_bf16 v[56:59], v[152:155], v[164:167], v[56:59]
	v_mfma_f32_16x16x32_bf16 v[52:55], v[152:155], v[176:179], v[52:55]
	v_mfma_f32_16x16x32_bf16 v[48:51], v[152:155], v[182:185], v[48:51]
	s_waitcnt lgkmcnt(10)
	v_mfma_f32_16x16x32_bf16 v[44:47], v[156:159], v[160:163], v[44:47]
	v_mfma_f32_16x16x32_bf16 v[40:43], v[156:159], v[164:167], v[40:43]
	v_mfma_f32_16x16x32_bf16 v[36:39], v[156:159], v[176:179], v[36:39]
	v_mfma_f32_16x16x32_bf16 v[32:35], v[156:159], v[182:185], v[32:35]
	s_waitcnt lgkmcnt(9)
	v_mfma_f32_16x16x32_bf16 v[28:31], v[168:171], v[160:163], v[28:31]
	v_mfma_f32_16x16x32_bf16 v[24:27], v[168:171], v[164:167], v[24:27]
	v_mfma_f32_16x16x32_bf16 v[20:23], v[168:171], v[176:179], v[20:23]
	v_mfma_f32_16x16x32_bf16 v[16:19], v[168:171], v[182:185], v[16:19]
	s_waitcnt lgkmcnt(8)
	v_mfma_f32_16x16x32_bf16 v[12:15], v[172:175], v[160:163], v[12:15]
	v_mfma_f32_16x16x32_bf16 v[8:11], v[172:175], v[164:167], v[8:11]
	v_mfma_f32_16x16x32_bf16 v[4:7], v[172:175], v[176:179], v[4:7]
	v_mfma_f32_16x16x32_bf16 v[0:3], v[172:175], v[182:185], v[0:3]
	s_waitcnt lgkmcnt(3)
	v_mfma_f32_16x16x32_bf16 v[60:63], v[204:207], v[208:211], v[60:63]
	v_mfma_f32_16x16x32_bf16 v[56:59], v[204:207], v[212:215], v[56:59]
	v_mfma_f32_16x16x32_bf16 v[52:55], v[204:207], v[216:219], v[52:55]
	v_mfma_f32_16x16x32_bf16 v[48:51], v[204:207], v[220:223], v[48:51]
	s_waitcnt lgkmcnt(2)
	v_mfma_f32_16x16x32_bf16 v[44:47], v[224:227], v[208:211], v[44:47]
	v_mfma_f32_16x16x32_bf16 v[40:43], v[224:227], v[212:215], v[40:43]
	v_mfma_f32_16x16x32_bf16 v[36:39], v[224:227], v[216:219], v[36:39]
	v_mfma_f32_16x16x32_bf16 v[32:35], v[224:227], v[220:223], v[32:35]
	s_waitcnt lgkmcnt(1)
	v_mfma_f32_16x16x32_bf16 v[28:31], v[228:231], v[208:211], v[28:31]
	v_mfma_f32_16x16x32_bf16 v[24:27], v[228:231], v[212:215], v[24:27]
	v_mfma_f32_16x16x32_bf16 v[20:23], v[228:231], v[216:219], v[20:23]
	v_mfma_f32_16x16x32_bf16 v[16:19], v[228:231], v[220:223], v[16:19]
	s_waitcnt lgkmcnt(0)
	v_mfma_f32_16x16x32_bf16 v[12:15], v[232:235], v[208:211], v[12:15]
	v_mfma_f32_16x16x32_bf16 v[8:11], v[232:235], v[212:215], v[8:11]
	v_mfma_f32_16x16x32_bf16 v[4:7], v[232:235], v[216:219], v[4:7]
	v_mfma_f32_16x16x32_bf16 v[0:3], v[232:235], v[220:223], v[0:3]
	s_setprio 0
	s_add_u32 s10, s10, 0x80
	s_addc_u32 s11, s11, 0
	s_addk_i32 s24, 0x4000
	s_cmpk_eq_i32 s10, 0x780
	s_waitcnt vmcnt(0)
	s_barrier
	s_cbranch_scc0 .LBB0_443
	ds_read_b128 v[96:99], v69 offset:32768
	ds_read_b128 v[100:103], v69 offset:34816
	ds_read_b128 v[104:107], v135 offset:49152
	ds_read_b128 v[108:111], v135 offset:51200
	ds_read_b128 v[152:155], v69 offset:36864
	ds_read_b128 v[156:159], v69 offset:38912
	ds_read_b128 v[160:163], v135 offset:53248
	ds_read_b128 v[164:167], v135 offset:55296
	s_setprio 1
	s_waitcnt lgkmcnt(1)
	v_mfma_f32_16x16x32_bf16 v[4:7], v[156:159], v[160:163], v[4:7]
	s_waitcnt lgkmcnt(0)
	v_mfma_f32_16x16x32_bf16 v[0:3], v[156:159], v[164:167], v[0:3]
	v_mfma_f32_16x16x32_bf16 v[60:63], v[96:99], v[104:107], v[60:63]
	v_mfma_f32_16x16x32_bf16 v[56:59], v[96:99], v[108:111], v[56:59]
	v_mfma_f32_16x16x32_bf16 v[52:55], v[96:99], v[160:163], v[52:55]
	v_mfma_f32_16x16x32_bf16 v[48:51], v[96:99], v[164:167], v[48:51]
	v_mfma_f32_16x16x32_bf16 v[44:47], v[100:103], v[104:107], v[44:47]
	v_mfma_f32_16x16x32_bf16 v[40:43], v[100:103], v[108:111], v[40:43]
	v_mfma_f32_16x16x32_bf16 v[36:39], v[100:103], v[160:163], v[36:39]
	v_mfma_f32_16x16x32_bf16 v[32:35], v[100:103], v[164:167], v[32:35]
	v_mfma_f32_16x16x32_bf16 v[28:31], v[152:155], v[104:107], v[28:31]
	v_mfma_f32_16x16x32_bf16 v[24:27], v[152:155], v[108:111], v[24:27]
	v_mfma_f32_16x16x32_bf16 v[20:23], v[152:155], v[160:163], v[20:23]
	v_mfma_f32_16x16x32_bf16 v[16:19], v[152:155], v[164:167], v[16:19]
	v_mfma_f32_16x16x32_bf16 v[12:15], v[156:159], v[104:107], v[12:15]
	v_mfma_f32_16x16x32_bf16 v[8:11], v[156:159], v[108:111], v[8:11]
	s_setprio 0
	ds_read_b128 v[96:99], v136 offset:32768
	ds_read_b128 v[100:103], v136 offset:34816
	ds_read_b128 v[104:107], v137 offset:49152
	ds_read_b128 v[108:111], v137 offset:51200
	ds_read_b128 v[152:155], v136 offset:36864
	ds_read_b128 v[156:159], v136 offset:38912
	ds_read_b128 v[160:163], v137 offset:53248
	ds_read_b128 v[164:167], v137 offset:55296
	s_setprio 1
	s_waitcnt lgkmcnt(1)
	v_mfma_f32_16x16x32_bf16 v[4:7], v[156:159], v[160:163], v[4:7]
	s_waitcnt lgkmcnt(0)
	v_mfma_f32_16x16x32_bf16 v[0:3], v[156:159], v[164:167], v[0:3]
	v_mfma_f32_16x16x32_bf16 v[60:63], v[96:99], v[104:107], v[60:63]
	v_mfma_f32_16x16x32_bf16 v[56:59], v[96:99], v[108:111], v[56:59]
	v_mfma_f32_16x16x32_bf16 v[52:55], v[96:99], v[160:163], v[52:55]
	v_mfma_f32_16x16x32_bf16 v[48:51], v[96:99], v[164:167], v[48:51]
	v_mfma_f32_16x16x32_bf16 v[44:47], v[100:103], v[104:107], v[44:47]
	v_mfma_f32_16x16x32_bf16 v[40:43], v[100:103], v[108:111], v[40:43]
	v_mfma_f32_16x16x32_bf16 v[36:39], v[100:103], v[160:163], v[36:39]
	v_mfma_f32_16x16x32_bf16 v[32:35], v[100:103], v[164:167], v[32:35]
	v_mfma_f32_16x16x32_bf16 v[28:31], v[152:155], v[104:107], v[28:31]
	v_mfma_f32_16x16x32_bf16 v[24:27], v[152:155], v[108:111], v[24:27]
	v_mfma_f32_16x16x32_bf16 v[20:23], v[152:155], v[160:163], v[20:23]
	v_mfma_f32_16x16x32_bf16 v[16:19], v[152:155], v[164:167], v[16:19]
	v_mfma_f32_16x16x32_bf16 v[12:15], v[156:159], v[104:107], v[12:15]
	v_mfma_f32_16x16x32_bf16 v[8:11], v[156:159], v[108:111], v[8:11]
	s_setprio 0
	s_barrier
	ds_write2_b32 v134, v60, v56 offset1:16
	ds_write2_b32 v134, v61, v57 offset0:132 offset1:148
	v_add_u32_e32 v56, 0x400, v134
	ds_write2_b32 v56, v62, v58 offset0:8 offset1:24
	ds_write2_b32 v56, v63, v59 offset0:140 offset1:156
	ds_write2_b32 v134, v52, v48 offset0:32 offset1:48
	ds_write2_b32 v134, v53, v49 offset0:164 offset1:180
	ds_write2_b32 v56, v54, v50 offset0:40 offset1:56
	ds_write2_b32 v56, v55, v51 offset0:172 offset1:188
	v_add_u32_e32 v48, 0x2000, v134
	ds_write2_b32 v48, v44, v40 offset0:64 offset1:80
	ds_write2_b32 v48, v45, v41 offset0:196 offset1:212
	v_add_u32_e32 v40, 0x2400, v134
	ds_write2_b32 v40, v46, v42 offset0:72 offset1:88
	ds_write2_b32 v40, v47, v43 offset0:204 offset1:220
	ds_write2_b32 v48, v36, v32 offset0:96 offset1:112
	ds_write2_b32 v48, v37, v33 offset0:228 offset1:244
	ds_write2_b32 v40, v38, v34 offset0:104 offset1:120
	ds_write2_b32 v40, v39, v35 offset0:236 offset1:252
	v_add_u32_e32 v32, 0x4000, v134
	ds_write2_b32 v32, v28, v24 offset0:128 offset1:144
	v_add_u32_e32 v24, 0x4400, v134
	ds_write2_b32 v24, v29, v25 offset0:4 offset1:20
	ds_write2_b32 v24, v30, v26 offset0:136 offset1:152
	v_add_u32_e32 v25, 0x4800, v134
	ds_write2_b32 v25, v31, v27 offset0:12 offset1:28
	ds_write2_b32 v32, v20, v16 offset0:160 offset1:176
	ds_write2_b32 v24, v21, v17 offset0:36 offset1:52
	ds_write2_b32 v24, v22, v18 offset0:168 offset1:184
	ds_write2_b32 v25, v23, v19 offset0:44 offset1:60
	v_add_u32_e32 v16, 0x6000, v134
	ds_write2_b32 v16, v12, v8 offset0:192 offset1:208
	v_add_u32_e32 v8, 0x6400, v134
	ds_write2_b32 v8, v13, v9 offset0:68 offset1:84
	ds_write2_b32 v8, v14, v10 offset0:200 offset1:216
	v_add_u32_e32 v9, 0x6800, v134
	ds_write2_b32 v9, v15, v11 offset0:76 offset1:92
	ds_write2_b32 v16, v4, v0 offset0:224 offset1:240
	ds_write2_b32 v8, v5, v1 offset0:100 offset1:116
	ds_write2_b32 v8, v6, v2 offset0:232 offset1:248
	ds_write2_b32 v9, v7, v3 offset0:108 offset1:124
	v_or_b32_e32 v0, s22, v113
	v_lshlrev_b32_e32 v70, 2, v0
	v_lshl_add_u64 v[0:1], s[12:13], 0, v[70:71]
	v_lshl_add_u64 v[2:3], s[8:9], 0, v[70:71]
	v_add_u32_e32 v4, s23, v146
	s_mov_b32 s10, 0
	s_waitcnt lgkmcnt(0)
	s_barrier

.LBB0_605:
	s_and_b32 s18, s17, 0x4000
	s_xor_b32 s19, s18, 0x4000
	s_lshl_b32 s19, s19, 1
	s_add_i32 s19, s19, 32
	s_add_u32 s90, s52, s10
	s_addc_u32 s91, s53, s11
	s_add_i32 m0, s19, s82
	s_lshl_b32 s18, s18, 1
	global_load_lds_dwordx4 v184, s[90:91]
	s_add_i32 m0, s19, s83
	s_add_i32 s18, s18, 32
	global_load_lds_dwordx4 v185, s[90:91]
	s_add_i32 m0, s19, s84
	v_lshl_add_u32 v137, v114, 1, s18
	global_load_lds_dwordx4 v186, s[90:91]
	s_add_i32 m0, s19, s85
	v_lshl_add_u32 v170, v115, 1, s18
	global_load_lds_dwordx4 v187, s[90:91]
	s_add_i32 m0, s19, s86
	v_add_u32_e32 v158, v137, v135
	global_load_lds_dwordx4 v188, s[90:91]
	s_add_i32 m0, s19, s87
	v_add_u32_e32 v166, v170, v135
	global_load_lds_dwordx4 v189, s[90:91]
	s_add_i32 m0, s19, s88
	s_addk_i32 s17, 0x4000
	global_load_lds_dwordx4 v190, s[90:91]
	s_add_i32 m0, s19, s89
	s_add_u32 s10, s10, 0x80
	s_addc_u32 s11, s11, 0
	global_load_lds_dwordx4 v191, s[90:91]
	ds_read_b128 v[138:141], v158
	ds_read_b128 v[146:149], v166 offset:16384
	ds_read_b128 v[150:153], v166 offset:18432
	ds_read_b128 v[162:165], v166 offset:20480
	ds_read_b128 v[166:169], v166 offset:22528
	ds_read_b128 v[142:145], v158 offset:2048
	ds_read_b128 v[154:157], v158 offset:4096
	ds_read_b128 v[158:161], v158 offset:6144
	v_add_u32_e32 v137, v137, v136
	v_add_u32_e32 v236, v170, v136
	ds_read_b128 v[204:207], v137
	ds_read_b128 v[208:211], v236 offset:16384
	ds_read_b128 v[212:215], v236 offset:18432
	ds_read_b128 v[216:219], v236 offset:20480
	ds_read_b128 v[220:223], v236 offset:22528
	ds_read_b128 v[224:227], v137 offset:2048
	ds_read_b128 v[228:231], v137 offset:4096
	ds_read_b128 v[232:235], v137 offset:6144
	s_setprio 1
	s_waitcnt lgkmcnt(11)
	v_mfma_f32_16x16x32_bf16 v[60:63], v[138:141], v[146:149], v[60:63]
	v_mfma_f32_16x16x32_bf16 v[56:59], v[138:141], v[150:153], v[56:59]
	v_mfma_f32_16x16x32_bf16 v[52:55], v[138:141], v[162:165], v[52:55]
	v_mfma_f32_16x16x32_bf16 v[48:51], v[138:141], v[166:169], v[48:51]
	s_waitcnt lgkmcnt(10)
	v_mfma_f32_16x16x32_bf16 v[44:47], v[142:145], v[146:149], v[44:47]
	v_mfma_f32_16x16x32_bf16 v[40:43], v[142:145], v[150:153], v[40:43]
	v_mfma_f32_16x16x32_bf16 v[36:39], v[142:145], v[162:165], v[36:39]
	v_mfma_f32_16x16x32_bf16 v[32:35], v[142:145], v[166:169], v[32:35]
	s_waitcnt lgkmcnt(9)
	v_mfma_f32_16x16x32_bf16 v[28:31], v[154:157], v[146:149], v[28:31]
	v_mfma_f32_16x16x32_bf16 v[24:27], v[154:157], v[150:153], v[24:27]
	v_mfma_f32_16x16x32_bf16 v[20:23], v[154:157], v[162:165], v[20:23]
	v_mfma_f32_16x16x32_bf16 v[16:19], v[154:157], v[166:169], v[16:19]
	s_waitcnt lgkmcnt(8)
	v_mfma_f32_16x16x32_bf16 v[12:15], v[158:161], v[146:149], v[12:15]
	v_mfma_f32_16x16x32_bf16 v[8:11], v[158:161], v[150:153], v[8:11]
	v_mfma_f32_16x16x32_bf16 v[4:7], v[158:161], v[162:165], v[4:7]
	v_mfma_f32_16x16x32_bf16 v[0:3], v[158:161], v[166:169], v[0:3]
	s_waitcnt lgkmcnt(3)
	v_mfma_f32_16x16x32_bf16 v[60:63], v[204:207], v[208:211], v[60:63]
	v_mfma_f32_16x16x32_bf16 v[56:59], v[204:207], v[212:215], v[56:59]
	v_mfma_f32_16x16x32_bf16 v[52:55], v[204:207], v[216:219], v[52:55]
	v_mfma_f32_16x16x32_bf16 v[48:51], v[204:207], v[220:223], v[48:51]
	s_waitcnt lgkmcnt(2)
	v_mfma_f32_16x16x32_bf16 v[44:47], v[224:227], v[208:211], v[44:47]
	v_mfma_f32_16x16x32_bf16 v[40:43], v[224:227], v[212:215], v[40:43]
	v_mfma_f32_16x16x32_bf16 v[36:39], v[224:227], v[216:219], v[36:39]
	v_mfma_f32_16x16x32_bf16 v[32:35], v[224:227], v[220:223], v[32:35]
	s_waitcnt lgkmcnt(1)
	v_mfma_f32_16x16x32_bf16 v[28:31], v[228:231], v[208:211], v[28:31]
	v_mfma_f32_16x16x32_bf16 v[24:27], v[228:231], v[212:215], v[24:27]
	v_mfma_f32_16x16x32_bf16 v[20:23], v[228:231], v[216:219], v[20:23]
	v_mfma_f32_16x16x32_bf16 v[16:19], v[228:231], v[220:223], v[16:19]
	s_waitcnt lgkmcnt(0)
	v_mfma_f32_16x16x32_bf16 v[12:15], v[232:235], v[208:211], v[12:15]
	v_mfma_f32_16x16x32_bf16 v[8:11], v[232:235], v[212:215], v[8:11]
	v_mfma_f32_16x16x32_bf16 v[4:7], v[232:235], v[216:219], v[4:7]
	v_mfma_f32_16x16x32_bf16 v[0:3], v[232:235], v[220:223], v[0:3]
	s_setprio 0
	s_cmpk_eq_i32 s10, 0x780
	s_waitcnt vmcnt(0)
	s_barrier
	s_cbranch_scc0 .LBB0_605
	ds_read_b128 v[90:93], v116 offset:55296
	ds_read_b128 v[94:97], v116 offset:53248
	ds_read_b128 v[98:101], v117 offset:38912
	ds_read_b128 v[102:105], v117 offset:36864
	ds_read_b128 v[138:141], v116 offset:51200
	ds_read_b128 v[142:145], v116 offset:49152
	ds_read_b128 v[146:149], v117 offset:34816
	ds_read_b128 v[150:153], v117 offset:32768
	s_setprio 1
	s_waitcnt lgkmcnt(5)
	v_mfma_f32_16x16x32_bf16 v[0:3], v[98:101], v[90:93], v[0:3]
	s_waitcnt lgkmcnt(0)
	v_mfma_f32_16x16x32_bf16 v[60:63], v[150:153], v[142:145], v[60:63]
	v_mfma_f32_16x16x32_bf16 v[56:59], v[150:153], v[138:141], v[56:59]
	v_mfma_f32_16x16x32_bf16 v[52:55], v[150:153], v[94:97], v[52:55]
	v_mfma_f32_16x16x32_bf16 v[48:51], v[150:153], v[90:93], v[48:51]
	v_mfma_f32_16x16x32_bf16 v[44:47], v[146:149], v[142:145], v[44:47]
	v_mfma_f32_16x16x32_bf16 v[40:43], v[146:149], v[138:141], v[40:43]
	v_mfma_f32_16x16x32_bf16 v[36:39], v[146:149], v[94:97], v[36:39]
	v_mfma_f32_16x16x32_bf16 v[32:35], v[146:149], v[90:93], v[32:35]
	v_mfma_f32_16x16x32_bf16 v[28:31], v[102:105], v[142:145], v[28:31]
	v_mfma_f32_16x16x32_bf16 v[24:27], v[102:105], v[138:141], v[24:27]
	v_mfma_f32_16x16x32_bf16 v[20:23], v[102:105], v[94:97], v[20:23]
	v_mfma_f32_16x16x32_bf16 v[16:19], v[102:105], v[90:93], v[16:19]
	v_mfma_f32_16x16x32_bf16 v[12:15], v[98:101], v[142:145], v[12:15]
	v_mfma_f32_16x16x32_bf16 v[8:11], v[98:101], v[138:141], v[8:11]
	v_mfma_f32_16x16x32_bf16 v[4:7], v[98:101], v[94:97], v[4:7]
	s_setprio 0
	ds_read_b128 v[90:93], v118 offset:32768
	ds_read_b128 v[94:97], v118 offset:34816
	ds_read_b128 v[98:101], v119 offset:49152
	ds_read_b128 v[102:105], v119 offset:51200
	ds_read_b128 v[138:141], v118 offset:36864
	ds_read_b128 v[142:145], v118 offset:38912
	ds_read_b128 v[146:149], v119 offset:53248
	ds_read_b128 v[150:153], v119 offset:55296
	s_setprio 1
	s_waitcnt lgkmcnt(0)
	v_mfma_f32_16x16x32_bf16 v[0:3], v[142:145], v[150:153], v[0:3]
	v_mfma_f32_16x16x32_bf16 v[60:63], v[90:93], v[98:101], v[60:63]
	v_mfma_f32_16x16x32_bf16 v[56:59], v[90:93], v[102:105], v[56:59]
	v_mfma_f32_16x16x32_bf16 v[52:55], v[90:93], v[146:149], v[52:55]
	v_mfma_f32_16x16x32_bf16 v[48:51], v[90:93], v[150:153], v[48:51]
	v_mfma_f32_16x16x32_bf16 v[44:47], v[94:97], v[98:101], v[44:47]
	v_mfma_f32_16x16x32_bf16 v[40:43], v[94:97], v[102:105], v[40:43]
	v_mfma_f32_16x16x32_bf16 v[36:39], v[94:97], v[146:149], v[36:39]
	v_mfma_f32_16x16x32_bf16 v[32:35], v[94:97], v[150:153], v[32:35]
	v_mfma_f32_16x16x32_bf16 v[28:31], v[138:141], v[98:101], v[28:31]
	v_mfma_f32_16x16x32_bf16 v[24:27], v[138:141], v[102:105], v[24:27]
	v_mfma_f32_16x16x32_bf16 v[20:23], v[138:141], v[146:149], v[20:23]
	v_mfma_f32_16x16x32_bf16 v[16:19], v[138:141], v[150:153], v[16:19]
	v_mfma_f32_16x16x32_bf16 v[12:15], v[142:145], v[98:101], v[12:15]
	v_mfma_f32_16x16x32_bf16 v[8:11], v[142:145], v[102:105], v[8:11]
	v_mfma_f32_16x16x32_bf16 v[4:7], v[142:145], v[146:149], v[4:7]
	s_setprio 0
	s_barrier
	ds_write2_b32 v120, v60, v56 offset1:16
	ds_write2_b32 v120, v61, v57 offset0:132 offset1:148
	v_add_u32_e32 v56, 0x400, v120
	ds_write2_b32 v56, v62, v58 offset0:8 offset1:24
	ds_write2_b32 v56, v63, v59 offset0:140 offset1:156
	ds_write2_b32 v120, v52, v48 offset0:32 offset1:48
	ds_write2_b32 v120, v53, v49 offset0:164 offset1:180
	ds_write2_b32 v56, v54, v50 offset0:40 offset1:56
	ds_write2_b32 v56, v55, v51 offset0:172 offset1:188
	v_add_u32_e32 v48, 0x2000, v120
	ds_write2_b32 v48, v44, v40 offset0:64 offset1:80
	ds_write2_b32 v48, v45, v41 offset0:196 offset1:212
	v_add_u32_e32 v40, 0x2400, v120
	ds_write2_b32 v40, v46, v42 offset0:72 offset1:88
	ds_write2_b32 v40, v47, v43 offset0:204 offset1:220
	ds_write2_b32 v48, v36, v32 offset0:96 offset1:112
	ds_write2_b32 v48, v37, v33 offset0:228 offset1:244
	ds_write2_b32 v40, v38, v34 offset0:104 offset1:120
	ds_write2_b32 v40, v39, v35 offset0:236 offset1:252
	v_add_u32_e32 v32, 0x4000, v120
	ds_write2_b32 v32, v28, v24 offset0:128 offset1:144
	v_add_u32_e32 v24, 0x4400, v120
	ds_write2_b32 v24, v29, v25 offset0:4 offset1:20
	ds_write2_b32 v24, v30, v26 offset0:136 offset1:152
	v_add_u32_e32 v25, 0x4800, v120
	ds_write2_b32 v25, v31, v27 offset0:12 offset1:28
	ds_write2_b32 v32, v20, v16 offset0:160 offset1:176
	ds_write2_b32 v24, v21, v17 offset0:36 offset1:52
	ds_write2_b32 v24, v22, v18 offset0:168 offset1:184
	ds_write2_b32 v25, v23, v19 offset0:44 offset1:60
	v_add_u32_e32 v16, 0x6000, v120
	ds_write2_b32 v16, v12, v8 offset0:192 offset1:208
	v_add_u32_e32 v8, 0x6400, v120
	ds_write2_b32 v8, v13, v9 offset0:68 offset1:84
	ds_write2_b32 v8, v14, v10 offset0:200 offset1:216
	v_add_u32_e32 v9, 0x6800, v120
	ds_write2_b32 v9, v15, v11 offset0:76 offset1:92
	ds_write2_b32 v16, v4, v0 offset0:224 offset1:240
	ds_write2_b32 v8, v5, v1 offset0:100 offset1:116
	ds_write2_b32 v8, v6, v2 offset0:232 offset1:248
	ds_write2_b32 v9, v7, v3 offset0:108 offset1:124
	v_or_b32_e32 v0, s16, v121
	v_ashrrev_i32_e32 v1, 31, v0
	v_lshl_add_u64 v[0:1], v[0:1], 1, s[4:5]
	v_add_u32_e32 v2, s15, v128
	s_mov_b32 s10, 0
	s_waitcnt lgkmcnt(0)
	s_barrier

.LBB0_616:
	s_and_b32 s15, s14, 0x4000
	s_xor_b32 s16, s15, 0x4000
	s_lshl_b32 s16, s16, 1
	s_add_i32 s16, s16, 32
	s_add_u32 s90, s52, s6
	s_addc_u32 s91, s53, s7
	s_add_i32 m0, s16, s82
	s_lshl_b32 s15, s15, 1
	global_load_lds_dwordx4 v184, s[90:91]
	s_add_i32 m0, s16, s83
	s_add_i32 s15, s15, 32
	global_load_lds_dwordx4 v185, s[90:91]
	s_add_i32 m0, s16, s84
	v_lshl_add_u32 v137, v113, 1, s15
	global_load_lds_dwordx4 v186, s[90:91]
	s_add_i32 m0, s16, s85
	v_lshl_add_u32 v170, v114, 1, s15
	global_load_lds_dwordx4 v187, s[90:91]
	s_add_i32 m0, s16, s86
	v_add_u32_e32 v158, v137, v135
	global_load_lds_dwordx4 v188, s[90:91]
	s_add_i32 m0, s16, s87
	v_add_u32_e32 v166, v170, v135
	global_load_lds_dwordx4 v189, s[90:91]
	s_add_i32 m0, s16, s88
	s_addk_i32 s14, 0x4000
	global_load_lds_dwordx4 v190, s[90:91]
	s_add_i32 m0, s16, s89
	s_add_u32 s6, s6, 0x80
	s_addc_u32 s7, s7, 0
	global_load_lds_dwordx4 v191, s[90:91]
	ds_read_b128 v[138:141], v158
	ds_read_b128 v[146:149], v166 offset:16384
	ds_read_b128 v[150:153], v166 offset:18432
	ds_read_b128 v[162:165], v166 offset:20480
	ds_read_b128 v[166:169], v166 offset:22528
	ds_read_b128 v[142:145], v158 offset:2048
	ds_read_b128 v[154:157], v158 offset:4096
	ds_read_b128 v[158:161], v158 offset:6144
	v_add_u32_e32 v137, v137, v136
	v_add_u32_e32 v236, v170, v136
	ds_read_b128 v[204:207], v137
	ds_read_b128 v[208:211], v236 offset:16384
	ds_read_b128 v[212:215], v236 offset:18432
	ds_read_b128 v[216:219], v236 offset:20480
	ds_read_b128 v[220:223], v236 offset:22528
	ds_read_b128 v[224:227], v137 offset:2048
	ds_read_b128 v[228:231], v137 offset:4096
	ds_read_b128 v[232:235], v137 offset:6144
	s_setprio 1
	s_waitcnt lgkmcnt(11)
	v_mfma_f32_16x16x32_bf16 v[60:63], v[138:141], v[146:149], v[60:63]
	v_mfma_f32_16x16x32_bf16 v[56:59], v[138:141], v[150:153], v[56:59]
	v_mfma_f32_16x16x32_bf16 v[52:55], v[138:141], v[162:165], v[52:55]
	v_mfma_f32_16x16x32_bf16 v[48:51], v[138:141], v[166:169], v[48:51]
	s_waitcnt lgkmcnt(10)
	v_mfma_f32_16x16x32_bf16 v[44:47], v[142:145], v[146:149], v[44:47]
	v_mfma_f32_16x16x32_bf16 v[40:43], v[142:145], v[150:153], v[40:43]
	v_mfma_f32_16x16x32_bf16 v[36:39], v[142:145], v[162:165], v[36:39]
	v_mfma_f32_16x16x32_bf16 v[32:35], v[142:145], v[166:169], v[32:35]
	s_waitcnt lgkmcnt(9)
	v_mfma_f32_16x16x32_bf16 v[28:31], v[154:157], v[146:149], v[28:31]
	v_mfma_f32_16x16x32_bf16 v[24:27], v[154:157], v[150:153], v[24:27]
	v_mfma_f32_16x16x32_bf16 v[20:23], v[154:157], v[162:165], v[20:23]
	v_mfma_f32_16x16x32_bf16 v[16:19], v[154:157], v[166:169], v[16:19]
	s_waitcnt lgkmcnt(8)
	v_mfma_f32_16x16x32_bf16 v[12:15], v[158:161], v[146:149], v[12:15]
	v_mfma_f32_16x16x32_bf16 v[8:11], v[158:161], v[150:153], v[8:11]
	v_mfma_f32_16x16x32_bf16 v[4:7], v[158:161], v[162:165], v[4:7]
	v_mfma_f32_16x16x32_bf16 v[0:3], v[158:161], v[166:169], v[0:3]
	s_waitcnt lgkmcnt(3)
	v_mfma_f32_16x16x32_bf16 v[60:63], v[204:207], v[208:211], v[60:63]
	v_mfma_f32_16x16x32_bf16 v[56:59], v[204:207], v[212:215], v[56:59]
	v_mfma_f32_16x16x32_bf16 v[52:55], v[204:207], v[216:219], v[52:55]
	v_mfma_f32_16x16x32_bf16 v[48:51], v[204:207], v[220:223], v[48:51]
	s_waitcnt lgkmcnt(2)
	v_mfma_f32_16x16x32_bf16 v[44:47], v[224:227], v[208:211], v[44:47]
	v_mfma_f32_16x16x32_bf16 v[40:43], v[224:227], v[212:215], v[40:43]
	v_mfma_f32_16x16x32_bf16 v[36:39], v[224:227], v[216:219], v[36:39]
	v_mfma_f32_16x16x32_bf16 v[32:35], v[224:227], v[220:223], v[32:35]
	s_waitcnt lgkmcnt(1)
	v_mfma_f32_16x16x32_bf16 v[28:31], v[228:231], v[208:211], v[28:31]
	v_mfma_f32_16x16x32_bf16 v[24:27], v[228:231], v[212:215], v[24:27]
	v_mfma_f32_16x16x32_bf16 v[20:23], v[228:231], v[216:219], v[20:23]
	v_mfma_f32_16x16x32_bf16 v[16:19], v[228:231], v[220:223], v[16:19]
	s_waitcnt lgkmcnt(0)
	v_mfma_f32_16x16x32_bf16 v[12:15], v[232:235], v[208:211], v[12:15]
	v_mfma_f32_16x16x32_bf16 v[8:11], v[232:235], v[212:215], v[8:11]
	v_mfma_f32_16x16x32_bf16 v[4:7], v[232:235], v[216:219], v[4:7]
	v_mfma_f32_16x16x32_bf16 v[0:3], v[232:235], v[220:223], v[0:3]
	s_setprio 0
	s_cmpk_eq_i32 s6, 0x780
	s_waitcnt vmcnt(0)
	s_barrier
	s_cbranch_scc0 .LBB0_616
	ds_read_b128 v[88:91], v115 offset:55296
	ds_read_b128 v[92:95], v115 offset:53248
	ds_read_b128 v[96:99], v116 offset:38912
	ds_read_b128 v[100:103], v116 offset:36864
	ds_read_b128 v[138:141], v115 offset:51200
	ds_read_b128 v[142:145], v115 offset:49152
	ds_read_b128 v[146:149], v116 offset:34816
	ds_read_b128 v[150:153], v116 offset:32768
	s_setprio 1
	s_waitcnt lgkmcnt(5)
	v_mfma_f32_16x16x32_bf16 v[0:3], v[96:99], v[88:91], v[0:3]
	s_waitcnt lgkmcnt(0)
	v_mfma_f32_16x16x32_bf16 v[60:63], v[150:153], v[142:145], v[60:63]
	v_mfma_f32_16x16x32_bf16 v[56:59], v[150:153], v[138:141], v[56:59]
	v_mfma_f32_16x16x32_bf16 v[52:55], v[150:153], v[92:95], v[52:55]
	v_mfma_f32_16x16x32_bf16 v[48:51], v[150:153], v[88:91], v[48:51]
	v_mfma_f32_16x16x32_bf16 v[44:47], v[146:149], v[142:145], v[44:47]
	v_mfma_f32_16x16x32_bf16 v[40:43], v[146:149], v[138:141], v[40:43]
	v_mfma_f32_16x16x32_bf16 v[36:39], v[146:149], v[92:95], v[36:39]
	v_mfma_f32_16x16x32_bf16 v[32:35], v[146:149], v[88:91], v[32:35]
	v_mfma_f32_16x16x32_bf16 v[28:31], v[100:103], v[142:145], v[28:31]
	v_mfma_f32_16x16x32_bf16 v[24:27], v[100:103], v[138:141], v[24:27]
	v_mfma_f32_16x16x32_bf16 v[20:23], v[100:103], v[92:95], v[20:23]
	v_mfma_f32_16x16x32_bf16 v[16:19], v[100:103], v[88:91], v[16:19]
	v_mfma_f32_16x16x32_bf16 v[12:15], v[96:99], v[142:145], v[12:15]
	v_mfma_f32_16x16x32_bf16 v[8:11], v[96:99], v[138:141], v[8:11]
	v_mfma_f32_16x16x32_bf16 v[4:7], v[96:99], v[92:95], v[4:7]
	s_setprio 0
	ds_read_b128 v[88:91], v117 offset:32768
	ds_read_b128 v[92:95], v117 offset:34816
	ds_read_b128 v[96:99], v118 offset:49152
	ds_read_b128 v[100:103], v118 offset:51200
	ds_read_b128 v[138:141], v117 offset:36864
	ds_read_b128 v[142:145], v117 offset:38912
	ds_read_b128 v[146:149], v118 offset:53248
	ds_read_b128 v[150:153], v118 offset:55296
	s_setprio 1
	s_waitcnt lgkmcnt(0)
	v_mfma_f32_16x16x32_bf16 v[0:3], v[142:145], v[150:153], v[0:3]
	v_mfma_f32_16x16x32_bf16 v[60:63], v[88:91], v[96:99], v[60:63]
	v_mfma_f32_16x16x32_bf16 v[56:59], v[88:91], v[100:103], v[56:59]
	v_mfma_f32_16x16x32_bf16 v[52:55], v[88:91], v[146:149], v[52:55]
	v_mfma_f32_16x16x32_bf16 v[48:51], v[88:91], v[150:153], v[48:51]
	v_mfma_f32_16x16x32_bf16 v[44:47], v[92:95], v[96:99], v[44:47]
	v_mfma_f32_16x16x32_bf16 v[40:43], v[92:95], v[100:103], v[40:43]
	v_mfma_f32_16x16x32_bf16 v[36:39], v[92:95], v[146:149], v[36:39]
	v_mfma_f32_16x16x32_bf16 v[32:35], v[92:95], v[150:153], v[32:35]
	v_mfma_f32_16x16x32_bf16 v[28:31], v[138:141], v[96:99], v[28:31]
	v_mfma_f32_16x16x32_bf16 v[24:27], v[138:141], v[100:103], v[24:27]
	v_mfma_f32_16x16x32_bf16 v[20:23], v[138:141], v[146:149], v[20:23]
	v_mfma_f32_16x16x32_bf16 v[16:19], v[138:141], v[150:153], v[16:19]
	v_mfma_f32_16x16x32_bf16 v[12:15], v[142:145], v[96:99], v[12:15]
	v_mfma_f32_16x16x32_bf16 v[8:11], v[142:145], v[100:103], v[8:11]
	v_mfma_f32_16x16x32_bf16 v[4:7], v[142:145], v[146:149], v[4:7]
	s_setprio 0
	s_barrier
	ds_write2_b32 v119, v60, v56 offset1:16
	ds_write2_b32 v119, v61, v57 offset0:132 offset1:148
	v_add_u32_e32 v56, 0x400, v119
	ds_write2_b32 v56, v62, v58 offset0:8 offset1:24
	ds_write2_b32 v56, v63, v59 offset0:140 offset1:156
	ds_write2_b32 v119, v52, v48 offset0:32 offset1:48
	ds_write2_b32 v119, v53, v49 offset0:164 offset1:180
	ds_write2_b32 v56, v54, v50 offset0:40 offset1:56
	ds_write2_b32 v56, v55, v51 offset0:172 offset1:188
	v_add_u32_e32 v48, 0x2000, v119
	ds_write2_b32 v48, v44, v40 offset0:64 offset1:80
	ds_write2_b32 v48, v45, v41 offset0:196 offset1:212
	v_add_u32_e32 v40, 0x2400, v119
	ds_write2_b32 v40, v46, v42 offset0:72 offset1:88
	ds_write2_b32 v40, v47, v43 offset0:204 offset1:220
	ds_write2_b32 v48, v36, v32 offset0:96 offset1:112
	ds_write2_b32 v48, v37, v33 offset0:228 offset1:244
	ds_write2_b32 v40, v38, v34 offset0:104 offset1:120
	ds_write2_b32 v40, v39, v35 offset0:236 offset1:252
	v_add_u32_e32 v32, 0x4000, v119
	ds_write2_b32 v32, v28, v24 offset0:128 offset1:144
	v_add_u32_e32 v24, 0x4400, v119
	ds_write2_b32 v24, v29, v25 offset0:4 offset1:20
	ds_write2_b32 v24, v30, v26 offset0:136 offset1:152
	v_add_u32_e32 v25, 0x4800, v119
	ds_write2_b32 v25, v31, v27 offset0:12 offset1:28
	ds_write2_b32 v32, v20, v16 offset0:160 offset1:176
	ds_write2_b32 v24, v21, v17 offset0:36 offset1:52
	ds_write2_b32 v24, v22, v18 offset0:168 offset1:184
	ds_write2_b32 v25, v23, v19 offset0:44 offset1:60
	v_add_u32_e32 v16, 0x6000, v119
	ds_write2_b32 v16, v12, v8 offset0:192 offset1:208
	v_add_u32_e32 v8, 0x6400, v119
	ds_write2_b32 v8, v13, v9 offset0:68 offset1:84
	ds_write2_b32 v8, v14, v10 offset0:200 offset1:216
	v_add_u32_e32 v9, 0x6800, v119
	ds_write2_b32 v9, v15, v11 offset0:76 offset1:92
	ds_write2_b32 v16, v4, v0 offset0:224 offset1:240
	ds_write2_b32 v8, v5, v1 offset0:100 offset1:116
	ds_write2_b32 v8, v6, v2 offset0:232 offset1:248
	ds_write2_b32 v9, v7, v3 offset0:108 offset1:124
	v_or_b32_e32 v0, s12, v120
	v_ashrrev_i32_e32 v1, 31, v0
	v_lshl_add_u64 v[0:1], v[0:1], 1, s[4:5]
	v_add_u32_e32 v2, s13, v128
	s_mov_b32 s6, 0
	s_waitcnt lgkmcnt(0)
	s_barrier

.LBB0_682:
	s_and_b32 s25, s24, 0x4000
	s_xor_b32 s26, s25, 0x4000
	s_lshl_b32 s26, s26, 1
	s_add_i32 s26, s26, 32
	s_add_u32 s90, s52, s14
	s_addc_u32 s91, s53, s15
	s_add_i32 m0, s26, s82
	s_lshl_b32 s25, s25, 1
	global_load_lds_dwordx4 v192, s[90:91]
	s_add_i32 m0, s26, s83
	s_add_i32 s25, s25, 32
	global_load_lds_dwordx4 v193, s[90:91]
	s_add_i32 m0, s26, s84
	v_add3_u32 v170, s25, v114, v135
	global_load_lds_dwordx4 v194, s[90:91]
	s_add_i32 m0, s26, s85
	v_add3_u32 v171, s25, v115, v135
	global_load_lds_dwordx4 v195, s[90:91]
	s_add_i32 m0, s26, s86
	v_add_u32_e32 v158, v170, v136
	global_load_lds_dwordx4 v196, s[90:91]
	s_add_i32 m0, s26, s87
	v_add_u32_e32 v166, v171, v136
	global_load_lds_dwordx4 v197, s[90:91]
	s_add_i32 m0, s26, s88
	s_addk_i32 s24, 0x4000
	global_load_lds_dwordx4 v198, s[90:91]
	s_add_i32 m0, s26, s89
	s_add_u32 s14, s14, 0x80
	s_addc_u32 s15, s15, 0
	global_load_lds_dwordx4 v199, s[90:91]
	ds_read_b128 v[138:141], v158
	ds_read_b128 v[146:149], v166 offset:16384
	ds_read_b128 v[150:153], v166 offset:18432
	ds_read_b128 v[162:165], v166 offset:20480
	ds_read_b128 v[166:169], v166 offset:22528
	ds_read_b128 v[142:145], v158 offset:2048
	ds_read_b128 v[154:157], v158 offset:4096
	ds_read_b128 v[158:161], v158 offset:6144
	v_add_u32_e32 v236, v170, v137
	v_add_u32_e32 v237, v171, v137
	ds_read_b128 v[204:207], v236
	ds_read_b128 v[208:211], v237 offset:16384
	ds_read_b128 v[212:215], v237 offset:18432
	ds_read_b128 v[216:219], v237 offset:20480
	ds_read_b128 v[220:223], v237 offset:22528
	ds_read_b128 v[224:227], v236 offset:2048
	ds_read_b128 v[228:231], v236 offset:4096
	ds_read_b128 v[232:235], v236 offset:6144
	s_setprio 1
	s_waitcnt lgkmcnt(11)
	v_mfma_f32_16x16x32_bf16 v[60:63], v[138:141], v[146:149], v[60:63]
	v_mfma_f32_16x16x32_bf16 v[56:59], v[138:141], v[150:153], v[56:59]
	v_mfma_f32_16x16x32_bf16 v[52:55], v[138:141], v[162:165], v[52:55]
	v_mfma_f32_16x16x32_bf16 v[48:51], v[138:141], v[166:169], v[48:51]
	s_waitcnt lgkmcnt(10)
	v_mfma_f32_16x16x32_bf16 v[44:47], v[142:145], v[146:149], v[44:47]
	v_mfma_f32_16x16x32_bf16 v[40:43], v[142:145], v[150:153], v[40:43]
	v_mfma_f32_16x16x32_bf16 v[36:39], v[142:145], v[162:165], v[36:39]
	v_mfma_f32_16x16x32_bf16 v[32:35], v[142:145], v[166:169], v[32:35]
	s_waitcnt lgkmcnt(9)
	v_mfma_f32_16x16x32_bf16 v[28:31], v[154:157], v[146:149], v[28:31]
	v_mfma_f32_16x16x32_bf16 v[24:27], v[154:157], v[150:153], v[24:27]
	v_mfma_f32_16x16x32_bf16 v[20:23], v[154:157], v[162:165], v[20:23]
	v_mfma_f32_16x16x32_bf16 v[16:19], v[154:157], v[166:169], v[16:19]
	s_waitcnt lgkmcnt(8)
	v_mfma_f32_16x16x32_bf16 v[12:15], v[158:161], v[146:149], v[12:15]
	v_mfma_f32_16x16x32_bf16 v[8:11], v[158:161], v[150:153], v[8:11]
	v_mfma_f32_16x16x32_bf16 v[4:7], v[158:161], v[162:165], v[4:7]
	v_mfma_f32_16x16x32_bf16 v[0:3], v[158:161], v[166:169], v[0:3]
	s_waitcnt lgkmcnt(3)
	v_mfma_f32_16x16x32_bf16 v[60:63], v[204:207], v[208:211], v[60:63]
	v_mfma_f32_16x16x32_bf16 v[56:59], v[204:207], v[212:215], v[56:59]
	v_mfma_f32_16x16x32_bf16 v[52:55], v[204:207], v[216:219], v[52:55]
	v_mfma_f32_16x16x32_bf16 v[48:51], v[204:207], v[220:223], v[48:51]
	s_waitcnt lgkmcnt(2)
	v_mfma_f32_16x16x32_bf16 v[44:47], v[224:227], v[208:211], v[44:47]
	v_mfma_f32_16x16x32_bf16 v[40:43], v[224:227], v[212:215], v[40:43]
	v_mfma_f32_16x16x32_bf16 v[36:39], v[224:227], v[216:219], v[36:39]
	v_mfma_f32_16x16x32_bf16 v[32:35], v[224:227], v[220:223], v[32:35]
	s_waitcnt lgkmcnt(1)
	v_mfma_f32_16x16x32_bf16 v[28:31], v[228:231], v[208:211], v[28:31]
	v_mfma_f32_16x16x32_bf16 v[24:27], v[228:231], v[212:215], v[24:27]
	v_mfma_f32_16x16x32_bf16 v[20:23], v[228:231], v[216:219], v[20:23]
	v_mfma_f32_16x16x32_bf16 v[16:19], v[228:231], v[220:223], v[16:19]
	s_waitcnt lgkmcnt(0)
	v_mfma_f32_16x16x32_bf16 v[12:15], v[232:235], v[208:211], v[12:15]
	v_mfma_f32_16x16x32_bf16 v[8:11], v[232:235], v[212:215], v[8:11]
	v_mfma_f32_16x16x32_bf16 v[4:7], v[232:235], v[216:219], v[4:7]
	v_mfma_f32_16x16x32_bf16 v[0:3], v[232:235], v[220:223], v[0:3]
	s_setprio 0
	s_cmpk_eq_i32 s14, 0x1f80
	s_waitcnt vmcnt(0)
	s_barrier
	s_cbranch_scc0 .LBB0_682
	ds_read_b128 v[90:93], v118 offset:55296
	ds_read_b128 v[94:97], v118 offset:53248
	ds_read_b128 v[98:101], v119 offset:38912
	ds_read_b128 v[102:105], v119 offset:36864
	ds_read_b128 v[138:141], v118 offset:51200
	ds_read_b128 v[142:145], v118 offset:49152
	ds_read_b128 v[146:149], v119 offset:34816
	ds_read_b128 v[150:153], v119 offset:32768
	s_setprio 1
	s_waitcnt lgkmcnt(5)
	v_mfma_f32_16x16x32_bf16 v[4:7], v[98:101], v[94:97], v[4:7]
	v_mfma_f32_16x16x32_bf16 v[0:3], v[98:101], v[90:93], v[0:3]
	s_waitcnt lgkmcnt(0)
	v_mfma_f32_16x16x32_bf16 v[60:63], v[150:153], v[142:145], v[60:63]
	v_mfma_f32_16x16x32_bf16 v[56:59], v[150:153], v[138:141], v[56:59]
	v_mfma_f32_16x16x32_bf16 v[52:55], v[150:153], v[94:97], v[52:55]
	v_mfma_f32_16x16x32_bf16 v[48:51], v[150:153], v[90:93], v[48:51]
	v_mfma_f32_16x16x32_bf16 v[44:47], v[146:149], v[142:145], v[44:47]
	v_mfma_f32_16x16x32_bf16 v[40:43], v[146:149], v[138:141], v[40:43]
	v_mfma_f32_16x16x32_bf16 v[36:39], v[146:149], v[94:97], v[36:39]
	v_mfma_f32_16x16x32_bf16 v[32:35], v[146:149], v[90:93], v[32:35]
	v_mfma_f32_16x16x32_bf16 v[28:31], v[102:105], v[142:145], v[28:31]
	v_mfma_f32_16x16x32_bf16 v[24:27], v[102:105], v[138:141], v[24:27]
	v_mfma_f32_16x16x32_bf16 v[20:23], v[102:105], v[94:97], v[20:23]
	v_mfma_f32_16x16x32_bf16 v[16:19], v[102:105], v[90:93], v[16:19]
	v_mfma_f32_16x16x32_bf16 v[12:15], v[98:101], v[142:145], v[12:15]
	v_mfma_f32_16x16x32_bf16 v[8:11], v[98:101], v[138:141], v[8:11]
	s_setprio 0
	ds_read_b128 v[90:93], v120 offset:32768
	ds_read_b128 v[94:97], v120 offset:34816
	ds_read_b128 v[98:101], v121 offset:49152
	ds_read_b128 v[102:105], v121 offset:51200
	ds_read_b128 v[138:141], v120 offset:36864
	ds_read_b128 v[142:145], v120 offset:38912
	ds_read_b128 v[146:149], v121 offset:53248
	ds_read_b128 v[150:153], v121 offset:55296
	s_setprio 1
	s_waitcnt lgkmcnt(1)
	v_mfma_f32_16x16x32_bf16 v[4:7], v[142:145], v[146:149], v[4:7]
	s_waitcnt lgkmcnt(0)
	v_mfma_f32_16x16x32_bf16 v[0:3], v[142:145], v[150:153], v[0:3]
	v_mfma_f32_16x16x32_bf16 v[60:63], v[90:93], v[98:101], v[60:63]
	v_mfma_f32_16x16x32_bf16 v[56:59], v[90:93], v[102:105], v[56:59]
	v_mfma_f32_16x16x32_bf16 v[52:55], v[90:93], v[146:149], v[52:55]
	v_mfma_f32_16x16x32_bf16 v[48:51], v[90:93], v[150:153], v[48:51]
	v_mfma_f32_16x16x32_bf16 v[44:47], v[94:97], v[98:101], v[44:47]
	v_mfma_f32_16x16x32_bf16 v[40:43], v[94:97], v[102:105], v[40:43]
	v_mfma_f32_16x16x32_bf16 v[36:39], v[94:97], v[146:149], v[36:39]
	v_mfma_f32_16x16x32_bf16 v[32:35], v[94:97], v[150:153], v[32:35]
	v_mfma_f32_16x16x32_bf16 v[28:31], v[138:141], v[98:101], v[28:31]
	v_mfma_f32_16x16x32_bf16 v[24:27], v[138:141], v[102:105], v[24:27]
	v_mfma_f32_16x16x32_bf16 v[20:23], v[138:141], v[146:149], v[20:23]
	v_mfma_f32_16x16x32_bf16 v[16:19], v[138:141], v[150:153], v[16:19]
	v_mfma_f32_16x16x32_bf16 v[12:15], v[142:145], v[98:101], v[12:15]
	v_mfma_f32_16x16x32_bf16 v[8:11], v[142:145], v[102:105], v[8:11]
	s_setprio 0
	s_barrier
	ds_write2_b32 v116, v60, v56 offset1:16
	ds_write2_b32 v116, v61, v57 offset0:132 offset1:148
	v_add_u32_e32 v56, 0x400, v116
	ds_write2_b32 v56, v62, v58 offset0:8 offset1:24
	ds_write2_b32 v56, v63, v59 offset0:140 offset1:156
	ds_write2_b32 v116, v52, v48 offset0:32 offset1:48
	ds_write2_b32 v116, v53, v49 offset0:164 offset1:180
	ds_write2_b32 v56, v54, v50 offset0:40 offset1:56
	ds_write2_b32 v56, v55, v51 offset0:172 offset1:188
	v_add_u32_e32 v48, 0x2000, v116
	ds_write2_b32 v48, v44, v40 offset0:64 offset1:80
	ds_write2_b32 v48, v45, v41 offset0:196 offset1:212
	v_add_u32_e32 v40, 0x2400, v116
	ds_write2_b32 v40, v46, v42 offset0:72 offset1:88
	ds_write2_b32 v40, v47, v43 offset0:204 offset1:220
	ds_write2_b32 v48, v36, v32 offset0:96 offset1:112
	ds_write2_b32 v48, v37, v33 offset0:228 offset1:244
	ds_write2_b32 v40, v38, v34 offset0:104 offset1:120
	ds_write2_b32 v40, v39, v35 offset0:236 offset1:252
	v_add_u32_e32 v32, 0x4000, v116
	ds_write2_b32 v32, v28, v24 offset0:128 offset1:144
	v_add_u32_e32 v24, 0x4400, v116
	ds_write2_b32 v24, v29, v25 offset0:4 offset1:20
	ds_write2_b32 v24, v30, v26 offset0:136 offset1:152
	v_add_u32_e32 v25, 0x4800, v116
	ds_write2_b32 v25, v31, v27 offset0:12 offset1:28
	ds_write2_b32 v32, v20, v16 offset0:160 offset1:176
	ds_write2_b32 v24, v21, v17 offset0:36 offset1:52
	ds_write2_b32 v24, v22, v18 offset0:168 offset1:184
	ds_write2_b32 v25, v23, v19 offset0:44 offset1:60
	v_add_u32_e32 v16, 0x6000, v116
	ds_write2_b32 v16, v12, v8 offset0:192 offset1:208
	v_add_u32_e32 v8, 0x6400, v116
	ds_write2_b32 v8, v13, v9 offset0:68 offset1:84
	ds_write2_b32 v8, v14, v10 offset0:200 offset1:216
	v_add_u32_e32 v9, 0x6800, v116
	ds_write2_b32 v9, v15, v11 offset0:76 offset1:92
	ds_write2_b32 v16, v4, v0 offset0:224 offset1:240
	ds_write2_b32 v8, v5, v1 offset0:100 offset1:116
	ds_write2_b32 v8, v6, v2 offset0:232 offset1:248
	ds_write2_b32 v9, v7, v3 offset0:108 offset1:124
	v_or_b32_e32 v0, s23, v117
	v_ashrrev_i32_e32 v1, 31, v0
	v_lshlrev_b64 v[2:3], 2, v[0:1]
	v_lshl_add_u64 v[0:1], s[12:13], 0, v[2:3]
	v_lshl_add_u64 v[2:3], s[10:11], 0, v[2:3]
	v_add_u32_e32 v4, s22, v128
	s_mov_b32 s14, 0
	s_waitcnt lgkmcnt(0)
	s_barrier

.LBB0_691:
	s_and_b32 s26, s25, 0x4000
	s_xor_b32 s27, s26, 0x4000
	s_lshl_b32 s27, s27, 1
	s_add_i32 s27, s27, 32
	s_add_u32 s90, s52, s14
	s_addc_u32 s91, s53, s15
	s_add_i32 m0, s27, s82
	s_lshl_b32 s26, s26, 1
	global_load_lds_dwordx4 v192, s[90:91]
	s_add_i32 m0, s27, s83
	s_add_i32 s26, s26, 32
	global_load_lds_dwordx4 v193, s[90:91]
	s_add_i32 m0, s27, s84
	v_add3_u32 v139, s26, v113, v136
	global_load_lds_dwordx4 v194, s[90:91]
	s_add_i32 m0, s27, s85
	v_add3_u32 v172, s26, v114, v136
	global_load_lds_dwordx4 v195, s[90:91]
	s_add_i32 m0, s27, s86
	v_add_u32_e32 v160, v139, v137
	global_load_lds_dwordx4 v196, s[90:91]
	s_add_i32 m0, s27, s87
	v_add_u32_e32 v168, v172, v137
	global_load_lds_dwordx4 v197, s[90:91]
	s_add_i32 m0, s27, s88
	s_addk_i32 s25, 0x4000
	global_load_lds_dwordx4 v198, s[90:91]
	s_add_i32 m0, s27, s89
	s_add_u32 s14, s14, 0x80
	s_addc_u32 s15, s15, 0
	global_load_lds_dwordx4 v199, s[90:91]
	ds_read_b128 v[140:143], v160
	ds_read_b128 v[148:151], v168 offset:16384
	ds_read_b128 v[152:155], v168 offset:18432
	ds_read_b128 v[164:167], v168 offset:20480
	ds_read_b128 v[168:171], v168 offset:22528
	ds_read_b128 v[144:147], v160 offset:2048
	ds_read_b128 v[156:159], v160 offset:4096
	ds_read_b128 v[160:163], v160 offset:6144
	v_add_u32_e32 v139, v139, v138
	v_add_u32_e32 v236, v172, v138
	ds_read_b128 v[204:207], v139
	ds_read_b128 v[208:211], v236 offset:16384
	ds_read_b128 v[212:215], v236 offset:18432
	ds_read_b128 v[216:219], v236 offset:20480
	ds_read_b128 v[220:223], v236 offset:22528
	ds_read_b128 v[224:227], v139 offset:2048
	ds_read_b128 v[228:231], v139 offset:4096
	ds_read_b128 v[232:235], v139 offset:6144
	s_setprio 1
	s_waitcnt lgkmcnt(11)
	v_mfma_f32_16x16x32_bf16 v[60:63], v[140:143], v[148:151], v[60:63]
	v_mfma_f32_16x16x32_bf16 v[56:59], v[140:143], v[152:155], v[56:59]
	v_mfma_f32_16x16x32_bf16 v[52:55], v[140:143], v[164:167], v[52:55]
	v_mfma_f32_16x16x32_bf16 v[48:51], v[140:143], v[168:171], v[48:51]
	s_waitcnt lgkmcnt(10)
	v_mfma_f32_16x16x32_bf16 v[44:47], v[144:147], v[148:151], v[44:47]
	v_mfma_f32_16x16x32_bf16 v[40:43], v[144:147], v[152:155], v[40:43]
	v_mfma_f32_16x16x32_bf16 v[36:39], v[144:147], v[164:167], v[36:39]
	v_mfma_f32_16x16x32_bf16 v[32:35], v[144:147], v[168:171], v[32:35]
	s_waitcnt lgkmcnt(9)
	v_mfma_f32_16x16x32_bf16 v[28:31], v[156:159], v[148:151], v[28:31]
	v_mfma_f32_16x16x32_bf16 v[24:27], v[156:159], v[152:155], v[24:27]
	v_mfma_f32_16x16x32_bf16 v[20:23], v[156:159], v[164:167], v[20:23]
	v_mfma_f32_16x16x32_bf16 v[16:19], v[156:159], v[168:171], v[16:19]
	s_waitcnt lgkmcnt(8)
	v_mfma_f32_16x16x32_bf16 v[12:15], v[160:163], v[148:151], v[12:15]
	v_mfma_f32_16x16x32_bf16 v[8:11], v[160:163], v[152:155], v[8:11]
	v_mfma_f32_16x16x32_bf16 v[4:7], v[160:163], v[164:167], v[4:7]
	v_mfma_f32_16x16x32_bf16 v[0:3], v[160:163], v[168:171], v[0:3]
	s_waitcnt lgkmcnt(3)
	v_mfma_f32_16x16x32_bf16 v[60:63], v[204:207], v[208:211], v[60:63]
	v_mfma_f32_16x16x32_bf16 v[56:59], v[204:207], v[212:215], v[56:59]
	v_mfma_f32_16x16x32_bf16 v[52:55], v[204:207], v[216:219], v[52:55]
	v_mfma_f32_16x16x32_bf16 v[48:51], v[204:207], v[220:223], v[48:51]
	s_waitcnt lgkmcnt(2)
	v_mfma_f32_16x16x32_bf16 v[44:47], v[224:227], v[208:211], v[44:47]
	v_mfma_f32_16x16x32_bf16 v[40:43], v[224:227], v[212:215], v[40:43]
	v_mfma_f32_16x16x32_bf16 v[36:39], v[224:227], v[216:219], v[36:39]
	v_mfma_f32_16x16x32_bf16 v[32:35], v[224:227], v[220:223], v[32:35]
	s_waitcnt lgkmcnt(1)
	v_mfma_f32_16x16x32_bf16 v[28:31], v[228:231], v[208:211], v[28:31]
	v_mfma_f32_16x16x32_bf16 v[24:27], v[228:231], v[212:215], v[24:27]
	v_mfma_f32_16x16x32_bf16 v[20:23], v[228:231], v[216:219], v[20:23]
	v_mfma_f32_16x16x32_bf16 v[16:19], v[228:231], v[220:223], v[16:19]
	s_waitcnt lgkmcnt(0)
	v_mfma_f32_16x16x32_bf16 v[12:15], v[232:235], v[208:211], v[12:15]
	v_mfma_f32_16x16x32_bf16 v[8:11], v[232:235], v[212:215], v[8:11]
	v_mfma_f32_16x16x32_bf16 v[4:7], v[232:235], v[216:219], v[4:7]
	v_mfma_f32_16x16x32_bf16 v[0:3], v[232:235], v[220:223], v[0:3]
	s_setprio 0
	s_cmpk_eq_i32 s14, 0x1f80
	s_waitcnt vmcnt(0)
	s_barrier
	s_cbranch_scc0 .LBB0_691
	ds_read_b128 v[88:91], v117 offset:55296
	ds_read_b128 v[92:95], v117 offset:53248
	ds_read_b128 v[96:99], v118 offset:38912
	ds_read_b128 v[100:103], v118 offset:36864
	ds_read_b128 v[140:143], v117 offset:51200
	ds_read_b128 v[144:147], v117 offset:49152
	ds_read_b128 v[148:151], v118 offset:34816
	ds_read_b128 v[152:155], v118 offset:32768
	s_setprio 1
	s_waitcnt lgkmcnt(5)
	v_mfma_f32_16x16x32_bf16 v[4:7], v[96:99], v[92:95], v[4:7]
	v_mfma_f32_16x16x32_bf16 v[0:3], v[96:99], v[88:91], v[0:3]
	s_waitcnt lgkmcnt(0)
	v_mfma_f32_16x16x32_bf16 v[60:63], v[152:155], v[144:147], v[60:63]
	v_mfma_f32_16x16x32_bf16 v[56:59], v[152:155], v[140:143], v[56:59]
	v_mfma_f32_16x16x32_bf16 v[52:55], v[152:155], v[92:95], v[52:55]
	v_mfma_f32_16x16x32_bf16 v[48:51], v[152:155], v[88:91], v[48:51]
	v_mfma_f32_16x16x32_bf16 v[44:47], v[148:151], v[144:147], v[44:47]
	v_mfma_f32_16x16x32_bf16 v[40:43], v[148:151], v[140:143], v[40:43]
	v_mfma_f32_16x16x32_bf16 v[36:39], v[148:151], v[92:95], v[36:39]
	v_mfma_f32_16x16x32_bf16 v[32:35], v[148:151], v[88:91], v[32:35]
	v_mfma_f32_16x16x32_bf16 v[28:31], v[100:103], v[144:147], v[28:31]
	v_mfma_f32_16x16x32_bf16 v[24:27], v[100:103], v[140:143], v[24:27]
	v_mfma_f32_16x16x32_bf16 v[20:23], v[100:103], v[92:95], v[20:23]
	v_mfma_f32_16x16x32_bf16 v[16:19], v[100:103], v[88:91], v[16:19]
	v_mfma_f32_16x16x32_bf16 v[12:15], v[96:99], v[144:147], v[12:15]
	v_mfma_f32_16x16x32_bf16 v[8:11], v[96:99], v[140:143], v[8:11]
	s_setprio 0
	ds_read_b128 v[88:91], v119 offset:32768
	ds_read_b128 v[92:95], v119 offset:34816
	ds_read_b128 v[96:99], v120 offset:49152
	ds_read_b128 v[100:103], v120 offset:51200
	ds_read_b128 v[140:143], v119 offset:36864
	ds_read_b128 v[144:147], v119 offset:38912
	ds_read_b128 v[148:151], v120 offset:53248
	ds_read_b128 v[152:155], v120 offset:55296
	s_setprio 1
	s_waitcnt lgkmcnt(1)
	v_mfma_f32_16x16x32_bf16 v[4:7], v[144:147], v[148:151], v[4:7]
	s_waitcnt lgkmcnt(0)
	v_mfma_f32_16x16x32_bf16 v[0:3], v[144:147], v[152:155], v[0:3]
	v_mfma_f32_16x16x32_bf16 v[60:63], v[88:91], v[96:99], v[60:63]
	v_mfma_f32_16x16x32_bf16 v[56:59], v[88:91], v[100:103], v[56:59]
	v_mfma_f32_16x16x32_bf16 v[52:55], v[88:91], v[148:151], v[52:55]
	v_mfma_f32_16x16x32_bf16 v[48:51], v[88:91], v[152:155], v[48:51]
	v_mfma_f32_16x16x32_bf16 v[44:47], v[92:95], v[96:99], v[44:47]
	v_mfma_f32_16x16x32_bf16 v[40:43], v[92:95], v[100:103], v[40:43]
	v_mfma_f32_16x16x32_bf16 v[36:39], v[92:95], v[148:151], v[36:39]
	v_mfma_f32_16x16x32_bf16 v[32:35], v[92:95], v[152:155], v[32:35]
	v_mfma_f32_16x16x32_bf16 v[28:31], v[140:143], v[96:99], v[28:31]
	v_mfma_f32_16x16x32_bf16 v[24:27], v[140:143], v[100:103], v[24:27]
	v_mfma_f32_16x16x32_bf16 v[20:23], v[140:143], v[148:151], v[20:23]
	v_mfma_f32_16x16x32_bf16 v[16:19], v[140:143], v[152:155], v[16:19]
	v_mfma_f32_16x16x32_bf16 v[12:15], v[144:147], v[96:99], v[12:15]
	v_mfma_f32_16x16x32_bf16 v[8:11], v[144:147], v[100:103], v[8:11]
	s_setprio 0
	s_barrier
	ds_write2_b32 v115, v60, v56 offset1:16
	ds_write2_b32 v115, v61, v57 offset0:132 offset1:148
	v_add_u32_e32 v56, 0x400, v115
	ds_write2_b32 v56, v62, v58 offset0:8 offset1:24
	ds_write2_b32 v56, v63, v59 offset0:140 offset1:156
	ds_write2_b32 v115, v52, v48 offset0:32 offset1:48
	ds_write2_b32 v115, v53, v49 offset0:164 offset1:180
	ds_write2_b32 v56, v54, v50 offset0:40 offset1:56
	ds_write2_b32 v56, v55, v51 offset0:172 offset1:188
	v_add_u32_e32 v48, 0x2000, v115
	ds_write2_b32 v48, v44, v40 offset0:64 offset1:80
	ds_write2_b32 v48, v45, v41 offset0:196 offset1:212
	v_add_u32_e32 v40, 0x2400, v115
	ds_write2_b32 v40, v46, v42 offset0:72 offset1:88
	ds_write2_b32 v40, v47, v43 offset0:204 offset1:220
	ds_write2_b32 v48, v36, v32 offset0:96 offset1:112
	ds_write2_b32 v48, v37, v33 offset0:228 offset1:244
	ds_write2_b32 v40, v38, v34 offset0:104 offset1:120
	ds_write2_b32 v40, v39, v35 offset0:236 offset1:252
	v_add_u32_e32 v32, 0x4000, v115
	ds_write2_b32 v32, v28, v24 offset0:128 offset1:144
	v_add_u32_e32 v24, 0x4400, v115
	ds_write2_b32 v24, v29, v25 offset0:4 offset1:20
	ds_write2_b32 v24, v30, v26 offset0:136 offset1:152
	v_add_u32_e32 v25, 0x4800, v115
	ds_write2_b32 v25, v31, v27 offset0:12 offset1:28
	ds_write2_b32 v32, v20, v16 offset0:160 offset1:176
	ds_write2_b32 v24, v21, v17 offset0:36 offset1:52
	ds_write2_b32 v24, v22, v18 offset0:168 offset1:184
	ds_write2_b32 v25, v23, v19 offset0:44 offset1:60
	v_add_u32_e32 v16, 0x6000, v115
	ds_write2_b32 v16, v12, v8 offset0:192 offset1:208
	v_add_u32_e32 v8, 0x6400, v115
	ds_write2_b32 v8, v13, v9 offset0:68 offset1:84
	ds_write2_b32 v8, v14, v10 offset0:200 offset1:216
	v_add_u32_e32 v9, 0x6800, v115
	ds_write2_b32 v9, v15, v11 offset0:76 offset1:92
	ds_write2_b32 v16, v4, v0 offset0:224 offset1:240
	ds_write2_b32 v8, v5, v1 offset0:100 offset1:116
	ds_write2_b32 v8, v6, v2 offset0:232 offset1:248
	ds_write2_b32 v9, v7, v3 offset0:108 offset1:124
	v_or_b32_e32 v0, s23, v116
	v_ashrrev_i32_e32 v1, 31, v0
	v_lshlrev_b64 v[2:3], 2, v[0:1]
	v_lshl_add_u64 v[0:1], s[12:13], 0, v[2:3]
	v_lshl_add_u64 v[2:3], s[10:11], 0, v[2:3]
	v_add_u32_e32 v4, s24, v129
	s_mov_b32 s14, 0
	s_waitcnt lgkmcnt(0)
	s_barrier

.LBB0_702:
	s_and_b32 s27, s26, 0x4000
	s_xor_b32 s28, s27, 0x4000
	s_lshl_b32 s28, s28, 1
	s_add_i32 s28, s28, 32
	s_add_u32 s90, s52, s14
	s_addc_u32 s91, s53, s15
	s_add_i32 m0, s28, s82
	s_lshl_b32 s27, s27, 1
	global_load_lds_dwordx4 v193, s[90:91]
	s_add_i32 m0, s28, s83
	s_add_i32 s27, s27, 32
	global_load_lds_dwordx4 v194, s[90:91]
	s_add_i32 m0, s28, s84
	v_lshlrev_b32_e32 v72, 1, v131
	global_load_lds_dwordx4 v195, s[90:91]
	s_add_i32 m0, s28, s85
	v_add3_u32 v178, s27, v129, v72
	global_load_lds_dwordx4 v196, s[90:91]
	s_add_i32 m0, s28, s86
	v_lshlrev_b32_e32 v154, 1, v121
	global_load_lds_dwordx4 v197, s[90:91]
	s_add_i32 m0, s28, s87
	v_add3_u32 v72, s27, v130, v72
	global_load_lds_dwordx4 v198, s[90:91]
	s_add_i32 m0, s28, s88
	v_add_u32_e32 v174, v178, v154
	global_load_lds_dwordx4 v199, s[90:91]
	s_add_i32 m0, s28, s89
	v_add_u32_e32 v179, v72, v154
	global_load_lds_dwordx4 v200, s[90:91]
	ds_read_b128 v[154:157], v174
	ds_read_b128 v[162:165], v179 offset:16384
	ds_read_b128 v[166:169], v179 offset:18432
	ds_read_b128 v[182:185], v179 offset:20480
	ds_read_b128 v[186:189], v179 offset:22528
	ds_read_b128 v[158:161], v174 offset:2048
	ds_read_b128 v[170:173], v174 offset:4096
	ds_read_b128 v[174:177], v174 offset:6144
	v_lshlrev_b32_e32 v236, 1, v122
	v_add_u32_e32 v237, v178, v236
	v_add_u32_e32 v72, v72, v236
	ds_read_b128 v[204:207], v237
	ds_read_b128 v[208:211], v72 offset:16384
	ds_read_b128 v[212:215], v72 offset:18432
	ds_read_b128 v[216:219], v72 offset:20480
	ds_read_b128 v[220:223], v72 offset:22528
	ds_read_b128 v[224:227], v237 offset:2048
	ds_read_b128 v[228:231], v237 offset:4096
	ds_read_b128 v[232:235], v237 offset:6144
	s_setprio 1
	s_waitcnt lgkmcnt(11)
	v_mfma_f32_16x16x32_bf16 v[60:63], v[154:157], v[162:165], v[60:63]
	v_mfma_f32_16x16x32_bf16 v[56:59], v[154:157], v[166:169], v[56:59]
	v_mfma_f32_16x16x32_bf16 v[52:55], v[154:157], v[182:185], v[52:55]
	v_mfma_f32_16x16x32_bf16 v[48:51], v[154:157], v[186:189], v[48:51]
	s_waitcnt lgkmcnt(10)
	v_mfma_f32_16x16x32_bf16 v[44:47], v[158:161], v[162:165], v[44:47]
	v_mfma_f32_16x16x32_bf16 v[40:43], v[158:161], v[166:169], v[40:43]
	v_mfma_f32_16x16x32_bf16 v[36:39], v[158:161], v[182:185], v[36:39]
	v_mfma_f32_16x16x32_bf16 v[32:35], v[158:161], v[186:189], v[32:35]
	s_waitcnt lgkmcnt(9)
	v_mfma_f32_16x16x32_bf16 v[28:31], v[170:173], v[162:165], v[28:31]
	v_mfma_f32_16x16x32_bf16 v[24:27], v[170:173], v[166:169], v[24:27]
	v_mfma_f32_16x16x32_bf16 v[20:23], v[170:173], v[182:185], v[20:23]
	v_mfma_f32_16x16x32_bf16 v[16:19], v[170:173], v[186:189], v[16:19]
	s_waitcnt lgkmcnt(8)
	v_mfma_f32_16x16x32_bf16 v[12:15], v[174:177], v[162:165], v[12:15]
	v_mfma_f32_16x16x32_bf16 v[8:11], v[174:177], v[166:169], v[8:11]
	v_mfma_f32_16x16x32_bf16 v[4:7], v[174:177], v[182:185], v[4:7]
	v_mfma_f32_16x16x32_bf16 v[0:3], v[174:177], v[186:189], v[0:3]
	s_waitcnt lgkmcnt(3)
	v_mfma_f32_16x16x32_bf16 v[60:63], v[204:207], v[208:211], v[60:63]
	v_mfma_f32_16x16x32_bf16 v[56:59], v[204:207], v[212:215], v[56:59]
	v_mfma_f32_16x16x32_bf16 v[52:55], v[204:207], v[216:219], v[52:55]
	v_mfma_f32_16x16x32_bf16 v[48:51], v[204:207], v[220:223], v[48:51]
	s_waitcnt lgkmcnt(2)
	v_mfma_f32_16x16x32_bf16 v[44:47], v[224:227], v[208:211], v[44:47]
	v_mfma_f32_16x16x32_bf16 v[40:43], v[224:227], v[212:215], v[40:43]
	v_mfma_f32_16x16x32_bf16 v[36:39], v[224:227], v[216:219], v[36:39]
	v_mfma_f32_16x16x32_bf16 v[32:35], v[224:227], v[220:223], v[32:35]
	s_waitcnt lgkmcnt(1)
	v_mfma_f32_16x16x32_bf16 v[28:31], v[228:231], v[208:211], v[28:31]
	v_mfma_f32_16x16x32_bf16 v[24:27], v[228:231], v[212:215], v[24:27]
	v_mfma_f32_16x16x32_bf16 v[20:23], v[228:231], v[216:219], v[20:23]
	v_mfma_f32_16x16x32_bf16 v[16:19], v[228:231], v[220:223], v[16:19]
	s_waitcnt lgkmcnt(0)
	v_mfma_f32_16x16x32_bf16 v[12:15], v[232:235], v[208:211], v[12:15]
	v_mfma_f32_16x16x32_bf16 v[8:11], v[232:235], v[212:215], v[8:11]
	v_mfma_f32_16x16x32_bf16 v[4:7], v[232:235], v[216:219], v[4:7]
	v_mfma_f32_16x16x32_bf16 v[0:3], v[232:235], v[220:223], v[0:3]
	s_setprio 0
	s_add_u32 s14, s14, 0x80
	s_addc_u32 s15, s15, 0
	s_addk_i32 s26, 0x4000
	s_cmpk_eq_i32 s14, 0x1f80
	s_waitcnt vmcnt(0)
	s_barrier
	s_cbranch_scc0 .LBB0_702
	ds_read_b128 v[98:101], v71 offset:32768
	ds_read_b128 v[102:105], v71 offset:34816
	ds_read_b128 v[106:109], v138 offset:49152
	ds_read_b128 v[110:113], v138 offset:51200
	ds_read_b128 v[154:157], v71 offset:36864
	ds_read_b128 v[158:161], v71 offset:38912
	ds_read_b128 v[162:165], v138 offset:53248
	ds_read_b128 v[166:169], v138 offset:55296
	s_setprio 1
	s_waitcnt lgkmcnt(1)
	v_mfma_f32_16x16x32_bf16 v[4:7], v[158:161], v[162:165], v[4:7]
	s_waitcnt lgkmcnt(0)
	v_mfma_f32_16x16x32_bf16 v[0:3], v[158:161], v[166:169], v[0:3]
	v_mfma_f32_16x16x32_bf16 v[60:63], v[98:101], v[106:109], v[60:63]
	v_mfma_f32_16x16x32_bf16 v[56:59], v[98:101], v[110:113], v[56:59]
	v_mfma_f32_16x16x32_bf16 v[52:55], v[98:101], v[162:165], v[52:55]
	v_mfma_f32_16x16x32_bf16 v[48:51], v[98:101], v[166:169], v[48:51]
	v_mfma_f32_16x16x32_bf16 v[44:47], v[102:105], v[106:109], v[44:47]
	v_mfma_f32_16x16x32_bf16 v[40:43], v[102:105], v[110:113], v[40:43]
	v_mfma_f32_16x16x32_bf16 v[36:39], v[102:105], v[162:165], v[36:39]
	v_mfma_f32_16x16x32_bf16 v[32:35], v[102:105], v[166:169], v[32:35]
	v_mfma_f32_16x16x32_bf16 v[28:31], v[154:157], v[106:109], v[28:31]
	v_mfma_f32_16x16x32_bf16 v[24:27], v[154:157], v[110:113], v[24:27]
	v_mfma_f32_16x16x32_bf16 v[20:23], v[154:157], v[162:165], v[20:23]
	v_mfma_f32_16x16x32_bf16 v[16:19], v[154:157], v[166:169], v[16:19]
	v_mfma_f32_16x16x32_bf16 v[12:15], v[158:161], v[106:109], v[12:15]
	v_mfma_f32_16x16x32_bf16 v[8:11], v[158:161], v[110:113], v[8:11]
	s_setprio 0
	ds_read_b128 v[98:101], v139 offset:32768
	ds_read_b128 v[102:105], v139 offset:34816
	ds_read_b128 v[106:109], v140 offset:49152
	ds_read_b128 v[110:113], v140 offset:51200
	ds_read_b128 v[154:157], v139 offset:36864
	ds_read_b128 v[158:161], v139 offset:38912
	ds_read_b128 v[162:165], v140 offset:53248
	ds_read_b128 v[166:169], v140 offset:55296
	s_setprio 1
	s_waitcnt lgkmcnt(1)
	v_mfma_f32_16x16x32_bf16 v[4:7], v[158:161], v[162:165], v[4:7]
	s_waitcnt lgkmcnt(0)
	v_mfma_f32_16x16x32_bf16 v[0:3], v[158:161], v[166:169], v[0:3]
	v_mfma_f32_16x16x32_bf16 v[60:63], v[98:101], v[106:109], v[60:63]
	v_mfma_f32_16x16x32_bf16 v[56:59], v[98:101], v[110:113], v[56:59]
	v_mfma_f32_16x16x32_bf16 v[52:55], v[98:101], v[162:165], v[52:55]
	v_mfma_f32_16x16x32_bf16 v[48:51], v[98:101], v[166:169], v[48:51]
	v_mfma_f32_16x16x32_bf16 v[44:47], v[102:105], v[106:109], v[44:47]
	v_mfma_f32_16x16x32_bf16 v[40:43], v[102:105], v[110:113], v[40:43]
	v_mfma_f32_16x16x32_bf16 v[36:39], v[102:105], v[162:165], v[36:39]
	v_mfma_f32_16x16x32_bf16 v[32:35], v[102:105], v[166:169], v[32:35]
	v_mfma_f32_16x16x32_bf16 v[28:31], v[154:157], v[106:109], v[28:31]
	v_mfma_f32_16x16x32_bf16 v[24:27], v[154:157], v[110:113], v[24:27]
	v_mfma_f32_16x16x32_bf16 v[20:23], v[154:157], v[162:165], v[20:23]
	v_mfma_f32_16x16x32_bf16 v[16:19], v[154:157], v[166:169], v[16:19]
	v_mfma_f32_16x16x32_bf16 v[12:15], v[158:161], v[106:109], v[12:15]
	v_mfma_f32_16x16x32_bf16 v[8:11], v[158:161], v[110:113], v[8:11]
	s_setprio 0
	s_barrier
	ds_write2_b32 v136, v60, v56 offset1:16
	ds_write2_b32 v136, v61, v57 offset0:132 offset1:148
	v_add_u32_e32 v56, 0x400, v136
	ds_write2_b32 v56, v62, v58 offset0:8 offset1:24
	ds_write2_b32 v56, v63, v59 offset0:140 offset1:156
	ds_write2_b32 v136, v52, v48 offset0:32 offset1:48
	ds_write2_b32 v136, v53, v49 offset0:164 offset1:180
	ds_write2_b32 v56, v54, v50 offset0:40 offset1:56
	ds_write2_b32 v56, v55, v51 offset0:172 offset1:188
	v_add_u32_e32 v48, 0x2000, v136
	ds_write2_b32 v48, v44, v40 offset0:64 offset1:80
	ds_write2_b32 v48, v45, v41 offset0:196 offset1:212
	v_add_u32_e32 v40, 0x2400, v136
	ds_write2_b32 v40, v46, v42 offset0:72 offset1:88
	ds_write2_b32 v40, v47, v43 offset0:204 offset1:220
	ds_write2_b32 v48, v36, v32 offset0:96 offset1:112
	ds_write2_b32 v48, v37, v33 offset0:228 offset1:244
	ds_write2_b32 v40, v38, v34 offset0:104 offset1:120
	ds_write2_b32 v40, v39, v35 offset0:236 offset1:252
	v_add_u32_e32 v32, 0x4000, v136
	ds_write2_b32 v32, v28, v24 offset0:128 offset1:144
	v_add_u32_e32 v24, 0x4400, v136
	ds_write2_b32 v24, v29, v25 offset0:4 offset1:20
	ds_write2_b32 v24, v30, v26 offset0:136 offset1:152
	v_add_u32_e32 v25, 0x4800, v136
	ds_write2_b32 v25, v31, v27 offset0:12 offset1:28
	ds_write2_b32 v32, v20, v16 offset0:160 offset1:176
	ds_write2_b32 v24, v21, v17 offset0:36 offset1:52
	ds_write2_b32 v24, v22, v18 offset0:168 offset1:184
	ds_write2_b32 v25, v23, v19 offset0:44 offset1:60
	v_add_u32_e32 v16, 0x6000, v136
	ds_write2_b32 v16, v12, v8 offset0:192 offset1:208
	v_add_u32_e32 v8, 0x6400, v136
	ds_write2_b32 v8, v13, v9 offset0:68 offset1:84
	ds_write2_b32 v8, v14, v10 offset0:200 offset1:216
	v_add_u32_e32 v9, 0x6800, v136
	ds_write2_b32 v9, v15, v11 offset0:76 offset1:92
	ds_write2_b32 v16, v4, v0 offset0:224 offset1:240
	ds_write2_b32 v8, v5, v1 offset0:100 offset1:116
	ds_write2_b32 v8, v6, v2 offset0:232 offset1:248
	ds_write2_b32 v9, v7, v3 offset0:108 offset1:124
	v_or_b32_e32 v0, s24, v137
	v_lshlrev_b32_e32 v72, 2, v0
	v_lshl_add_u64 v[0:1], s[12:13], 0, v[72:73]
	v_lshl_add_u64 v[2:3], s[10:11], 0, v[72:73]
	v_add_u32_e32 v4, s25, v149
	s_mov_b32 s14, 0
	s_waitcnt lgkmcnt(0)
	s_barrier

.LBB0_708:
	s_and_b32 s6, s11, 0x4000
	s_xor_b32 s7, s6, 0x4000
	s_lshl_b32 s7, s7, 1
	s_add_i32 s7, s7, 32
	s_add_u32 s90, s52, s4
	s_addc_u32 s91, s53, s5
	s_add_i32 m0, s7, s82
	s_lshl_b32 s6, s6, 1
	global_load_lds_dwordx4 v192, s[90:91]
	s_add_i32 m0, s7, s83
	s_add_i32 s6, s6, 32
	global_load_lds_dwordx4 v193, s[90:91]
	s_add_i32 m0, s7, s84
	v_lshlrev_b32_e32 v85, 1, v80
	global_load_lds_dwordx4 v194, s[90:91]
	s_add_i32 m0, s7, s85
	v_add3_u32 v112, s6, v81, v85
	global_load_lds_dwordx4 v195, s[90:91]
	s_add_i32 m0, s7, s86
	v_lshlrev_b32_e32 v86, 1, v121
	global_load_lds_dwordx4 v196, s[90:91]
	s_add_i32 m0, s7, s87
	v_add3_u32 v113, s6, v82, v85
	global_load_lds_dwordx4 v197, s[90:91]
	s_add_i32 m0, s7, s88
	v_add_u32_e32 v87, v112, v86
	global_load_lds_dwordx4 v198, s[90:91]
	s_add_i32 m0, s7, s89
	v_add_u32_e32 v123, v113, v86
	global_load_lds_dwordx4 v199, s[90:91]
	ds_read_b128 v[88:91], v87
	ds_read_b128 v[96:99], v123 offset:16384
	ds_read_b128 v[100:103], v123 offset:18432
	ds_read_b128 v[124:127], v123 offset:20480
	ds_read_b128 v[128:131], v123 offset:22528
	ds_read_b128 v[92:95], v87 offset:2048
	ds_read_b128 v[104:107], v87 offset:4096
	ds_read_b128 v[108:111], v87 offset:6144
	v_lshlrev_b32_e32 v87, 1, v122
	v_add_u32_e32 v236, v112, v87
	v_add_u32_e32 v112, v113, v87
	ds_read_b128 v[204:207], v236
	ds_read_b128 v[208:211], v112 offset:16384
	ds_read_b128 v[212:215], v112 offset:18432
	ds_read_b128 v[216:219], v112 offset:20480
	ds_read_b128 v[220:223], v112 offset:22528
	ds_read_b128 v[224:227], v236 offset:2048
	ds_read_b128 v[228:231], v236 offset:4096
	ds_read_b128 v[232:235], v236 offset:6144
	s_setprio 1
	s_waitcnt lgkmcnt(11)
	v_mfma_f32_16x16x32_bf16 v[60:63], v[88:91], v[96:99], v[60:63]
	v_mfma_f32_16x16x32_bf16 v[56:59], v[88:91], v[100:103], v[56:59]
	v_mfma_f32_16x16x32_bf16 v[52:55], v[88:91], v[124:127], v[52:55]
	v_mfma_f32_16x16x32_bf16 v[48:51], v[88:91], v[128:131], v[48:51]
	s_waitcnt lgkmcnt(10)
	v_mfma_f32_16x16x32_bf16 v[44:47], v[92:95], v[96:99], v[44:47]
	v_mfma_f32_16x16x32_bf16 v[40:43], v[92:95], v[100:103], v[40:43]
	v_mfma_f32_16x16x32_bf16 v[36:39], v[92:95], v[124:127], v[36:39]
	v_mfma_f32_16x16x32_bf16 v[32:35], v[92:95], v[128:131], v[32:35]
	s_waitcnt lgkmcnt(9)
	v_mfma_f32_16x16x32_bf16 v[28:31], v[104:107], v[96:99], v[28:31]
	v_mfma_f32_16x16x32_bf16 v[24:27], v[104:107], v[100:103], v[24:27]
	v_mfma_f32_16x16x32_bf16 v[20:23], v[104:107], v[124:127], v[20:23]
	v_mfma_f32_16x16x32_bf16 v[16:19], v[104:107], v[128:131], v[16:19]
	s_waitcnt lgkmcnt(8)
	v_mfma_f32_16x16x32_bf16 v[12:15], v[108:111], v[96:99], v[12:15]
	v_mfma_f32_16x16x32_bf16 v[8:11], v[108:111], v[100:103], v[8:11]
	v_mfma_f32_16x16x32_bf16 v[4:7], v[108:111], v[124:127], v[4:7]
	v_mfma_f32_16x16x32_bf16 v[0:3], v[108:111], v[128:131], v[0:3]
	s_waitcnt lgkmcnt(3)
	v_mfma_f32_16x16x32_bf16 v[60:63], v[204:207], v[208:211], v[60:63]
	v_mfma_f32_16x16x32_bf16 v[56:59], v[204:207], v[212:215], v[56:59]
	v_mfma_f32_16x16x32_bf16 v[52:55], v[204:207], v[216:219], v[52:55]
	v_mfma_f32_16x16x32_bf16 v[48:51], v[204:207], v[220:223], v[48:51]
	s_waitcnt lgkmcnt(2)
	v_mfma_f32_16x16x32_bf16 v[44:47], v[224:227], v[208:211], v[44:47]
	v_mfma_f32_16x16x32_bf16 v[40:43], v[224:227], v[212:215], v[40:43]
	v_mfma_f32_16x16x32_bf16 v[36:39], v[224:227], v[216:219], v[36:39]
	v_mfma_f32_16x16x32_bf16 v[32:35], v[224:227], v[220:223], v[32:35]
	s_waitcnt lgkmcnt(1)
	v_mfma_f32_16x16x32_bf16 v[28:31], v[228:231], v[208:211], v[28:31]
	v_mfma_f32_16x16x32_bf16 v[24:27], v[228:231], v[212:215], v[24:27]
	v_mfma_f32_16x16x32_bf16 v[20:23], v[228:231], v[216:219], v[20:23]
	v_mfma_f32_16x16x32_bf16 v[16:19], v[228:231], v[220:223], v[16:19]
	s_waitcnt lgkmcnt(0)
	v_mfma_f32_16x16x32_bf16 v[12:15], v[232:235], v[208:211], v[12:15]
	v_mfma_f32_16x16x32_bf16 v[8:11], v[232:235], v[212:215], v[8:11]
	v_mfma_f32_16x16x32_bf16 v[4:7], v[232:235], v[216:219], v[4:7]
	v_mfma_f32_16x16x32_bf16 v[0:3], v[232:235], v[220:223], v[0:3]
	s_setprio 0
	s_add_u32 s4, s4, 0x80
	s_addc_u32 s5, s5, 0
	s_addk_i32 s11, 0x4000
	s_cmpk_eq_i32 s4, 0x780
	s_waitcnt vmcnt(0)
	s_barrier
	s_cbranch_scc0 .LBB0_708
	v_add3_u32 v84, 32, v81, v85
	v_add3_u32 v85, 32, v82, v85
	v_add_u32_e32 v88, v84, v86
	v_add_u32_e32 v86, v85, v86
	ds_read_b128 v[64:67], v88 offset:32768
	ds_read_b128 v[68:71], v88 offset:34816
	ds_read_b128 v[72:75], v86 offset:49152
	ds_read_b128 v[76:79], v86 offset:51200
	ds_read_b128 v[80:83], v88 offset:36864
	ds_read_b128 v[88:91], v88 offset:38912
	ds_read_b128 v[92:95], v86 offset:53248
	ds_read_b128 v[96:99], v86 offset:55296
	s_setprio 1
	s_waitcnt lgkmcnt(0)
	v_mfma_f32_16x16x32_bf16 v[0:3], v[88:91], v[96:99], v[0:3]
	v_mfma_f32_16x16x32_bf16 v[60:63], v[64:67], v[72:75], v[60:63]
	v_mfma_f32_16x16x32_bf16 v[56:59], v[64:67], v[76:79], v[56:59]
	v_mfma_f32_16x16x32_bf16 v[52:55], v[64:67], v[92:95], v[52:55]
	v_mfma_f32_16x16x32_bf16 v[48:51], v[64:67], v[96:99], v[48:51]
	v_mfma_f32_16x16x32_bf16 v[44:47], v[68:71], v[72:75], v[44:47]
	v_mfma_f32_16x16x32_bf16 v[40:43], v[68:71], v[76:79], v[40:43]
	v_mfma_f32_16x16x32_bf16 v[36:39], v[68:71], v[92:95], v[36:39]
	v_mfma_f32_16x16x32_bf16 v[32:35], v[68:71], v[96:99], v[32:35]
	v_mfma_f32_16x16x32_bf16 v[28:31], v[80:83], v[72:75], v[28:31]
	v_mfma_f32_16x16x32_bf16 v[24:27], v[80:83], v[76:79], v[24:27]
	v_mfma_f32_16x16x32_bf16 v[20:23], v[80:83], v[92:95], v[20:23]
	v_mfma_f32_16x16x32_bf16 v[16:19], v[80:83], v[96:99], v[16:19]
	v_mfma_f32_16x16x32_bf16 v[12:15], v[88:91], v[72:75], v[12:15]
	v_mfma_f32_16x16x32_bf16 v[8:11], v[88:91], v[76:79], v[8:11]
	v_mfma_f32_16x16x32_bf16 v[4:7], v[88:91], v[92:95], v[4:7]
	s_setprio 0
	v_add_u32_e32 v84, v84, v87
	v_add_u32_e32 v92, v85, v87
	ds_read_b128 v[64:67], v84 offset:32768
	ds_read_b128 v[68:71], v84 offset:34816
	ds_read_b128 v[72:75], v92 offset:49152
	ds_read_b128 v[76:79], v92 offset:51200
	ds_read_b128 v[80:83], v84 offset:36864
	ds_read_b128 v[84:87], v84 offset:38912
	ds_read_b128 v[88:91], v92 offset:53248
	ds_read_b128 v[92:95], v92 offset:55296
	s_setprio 1
	s_waitcnt lgkmcnt(0)
	v_mfma_f32_16x16x32_bf16 v[0:3], v[84:87], v[92:95], v[0:3]
	v_mfma_f32_16x16x32_bf16 v[60:63], v[64:67], v[72:75], v[60:63]
	v_mfma_f32_16x16x32_bf16 v[56:59], v[64:67], v[76:79], v[56:59]
	v_mfma_f32_16x16x32_bf16 v[52:55], v[64:67], v[88:91], v[52:55]
	v_mfma_f32_16x16x32_bf16 v[48:51], v[64:67], v[92:95], v[48:51]
	v_mfma_f32_16x16x32_bf16 v[44:47], v[68:71], v[72:75], v[44:47]
	v_mfma_f32_16x16x32_bf16 v[40:43], v[68:71], v[76:79], v[40:43]
	v_mfma_f32_16x16x32_bf16 v[36:39], v[68:71], v[88:91], v[36:39]
	v_mfma_f32_16x16x32_bf16 v[32:35], v[68:71], v[92:95], v[32:35]
	v_mfma_f32_16x16x32_bf16 v[28:31], v[80:83], v[72:75], v[28:31]
	v_mfma_f32_16x16x32_bf16 v[24:27], v[80:83], v[76:79], v[24:27]
	v_mfma_f32_16x16x32_bf16 v[20:23], v[80:83], v[88:91], v[20:23]
	v_mfma_f32_16x16x32_bf16 v[16:19], v[80:83], v[92:95], v[16:19]
	v_mfma_f32_16x16x32_bf16 v[12:15], v[84:87], v[72:75], v[12:15]
	v_mfma_f32_16x16x32_bf16 v[8:11], v[84:87], v[76:79], v[8:11]
	v_mfma_f32_16x16x32_bf16 v[4:7], v[84:87], v[88:91], v[4:7]
	s_setprio 0
	v_lshl_or_b32 v64, v114, 2, v116
	v_mul_u32_u24_e32 v64, 0x210, v64
	v_add3_u32 v64, v115, v117, v64
	s_barrier
	ds_write2_b32 v64, v60, v56 offset1:16
	ds_write2_b32 v64, v61, v57 offset0:132 offset1:148
	v_add_u32_e32 v56, 0x400, v64
	ds_write2_b32 v56, v62, v58 offset0:8 offset1:24
	ds_write2_b32 v56, v63, v59 offset0:140 offset1:156
	ds_write2_b32 v64, v52, v48 offset0:32 offset1:48
	ds_write2_b32 v64, v53, v49 offset0:164 offset1:180
	ds_write2_b32 v56, v54, v50 offset0:40 offset1:56
	ds_write2_b32 v56, v55, v51 offset0:172 offset1:188
	v_add_u32_e32 v48, 0x2000, v64
	ds_write2_b32 v48, v44, v40 offset0:64 offset1:80
	ds_write2_b32 v48, v45, v41 offset0:196 offset1:212
	v_add_u32_e32 v40, 0x2400, v64
	ds_write2_b32 v40, v46, v42 offset0:72 offset1:88
	ds_write2_b32 v40, v47, v43 offset0:204 offset1:220
	ds_write2_b32 v48, v36, v32 offset0:96 offset1:112
	ds_write2_b32 v48, v37, v33 offset0:228 offset1:244
	ds_write2_b32 v40, v38, v34 offset0:104 offset1:120
	ds_write2_b32 v40, v39, v35 offset0:236 offset1:252
	v_add_u32_e32 v32, 0x4000, v64
	ds_write2_b32 v32, v28, v24 offset0:128 offset1:144
	v_add_u32_e32 v24, 0x4400, v64
	ds_write2_b32 v24, v29, v25 offset0:4 offset1:20
	ds_write2_b32 v24, v30, v26 offset0:136 offset1:152
	v_add_u32_e32 v25, 0x4800, v64
	ds_write2_b32 v25, v31, v27 offset0:12 offset1:28
	ds_write2_b32 v32, v20, v16 offset0:160 offset1:176
	ds_write2_b32 v24, v21, v17 offset0:36 offset1:52
	ds_write2_b32 v24, v22, v18 offset0:168 offset1:184
	ds_write2_b32 v25, v23, v19 offset0:44 offset1:60
	v_add_u32_e32 v16, 0x6000, v64
	ds_write2_b32 v16, v12, v8 offset0:192 offset1:208
	v_add_u32_e32 v8, 0x6400, v64
	ds_write2_b32 v8, v13, v9 offset0:68 offset1:84
	ds_write2_b32 v8, v14, v10 offset0:200 offset1:216
	v_add_u32_e32 v9, 0x6800, v64
	ds_write2_b32 v9, v15, v11 offset0:76 offset1:92
	ds_write2_b32 v16, v4, v0 offset0:224 offset1:240
	ds_write2_b32 v8, v5, v1 offset0:100 offset1:116
	ds_write2_b32 v8, v6, v2 offset0:232 offset1:248
	ds_write2_b32 v9, v7, v3 offset0:108 offset1:124
	v_lshlrev_b32_e32 v0, 4, v180
	v_and_b32_e32 v0, 0x70, v0
	s_lshl_b32 s5, s14, 23
	v_or_b32_e32 v0, s9, v0
	s_add_u32 s6, s12, s5
	s_addc_u32 s7, s13, 0
	v_lshlrev_b32_e32 v0, 2, v0
	v_mov_b32_e32 v1, 0
	v_lshrrev_b32_e32 v2, 3, v180
	v_and_b32_e32 v4, 7, v180
	v_lshl_add_u64 v[0:1], s[6:7], 0, v[0:1]
	s_mov_b64 s[6:7], 0x11600000
	v_mul_u32_u24_e32 v3, 0x210, v2
	v_lshlrev_b32_e32 v4, 6, v4
	s_mov_b32 s4, 0
	v_lshl_add_u64 v[0:1], v[0:1], 0, s[6:7]
	v_add3_u32 v3, v3, v4, 32
	s_mov_b32 s5, 0x38e38e39
	s_mov_b32 s6, 0x1ffffee
	s_movk_i32 s7, 0xf800
	s_waitcnt lgkmcnt(0)
	s_barrier

.LBB0_1814:
	s_and_b32 s27, s26, 0x4000
	s_xor_b32 s28, s27, 0x4000
	s_lshl_b32 s28, s28, 1
	s_add_i32 s28, s28, 32
	s_add_u32 s90, s52, s16
	s_addc_u32 s91, s53, s17
	s_add_i32 m0, s28, s82
	s_lshl_b32 s27, s27, 1
	global_load_lds_dwordx4 v188, s[90:91]
	s_add_i32 m0, s28, s83
	s_add_i32 s27, s27, 32
	global_load_lds_dwordx4 v189, s[90:91]
	s_add_i32 m0, s28, s84
	v_add3_u32 v170, s27, v114, v135
	global_load_lds_dwordx4 v190, s[90:91]
	s_add_i32 m0, s28, s85
	v_add3_u32 v171, s27, v115, v135
	global_load_lds_dwordx4 v191, s[90:91]
	s_add_i32 m0, s28, s86
	v_add_u32_e32 v158, v170, v136
	global_load_lds_dwordx4 v192, s[90:91]
	s_add_i32 m0, s28, s87
	v_add_u32_e32 v166, v171, v136
	global_load_lds_dwordx4 v193, s[90:91]
	s_add_i32 m0, s28, s88
	s_addk_i32 s26, 0x4000
	global_load_lds_dwordx4 v194, s[90:91]
	s_add_i32 m0, s28, s89
	s_add_u32 s16, s16, 0x80
	s_addc_u32 s17, s17, 0
	global_load_lds_dwordx4 v195, s[90:91]
	ds_read_b128 v[138:141], v158
	ds_read_b128 v[146:149], v166 offset:16384
	ds_read_b128 v[150:153], v166 offset:18432
	ds_read_b128 v[162:165], v166 offset:20480
	ds_read_b128 v[166:169], v166 offset:22528
	ds_read_b128 v[142:145], v158 offset:2048
	ds_read_b128 v[154:157], v158 offset:4096
	ds_read_b128 v[158:161], v158 offset:6144
	v_add_u32_e32 v236, v170, v137
	v_add_u32_e32 v237, v171, v137
	ds_read_b128 v[204:207], v236
	ds_read_b128 v[208:211], v237 offset:16384
	ds_read_b128 v[212:215], v237 offset:18432
	ds_read_b128 v[216:219], v237 offset:20480
	ds_read_b128 v[220:223], v237 offset:22528
	ds_read_b128 v[224:227], v236 offset:2048
	ds_read_b128 v[228:231], v236 offset:4096
	ds_read_b128 v[232:235], v236 offset:6144
	s_setprio 1
	s_waitcnt lgkmcnt(11)
	v_mfma_f32_16x16x32_bf16 v[60:63], v[138:141], v[146:149], v[60:63]
	v_mfma_f32_16x16x32_bf16 v[56:59], v[138:141], v[150:153], v[56:59]
	v_mfma_f32_16x16x32_bf16 v[52:55], v[138:141], v[162:165], v[52:55]
	v_mfma_f32_16x16x32_bf16 v[48:51], v[138:141], v[166:169], v[48:51]
	s_waitcnt lgkmcnt(10)
	v_mfma_f32_16x16x32_bf16 v[44:47], v[142:145], v[146:149], v[44:47]
	v_mfma_f32_16x16x32_bf16 v[40:43], v[142:145], v[150:153], v[40:43]
	v_mfma_f32_16x16x32_bf16 v[36:39], v[142:145], v[162:165], v[36:39]
	v_mfma_f32_16x16x32_bf16 v[32:35], v[142:145], v[166:169], v[32:35]
	s_waitcnt lgkmcnt(9)
	v_mfma_f32_16x16x32_bf16 v[28:31], v[154:157], v[146:149], v[28:31]
	v_mfma_f32_16x16x32_bf16 v[24:27], v[154:157], v[150:153], v[24:27]
	v_mfma_f32_16x16x32_bf16 v[20:23], v[154:157], v[162:165], v[20:23]
	v_mfma_f32_16x16x32_bf16 v[16:19], v[154:157], v[166:169], v[16:19]
	s_waitcnt lgkmcnt(8)
	v_mfma_f32_16x16x32_bf16 v[12:15], v[158:161], v[146:149], v[12:15]
	v_mfma_f32_16x16x32_bf16 v[8:11], v[158:161], v[150:153], v[8:11]
	v_mfma_f32_16x16x32_bf16 v[4:7], v[158:161], v[162:165], v[4:7]
	v_mfma_f32_16x16x32_bf16 v[0:3], v[158:161], v[166:169], v[0:3]
	s_waitcnt lgkmcnt(3)
	v_mfma_f32_16x16x32_bf16 v[60:63], v[204:207], v[208:211], v[60:63]
	v_mfma_f32_16x16x32_bf16 v[56:59], v[204:207], v[212:215], v[56:59]
	v_mfma_f32_16x16x32_bf16 v[52:55], v[204:207], v[216:219], v[52:55]
	v_mfma_f32_16x16x32_bf16 v[48:51], v[204:207], v[220:223], v[48:51]
	s_waitcnt lgkmcnt(2)
	v_mfma_f32_16x16x32_bf16 v[44:47], v[224:227], v[208:211], v[44:47]
	v_mfma_f32_16x16x32_bf16 v[40:43], v[224:227], v[212:215], v[40:43]
	v_mfma_f32_16x16x32_bf16 v[36:39], v[224:227], v[216:219], v[36:39]
	v_mfma_f32_16x16x32_bf16 v[32:35], v[224:227], v[220:223], v[32:35]
	s_waitcnt lgkmcnt(1)
	v_mfma_f32_16x16x32_bf16 v[28:31], v[228:231], v[208:211], v[28:31]
	v_mfma_f32_16x16x32_bf16 v[24:27], v[228:231], v[212:215], v[24:27]
	v_mfma_f32_16x16x32_bf16 v[20:23], v[228:231], v[216:219], v[20:23]
	v_mfma_f32_16x16x32_bf16 v[16:19], v[228:231], v[220:223], v[16:19]
	s_waitcnt lgkmcnt(0)
	v_mfma_f32_16x16x32_bf16 v[12:15], v[232:235], v[208:211], v[12:15]
	v_mfma_f32_16x16x32_bf16 v[8:11], v[232:235], v[212:215], v[8:11]
	v_mfma_f32_16x16x32_bf16 v[4:7], v[232:235], v[216:219], v[4:7]
	v_mfma_f32_16x16x32_bf16 v[0:3], v[232:235], v[220:223], v[0:3]
	s_setprio 0
	s_cmpk_eq_i32 s16, 0x780
	s_waitcnt vmcnt(0)
	s_barrier
	s_cbranch_scc0 .LBB0_1814
	ds_read_b128 v[90:93], v118 offset:55296
	ds_read_b128 v[94:97], v118 offset:53248
	ds_read_b128 v[98:101], v119 offset:38912
	ds_read_b128 v[102:105], v119 offset:36864
	ds_read_b128 v[138:141], v118 offset:51200
	ds_read_b128 v[142:145], v118 offset:49152
	ds_read_b128 v[146:149], v119 offset:34816
	ds_read_b128 v[150:153], v119 offset:32768
	s_setprio 1
	s_waitcnt lgkmcnt(5)
	v_mfma_f32_16x16x32_bf16 v[4:7], v[98:101], v[94:97], v[4:7]
	v_mfma_f32_16x16x32_bf16 v[0:3], v[98:101], v[90:93], v[0:3]
	s_waitcnt lgkmcnt(0)
	v_mfma_f32_16x16x32_bf16 v[60:63], v[150:153], v[142:145], v[60:63]
	v_mfma_f32_16x16x32_bf16 v[56:59], v[150:153], v[138:141], v[56:59]
	v_mfma_f32_16x16x32_bf16 v[52:55], v[150:153], v[94:97], v[52:55]
	v_mfma_f32_16x16x32_bf16 v[48:51], v[150:153], v[90:93], v[48:51]
	v_mfma_f32_16x16x32_bf16 v[44:47], v[146:149], v[142:145], v[44:47]
	v_mfma_f32_16x16x32_bf16 v[40:43], v[146:149], v[138:141], v[40:43]
	v_mfma_f32_16x16x32_bf16 v[36:39], v[146:149], v[94:97], v[36:39]
	v_mfma_f32_16x16x32_bf16 v[32:35], v[146:149], v[90:93], v[32:35]
	v_mfma_f32_16x16x32_bf16 v[28:31], v[102:105], v[142:145], v[28:31]
	v_mfma_f32_16x16x32_bf16 v[24:27], v[102:105], v[138:141], v[24:27]
	v_mfma_f32_16x16x32_bf16 v[20:23], v[102:105], v[94:97], v[20:23]
	v_mfma_f32_16x16x32_bf16 v[16:19], v[102:105], v[90:93], v[16:19]
	v_mfma_f32_16x16x32_bf16 v[12:15], v[98:101], v[142:145], v[12:15]
	v_mfma_f32_16x16x32_bf16 v[8:11], v[98:101], v[138:141], v[8:11]
	s_setprio 0
	ds_read_b128 v[90:93], v120 offset:32768
	ds_read_b128 v[94:97], v120 offset:34816
	ds_read_b128 v[98:101], v121 offset:49152
	ds_read_b128 v[102:105], v121 offset:51200
	ds_read_b128 v[138:141], v120 offset:36864
	ds_read_b128 v[142:145], v120 offset:38912
	ds_read_b128 v[146:149], v121 offset:53248
	ds_read_b128 v[150:153], v121 offset:55296
	s_setprio 1
	s_waitcnt lgkmcnt(1)
	v_mfma_f32_16x16x32_bf16 v[4:7], v[142:145], v[146:149], v[4:7]
	s_waitcnt lgkmcnt(0)
	v_mfma_f32_16x16x32_bf16 v[0:3], v[142:145], v[150:153], v[0:3]
	v_mfma_f32_16x16x32_bf16 v[60:63], v[90:93], v[98:101], v[60:63]
	v_mfma_f32_16x16x32_bf16 v[56:59], v[90:93], v[102:105], v[56:59]
	v_mfma_f32_16x16x32_bf16 v[52:55], v[90:93], v[146:149], v[52:55]
	v_mfma_f32_16x16x32_bf16 v[48:51], v[90:93], v[150:153], v[48:51]
	v_mfma_f32_16x16x32_bf16 v[44:47], v[94:97], v[98:101], v[44:47]
	v_mfma_f32_16x16x32_bf16 v[40:43], v[94:97], v[102:105], v[40:43]
	v_mfma_f32_16x16x32_bf16 v[36:39], v[94:97], v[146:149], v[36:39]
	v_mfma_f32_16x16x32_bf16 v[32:35], v[94:97], v[150:153], v[32:35]
	v_mfma_f32_16x16x32_bf16 v[28:31], v[138:141], v[98:101], v[28:31]
	v_mfma_f32_16x16x32_bf16 v[24:27], v[138:141], v[102:105], v[24:27]
	v_mfma_f32_16x16x32_bf16 v[20:23], v[138:141], v[146:149], v[20:23]
	v_mfma_f32_16x16x32_bf16 v[16:19], v[138:141], v[150:153], v[16:19]
	v_mfma_f32_16x16x32_bf16 v[12:15], v[142:145], v[98:101], v[12:15]
	v_mfma_f32_16x16x32_bf16 v[8:11], v[142:145], v[102:105], v[8:11]
	s_setprio 0
	s_barrier
	ds_write2_b32 v116, v60, v56 offset1:16
	ds_write2_b32 v116, v61, v57 offset0:132 offset1:148
	v_add_u32_e32 v56, 0x400, v116
	ds_write2_b32 v56, v62, v58 offset0:8 offset1:24
	ds_write2_b32 v56, v63, v59 offset0:140 offset1:156
	ds_write2_b32 v116, v52, v48 offset0:32 offset1:48
	ds_write2_b32 v116, v53, v49 offset0:164 offset1:180
	ds_write2_b32 v56, v54, v50 offset0:40 offset1:56
	ds_write2_b32 v56, v55, v51 offset0:172 offset1:188
	v_add_u32_e32 v48, 0x2000, v116
	ds_write2_b32 v48, v44, v40 offset0:64 offset1:80
	ds_write2_b32 v48, v45, v41 offset0:196 offset1:212
	v_add_u32_e32 v40, 0x2400, v116
	ds_write2_b32 v40, v46, v42 offset0:72 offset1:88
	ds_write2_b32 v40, v47, v43 offset0:204 offset1:220
	ds_write2_b32 v48, v36, v32 offset0:96 offset1:112
	ds_write2_b32 v48, v37, v33 offset0:228 offset1:244
	ds_write2_b32 v40, v38, v34 offset0:104 offset1:120
	ds_write2_b32 v40, v39, v35 offset0:236 offset1:252
	v_add_u32_e32 v32, 0x4000, v116
	ds_write2_b32 v32, v28, v24 offset0:128 offset1:144
	v_add_u32_e32 v24, 0x4400, v116
	ds_write2_b32 v24, v29, v25 offset0:4 offset1:20
	ds_write2_b32 v24, v30, v26 offset0:136 offset1:152
	v_add_u32_e32 v25, 0x4800, v116
	ds_write2_b32 v25, v31, v27 offset0:12 offset1:28
	ds_write2_b32 v32, v20, v16 offset0:160 offset1:176
	ds_write2_b32 v24, v21, v17 offset0:36 offset1:52
	ds_write2_b32 v24, v22, v18 offset0:168 offset1:184
	ds_write2_b32 v25, v23, v19 offset0:44 offset1:60
	v_add_u32_e32 v16, 0x6000, v116
	ds_write2_b32 v16, v12, v8 offset0:192 offset1:208
	v_add_u32_e32 v8, 0x6400, v116
	ds_write2_b32 v8, v13, v9 offset0:68 offset1:84
	ds_write2_b32 v8, v14, v10 offset0:200 offset1:216
	v_add_u32_e32 v9, 0x6800, v116
	ds_write2_b32 v9, v15, v11 offset0:76 offset1:92
	ds_write2_b32 v16, v4, v0 offset0:224 offset1:240
	ds_write2_b32 v8, v5, v1 offset0:100 offset1:116
	ds_write2_b32 v8, v6, v2 offset0:232 offset1:248
	ds_write2_b32 v9, v7, v3 offset0:108 offset1:124
	v_or_b32_e32 v0, s25, v117
	v_ashrrev_i32_e32 v1, 31, v0
	v_lshlrev_b64 v[2:3], 2, v[0:1]
	v_lshl_add_u64 v[0:1], s[14:15], 0, v[2:3]
	v_lshl_add_u64 v[2:3], s[10:11], 0, v[2:3]
	v_add_u32_e32 v4, s24, v128
	s_mov_b32 s16, 0
	s_waitcnt lgkmcnt(0)
	s_barrier

.LBB0_1823:
	s_and_b32 s28, s27, 0x4000
	s_xor_b32 s29, s28, 0x4000
	s_lshl_b32 s29, s29, 1
	s_add_i32 s29, s29, 32
	s_add_u32 s90, s52, s16
	s_addc_u32 s91, s53, s17
	s_add_i32 m0, s29, s82
	s_lshl_b32 s28, s28, 1
	global_load_lds_dwordx4 v188, s[90:91]
	s_add_i32 m0, s29, s83
	s_add_i32 s28, s28, 32
	global_load_lds_dwordx4 v189, s[90:91]
	s_add_i32 m0, s29, s84
	v_add3_u32 v139, s28, v113, v136
	global_load_lds_dwordx4 v190, s[90:91]
	s_add_i32 m0, s29, s85
	v_add3_u32 v172, s28, v114, v136
	global_load_lds_dwordx4 v191, s[90:91]
	s_add_i32 m0, s29, s86
	v_add_u32_e32 v160, v139, v137
	global_load_lds_dwordx4 v192, s[90:91]
	s_add_i32 m0, s29, s87
	v_add_u32_e32 v168, v172, v137
	global_load_lds_dwordx4 v193, s[90:91]
	s_add_i32 m0, s29, s88
	s_addk_i32 s27, 0x4000
	global_load_lds_dwordx4 v194, s[90:91]
	s_add_i32 m0, s29, s89
	s_add_u32 s16, s16, 0x80
	s_addc_u32 s17, s17, 0
	global_load_lds_dwordx4 v195, s[90:91]
	ds_read_b128 v[140:143], v160
	ds_read_b128 v[148:151], v168 offset:16384
	ds_read_b128 v[152:155], v168 offset:18432
	ds_read_b128 v[164:167], v168 offset:20480
	ds_read_b128 v[168:171], v168 offset:22528
	ds_read_b128 v[144:147], v160 offset:2048
	ds_read_b128 v[156:159], v160 offset:4096
	ds_read_b128 v[160:163], v160 offset:6144
	v_add_u32_e32 v139, v139, v138
	v_add_u32_e32 v236, v172, v138
	ds_read_b128 v[204:207], v139
	ds_read_b128 v[208:211], v236 offset:16384
	ds_read_b128 v[212:215], v236 offset:18432
	ds_read_b128 v[216:219], v236 offset:20480
	ds_read_b128 v[220:223], v236 offset:22528
	ds_read_b128 v[224:227], v139 offset:2048
	ds_read_b128 v[228:231], v139 offset:4096
	ds_read_b128 v[232:235], v139 offset:6144
	s_setprio 1
	s_waitcnt lgkmcnt(11)
	v_mfma_f32_16x16x32_bf16 v[60:63], v[140:143], v[148:151], v[60:63]
	v_mfma_f32_16x16x32_bf16 v[56:59], v[140:143], v[152:155], v[56:59]
	v_mfma_f32_16x16x32_bf16 v[52:55], v[140:143], v[164:167], v[52:55]
	v_mfma_f32_16x16x32_bf16 v[48:51], v[140:143], v[168:171], v[48:51]
	s_waitcnt lgkmcnt(10)
	v_mfma_f32_16x16x32_bf16 v[44:47], v[144:147], v[148:151], v[44:47]
	v_mfma_f32_16x16x32_bf16 v[40:43], v[144:147], v[152:155], v[40:43]
	v_mfma_f32_16x16x32_bf16 v[36:39], v[144:147], v[164:167], v[36:39]
	v_mfma_f32_16x16x32_bf16 v[32:35], v[144:147], v[168:171], v[32:35]
	s_waitcnt lgkmcnt(9)
	v_mfma_f32_16x16x32_bf16 v[28:31], v[156:159], v[148:151], v[28:31]
	v_mfma_f32_16x16x32_bf16 v[24:27], v[156:159], v[152:155], v[24:27]
	v_mfma_f32_16x16x32_bf16 v[20:23], v[156:159], v[164:167], v[20:23]
	v_mfma_f32_16x16x32_bf16 v[16:19], v[156:159], v[168:171], v[16:19]
	s_waitcnt lgkmcnt(8)
	v_mfma_f32_16x16x32_bf16 v[12:15], v[160:163], v[148:151], v[12:15]
	v_mfma_f32_16x16x32_bf16 v[8:11], v[160:163], v[152:155], v[8:11]
	v_mfma_f32_16x16x32_bf16 v[4:7], v[160:163], v[164:167], v[4:7]
	v_mfma_f32_16x16x32_bf16 v[0:3], v[160:163], v[168:171], v[0:3]
	s_waitcnt lgkmcnt(3)
	v_mfma_f32_16x16x32_bf16 v[60:63], v[204:207], v[208:211], v[60:63]
	v_mfma_f32_16x16x32_bf16 v[56:59], v[204:207], v[212:215], v[56:59]
	v_mfma_f32_16x16x32_bf16 v[52:55], v[204:207], v[216:219], v[52:55]
	v_mfma_f32_16x16x32_bf16 v[48:51], v[204:207], v[220:223], v[48:51]
	s_waitcnt lgkmcnt(2)
	v_mfma_f32_16x16x32_bf16 v[44:47], v[224:227], v[208:211], v[44:47]
	v_mfma_f32_16x16x32_bf16 v[40:43], v[224:227], v[212:215], v[40:43]
	v_mfma_f32_16x16x32_bf16 v[36:39], v[224:227], v[216:219], v[36:39]
	v_mfma_f32_16x16x32_bf16 v[32:35], v[224:227], v[220:223], v[32:35]
	s_waitcnt lgkmcnt(1)
	v_mfma_f32_16x16x32_bf16 v[28:31], v[228:231], v[208:211], v[28:31]
	v_mfma_f32_16x16x32_bf16 v[24:27], v[228:231], v[212:215], v[24:27]
	v_mfma_f32_16x16x32_bf16 v[20:23], v[228:231], v[216:219], v[20:23]
	v_mfma_f32_16x16x32_bf16 v[16:19], v[228:231], v[220:223], v[16:19]
	s_waitcnt lgkmcnt(0)
	v_mfma_f32_16x16x32_bf16 v[12:15], v[232:235], v[208:211], v[12:15]
	v_mfma_f32_16x16x32_bf16 v[8:11], v[232:235], v[212:215], v[8:11]
	v_mfma_f32_16x16x32_bf16 v[4:7], v[232:235], v[216:219], v[4:7]
	v_mfma_f32_16x16x32_bf16 v[0:3], v[232:235], v[220:223], v[0:3]
	s_setprio 0
	s_cmpk_eq_i32 s16, 0x780
	s_waitcnt vmcnt(0)
	s_barrier
	s_cbranch_scc0 .LBB0_1823
	ds_read_b128 v[88:91], v117 offset:55296
	ds_read_b128 v[92:95], v117 offset:53248
	ds_read_b128 v[96:99], v118 offset:38912
	ds_read_b128 v[100:103], v118 offset:36864
	ds_read_b128 v[140:143], v117 offset:51200
	ds_read_b128 v[144:147], v117 offset:49152
	ds_read_b128 v[148:151], v118 offset:34816
	ds_read_b128 v[152:155], v118 offset:32768
	s_setprio 1
	s_waitcnt lgkmcnt(5)
	v_mfma_f32_16x16x32_bf16 v[4:7], v[96:99], v[92:95], v[4:7]
	v_mfma_f32_16x16x32_bf16 v[0:3], v[96:99], v[88:91], v[0:3]
	s_waitcnt lgkmcnt(0)
	v_mfma_f32_16x16x32_bf16 v[60:63], v[152:155], v[144:147], v[60:63]
	v_mfma_f32_16x16x32_bf16 v[56:59], v[152:155], v[140:143], v[56:59]
	v_mfma_f32_16x16x32_bf16 v[52:55], v[152:155], v[92:95], v[52:55]
	v_mfma_f32_16x16x32_bf16 v[48:51], v[152:155], v[88:91], v[48:51]
	v_mfma_f32_16x16x32_bf16 v[44:47], v[148:151], v[144:147], v[44:47]
	v_mfma_f32_16x16x32_bf16 v[40:43], v[148:151], v[140:143], v[40:43]
	v_mfma_f32_16x16x32_bf16 v[36:39], v[148:151], v[92:95], v[36:39]
	v_mfma_f32_16x16x32_bf16 v[32:35], v[148:151], v[88:91], v[32:35]
	v_mfma_f32_16x16x32_bf16 v[28:31], v[100:103], v[144:147], v[28:31]
	v_mfma_f32_16x16x32_bf16 v[24:27], v[100:103], v[140:143], v[24:27]
	v_mfma_f32_16x16x32_bf16 v[20:23], v[100:103], v[92:95], v[20:23]
	v_mfma_f32_16x16x32_bf16 v[16:19], v[100:103], v[88:91], v[16:19]
	v_mfma_f32_16x16x32_bf16 v[12:15], v[96:99], v[144:147], v[12:15]
	v_mfma_f32_16x16x32_bf16 v[8:11], v[96:99], v[140:143], v[8:11]
	s_setprio 0
	ds_read_b128 v[88:91], v119 offset:32768
	ds_read_b128 v[92:95], v119 offset:34816
	ds_read_b128 v[96:99], v120 offset:49152
	ds_read_b128 v[100:103], v120 offset:51200
	ds_read_b128 v[140:143], v119 offset:36864
	ds_read_b128 v[144:147], v119 offset:38912
	ds_read_b128 v[148:151], v120 offset:53248
	ds_read_b128 v[152:155], v120 offset:55296
	s_setprio 1
	s_waitcnt lgkmcnt(1)
	v_mfma_f32_16x16x32_bf16 v[4:7], v[144:147], v[148:151], v[4:7]
	s_waitcnt lgkmcnt(0)
	v_mfma_f32_16x16x32_bf16 v[0:3], v[144:147], v[152:155], v[0:3]
	v_mfma_f32_16x16x32_bf16 v[60:63], v[88:91], v[96:99], v[60:63]
	v_mfma_f32_16x16x32_bf16 v[56:59], v[88:91], v[100:103], v[56:59]
	v_mfma_f32_16x16x32_bf16 v[52:55], v[88:91], v[148:151], v[52:55]
	v_mfma_f32_16x16x32_bf16 v[48:51], v[88:91], v[152:155], v[48:51]
	v_mfma_f32_16x16x32_bf16 v[44:47], v[92:95], v[96:99], v[44:47]
	v_mfma_f32_16x16x32_bf16 v[40:43], v[92:95], v[100:103], v[40:43]
	v_mfma_f32_16x16x32_bf16 v[36:39], v[92:95], v[148:151], v[36:39]
	v_mfma_f32_16x16x32_bf16 v[32:35], v[92:95], v[152:155], v[32:35]
	v_mfma_f32_16x16x32_bf16 v[28:31], v[140:143], v[96:99], v[28:31]
	v_mfma_f32_16x16x32_bf16 v[24:27], v[140:143], v[100:103], v[24:27]
	v_mfma_f32_16x16x32_bf16 v[20:23], v[140:143], v[148:151], v[20:23]
	v_mfma_f32_16x16x32_bf16 v[16:19], v[140:143], v[152:155], v[16:19]
	v_mfma_f32_16x16x32_bf16 v[12:15], v[144:147], v[96:99], v[12:15]
	v_mfma_f32_16x16x32_bf16 v[8:11], v[144:147], v[100:103], v[8:11]
	s_setprio 0
	s_barrier
	ds_write2_b32 v115, v60, v56 offset1:16
	ds_write2_b32 v115, v61, v57 offset0:132 offset1:148
	v_add_u32_e32 v56, 0x400, v115
	ds_write2_b32 v56, v62, v58 offset0:8 offset1:24
	ds_write2_b32 v56, v63, v59 offset0:140 offset1:156
	ds_write2_b32 v115, v52, v48 offset0:32 offset1:48
	ds_write2_b32 v115, v53, v49 offset0:164 offset1:180
	ds_write2_b32 v56, v54, v50 offset0:40 offset1:56
	ds_write2_b32 v56, v55, v51 offset0:172 offset1:188
	v_add_u32_e32 v48, 0x2000, v115
	ds_write2_b32 v48, v44, v40 offset0:64 offset1:80
	ds_write2_b32 v48, v45, v41 offset0:196 offset1:212
	v_add_u32_e32 v40, 0x2400, v115
	ds_write2_b32 v40, v46, v42 offset0:72 offset1:88
	ds_write2_b32 v40, v47, v43 offset0:204 offset1:220
	ds_write2_b32 v48, v36, v32 offset0:96 offset1:112
	ds_write2_b32 v48, v37, v33 offset0:228 offset1:244
	ds_write2_b32 v40, v38, v34 offset0:104 offset1:120
	ds_write2_b32 v40, v39, v35 offset0:236 offset1:252
	v_add_u32_e32 v32, 0x4000, v115
	ds_write2_b32 v32, v28, v24 offset0:128 offset1:144
	v_add_u32_e32 v24, 0x4400, v115
	ds_write2_b32 v24, v29, v25 offset0:4 offset1:20
	ds_write2_b32 v24, v30, v26 offset0:136 offset1:152
	v_add_u32_e32 v25, 0x4800, v115
	ds_write2_b32 v25, v31, v27 offset0:12 offset1:28
	ds_write2_b32 v32, v20, v16 offset0:160 offset1:176
	ds_write2_b32 v24, v21, v17 offset0:36 offset1:52
	ds_write2_b32 v24, v22, v18 offset0:168 offset1:184
	ds_write2_b32 v25, v23, v19 offset0:44 offset1:60
	v_add_u32_e32 v16, 0x6000, v115
	ds_write2_b32 v16, v12, v8 offset0:192 offset1:208
	v_add_u32_e32 v8, 0x6400, v115
	ds_write2_b32 v8, v13, v9 offset0:68 offset1:84
	ds_write2_b32 v8, v14, v10 offset0:200 offset1:216
	v_add_u32_e32 v9, 0x6800, v115
	ds_write2_b32 v9, v15, v11 offset0:76 offset1:92
	ds_write2_b32 v16, v4, v0 offset0:224 offset1:240
	ds_write2_b32 v8, v5, v1 offset0:100 offset1:116
	ds_write2_b32 v8, v6, v2 offset0:232 offset1:248
	ds_write2_b32 v9, v7, v3 offset0:108 offset1:124
	v_or_b32_e32 v0, s25, v116
	v_ashrrev_i32_e32 v1, 31, v0
	v_lshlrev_b64 v[2:3], 2, v[0:1]
	v_lshl_add_u64 v[0:1], s[14:15], 0, v[2:3]
	v_lshl_add_u64 v[2:3], s[10:11], 0, v[2:3]
	v_add_u32_e32 v4, s26, v129
	s_mov_b32 s16, 0
	s_waitcnt lgkmcnt(0)
	s_barrier

.LBB0_1834:
	s_and_b32 s27, s26, 0x4000
	s_xor_b32 s28, s27, 0x4000
	s_lshl_b32 s28, s28, 1
	s_add_i32 s28, s28, 32
	s_add_u32 s90, s52, s12
	s_addc_u32 s91, s53, s13
	s_add_i32 m0, s28, s82
	s_lshl_b32 s27, s27, 1
	global_load_lds_dwordx4 v189, s[90:91]
	s_add_i32 m0, s28, s83
	s_add_i32 s27, s27, 32
	global_load_lds_dwordx4 v190, s[90:91]
	s_add_i32 m0, s28, s84
	v_lshlrev_b32_e32 v70, 1, v129
	global_load_lds_dwordx4 v191, s[90:91]
	s_add_i32 m0, s28, s85
	v_add3_u32 v151, s27, v124, v70
	global_load_lds_dwordx4 v192, s[90:91]
	s_add_i32 m0, s28, s86
	v_add3_u32 v70, s27, v125, v70
	global_load_lds_dwordx4 v193, s[90:91]
	s_add_i32 m0, s28, s87
	v_lshlrev_b32_e32 v152, 1, v117
	global_load_lds_dwordx4 v194, s[90:91]
	s_add_i32 m0, s28, s88
	v_add_u32_e32 v172, v151, v152
	global_load_lds_dwordx4 v195, s[90:91]
	s_add_i32 m0, s28, s89
	v_add_u32_e32 v182, v70, v152
	global_load_lds_dwordx4 v196, s[90:91]
	ds_read_b128 v[152:155], v172
	ds_read_b128 v[160:163], v182 offset:16384
	ds_read_b128 v[164:167], v182 offset:18432
	ds_read_b128 v[176:179], v182 offset:20480
	ds_read_b128 v[182:185], v182 offset:22528
	ds_read_b128 v[156:159], v172 offset:2048
	ds_read_b128 v[168:171], v172 offset:4096
	ds_read_b128 v[172:175], v172 offset:6144
	v_lshlrev_b32_e32 v236, 1, v116
	v_add_u32_e32 v151, v151, v236
	v_add_u32_e32 v70, v70, v236
	ds_read_b128 v[204:207], v151
	ds_read_b128 v[208:211], v70 offset:16384
	ds_read_b128 v[212:215], v70 offset:18432
	ds_read_b128 v[216:219], v70 offset:20480
	ds_read_b128 v[220:223], v70 offset:22528
	ds_read_b128 v[224:227], v151 offset:2048
	ds_read_b128 v[228:231], v151 offset:4096
	ds_read_b128 v[232:235], v151 offset:6144
	s_setprio 1
	s_waitcnt lgkmcnt(11)
	v_mfma_f32_16x16x32_bf16 v[60:63], v[152:155], v[160:163], v[60:63]
	v_mfma_f32_16x16x32_bf16 v[56:59], v[152:155], v[164:167], v[56:59]
	v_mfma_f32_16x16x32_bf16 v[52:55], v[152:155], v[176:179], v[52:55]
	v_mfma_f32_16x16x32_bf16 v[48:51], v[152:155], v[182:185], v[48:51]
	s_waitcnt lgkmcnt(10)
	v_mfma_f32_16x16x32_bf16 v[44:47], v[156:159], v[160:163], v[44:47]
	v_mfma_f32_16x16x32_bf16 v[40:43], v[156:159], v[164:167], v[40:43]
	v_mfma_f32_16x16x32_bf16 v[36:39], v[156:159], v[176:179], v[36:39]
	v_mfma_f32_16x16x32_bf16 v[32:35], v[156:159], v[182:185], v[32:35]
	s_waitcnt lgkmcnt(9)
	v_mfma_f32_16x16x32_bf16 v[28:31], v[168:171], v[160:163], v[28:31]
	v_mfma_f32_16x16x32_bf16 v[24:27], v[168:171], v[164:167], v[24:27]
	v_mfma_f32_16x16x32_bf16 v[20:23], v[168:171], v[176:179], v[20:23]
	v_mfma_f32_16x16x32_bf16 v[16:19], v[168:171], v[182:185], v[16:19]
	s_waitcnt lgkmcnt(8)
	v_mfma_f32_16x16x32_bf16 v[12:15], v[172:175], v[160:163], v[12:15]
	v_mfma_f32_16x16x32_bf16 v[8:11], v[172:175], v[164:167], v[8:11]
	v_mfma_f32_16x16x32_bf16 v[4:7], v[172:175], v[176:179], v[4:7]
	v_mfma_f32_16x16x32_bf16 v[0:3], v[172:175], v[182:185], v[0:3]
	s_waitcnt lgkmcnt(3)
	v_mfma_f32_16x16x32_bf16 v[60:63], v[204:207], v[208:211], v[60:63]
	v_mfma_f32_16x16x32_bf16 v[56:59], v[204:207], v[212:215], v[56:59]
	v_mfma_f32_16x16x32_bf16 v[52:55], v[204:207], v[216:219], v[52:55]
	v_mfma_f32_16x16x32_bf16 v[48:51], v[204:207], v[220:223], v[48:51]
	s_waitcnt lgkmcnt(2)
	v_mfma_f32_16x16x32_bf16 v[44:47], v[224:227], v[208:211], v[44:47]
	v_mfma_f32_16x16x32_bf16 v[40:43], v[224:227], v[212:215], v[40:43]
	v_mfma_f32_16x16x32_bf16 v[36:39], v[224:227], v[216:219], v[36:39]
	v_mfma_f32_16x16x32_bf16 v[32:35], v[224:227], v[220:223], v[32:35]
	s_waitcnt lgkmcnt(1)
	v_mfma_f32_16x16x32_bf16 v[28:31], v[228:231], v[208:211], v[28:31]
	v_mfma_f32_16x16x32_bf16 v[24:27], v[228:231], v[212:215], v[24:27]
	v_mfma_f32_16x16x32_bf16 v[20:23], v[228:231], v[216:219], v[20:23]
	v_mfma_f32_16x16x32_bf16 v[16:19], v[228:231], v[220:223], v[16:19]
	s_waitcnt lgkmcnt(0)
	v_mfma_f32_16x16x32_bf16 v[12:15], v[232:235], v[208:211], v[12:15]
	v_mfma_f32_16x16x32_bf16 v[8:11], v[232:235], v[212:215], v[8:11]
	v_mfma_f32_16x16x32_bf16 v[4:7], v[232:235], v[216:219], v[4:7]
	v_mfma_f32_16x16x32_bf16 v[0:3], v[232:235], v[220:223], v[0:3]
	s_setprio 0
	s_add_u32 s12, s12, 0x80
	s_addc_u32 s13, s13, 0
	s_addk_i32 s26, 0x4000
	s_cmpk_eq_i32 s12, 0x780
	s_waitcnt vmcnt(0)
	s_barrier
	s_cbranch_scc0 .LBB0_1834
	ds_read_b128 v[96:99], v69 offset:32768
	ds_read_b128 v[100:103], v69 offset:34816
	ds_read_b128 v[104:107], v135 offset:49152
	ds_read_b128 v[108:111], v135 offset:51200
	ds_read_b128 v[152:155], v69 offset:36864
	ds_read_b128 v[156:159], v69 offset:38912
	ds_read_b128 v[160:163], v135 offset:53248
	ds_read_b128 v[164:167], v135 offset:55296
	s_setprio 1
	s_waitcnt lgkmcnt(1)
	v_mfma_f32_16x16x32_bf16 v[4:7], v[156:159], v[160:163], v[4:7]
	s_waitcnt lgkmcnt(0)
	v_mfma_f32_16x16x32_bf16 v[0:3], v[156:159], v[164:167], v[0:3]
	v_mfma_f32_16x16x32_bf16 v[60:63], v[96:99], v[104:107], v[60:63]
	v_mfma_f32_16x16x32_bf16 v[56:59], v[96:99], v[108:111], v[56:59]
	v_mfma_f32_16x16x32_bf16 v[52:55], v[96:99], v[160:163], v[52:55]
	v_mfma_f32_16x16x32_bf16 v[48:51], v[96:99], v[164:167], v[48:51]
	v_mfma_f32_16x16x32_bf16 v[44:47], v[100:103], v[104:107], v[44:47]
	v_mfma_f32_16x16x32_bf16 v[40:43], v[100:103], v[108:111], v[40:43]
	v_mfma_f32_16x16x32_bf16 v[36:39], v[100:103], v[160:163], v[36:39]
	v_mfma_f32_16x16x32_bf16 v[32:35], v[100:103], v[164:167], v[32:35]
	v_mfma_f32_16x16x32_bf16 v[28:31], v[152:155], v[104:107], v[28:31]
	v_mfma_f32_16x16x32_bf16 v[24:27], v[152:155], v[108:111], v[24:27]
	v_mfma_f32_16x16x32_bf16 v[20:23], v[152:155], v[160:163], v[20:23]
	v_mfma_f32_16x16x32_bf16 v[16:19], v[152:155], v[164:167], v[16:19]
	v_mfma_f32_16x16x32_bf16 v[12:15], v[156:159], v[104:107], v[12:15]
	v_mfma_f32_16x16x32_bf16 v[8:11], v[156:159], v[108:111], v[8:11]
	s_setprio 0
	ds_read_b128 v[96:99], v136 offset:32768
	ds_read_b128 v[100:103], v136 offset:34816
	ds_read_b128 v[104:107], v137 offset:49152
	ds_read_b128 v[108:111], v137 offset:51200
	ds_read_b128 v[152:155], v136 offset:36864
	ds_read_b128 v[156:159], v136 offset:38912
	ds_read_b128 v[160:163], v137 offset:53248
	ds_read_b128 v[164:167], v137 offset:55296
	s_setprio 1
	s_waitcnt lgkmcnt(1)
	v_mfma_f32_16x16x32_bf16 v[4:7], v[156:159], v[160:163], v[4:7]
	s_waitcnt lgkmcnt(0)
	v_mfma_f32_16x16x32_bf16 v[0:3], v[156:159], v[164:167], v[0:3]
	v_mfma_f32_16x16x32_bf16 v[60:63], v[96:99], v[104:107], v[60:63]
	v_mfma_f32_16x16x32_bf16 v[56:59], v[96:99], v[108:111], v[56:59]
	v_mfma_f32_16x16x32_bf16 v[52:55], v[96:99], v[160:163], v[52:55]
	v_mfma_f32_16x16x32_bf16 v[48:51], v[96:99], v[164:167], v[48:51]
	v_mfma_f32_16x16x32_bf16 v[44:47], v[100:103], v[104:107], v[44:47]
	v_mfma_f32_16x16x32_bf16 v[40:43], v[100:103], v[108:111], v[40:43]
	v_mfma_f32_16x16x32_bf16 v[36:39], v[100:103], v[160:163], v[36:39]
	v_mfma_f32_16x16x32_bf16 v[32:35], v[100:103], v[164:167], v[32:35]
	v_mfma_f32_16x16x32_bf16 v[28:31], v[152:155], v[104:107], v[28:31]
	v_mfma_f32_16x16x32_bf16 v[24:27], v[152:155], v[108:111], v[24:27]
	v_mfma_f32_16x16x32_bf16 v[20:23], v[152:155], v[160:163], v[20:23]
	v_mfma_f32_16x16x32_bf16 v[16:19], v[152:155], v[164:167], v[16:19]
	v_mfma_f32_16x16x32_bf16 v[12:15], v[156:159], v[104:107], v[12:15]
	v_mfma_f32_16x16x32_bf16 v[8:11], v[156:159], v[108:111], v[8:11]
	s_setprio 0
	s_barrier
	ds_write2_b32 v134, v60, v56 offset1:16
	ds_write2_b32 v134, v61, v57 offset0:132 offset1:148
	v_add_u32_e32 v56, 0x400, v134
	ds_write2_b32 v56, v62, v58 offset0:8 offset1:24
	ds_write2_b32 v56, v63, v59 offset0:140 offset1:156
	ds_write2_b32 v134, v52, v48 offset0:32 offset1:48
	ds_write2_b32 v134, v53, v49 offset0:164 offset1:180
	ds_write2_b32 v56, v54, v50 offset0:40 offset1:56
	ds_write2_b32 v56, v55, v51 offset0:172 offset1:188
	v_add_u32_e32 v48, 0x2000, v134
	ds_write2_b32 v48, v44, v40 offset0:64 offset1:80
	ds_write2_b32 v48, v45, v41 offset0:196 offset1:212
	v_add_u32_e32 v40, 0x2400, v134
	ds_write2_b32 v40, v46, v42 offset0:72 offset1:88
	ds_write2_b32 v40, v47, v43 offset0:204 offset1:220
	ds_write2_b32 v48, v36, v32 offset0:96 offset1:112
	ds_write2_b32 v48, v37, v33 offset0:228 offset1:244
	ds_write2_b32 v40, v38, v34 offset0:104 offset1:120
	ds_write2_b32 v40, v39, v35 offset0:236 offset1:252
	v_add_u32_e32 v32, 0x4000, v134
	ds_write2_b32 v32, v28, v24 offset0:128 offset1:144
	v_add_u32_e32 v24, 0x4400, v134
	ds_write2_b32 v24, v29, v25 offset0:4 offset1:20
	ds_write2_b32 v24, v30, v26 offset0:136 offset1:152
	v_add_u32_e32 v25, 0x4800, v134
	ds_write2_b32 v25, v31, v27 offset0:12 offset1:28
	ds_write2_b32 v32, v20, v16 offset0:160 offset1:176
	ds_write2_b32 v24, v21, v17 offset0:36 offset1:52
	ds_write2_b32 v24, v22, v18 offset0:168 offset1:184
	ds_write2_b32 v25, v23, v19 offset0:44 offset1:60
	v_add_u32_e32 v16, 0x6000, v134
	ds_write2_b32 v16, v12, v8 offset0:192 offset1:208
	v_add_u32_e32 v8, 0x6400, v134
	ds_write2_b32 v8, v13, v9 offset0:68 offset1:84
	ds_write2_b32 v8, v14, v10 offset0:200 offset1:216
	v_add_u32_e32 v9, 0x6800, v134
	ds_write2_b32 v9, v15, v11 offset0:76 offset1:92
	ds_write2_b32 v16, v4, v0 offset0:224 offset1:240
	ds_write2_b32 v8, v5, v1 offset0:100 offset1:116
	ds_write2_b32 v8, v6, v2 offset0:232 offset1:248
	ds_write2_b32 v9, v7, v3 offset0:108 offset1:124
	v_or_b32_e32 v0, s24, v113
	v_lshlrev_b32_e32 v70, 2, v0
	v_lshl_add_u64 v[0:1], s[14:15], 0, v[70:71]
	v_lshl_add_u64 v[2:3], s[10:11], 0, v[70:71]
	v_add_u32_e32 v4, s25, v146
	s_mov_b32 s12, 0
	s_waitcnt lgkmcnt(0)
	s_barrier

.LBB0_1998:
	s_and_b32 s20, s19, 0x4000
	s_xor_b32 s21, s20, 0x4000
	s_lshl_b32 s21, s21, 1
	s_add_i32 s21, s21, 32
	s_add_u32 s90, s52, s12
	s_addc_u32 s91, s53, s13
	s_add_i32 m0, s21, s82
	s_lshl_b32 s20, s20, 1
	global_load_lds_dwordx4 v184, s[90:91]
	s_add_i32 m0, s21, s83
	s_add_i32 s20, s20, 32
	global_load_lds_dwordx4 v185, s[90:91]
	s_add_i32 m0, s21, s84
	v_lshl_add_u32 v137, v114, 1, s20
	global_load_lds_dwordx4 v186, s[90:91]
	s_add_i32 m0, s21, s85
	v_lshl_add_u32 v170, v115, 1, s20
	global_load_lds_dwordx4 v187, s[90:91]
	s_add_i32 m0, s21, s86
	v_add_u32_e32 v158, v137, v135
	global_load_lds_dwordx4 v188, s[90:91]
	s_add_i32 m0, s21, s87
	v_add_u32_e32 v166, v170, v135
	global_load_lds_dwordx4 v189, s[90:91]
	s_add_i32 m0, s21, s88
	s_addk_i32 s19, 0x4000
	global_load_lds_dwordx4 v190, s[90:91]
	s_add_i32 m0, s21, s89
	s_add_u32 s12, s12, 0x80
	s_addc_u32 s13, s13, 0
	global_load_lds_dwordx4 v191, s[90:91]
	ds_read_b128 v[138:141], v158
	ds_read_b128 v[146:149], v166 offset:16384
	ds_read_b128 v[150:153], v166 offset:18432
	ds_read_b128 v[162:165], v166 offset:20480
	ds_read_b128 v[166:169], v166 offset:22528
	ds_read_b128 v[142:145], v158 offset:2048
	ds_read_b128 v[154:157], v158 offset:4096
	ds_read_b128 v[158:161], v158 offset:6144
	v_add_u32_e32 v137, v137, v136
	v_add_u32_e32 v236, v170, v136
	ds_read_b128 v[204:207], v137
	ds_read_b128 v[208:211], v236 offset:16384
	ds_read_b128 v[212:215], v236 offset:18432
	ds_read_b128 v[216:219], v236 offset:20480
	ds_read_b128 v[220:223], v236 offset:22528
	ds_read_b128 v[224:227], v137 offset:2048
	ds_read_b128 v[228:231], v137 offset:4096
	ds_read_b128 v[232:235], v137 offset:6144
	s_setprio 1
	s_waitcnt lgkmcnt(11)
	v_mfma_f32_16x16x32_bf16 v[60:63], v[138:141], v[146:149], v[60:63]
	v_mfma_f32_16x16x32_bf16 v[56:59], v[138:141], v[150:153], v[56:59]
	v_mfma_f32_16x16x32_bf16 v[52:55], v[138:141], v[162:165], v[52:55]
	v_mfma_f32_16x16x32_bf16 v[48:51], v[138:141], v[166:169], v[48:51]
	s_waitcnt lgkmcnt(10)
	v_mfma_f32_16x16x32_bf16 v[44:47], v[142:145], v[146:149], v[44:47]
	v_mfma_f32_16x16x32_bf16 v[40:43], v[142:145], v[150:153], v[40:43]
	v_mfma_f32_16x16x32_bf16 v[36:39], v[142:145], v[162:165], v[36:39]
	v_mfma_f32_16x16x32_bf16 v[32:35], v[142:145], v[166:169], v[32:35]
	s_waitcnt lgkmcnt(9)
	v_mfma_f32_16x16x32_bf16 v[28:31], v[154:157], v[146:149], v[28:31]
	v_mfma_f32_16x16x32_bf16 v[24:27], v[154:157], v[150:153], v[24:27]
	v_mfma_f32_16x16x32_bf16 v[20:23], v[154:157], v[162:165], v[20:23]
	v_mfma_f32_16x16x32_bf16 v[16:19], v[154:157], v[166:169], v[16:19]
	s_waitcnt lgkmcnt(8)
	v_mfma_f32_16x16x32_bf16 v[12:15], v[158:161], v[146:149], v[12:15]
	v_mfma_f32_16x16x32_bf16 v[8:11], v[158:161], v[150:153], v[8:11]
	v_mfma_f32_16x16x32_bf16 v[4:7], v[158:161], v[162:165], v[4:7]
	v_mfma_f32_16x16x32_bf16 v[0:3], v[158:161], v[166:169], v[0:3]
	s_waitcnt lgkmcnt(3)
	v_mfma_f32_16x16x32_bf16 v[60:63], v[204:207], v[208:211], v[60:63]
	v_mfma_f32_16x16x32_bf16 v[56:59], v[204:207], v[212:215], v[56:59]
	v_mfma_f32_16x16x32_bf16 v[52:55], v[204:207], v[216:219], v[52:55]
	v_mfma_f32_16x16x32_bf16 v[48:51], v[204:207], v[220:223], v[48:51]
	s_waitcnt lgkmcnt(2)
	v_mfma_f32_16x16x32_bf16 v[44:47], v[224:227], v[208:211], v[44:47]
	v_mfma_f32_16x16x32_bf16 v[40:43], v[224:227], v[212:215], v[40:43]
	v_mfma_f32_16x16x32_bf16 v[36:39], v[224:227], v[216:219], v[36:39]
	v_mfma_f32_16x16x32_bf16 v[32:35], v[224:227], v[220:223], v[32:35]
	s_waitcnt lgkmcnt(1)
	v_mfma_f32_16x16x32_bf16 v[28:31], v[228:231], v[208:211], v[28:31]
	v_mfma_f32_16x16x32_bf16 v[24:27], v[228:231], v[212:215], v[24:27]
	v_mfma_f32_16x16x32_bf16 v[20:23], v[228:231], v[216:219], v[20:23]
	v_mfma_f32_16x16x32_bf16 v[16:19], v[228:231], v[220:223], v[16:19]
	s_waitcnt lgkmcnt(0)
	v_mfma_f32_16x16x32_bf16 v[12:15], v[232:235], v[208:211], v[12:15]
	v_mfma_f32_16x16x32_bf16 v[8:11], v[232:235], v[212:215], v[8:11]
	v_mfma_f32_16x16x32_bf16 v[4:7], v[232:235], v[216:219], v[4:7]
	v_mfma_f32_16x16x32_bf16 v[0:3], v[232:235], v[220:223], v[0:3]
	s_setprio 0
	s_cmpk_eq_i32 s12, 0x780
	s_waitcnt vmcnt(0)
	s_barrier
	s_cbranch_scc0 .LBB0_1998
	ds_read_b128 v[90:93], v116 offset:55296
	ds_read_b128 v[94:97], v116 offset:53248
	ds_read_b128 v[98:101], v117 offset:38912
	ds_read_b128 v[102:105], v117 offset:36864
	ds_read_b128 v[138:141], v116 offset:51200
	ds_read_b128 v[142:145], v116 offset:49152
	ds_read_b128 v[146:149], v117 offset:34816
	ds_read_b128 v[150:153], v117 offset:32768
	s_setprio 1
	s_waitcnt lgkmcnt(5)
	v_mfma_f32_16x16x32_bf16 v[0:3], v[98:101], v[90:93], v[0:3]
	s_waitcnt lgkmcnt(0)
	v_mfma_f32_16x16x32_bf16 v[60:63], v[150:153], v[142:145], v[60:63]
	v_mfma_f32_16x16x32_bf16 v[56:59], v[150:153], v[138:141], v[56:59]
	v_mfma_f32_16x16x32_bf16 v[52:55], v[150:153], v[94:97], v[52:55]
	v_mfma_f32_16x16x32_bf16 v[48:51], v[150:153], v[90:93], v[48:51]
	v_mfma_f32_16x16x32_bf16 v[44:47], v[146:149], v[142:145], v[44:47]
	v_mfma_f32_16x16x32_bf16 v[40:43], v[146:149], v[138:141], v[40:43]
	v_mfma_f32_16x16x32_bf16 v[36:39], v[146:149], v[94:97], v[36:39]
	v_mfma_f32_16x16x32_bf16 v[32:35], v[146:149], v[90:93], v[32:35]
	v_mfma_f32_16x16x32_bf16 v[28:31], v[102:105], v[142:145], v[28:31]
	v_mfma_f32_16x16x32_bf16 v[24:27], v[102:105], v[138:141], v[24:27]
	v_mfma_f32_16x16x32_bf16 v[20:23], v[102:105], v[94:97], v[20:23]
	v_mfma_f32_16x16x32_bf16 v[16:19], v[102:105], v[90:93], v[16:19]
	v_mfma_f32_16x16x32_bf16 v[12:15], v[98:101], v[142:145], v[12:15]
	v_mfma_f32_16x16x32_bf16 v[8:11], v[98:101], v[138:141], v[8:11]
	v_mfma_f32_16x16x32_bf16 v[4:7], v[98:101], v[94:97], v[4:7]
	s_setprio 0
	ds_read_b128 v[90:93], v118 offset:32768
	ds_read_b128 v[94:97], v118 offset:34816
	ds_read_b128 v[98:101], v119 offset:49152
	ds_read_b128 v[102:105], v119 offset:51200
	ds_read_b128 v[138:141], v118 offset:36864
	ds_read_b128 v[142:145], v118 offset:38912
	ds_read_b128 v[146:149], v119 offset:53248
	ds_read_b128 v[150:153], v119 offset:55296
	s_setprio 1
	s_waitcnt lgkmcnt(0)
	v_mfma_f32_16x16x32_bf16 v[0:3], v[142:145], v[150:153], v[0:3]
	v_mfma_f32_16x16x32_bf16 v[60:63], v[90:93], v[98:101], v[60:63]
	v_mfma_f32_16x16x32_bf16 v[56:59], v[90:93], v[102:105], v[56:59]
	v_mfma_f32_16x16x32_bf16 v[52:55], v[90:93], v[146:149], v[52:55]
	v_mfma_f32_16x16x32_bf16 v[48:51], v[90:93], v[150:153], v[48:51]
	v_mfma_f32_16x16x32_bf16 v[44:47], v[94:97], v[98:101], v[44:47]
	v_mfma_f32_16x16x32_bf16 v[40:43], v[94:97], v[102:105], v[40:43]
	v_mfma_f32_16x16x32_bf16 v[36:39], v[94:97], v[146:149], v[36:39]
	v_mfma_f32_16x16x32_bf16 v[32:35], v[94:97], v[150:153], v[32:35]
	v_mfma_f32_16x16x32_bf16 v[28:31], v[138:141], v[98:101], v[28:31]
	v_mfma_f32_16x16x32_bf16 v[24:27], v[138:141], v[102:105], v[24:27]
	v_mfma_f32_16x16x32_bf16 v[20:23], v[138:141], v[146:149], v[20:23]
	v_mfma_f32_16x16x32_bf16 v[16:19], v[138:141], v[150:153], v[16:19]
	v_mfma_f32_16x16x32_bf16 v[12:15], v[142:145], v[98:101], v[12:15]
	v_mfma_f32_16x16x32_bf16 v[8:11], v[142:145], v[102:105], v[8:11]
	v_mfma_f32_16x16x32_bf16 v[4:7], v[142:145], v[146:149], v[4:7]
	s_setprio 0
	s_barrier
	ds_write2_b32 v120, v60, v56 offset1:16
	ds_write2_b32 v120, v61, v57 offset0:132 offset1:148
	v_add_u32_e32 v56, 0x400, v120
	ds_write2_b32 v56, v62, v58 offset0:8 offset1:24
	ds_write2_b32 v56, v63, v59 offset0:140 offset1:156
	ds_write2_b32 v120, v52, v48 offset0:32 offset1:48
	ds_write2_b32 v120, v53, v49 offset0:164 offset1:180
	ds_write2_b32 v56, v54, v50 offset0:40 offset1:56
	ds_write2_b32 v56, v55, v51 offset0:172 offset1:188
	v_add_u32_e32 v48, 0x2000, v120
	ds_write2_b32 v48, v44, v40 offset0:64 offset1:80
	ds_write2_b32 v48, v45, v41 offset0:196 offset1:212
	v_add_u32_e32 v40, 0x2400, v120
	ds_write2_b32 v40, v46, v42 offset0:72 offset1:88
	ds_write2_b32 v40, v47, v43 offset0:204 offset1:220
	ds_write2_b32 v48, v36, v32 offset0:96 offset1:112
	ds_write2_b32 v48, v37, v33 offset0:228 offset1:244
	ds_write2_b32 v40, v38, v34 offset0:104 offset1:120
	ds_write2_b32 v40, v39, v35 offset0:236 offset1:252
	v_add_u32_e32 v32, 0x4000, v120
	ds_write2_b32 v32, v28, v24 offset0:128 offset1:144
	v_add_u32_e32 v24, 0x4400, v120
	ds_write2_b32 v24, v29, v25 offset0:4 offset1:20
	ds_write2_b32 v24, v30, v26 offset0:136 offset1:152
	v_add_u32_e32 v25, 0x4800, v120
	ds_write2_b32 v25, v31, v27 offset0:12 offset1:28
	ds_write2_b32 v32, v20, v16 offset0:160 offset1:176
	ds_write2_b32 v24, v21, v17 offset0:36 offset1:52
	ds_write2_b32 v24, v22, v18 offset0:168 offset1:184
	ds_write2_b32 v25, v23, v19 offset0:44 offset1:60
	v_add_u32_e32 v16, 0x6000, v120
	ds_write2_b32 v16, v12, v8 offset0:192 offset1:208
	v_add_u32_e32 v8, 0x6400, v120
	ds_write2_b32 v8, v13, v9 offset0:68 offset1:84
	ds_write2_b32 v8, v14, v10 offset0:200 offset1:216
	v_add_u32_e32 v9, 0x6800, v120
	ds_write2_b32 v9, v15, v11 offset0:76 offset1:92
	ds_write2_b32 v16, v4, v0 offset0:224 offset1:240
	ds_write2_b32 v8, v5, v1 offset0:100 offset1:116
	ds_write2_b32 v8, v6, v2 offset0:232 offset1:248
	ds_write2_b32 v9, v7, v3 offset0:108 offset1:124
	v_or_b32_e32 v0, s18, v121
	v_ashrrev_i32_e32 v1, 31, v0
	v_lshl_add_u64 v[0:1], v[0:1], 1, s[6:7]
	v_add_u32_e32 v2, s17, v128
	s_mov_b32 s12, 0
	s_waitcnt lgkmcnt(0)
	s_barrier

.LBB0_2009:
	s_and_b32 s17, s16, 0x4000
	s_xor_b32 s18, s17, 0x4000
	s_lshl_b32 s18, s18, 1
	s_add_i32 s18, s18, 32
	s_add_u32 s90, s52, s8
	s_addc_u32 s91, s53, s9
	s_add_i32 m0, s18, s82
	s_lshl_b32 s17, s17, 1
	global_load_lds_dwordx4 v184, s[90:91]
	s_add_i32 m0, s18, s83
	s_add_i32 s17, s17, 32
	global_load_lds_dwordx4 v185, s[90:91]
	s_add_i32 m0, s18, s84
	v_lshl_add_u32 v137, v113, 1, s17
	global_load_lds_dwordx4 v186, s[90:91]
	s_add_i32 m0, s18, s85
	v_lshl_add_u32 v170, v114, 1, s17
	global_load_lds_dwordx4 v187, s[90:91]
	s_add_i32 m0, s18, s86
	v_add_u32_e32 v158, v137, v135
	global_load_lds_dwordx4 v188, s[90:91]
	s_add_i32 m0, s18, s87
	v_add_u32_e32 v166, v170, v135
	global_load_lds_dwordx4 v189, s[90:91]
	s_add_i32 m0, s18, s88
	s_addk_i32 s16, 0x4000
	global_load_lds_dwordx4 v190, s[90:91]
	s_add_i32 m0, s18, s89
	s_add_u32 s8, s8, 0x80
	s_addc_u32 s9, s9, 0
	global_load_lds_dwordx4 v191, s[90:91]
	ds_read_b128 v[138:141], v158
	ds_read_b128 v[146:149], v166 offset:16384
	ds_read_b128 v[150:153], v166 offset:18432
	ds_read_b128 v[162:165], v166 offset:20480
	ds_read_b128 v[166:169], v166 offset:22528
	ds_read_b128 v[142:145], v158 offset:2048
	ds_read_b128 v[154:157], v158 offset:4096
	ds_read_b128 v[158:161], v158 offset:6144
	v_add_u32_e32 v137, v137, v136
	v_add_u32_e32 v236, v170, v136
	ds_read_b128 v[204:207], v137
	ds_read_b128 v[208:211], v236 offset:16384
	ds_read_b128 v[212:215], v236 offset:18432
	ds_read_b128 v[216:219], v236 offset:20480
	ds_read_b128 v[220:223], v236 offset:22528
	ds_read_b128 v[224:227], v137 offset:2048
	ds_read_b128 v[228:231], v137 offset:4096
	ds_read_b128 v[232:235], v137 offset:6144
	s_setprio 1
	s_waitcnt lgkmcnt(11)
	v_mfma_f32_16x16x32_bf16 v[60:63], v[138:141], v[146:149], v[60:63]
	v_mfma_f32_16x16x32_bf16 v[56:59], v[138:141], v[150:153], v[56:59]
	v_mfma_f32_16x16x32_bf16 v[52:55], v[138:141], v[162:165], v[52:55]
	v_mfma_f32_16x16x32_bf16 v[48:51], v[138:141], v[166:169], v[48:51]
	s_waitcnt lgkmcnt(10)
	v_mfma_f32_16x16x32_bf16 v[44:47], v[142:145], v[146:149], v[44:47]
	v_mfma_f32_16x16x32_bf16 v[40:43], v[142:145], v[150:153], v[40:43]
	v_mfma_f32_16x16x32_bf16 v[36:39], v[142:145], v[162:165], v[36:39]
	v_mfma_f32_16x16x32_bf16 v[32:35], v[142:145], v[166:169], v[32:35]
	s_waitcnt lgkmcnt(9)
	v_mfma_f32_16x16x32_bf16 v[28:31], v[154:157], v[146:149], v[28:31]
	v_mfma_f32_16x16x32_bf16 v[24:27], v[154:157], v[150:153], v[24:27]
	v_mfma_f32_16x16x32_bf16 v[20:23], v[154:157], v[162:165], v[20:23]
	v_mfma_f32_16x16x32_bf16 v[16:19], v[154:157], v[166:169], v[16:19]
	s_waitcnt lgkmcnt(8)
	v_mfma_f32_16x16x32_bf16 v[12:15], v[158:161], v[146:149], v[12:15]
	v_mfma_f32_16x16x32_bf16 v[8:11], v[158:161], v[150:153], v[8:11]
	v_mfma_f32_16x16x32_bf16 v[4:7], v[158:161], v[162:165], v[4:7]
	v_mfma_f32_16x16x32_bf16 v[0:3], v[158:161], v[166:169], v[0:3]
	s_waitcnt lgkmcnt(3)
	v_mfma_f32_16x16x32_bf16 v[60:63], v[204:207], v[208:211], v[60:63]
	v_mfma_f32_16x16x32_bf16 v[56:59], v[204:207], v[212:215], v[56:59]
	v_mfma_f32_16x16x32_bf16 v[52:55], v[204:207], v[216:219], v[52:55]
	v_mfma_f32_16x16x32_bf16 v[48:51], v[204:207], v[220:223], v[48:51]
	s_waitcnt lgkmcnt(2)
	v_mfma_f32_16x16x32_bf16 v[44:47], v[224:227], v[208:211], v[44:47]
	v_mfma_f32_16x16x32_bf16 v[40:43], v[224:227], v[212:215], v[40:43]
	v_mfma_f32_16x16x32_bf16 v[36:39], v[224:227], v[216:219], v[36:39]
	v_mfma_f32_16x16x32_bf16 v[32:35], v[224:227], v[220:223], v[32:35]
	s_waitcnt lgkmcnt(1)
	v_mfma_f32_16x16x32_bf16 v[28:31], v[228:231], v[208:211], v[28:31]
	v_mfma_f32_16x16x32_bf16 v[24:27], v[228:231], v[212:215], v[24:27]
	v_mfma_f32_16x16x32_bf16 v[20:23], v[228:231], v[216:219], v[20:23]
	v_mfma_f32_16x16x32_bf16 v[16:19], v[228:231], v[220:223], v[16:19]
	s_waitcnt lgkmcnt(0)
	v_mfma_f32_16x16x32_bf16 v[12:15], v[232:235], v[208:211], v[12:15]
	v_mfma_f32_16x16x32_bf16 v[8:11], v[232:235], v[212:215], v[8:11]
	v_mfma_f32_16x16x32_bf16 v[4:7], v[232:235], v[216:219], v[4:7]
	v_mfma_f32_16x16x32_bf16 v[0:3], v[232:235], v[220:223], v[0:3]
	s_setprio 0
	s_cmpk_eq_i32 s8, 0x780
	s_waitcnt vmcnt(0)
	s_barrier
	s_cbranch_scc0 .LBB0_2009
	ds_read_b128 v[88:91], v115 offset:55296
	ds_read_b128 v[92:95], v115 offset:53248
	ds_read_b128 v[96:99], v116 offset:38912
	ds_read_b128 v[100:103], v116 offset:36864
	ds_read_b128 v[138:141], v115 offset:51200
	ds_read_b128 v[142:145], v115 offset:49152
	ds_read_b128 v[146:149], v116 offset:34816
	ds_read_b128 v[150:153], v116 offset:32768
	s_setprio 1
	s_waitcnt lgkmcnt(5)
	v_mfma_f32_16x16x32_bf16 v[0:3], v[96:99], v[88:91], v[0:3]
	s_waitcnt lgkmcnt(0)
	v_mfma_f32_16x16x32_bf16 v[60:63], v[150:153], v[142:145], v[60:63]
	v_mfma_f32_16x16x32_bf16 v[56:59], v[150:153], v[138:141], v[56:59]
	v_mfma_f32_16x16x32_bf16 v[52:55], v[150:153], v[92:95], v[52:55]
	v_mfma_f32_16x16x32_bf16 v[48:51], v[150:153], v[88:91], v[48:51]
	v_mfma_f32_16x16x32_bf16 v[44:47], v[146:149], v[142:145], v[44:47]
	v_mfma_f32_16x16x32_bf16 v[40:43], v[146:149], v[138:141], v[40:43]
	v_mfma_f32_16x16x32_bf16 v[36:39], v[146:149], v[92:95], v[36:39]
	v_mfma_f32_16x16x32_bf16 v[32:35], v[146:149], v[88:91], v[32:35]
	v_mfma_f32_16x16x32_bf16 v[28:31], v[100:103], v[142:145], v[28:31]
	v_mfma_f32_16x16x32_bf16 v[24:27], v[100:103], v[138:141], v[24:27]
	v_mfma_f32_16x16x32_bf16 v[20:23], v[100:103], v[92:95], v[20:23]
	v_mfma_f32_16x16x32_bf16 v[16:19], v[100:103], v[88:91], v[16:19]
	v_mfma_f32_16x16x32_bf16 v[12:15], v[96:99], v[142:145], v[12:15]
	v_mfma_f32_16x16x32_bf16 v[8:11], v[96:99], v[138:141], v[8:11]
	v_mfma_f32_16x16x32_bf16 v[4:7], v[96:99], v[92:95], v[4:7]
	s_setprio 0
	ds_read_b128 v[88:91], v117 offset:32768
	ds_read_b128 v[92:95], v117 offset:34816
	ds_read_b128 v[96:99], v118 offset:49152
	ds_read_b128 v[100:103], v118 offset:51200
	ds_read_b128 v[138:141], v117 offset:36864
	ds_read_b128 v[142:145], v117 offset:38912
	ds_read_b128 v[146:149], v118 offset:53248
	ds_read_b128 v[150:153], v118 offset:55296
	s_setprio 1
	s_waitcnt lgkmcnt(0)
	v_mfma_f32_16x16x32_bf16 v[0:3], v[142:145], v[150:153], v[0:3]
	v_mfma_f32_16x16x32_bf16 v[60:63], v[88:91], v[96:99], v[60:63]
	v_mfma_f32_16x16x32_bf16 v[56:59], v[88:91], v[100:103], v[56:59]
	v_mfma_f32_16x16x32_bf16 v[52:55], v[88:91], v[146:149], v[52:55]
	v_mfma_f32_16x16x32_bf16 v[48:51], v[88:91], v[150:153], v[48:51]
	v_mfma_f32_16x16x32_bf16 v[44:47], v[92:95], v[96:99], v[44:47]
	v_mfma_f32_16x16x32_bf16 v[40:43], v[92:95], v[100:103], v[40:43]
	v_mfma_f32_16x16x32_bf16 v[36:39], v[92:95], v[146:149], v[36:39]
	v_mfma_f32_16x16x32_bf16 v[32:35], v[92:95], v[150:153], v[32:35]
	v_mfma_f32_16x16x32_bf16 v[28:31], v[138:141], v[96:99], v[28:31]
	v_mfma_f32_16x16x32_bf16 v[24:27], v[138:141], v[100:103], v[24:27]
	v_mfma_f32_16x16x32_bf16 v[20:23], v[138:141], v[146:149], v[20:23]
	v_mfma_f32_16x16x32_bf16 v[16:19], v[138:141], v[150:153], v[16:19]
	v_mfma_f32_16x16x32_bf16 v[12:15], v[142:145], v[96:99], v[12:15]
	v_mfma_f32_16x16x32_bf16 v[8:11], v[142:145], v[100:103], v[8:11]
	v_mfma_f32_16x16x32_bf16 v[4:7], v[142:145], v[146:149], v[4:7]
	s_setprio 0
	s_barrier
	ds_write2_b32 v119, v60, v56 offset1:16
	ds_write2_b32 v119, v61, v57 offset0:132 offset1:148
	v_add_u32_e32 v56, 0x400, v119
	ds_write2_b32 v56, v62, v58 offset0:8 offset1:24
	ds_write2_b32 v56, v63, v59 offset0:140 offset1:156
	ds_write2_b32 v119, v52, v48 offset0:32 offset1:48
	ds_write2_b32 v119, v53, v49 offset0:164 offset1:180
	ds_write2_b32 v56, v54, v50 offset0:40 offset1:56
	ds_write2_b32 v56, v55, v51 offset0:172 offset1:188
	v_add_u32_e32 v48, 0x2000, v119
	ds_write2_b32 v48, v44, v40 offset0:64 offset1:80
	ds_write2_b32 v48, v45, v41 offset0:196 offset1:212
	v_add_u32_e32 v40, 0x2400, v119
	ds_write2_b32 v40, v46, v42 offset0:72 offset1:88
	ds_write2_b32 v40, v47, v43 offset0:204 offset1:220
	ds_write2_b32 v48, v36, v32 offset0:96 offset1:112
	ds_write2_b32 v48, v37, v33 offset0:228 offset1:244
	ds_write2_b32 v40, v38, v34 offset0:104 offset1:120
	ds_write2_b32 v40, v39, v35 offset0:236 offset1:252
	v_add_u32_e32 v32, 0x4000, v119
	ds_write2_b32 v32, v28, v24 offset0:128 offset1:144
	v_add_u32_e32 v24, 0x4400, v119
	ds_write2_b32 v24, v29, v25 offset0:4 offset1:20
	ds_write2_b32 v24, v30, v26 offset0:136 offset1:152
	v_add_u32_e32 v25, 0x4800, v119
	ds_write2_b32 v25, v31, v27 offset0:12 offset1:28
	ds_write2_b32 v32, v20, v16 offset0:160 offset1:176
	ds_write2_b32 v24, v21, v17 offset0:36 offset1:52
	ds_write2_b32 v24, v22, v18 offset0:168 offset1:184
	ds_write2_b32 v25, v23, v19 offset0:44 offset1:60
	v_add_u32_e32 v16, 0x6000, v119
	ds_write2_b32 v16, v12, v8 offset0:192 offset1:208
	v_add_u32_e32 v8, 0x6400, v119
	ds_write2_b32 v8, v13, v9 offset0:68 offset1:84
	ds_write2_b32 v8, v14, v10 offset0:200 offset1:216
	v_add_u32_e32 v9, 0x6800, v119
	ds_write2_b32 v9, v15, v11 offset0:76 offset1:92
	ds_write2_b32 v16, v4, v0 offset0:224 offset1:240
	ds_write2_b32 v8, v5, v1 offset0:100 offset1:116
	ds_write2_b32 v8, v6, v2 offset0:232 offset1:248
	ds_write2_b32 v9, v7, v3 offset0:108 offset1:124
	v_or_b32_e32 v0, s14, v120
	v_ashrrev_i32_e32 v1, 31, v0
	v_lshl_add_u64 v[0:1], v[0:1], 1, s[6:7]
	v_add_u32_e32 v2, s15, v128
	s_mov_b32 s8, 0
	s_waitcnt lgkmcnt(0)
	s_barrier

.LBB0_2076:
	s_and_b32 s27, s26, 0x4000
	s_xor_b32 s28, s27, 0x4000
	s_lshl_b32 s28, s28, 1
	s_add_i32 s28, s28, 32
	s_add_u32 s90, s52, s16
	s_addc_u32 s91, s53, s17
	s_add_i32 m0, s28, s82
	s_lshl_b32 s27, s27, 1
	global_load_lds_dwordx4 v192, s[90:91]
	s_add_i32 m0, s28, s83
	s_add_i32 s27, s27, 32
	global_load_lds_dwordx4 v193, s[90:91]
	s_add_i32 m0, s28, s84
	v_add3_u32 v170, s27, v114, v135
	global_load_lds_dwordx4 v194, s[90:91]
	s_add_i32 m0, s28, s85
	v_add3_u32 v171, s27, v115, v135
	global_load_lds_dwordx4 v195, s[90:91]
	s_add_i32 m0, s28, s86
	v_add_u32_e32 v158, v170, v136
	global_load_lds_dwordx4 v196, s[90:91]
	s_add_i32 m0, s28, s87
	v_add_u32_e32 v166, v171, v136
	global_load_lds_dwordx4 v197, s[90:91]
	s_add_i32 m0, s28, s88
	s_addk_i32 s26, 0x4000
	global_load_lds_dwordx4 v198, s[90:91]
	s_add_i32 m0, s28, s89
	s_add_u32 s16, s16, 0x80
	s_addc_u32 s17, s17, 0
	global_load_lds_dwordx4 v199, s[90:91]
	ds_read_b128 v[138:141], v158
	ds_read_b128 v[146:149], v166 offset:16384
	ds_read_b128 v[150:153], v166 offset:18432
	ds_read_b128 v[162:165], v166 offset:20480
	ds_read_b128 v[166:169], v166 offset:22528
	ds_read_b128 v[142:145], v158 offset:2048
	ds_read_b128 v[154:157], v158 offset:4096
	ds_read_b128 v[158:161], v158 offset:6144
	v_add_u32_e32 v236, v170, v137
	v_add_u32_e32 v237, v171, v137
	ds_read_b128 v[204:207], v236
	ds_read_b128 v[208:211], v237 offset:16384
	ds_read_b128 v[212:215], v237 offset:18432
	ds_read_b128 v[216:219], v237 offset:20480
	ds_read_b128 v[220:223], v237 offset:22528
	ds_read_b128 v[224:227], v236 offset:2048
	ds_read_b128 v[228:231], v236 offset:4096
	ds_read_b128 v[232:235], v236 offset:6144
	s_setprio 1
	s_waitcnt lgkmcnt(11)
	v_mfma_f32_16x16x32_bf16 v[60:63], v[138:141], v[146:149], v[60:63]
	v_mfma_f32_16x16x32_bf16 v[56:59], v[138:141], v[150:153], v[56:59]
	v_mfma_f32_16x16x32_bf16 v[52:55], v[138:141], v[162:165], v[52:55]
	v_mfma_f32_16x16x32_bf16 v[48:51], v[138:141], v[166:169], v[48:51]
	s_waitcnt lgkmcnt(10)
	v_mfma_f32_16x16x32_bf16 v[44:47], v[142:145], v[146:149], v[44:47]
	v_mfma_f32_16x16x32_bf16 v[40:43], v[142:145], v[150:153], v[40:43]
	v_mfma_f32_16x16x32_bf16 v[36:39], v[142:145], v[162:165], v[36:39]
	v_mfma_f32_16x16x32_bf16 v[32:35], v[142:145], v[166:169], v[32:35]
	s_waitcnt lgkmcnt(9)
	v_mfma_f32_16x16x32_bf16 v[28:31], v[154:157], v[146:149], v[28:31]
	v_mfma_f32_16x16x32_bf16 v[24:27], v[154:157], v[150:153], v[24:27]
	v_mfma_f32_16x16x32_bf16 v[20:23], v[154:157], v[162:165], v[20:23]
	v_mfma_f32_16x16x32_bf16 v[16:19], v[154:157], v[166:169], v[16:19]
	s_waitcnt lgkmcnt(8)
	v_mfma_f32_16x16x32_bf16 v[12:15], v[158:161], v[146:149], v[12:15]
	v_mfma_f32_16x16x32_bf16 v[8:11], v[158:161], v[150:153], v[8:11]
	v_mfma_f32_16x16x32_bf16 v[4:7], v[158:161], v[162:165], v[4:7]
	v_mfma_f32_16x16x32_bf16 v[0:3], v[158:161], v[166:169], v[0:3]
	s_waitcnt lgkmcnt(3)
	v_mfma_f32_16x16x32_bf16 v[60:63], v[204:207], v[208:211], v[60:63]
	v_mfma_f32_16x16x32_bf16 v[56:59], v[204:207], v[212:215], v[56:59]
	v_mfma_f32_16x16x32_bf16 v[52:55], v[204:207], v[216:219], v[52:55]
	v_mfma_f32_16x16x32_bf16 v[48:51], v[204:207], v[220:223], v[48:51]
	s_waitcnt lgkmcnt(2)
	v_mfma_f32_16x16x32_bf16 v[44:47], v[224:227], v[208:211], v[44:47]
	v_mfma_f32_16x16x32_bf16 v[40:43], v[224:227], v[212:215], v[40:43]
	v_mfma_f32_16x16x32_bf16 v[36:39], v[224:227], v[216:219], v[36:39]
	v_mfma_f32_16x16x32_bf16 v[32:35], v[224:227], v[220:223], v[32:35]
	s_waitcnt lgkmcnt(1)
	v_mfma_f32_16x16x32_bf16 v[28:31], v[228:231], v[208:211], v[28:31]
	v_mfma_f32_16x16x32_bf16 v[24:27], v[228:231], v[212:215], v[24:27]
	v_mfma_f32_16x16x32_bf16 v[20:23], v[228:231], v[216:219], v[20:23]
	v_mfma_f32_16x16x32_bf16 v[16:19], v[228:231], v[220:223], v[16:19]
	s_waitcnt lgkmcnt(0)
	v_mfma_f32_16x16x32_bf16 v[12:15], v[232:235], v[208:211], v[12:15]
	v_mfma_f32_16x16x32_bf16 v[8:11], v[232:235], v[212:215], v[8:11]
	v_mfma_f32_16x16x32_bf16 v[4:7], v[232:235], v[216:219], v[4:7]
	v_mfma_f32_16x16x32_bf16 v[0:3], v[232:235], v[220:223], v[0:3]
	s_setprio 0
	s_cmpk_eq_i32 s16, 0x1f80
	s_waitcnt vmcnt(0)
	s_barrier
	s_cbranch_scc0 .LBB0_2076
	ds_read_b128 v[90:93], v118 offset:55296
	ds_read_b128 v[94:97], v118 offset:53248
	ds_read_b128 v[98:101], v119 offset:38912
	ds_read_b128 v[102:105], v119 offset:36864
	ds_read_b128 v[138:141], v118 offset:51200
	ds_read_b128 v[142:145], v118 offset:49152
	ds_read_b128 v[146:149], v119 offset:34816
	ds_read_b128 v[150:153], v119 offset:32768
	s_setprio 1
	s_waitcnt lgkmcnt(5)
	v_mfma_f32_16x16x32_bf16 v[4:7], v[98:101], v[94:97], v[4:7]
	v_mfma_f32_16x16x32_bf16 v[0:3], v[98:101], v[90:93], v[0:3]
	s_waitcnt lgkmcnt(0)
	v_mfma_f32_16x16x32_bf16 v[60:63], v[150:153], v[142:145], v[60:63]
	v_mfma_f32_16x16x32_bf16 v[56:59], v[150:153], v[138:141], v[56:59]
	v_mfma_f32_16x16x32_bf16 v[52:55], v[150:153], v[94:97], v[52:55]
	v_mfma_f32_16x16x32_bf16 v[48:51], v[150:153], v[90:93], v[48:51]
	v_mfma_f32_16x16x32_bf16 v[44:47], v[146:149], v[142:145], v[44:47]
	v_mfma_f32_16x16x32_bf16 v[40:43], v[146:149], v[138:141], v[40:43]
	v_mfma_f32_16x16x32_bf16 v[36:39], v[146:149], v[94:97], v[36:39]
	v_mfma_f32_16x16x32_bf16 v[32:35], v[146:149], v[90:93], v[32:35]
	v_mfma_f32_16x16x32_bf16 v[28:31], v[102:105], v[142:145], v[28:31]
	v_mfma_f32_16x16x32_bf16 v[24:27], v[102:105], v[138:141], v[24:27]
	v_mfma_f32_16x16x32_bf16 v[20:23], v[102:105], v[94:97], v[20:23]
	v_mfma_f32_16x16x32_bf16 v[16:19], v[102:105], v[90:93], v[16:19]
	v_mfma_f32_16x16x32_bf16 v[12:15], v[98:101], v[142:145], v[12:15]
	v_mfma_f32_16x16x32_bf16 v[8:11], v[98:101], v[138:141], v[8:11]
	s_setprio 0
	ds_read_b128 v[90:93], v120 offset:32768
	ds_read_b128 v[94:97], v120 offset:34816
	ds_read_b128 v[98:101], v121 offset:49152
	ds_read_b128 v[102:105], v121 offset:51200
	ds_read_b128 v[138:141], v120 offset:36864
	ds_read_b128 v[142:145], v120 offset:38912
	ds_read_b128 v[146:149], v121 offset:53248
	ds_read_b128 v[150:153], v121 offset:55296
	s_setprio 1
	s_waitcnt lgkmcnt(1)
	v_mfma_f32_16x16x32_bf16 v[4:7], v[142:145], v[146:149], v[4:7]
	s_waitcnt lgkmcnt(0)
	v_mfma_f32_16x16x32_bf16 v[0:3], v[142:145], v[150:153], v[0:3]
	v_mfma_f32_16x16x32_bf16 v[60:63], v[90:93], v[98:101], v[60:63]
	v_mfma_f32_16x16x32_bf16 v[56:59], v[90:93], v[102:105], v[56:59]
	v_mfma_f32_16x16x32_bf16 v[52:55], v[90:93], v[146:149], v[52:55]
	v_mfma_f32_16x16x32_bf16 v[48:51], v[90:93], v[150:153], v[48:51]
	v_mfma_f32_16x16x32_bf16 v[44:47], v[94:97], v[98:101], v[44:47]
	v_mfma_f32_16x16x32_bf16 v[40:43], v[94:97], v[102:105], v[40:43]
	v_mfma_f32_16x16x32_bf16 v[36:39], v[94:97], v[146:149], v[36:39]
	v_mfma_f32_16x16x32_bf16 v[32:35], v[94:97], v[150:153], v[32:35]
	v_mfma_f32_16x16x32_bf16 v[28:31], v[138:141], v[98:101], v[28:31]
	v_mfma_f32_16x16x32_bf16 v[24:27], v[138:141], v[102:105], v[24:27]
	v_mfma_f32_16x16x32_bf16 v[20:23], v[138:141], v[146:149], v[20:23]
	v_mfma_f32_16x16x32_bf16 v[16:19], v[138:141], v[150:153], v[16:19]
	v_mfma_f32_16x16x32_bf16 v[12:15], v[142:145], v[98:101], v[12:15]
	v_mfma_f32_16x16x32_bf16 v[8:11], v[142:145], v[102:105], v[8:11]
	s_setprio 0
	s_barrier
	ds_write2_b32 v116, v60, v56 offset1:16
	ds_write2_b32 v116, v61, v57 offset0:132 offset1:148
	v_add_u32_e32 v56, 0x400, v116
	ds_write2_b32 v56, v62, v58 offset0:8 offset1:24
	ds_write2_b32 v56, v63, v59 offset0:140 offset1:156
	ds_write2_b32 v116, v52, v48 offset0:32 offset1:48
	ds_write2_b32 v116, v53, v49 offset0:164 offset1:180
	ds_write2_b32 v56, v54, v50 offset0:40 offset1:56
	ds_write2_b32 v56, v55, v51 offset0:172 offset1:188
	v_add_u32_e32 v48, 0x2000, v116
	ds_write2_b32 v48, v44, v40 offset0:64 offset1:80
	ds_write2_b32 v48, v45, v41 offset0:196 offset1:212
	v_add_u32_e32 v40, 0x2400, v116
	ds_write2_b32 v40, v46, v42 offset0:72 offset1:88
	ds_write2_b32 v40, v47, v43 offset0:204 offset1:220
	ds_write2_b32 v48, v36, v32 offset0:96 offset1:112
	ds_write2_b32 v48, v37, v33 offset0:228 offset1:244
	ds_write2_b32 v40, v38, v34 offset0:104 offset1:120
	ds_write2_b32 v40, v39, v35 offset0:236 offset1:252
	v_add_u32_e32 v32, 0x4000, v116
	ds_write2_b32 v32, v28, v24 offset0:128 offset1:144
	v_add_u32_e32 v24, 0x4400, v116
	ds_write2_b32 v24, v29, v25 offset0:4 offset1:20
	ds_write2_b32 v24, v30, v26 offset0:136 offset1:152
	v_add_u32_e32 v25, 0x4800, v116
	ds_write2_b32 v25, v31, v27 offset0:12 offset1:28
	ds_write2_b32 v32, v20, v16 offset0:160 offset1:176
	ds_write2_b32 v24, v21, v17 offset0:36 offset1:52
	ds_write2_b32 v24, v22, v18 offset0:168 offset1:184
	ds_write2_b32 v25, v23, v19 offset0:44 offset1:60
	v_add_u32_e32 v16, 0x6000, v116
	ds_write2_b32 v16, v12, v8 offset0:192 offset1:208
	v_add_u32_e32 v8, 0x6400, v116
	ds_write2_b32 v8, v13, v9 offset0:68 offset1:84
	ds_write2_b32 v8, v14, v10 offset0:200 offset1:216
	v_add_u32_e32 v9, 0x6800, v116
	ds_write2_b32 v9, v15, v11 offset0:76 offset1:92
	ds_write2_b32 v16, v4, v0 offset0:224 offset1:240
	ds_write2_b32 v8, v5, v1 offset0:100 offset1:116
	ds_write2_b32 v8, v6, v2 offset0:232 offset1:248
	ds_write2_b32 v9, v7, v3 offset0:108 offset1:124
	v_or_b32_e32 v0, s25, v117
	v_ashrrev_i32_e32 v1, 31, v0
	v_lshlrev_b64 v[2:3], 2, v[0:1]
	v_lshl_add_u64 v[0:1], s[14:15], 0, v[2:3]
	v_lshl_add_u64 v[2:3], s[12:13], 0, v[2:3]
	v_add_u32_e32 v4, s24, v128
	s_mov_b32 s16, 0
	s_waitcnt lgkmcnt(0)
	s_barrier

.LBB0_2085:
	s_and_b32 s28, s27, 0x4000
	s_xor_b32 s29, s28, 0x4000
	s_lshl_b32 s29, s29, 1
	s_add_i32 s29, s29, 32
	s_add_u32 s90, s52, s16
	s_addc_u32 s91, s53, s17
	s_add_i32 m0, s29, s82
	s_lshl_b32 s28, s28, 1
	global_load_lds_dwordx4 v192, s[90:91]
	s_add_i32 m0, s29, s83
	s_add_i32 s28, s28, 32
	global_load_lds_dwordx4 v193, s[90:91]
	s_add_i32 m0, s29, s84
	v_add3_u32 v139, s28, v113, v136
	global_load_lds_dwordx4 v194, s[90:91]
	s_add_i32 m0, s29, s85
	v_add3_u32 v172, s28, v114, v136
	global_load_lds_dwordx4 v195, s[90:91]
	s_add_i32 m0, s29, s86
	v_add_u32_e32 v160, v139, v137
	global_load_lds_dwordx4 v196, s[90:91]
	s_add_i32 m0, s29, s87
	v_add_u32_e32 v168, v172, v137
	global_load_lds_dwordx4 v197, s[90:91]
	s_add_i32 m0, s29, s88
	s_addk_i32 s27, 0x4000
	global_load_lds_dwordx4 v198, s[90:91]
	s_add_i32 m0, s29, s89
	s_add_u32 s16, s16, 0x80
	s_addc_u32 s17, s17, 0
	global_load_lds_dwordx4 v199, s[90:91]
	ds_read_b128 v[140:143], v160
	ds_read_b128 v[148:151], v168 offset:16384
	ds_read_b128 v[152:155], v168 offset:18432
	ds_read_b128 v[164:167], v168 offset:20480
	ds_read_b128 v[168:171], v168 offset:22528
	ds_read_b128 v[144:147], v160 offset:2048
	ds_read_b128 v[156:159], v160 offset:4096
	ds_read_b128 v[160:163], v160 offset:6144
	v_add_u32_e32 v139, v139, v138
	v_add_u32_e32 v236, v172, v138
	ds_read_b128 v[204:207], v139
	ds_read_b128 v[208:211], v236 offset:16384
	ds_read_b128 v[212:215], v236 offset:18432
	ds_read_b128 v[216:219], v236 offset:20480
	ds_read_b128 v[220:223], v236 offset:22528
	ds_read_b128 v[224:227], v139 offset:2048
	ds_read_b128 v[228:231], v139 offset:4096
	ds_read_b128 v[232:235], v139 offset:6144
	s_setprio 1
	s_waitcnt lgkmcnt(11)
	v_mfma_f32_16x16x32_bf16 v[60:63], v[140:143], v[148:151], v[60:63]
	v_mfma_f32_16x16x32_bf16 v[56:59], v[140:143], v[152:155], v[56:59]
	v_mfma_f32_16x16x32_bf16 v[52:55], v[140:143], v[164:167], v[52:55]
	v_mfma_f32_16x16x32_bf16 v[48:51], v[140:143], v[168:171], v[48:51]
	s_waitcnt lgkmcnt(10)
	v_mfma_f32_16x16x32_bf16 v[44:47], v[144:147], v[148:151], v[44:47]
	v_mfma_f32_16x16x32_bf16 v[40:43], v[144:147], v[152:155], v[40:43]
	v_mfma_f32_16x16x32_bf16 v[36:39], v[144:147], v[164:167], v[36:39]
	v_mfma_f32_16x16x32_bf16 v[32:35], v[144:147], v[168:171], v[32:35]
	s_waitcnt lgkmcnt(9)
	v_mfma_f32_16x16x32_bf16 v[28:31], v[156:159], v[148:151], v[28:31]
	v_mfma_f32_16x16x32_bf16 v[24:27], v[156:159], v[152:155], v[24:27]
	v_mfma_f32_16x16x32_bf16 v[20:23], v[156:159], v[164:167], v[20:23]
	v_mfma_f32_16x16x32_bf16 v[16:19], v[156:159], v[168:171], v[16:19]
	s_waitcnt lgkmcnt(8)
	v_mfma_f32_16x16x32_bf16 v[12:15], v[160:163], v[148:151], v[12:15]
	v_mfma_f32_16x16x32_bf16 v[8:11], v[160:163], v[152:155], v[8:11]
	v_mfma_f32_16x16x32_bf16 v[4:7], v[160:163], v[164:167], v[4:7]
	v_mfma_f32_16x16x32_bf16 v[0:3], v[160:163], v[168:171], v[0:3]
	s_waitcnt lgkmcnt(3)
	v_mfma_f32_16x16x32_bf16 v[60:63], v[204:207], v[208:211], v[60:63]
	v_mfma_f32_16x16x32_bf16 v[56:59], v[204:207], v[212:215], v[56:59]
	v_mfma_f32_16x16x32_bf16 v[52:55], v[204:207], v[216:219], v[52:55]
	v_mfma_f32_16x16x32_bf16 v[48:51], v[204:207], v[220:223], v[48:51]
	s_waitcnt lgkmcnt(2)
	v_mfma_f32_16x16x32_bf16 v[44:47], v[224:227], v[208:211], v[44:47]
	v_mfma_f32_16x16x32_bf16 v[40:43], v[224:227], v[212:215], v[40:43]
	v_mfma_f32_16x16x32_bf16 v[36:39], v[224:227], v[216:219], v[36:39]
	v_mfma_f32_16x16x32_bf16 v[32:35], v[224:227], v[220:223], v[32:35]
	s_waitcnt lgkmcnt(1)
	v_mfma_f32_16x16x32_bf16 v[28:31], v[228:231], v[208:211], v[28:31]
	v_mfma_f32_16x16x32_bf16 v[24:27], v[228:231], v[212:215], v[24:27]
	v_mfma_f32_16x16x32_bf16 v[20:23], v[228:231], v[216:219], v[20:23]
	v_mfma_f32_16x16x32_bf16 v[16:19], v[228:231], v[220:223], v[16:19]
	s_waitcnt lgkmcnt(0)
	v_mfma_f32_16x16x32_bf16 v[12:15], v[232:235], v[208:211], v[12:15]
	v_mfma_f32_16x16x32_bf16 v[8:11], v[232:235], v[212:215], v[8:11]
	v_mfma_f32_16x16x32_bf16 v[4:7], v[232:235], v[216:219], v[4:7]
	v_mfma_f32_16x16x32_bf16 v[0:3], v[232:235], v[220:223], v[0:3]
	s_setprio 0
	s_cmpk_eq_i32 s16, 0x1f80
	s_waitcnt vmcnt(0)
	s_barrier
	s_cbranch_scc0 .LBB0_2085
	ds_read_b128 v[88:91], v117 offset:55296
	ds_read_b128 v[92:95], v117 offset:53248
	ds_read_b128 v[96:99], v118 offset:38912
	ds_read_b128 v[100:103], v118 offset:36864
	ds_read_b128 v[140:143], v117 offset:51200
	ds_read_b128 v[144:147], v117 offset:49152
	ds_read_b128 v[148:151], v118 offset:34816
	ds_read_b128 v[152:155], v118 offset:32768
	s_setprio 1
	s_waitcnt lgkmcnt(5)
	v_mfma_f32_16x16x32_bf16 v[4:7], v[96:99], v[92:95], v[4:7]
	v_mfma_f32_16x16x32_bf16 v[0:3], v[96:99], v[88:91], v[0:3]
	s_waitcnt lgkmcnt(0)
	v_mfma_f32_16x16x32_bf16 v[60:63], v[152:155], v[144:147], v[60:63]
	v_mfma_f32_16x16x32_bf16 v[56:59], v[152:155], v[140:143], v[56:59]
	v_mfma_f32_16x16x32_bf16 v[52:55], v[152:155], v[92:95], v[52:55]
	v_mfma_f32_16x16x32_bf16 v[48:51], v[152:155], v[88:91], v[48:51]
	v_mfma_f32_16x16x32_bf16 v[44:47], v[148:151], v[144:147], v[44:47]
	v_mfma_f32_16x16x32_bf16 v[40:43], v[148:151], v[140:143], v[40:43]
	v_mfma_f32_16x16x32_bf16 v[36:39], v[148:151], v[92:95], v[36:39]
	v_mfma_f32_16x16x32_bf16 v[32:35], v[148:151], v[88:91], v[32:35]
	v_mfma_f32_16x16x32_bf16 v[28:31], v[100:103], v[144:147], v[28:31]
	v_mfma_f32_16x16x32_bf16 v[24:27], v[100:103], v[140:143], v[24:27]
	v_mfma_f32_16x16x32_bf16 v[20:23], v[100:103], v[92:95], v[20:23]
	v_mfma_f32_16x16x32_bf16 v[16:19], v[100:103], v[88:91], v[16:19]
	v_mfma_f32_16x16x32_bf16 v[12:15], v[96:99], v[144:147], v[12:15]
	v_mfma_f32_16x16x32_bf16 v[8:11], v[96:99], v[140:143], v[8:11]
	s_setprio 0
	ds_read_b128 v[88:91], v119 offset:32768
	ds_read_b128 v[92:95], v119 offset:34816
	ds_read_b128 v[96:99], v120 offset:49152
	ds_read_b128 v[100:103], v120 offset:51200
	ds_read_b128 v[140:143], v119 offset:36864
	ds_read_b128 v[144:147], v119 offset:38912
	ds_read_b128 v[148:151], v120 offset:53248
	ds_read_b128 v[152:155], v120 offset:55296
	s_setprio 1
	s_waitcnt lgkmcnt(1)
	v_mfma_f32_16x16x32_bf16 v[4:7], v[144:147], v[148:151], v[4:7]
	s_waitcnt lgkmcnt(0)
	v_mfma_f32_16x16x32_bf16 v[0:3], v[144:147], v[152:155], v[0:3]
	v_mfma_f32_16x16x32_bf16 v[60:63], v[88:91], v[96:99], v[60:63]
	v_mfma_f32_16x16x32_bf16 v[56:59], v[88:91], v[100:103], v[56:59]
	v_mfma_f32_16x16x32_bf16 v[52:55], v[88:91], v[148:151], v[52:55]
	v_mfma_f32_16x16x32_bf16 v[48:51], v[88:91], v[152:155], v[48:51]
	v_mfma_f32_16x16x32_bf16 v[44:47], v[92:95], v[96:99], v[44:47]
	v_mfma_f32_16x16x32_bf16 v[40:43], v[92:95], v[100:103], v[40:43]
	v_mfma_f32_16x16x32_bf16 v[36:39], v[92:95], v[148:151], v[36:39]
	v_mfma_f32_16x16x32_bf16 v[32:35], v[92:95], v[152:155], v[32:35]
	v_mfma_f32_16x16x32_bf16 v[28:31], v[140:143], v[96:99], v[28:31]
	v_mfma_f32_16x16x32_bf16 v[24:27], v[140:143], v[100:103], v[24:27]
	v_mfma_f32_16x16x32_bf16 v[20:23], v[140:143], v[148:151], v[20:23]
	v_mfma_f32_16x16x32_bf16 v[16:19], v[140:143], v[152:155], v[16:19]
	v_mfma_f32_16x16x32_bf16 v[12:15], v[144:147], v[96:99], v[12:15]
	v_mfma_f32_16x16x32_bf16 v[8:11], v[144:147], v[100:103], v[8:11]
	s_setprio 0
	s_barrier
	ds_write2_b32 v115, v60, v56 offset1:16
	ds_write2_b32 v115, v61, v57 offset0:132 offset1:148
	v_add_u32_e32 v56, 0x400, v115
	ds_write2_b32 v56, v62, v58 offset0:8 offset1:24
	ds_write2_b32 v56, v63, v59 offset0:140 offset1:156
	ds_write2_b32 v115, v52, v48 offset0:32 offset1:48
	ds_write2_b32 v115, v53, v49 offset0:164 offset1:180
	ds_write2_b32 v56, v54, v50 offset0:40 offset1:56
	ds_write2_b32 v56, v55, v51 offset0:172 offset1:188
	v_add_u32_e32 v48, 0x2000, v115
	ds_write2_b32 v48, v44, v40 offset0:64 offset1:80
	ds_write2_b32 v48, v45, v41 offset0:196 offset1:212
	v_add_u32_e32 v40, 0x2400, v115
	ds_write2_b32 v40, v46, v42 offset0:72 offset1:88
	ds_write2_b32 v40, v47, v43 offset0:204 offset1:220
	ds_write2_b32 v48, v36, v32 offset0:96 offset1:112
	ds_write2_b32 v48, v37, v33 offset0:228 offset1:244
	ds_write2_b32 v40, v38, v34 offset0:104 offset1:120
	ds_write2_b32 v40, v39, v35 offset0:236 offset1:252
	v_add_u32_e32 v32, 0x4000, v115
	ds_write2_b32 v32, v28, v24 offset0:128 offset1:144
	v_add_u32_e32 v24, 0x4400, v115
	ds_write2_b32 v24, v29, v25 offset0:4 offset1:20
	ds_write2_b32 v24, v30, v26 offset0:136 offset1:152
	v_add_u32_e32 v25, 0x4800, v115
	ds_write2_b32 v25, v31, v27 offset0:12 offset1:28
	ds_write2_b32 v32, v20, v16 offset0:160 offset1:176
	ds_write2_b32 v24, v21, v17 offset0:36 offset1:52
	ds_write2_b32 v24, v22, v18 offset0:168 offset1:184
	ds_write2_b32 v25, v23, v19 offset0:44 offset1:60
	v_add_u32_e32 v16, 0x6000, v115
	ds_write2_b32 v16, v12, v8 offset0:192 offset1:208
	v_add_u32_e32 v8, 0x6400, v115
	ds_write2_b32 v8, v13, v9 offset0:68 offset1:84
	ds_write2_b32 v8, v14, v10 offset0:200 offset1:216
	v_add_u32_e32 v9, 0x6800, v115
	ds_write2_b32 v9, v15, v11 offset0:76 offset1:92
	ds_write2_b32 v16, v4, v0 offset0:224 offset1:240
	ds_write2_b32 v8, v5, v1 offset0:100 offset1:116
	ds_write2_b32 v8, v6, v2 offset0:232 offset1:248
	ds_write2_b32 v9, v7, v3 offset0:108 offset1:124
	v_or_b32_e32 v0, s25, v116
	v_ashrrev_i32_e32 v1, 31, v0
	v_lshlrev_b64 v[2:3], 2, v[0:1]
	v_lshl_add_u64 v[0:1], s[14:15], 0, v[2:3]
	v_lshl_add_u64 v[2:3], s[12:13], 0, v[2:3]
	v_add_u32_e32 v4, s26, v129
	s_mov_b32 s16, 0
	s_waitcnt lgkmcnt(0)
	s_barrier

.LBB0_2096:
	s_and_b32 s29, s28, 0x4000
	s_xor_b32 s30, s29, 0x4000
	s_lshl_b32 s30, s30, 1
	s_add_i32 s30, s30, 32
	s_add_u32 s90, s52, s16
	s_addc_u32 s91, s53, s17
	s_add_i32 m0, s30, s82
	s_lshl_b32 s29, s29, 1
	global_load_lds_dwordx4 v193, s[90:91]
	s_add_i32 m0, s30, s83
	s_add_i32 s29, s29, 32
	global_load_lds_dwordx4 v194, s[90:91]
	s_add_i32 m0, s30, s84
	v_lshlrev_b32_e32 v72, 1, v131
	global_load_lds_dwordx4 v195, s[90:91]
	s_add_i32 m0, s30, s85
	v_add3_u32 v178, s29, v129, v72
	global_load_lds_dwordx4 v196, s[90:91]
	s_add_i32 m0, s30, s86
	v_lshlrev_b32_e32 v154, 1, v121
	global_load_lds_dwordx4 v197, s[90:91]
	s_add_i32 m0, s30, s87
	v_add3_u32 v72, s29, v130, v72
	global_load_lds_dwordx4 v198, s[90:91]
	s_add_i32 m0, s30, s88
	v_add_u32_e32 v174, v178, v154
	global_load_lds_dwordx4 v199, s[90:91]
	s_add_i32 m0, s30, s89
	v_add_u32_e32 v179, v72, v154
	global_load_lds_dwordx4 v200, s[90:91]
	ds_read_b128 v[154:157], v174
	ds_read_b128 v[162:165], v179 offset:16384
	ds_read_b128 v[166:169], v179 offset:18432
	ds_read_b128 v[182:185], v179 offset:20480
	ds_read_b128 v[186:189], v179 offset:22528
	ds_read_b128 v[158:161], v174 offset:2048
	ds_read_b128 v[170:173], v174 offset:4096
	ds_read_b128 v[174:177], v174 offset:6144
	v_lshlrev_b32_e32 v236, 1, v122
	v_add_u32_e32 v237, v178, v236
	v_add_u32_e32 v72, v72, v236
	ds_read_b128 v[204:207], v237
	ds_read_b128 v[208:211], v72 offset:16384
	ds_read_b128 v[212:215], v72 offset:18432
	ds_read_b128 v[216:219], v72 offset:20480
	ds_read_b128 v[220:223], v72 offset:22528
	ds_read_b128 v[224:227], v237 offset:2048
	ds_read_b128 v[228:231], v237 offset:4096
	ds_read_b128 v[232:235], v237 offset:6144
	s_setprio 1
	s_waitcnt lgkmcnt(11)
	v_mfma_f32_16x16x32_bf16 v[60:63], v[154:157], v[162:165], v[60:63]
	v_mfma_f32_16x16x32_bf16 v[56:59], v[154:157], v[166:169], v[56:59]
	v_mfma_f32_16x16x32_bf16 v[52:55], v[154:157], v[182:185], v[52:55]
	v_mfma_f32_16x16x32_bf16 v[48:51], v[154:157], v[186:189], v[48:51]
	s_waitcnt lgkmcnt(10)
	v_mfma_f32_16x16x32_bf16 v[44:47], v[158:161], v[162:165], v[44:47]
	v_mfma_f32_16x16x32_bf16 v[40:43], v[158:161], v[166:169], v[40:43]
	v_mfma_f32_16x16x32_bf16 v[36:39], v[158:161], v[182:185], v[36:39]
	v_mfma_f32_16x16x32_bf16 v[32:35], v[158:161], v[186:189], v[32:35]
	s_waitcnt lgkmcnt(9)
	v_mfma_f32_16x16x32_bf16 v[28:31], v[170:173], v[162:165], v[28:31]
	v_mfma_f32_16x16x32_bf16 v[24:27], v[170:173], v[166:169], v[24:27]
	v_mfma_f32_16x16x32_bf16 v[20:23], v[170:173], v[182:185], v[20:23]
	v_mfma_f32_16x16x32_bf16 v[16:19], v[170:173], v[186:189], v[16:19]
	s_waitcnt lgkmcnt(8)
	v_mfma_f32_16x16x32_bf16 v[12:15], v[174:177], v[162:165], v[12:15]
	v_mfma_f32_16x16x32_bf16 v[8:11], v[174:177], v[166:169], v[8:11]
	v_mfma_f32_16x16x32_bf16 v[4:7], v[174:177], v[182:185], v[4:7]
	v_mfma_f32_16x16x32_bf16 v[0:3], v[174:177], v[186:189], v[0:3]
	s_waitcnt lgkmcnt(3)
	v_mfma_f32_16x16x32_bf16 v[60:63], v[204:207], v[208:211], v[60:63]
	v_mfma_f32_16x16x32_bf16 v[56:59], v[204:207], v[212:215], v[56:59]
	v_mfma_f32_16x16x32_bf16 v[52:55], v[204:207], v[216:219], v[52:55]
	v_mfma_f32_16x16x32_bf16 v[48:51], v[204:207], v[220:223], v[48:51]
	s_waitcnt lgkmcnt(2)
	v_mfma_f32_16x16x32_bf16 v[44:47], v[224:227], v[208:211], v[44:47]
	v_mfma_f32_16x16x32_bf16 v[40:43], v[224:227], v[212:215], v[40:43]
	v_mfma_f32_16x16x32_bf16 v[36:39], v[224:227], v[216:219], v[36:39]
	v_mfma_f32_16x16x32_bf16 v[32:35], v[224:227], v[220:223], v[32:35]
	s_waitcnt lgkmcnt(1)
	v_mfma_f32_16x16x32_bf16 v[28:31], v[228:231], v[208:211], v[28:31]
	v_mfma_f32_16x16x32_bf16 v[24:27], v[228:231], v[212:215], v[24:27]
	v_mfma_f32_16x16x32_bf16 v[20:23], v[228:231], v[216:219], v[20:23]
	v_mfma_f32_16x16x32_bf16 v[16:19], v[228:231], v[220:223], v[16:19]
	s_waitcnt lgkmcnt(0)
	v_mfma_f32_16x16x32_bf16 v[12:15], v[232:235], v[208:211], v[12:15]
	v_mfma_f32_16x16x32_bf16 v[8:11], v[232:235], v[212:215], v[8:11]
	v_mfma_f32_16x16x32_bf16 v[4:7], v[232:235], v[216:219], v[4:7]
	v_mfma_f32_16x16x32_bf16 v[0:3], v[232:235], v[220:223], v[0:3]
	s_setprio 0
	s_add_u32 s16, s16, 0x80
	s_addc_u32 s17, s17, 0
	s_addk_i32 s28, 0x4000
	s_cmpk_eq_i32 s16, 0x1f80
	s_waitcnt vmcnt(0)
	s_barrier
	s_cbranch_scc0 .LBB0_2096
	ds_read_b128 v[98:101], v71 offset:32768
	ds_read_b128 v[102:105], v71 offset:34816
	ds_read_b128 v[106:109], v138 offset:49152
	ds_read_b128 v[110:113], v138 offset:51200
	ds_read_b128 v[154:157], v71 offset:36864
	ds_read_b128 v[158:161], v71 offset:38912
	ds_read_b128 v[162:165], v138 offset:53248
	ds_read_b128 v[166:169], v138 offset:55296
	s_setprio 1
	s_waitcnt lgkmcnt(1)
	v_mfma_f32_16x16x32_bf16 v[4:7], v[158:161], v[162:165], v[4:7]
	s_waitcnt lgkmcnt(0)
	v_mfma_f32_16x16x32_bf16 v[0:3], v[158:161], v[166:169], v[0:3]
	v_mfma_f32_16x16x32_bf16 v[60:63], v[98:101], v[106:109], v[60:63]
	v_mfma_f32_16x16x32_bf16 v[56:59], v[98:101], v[110:113], v[56:59]
	v_mfma_f32_16x16x32_bf16 v[52:55], v[98:101], v[162:165], v[52:55]
	v_mfma_f32_16x16x32_bf16 v[48:51], v[98:101], v[166:169], v[48:51]
	v_mfma_f32_16x16x32_bf16 v[44:47], v[102:105], v[106:109], v[44:47]
	v_mfma_f32_16x16x32_bf16 v[40:43], v[102:105], v[110:113], v[40:43]
	v_mfma_f32_16x16x32_bf16 v[36:39], v[102:105], v[162:165], v[36:39]
	v_mfma_f32_16x16x32_bf16 v[32:35], v[102:105], v[166:169], v[32:35]
	v_mfma_f32_16x16x32_bf16 v[28:31], v[154:157], v[106:109], v[28:31]
	v_mfma_f32_16x16x32_bf16 v[24:27], v[154:157], v[110:113], v[24:27]
	v_mfma_f32_16x16x32_bf16 v[20:23], v[154:157], v[162:165], v[20:23]
	v_mfma_f32_16x16x32_bf16 v[16:19], v[154:157], v[166:169], v[16:19]
	v_mfma_f32_16x16x32_bf16 v[12:15], v[158:161], v[106:109], v[12:15]
	v_mfma_f32_16x16x32_bf16 v[8:11], v[158:161], v[110:113], v[8:11]
	s_setprio 0
	ds_read_b128 v[98:101], v139 offset:32768
	ds_read_b128 v[102:105], v139 offset:34816
	ds_read_b128 v[106:109], v140 offset:49152
	ds_read_b128 v[110:113], v140 offset:51200
	ds_read_b128 v[154:157], v139 offset:36864
	ds_read_b128 v[158:161], v139 offset:38912
	ds_read_b128 v[162:165], v140 offset:53248
	ds_read_b128 v[166:169], v140 offset:55296
	s_setprio 1
	s_waitcnt lgkmcnt(1)
	v_mfma_f32_16x16x32_bf16 v[4:7], v[158:161], v[162:165], v[4:7]
	s_waitcnt lgkmcnt(0)
	v_mfma_f32_16x16x32_bf16 v[0:3], v[158:161], v[166:169], v[0:3]
	v_mfma_f32_16x16x32_bf16 v[60:63], v[98:101], v[106:109], v[60:63]
	v_mfma_f32_16x16x32_bf16 v[56:59], v[98:101], v[110:113], v[56:59]
	v_mfma_f32_16x16x32_bf16 v[52:55], v[98:101], v[162:165], v[52:55]
	v_mfma_f32_16x16x32_bf16 v[48:51], v[98:101], v[166:169], v[48:51]
	v_mfma_f32_16x16x32_bf16 v[44:47], v[102:105], v[106:109], v[44:47]
	v_mfma_f32_16x16x32_bf16 v[40:43], v[102:105], v[110:113], v[40:43]
	v_mfma_f32_16x16x32_bf16 v[36:39], v[102:105], v[162:165], v[36:39]
	v_mfma_f32_16x16x32_bf16 v[32:35], v[102:105], v[166:169], v[32:35]
	v_mfma_f32_16x16x32_bf16 v[28:31], v[154:157], v[106:109], v[28:31]
	v_mfma_f32_16x16x32_bf16 v[24:27], v[154:157], v[110:113], v[24:27]
	v_mfma_f32_16x16x32_bf16 v[20:23], v[154:157], v[162:165], v[20:23]
	v_mfma_f32_16x16x32_bf16 v[16:19], v[154:157], v[166:169], v[16:19]
	v_mfma_f32_16x16x32_bf16 v[12:15], v[158:161], v[106:109], v[12:15]
	v_mfma_f32_16x16x32_bf16 v[8:11], v[158:161], v[110:113], v[8:11]
	s_setprio 0
	s_barrier
	ds_write2_b32 v136, v60, v56 offset1:16
	ds_write2_b32 v136, v61, v57 offset0:132 offset1:148
	v_add_u32_e32 v56, 0x400, v136
	ds_write2_b32 v56, v62, v58 offset0:8 offset1:24
	ds_write2_b32 v56, v63, v59 offset0:140 offset1:156
	ds_write2_b32 v136, v52, v48 offset0:32 offset1:48
	ds_write2_b32 v136, v53, v49 offset0:164 offset1:180
	ds_write2_b32 v56, v54, v50 offset0:40 offset1:56
	ds_write2_b32 v56, v55, v51 offset0:172 offset1:188
	v_add_u32_e32 v48, 0x2000, v136
	ds_write2_b32 v48, v44, v40 offset0:64 offset1:80
	ds_write2_b32 v48, v45, v41 offset0:196 offset1:212
	v_add_u32_e32 v40, 0x2400, v136
	ds_write2_b32 v40, v46, v42 offset0:72 offset1:88
	ds_write2_b32 v40, v47, v43 offset0:204 offset1:220
	ds_write2_b32 v48, v36, v32 offset0:96 offset1:112
	ds_write2_b32 v48, v37, v33 offset0:228 offset1:244
	ds_write2_b32 v40, v38, v34 offset0:104 offset1:120
	ds_write2_b32 v40, v39, v35 offset0:236 offset1:252
	v_add_u32_e32 v32, 0x4000, v136
	ds_write2_b32 v32, v28, v24 offset0:128 offset1:144
	v_add_u32_e32 v24, 0x4400, v136
	ds_write2_b32 v24, v29, v25 offset0:4 offset1:20
	ds_write2_b32 v24, v30, v26 offset0:136 offset1:152
	v_add_u32_e32 v25, 0x4800, v136
	ds_write2_b32 v25, v31, v27 offset0:12 offset1:28
	ds_write2_b32 v32, v20, v16 offset0:160 offset1:176
	ds_write2_b32 v24, v21, v17 offset0:36 offset1:52
	ds_write2_b32 v24, v22, v18 offset0:168 offset1:184
	ds_write2_b32 v25, v23, v19 offset0:44 offset1:60
	v_add_u32_e32 v16, 0x6000, v136
	ds_write2_b32 v16, v12, v8 offset0:192 offset1:208
	v_add_u32_e32 v8, 0x6400, v136
	ds_write2_b32 v8, v13, v9 offset0:68 offset1:84
	ds_write2_b32 v8, v14, v10 offset0:200 offset1:216
	v_add_u32_e32 v9, 0x6800, v136
	ds_write2_b32 v9, v15, v11 offset0:76 offset1:92
	ds_write2_b32 v16, v4, v0 offset0:224 offset1:240
	ds_write2_b32 v8, v5, v1 offset0:100 offset1:116
	ds_write2_b32 v8, v6, v2 offset0:232 offset1:248
	ds_write2_b32 v9, v7, v3 offset0:108 offset1:124
	v_or_b32_e32 v0, s26, v137
	v_lshlrev_b32_e32 v72, 2, v0
	v_lshl_add_u64 v[0:1], s[14:15], 0, v[72:73]
	v_lshl_add_u64 v[2:3], s[12:13], 0, v[72:73]
	v_add_u32_e32 v4, s27, v149
	s_mov_b32 s16, 0
	s_waitcnt lgkmcnt(0)
	s_barrier

.LBB0_2102:
	s_and_b32 s8, s13, 0x4000
	s_xor_b32 s9, s8, 0x4000
	s_lshl_b32 s9, s9, 1
	s_add_i32 s9, s9, 32
	s_add_u32 s90, s52, s6
	s_addc_u32 s91, s53, s7
	s_add_i32 m0, s9, s82
	s_lshl_b32 s8, s8, 1
	global_load_lds_dwordx4 v192, s[90:91]
	s_add_i32 m0, s9, s83
	s_add_i32 s8, s8, 32
	global_load_lds_dwordx4 v193, s[90:91]
	s_add_i32 m0, s9, s84
	v_lshlrev_b32_e32 v85, 1, v80
	global_load_lds_dwordx4 v194, s[90:91]
	s_add_i32 m0, s9, s85
	v_add3_u32 v112, s8, v81, v85
	global_load_lds_dwordx4 v195, s[90:91]
	s_add_i32 m0, s9, s86
	v_lshlrev_b32_e32 v86, 1, v121
	global_load_lds_dwordx4 v196, s[90:91]
	s_add_i32 m0, s9, s87
	v_add3_u32 v113, s8, v82, v85
	global_load_lds_dwordx4 v197, s[90:91]
	s_add_i32 m0, s9, s88
	v_add_u32_e32 v87, v112, v86
	global_load_lds_dwordx4 v198, s[90:91]
	s_add_i32 m0, s9, s89
	v_add_u32_e32 v123, v113, v86
	global_load_lds_dwordx4 v199, s[90:91]
	ds_read_b128 v[88:91], v87
	ds_read_b128 v[96:99], v123 offset:16384
	ds_read_b128 v[100:103], v123 offset:18432
	ds_read_b128 v[124:127], v123 offset:20480
	ds_read_b128 v[128:131], v123 offset:22528
	ds_read_b128 v[92:95], v87 offset:2048
	ds_read_b128 v[104:107], v87 offset:4096
	ds_read_b128 v[108:111], v87 offset:6144
	v_lshlrev_b32_e32 v87, 1, v122
	v_add_u32_e32 v236, v112, v87
	v_add_u32_e32 v112, v113, v87
	ds_read_b128 v[204:207], v236
	ds_read_b128 v[208:211], v112 offset:16384
	ds_read_b128 v[212:215], v112 offset:18432
	ds_read_b128 v[216:219], v112 offset:20480
	ds_read_b128 v[220:223], v112 offset:22528
	ds_read_b128 v[224:227], v236 offset:2048
	ds_read_b128 v[228:231], v236 offset:4096
	ds_read_b128 v[232:235], v236 offset:6144
	s_setprio 1
	s_waitcnt lgkmcnt(11)
	v_mfma_f32_16x16x32_bf16 v[60:63], v[88:91], v[96:99], v[60:63]
	v_mfma_f32_16x16x32_bf16 v[56:59], v[88:91], v[100:103], v[56:59]
	v_mfma_f32_16x16x32_bf16 v[52:55], v[88:91], v[124:127], v[52:55]
	v_mfma_f32_16x16x32_bf16 v[48:51], v[88:91], v[128:131], v[48:51]
	s_waitcnt lgkmcnt(10)
	v_mfma_f32_16x16x32_bf16 v[44:47], v[92:95], v[96:99], v[44:47]
	v_mfma_f32_16x16x32_bf16 v[40:43], v[92:95], v[100:103], v[40:43]
	v_mfma_f32_16x16x32_bf16 v[36:39], v[92:95], v[124:127], v[36:39]
	v_mfma_f32_16x16x32_bf16 v[32:35], v[92:95], v[128:131], v[32:35]
	s_waitcnt lgkmcnt(9)
	v_mfma_f32_16x16x32_bf16 v[28:31], v[104:107], v[96:99], v[28:31]
	v_mfma_f32_16x16x32_bf16 v[24:27], v[104:107], v[100:103], v[24:27]
	v_mfma_f32_16x16x32_bf16 v[20:23], v[104:107], v[124:127], v[20:23]
	v_mfma_f32_16x16x32_bf16 v[16:19], v[104:107], v[128:131], v[16:19]
	s_waitcnt lgkmcnt(8)
	v_mfma_f32_16x16x32_bf16 v[12:15], v[108:111], v[96:99], v[12:15]
	v_mfma_f32_16x16x32_bf16 v[8:11], v[108:111], v[100:103], v[8:11]
	v_mfma_f32_16x16x32_bf16 v[4:7], v[108:111], v[124:127], v[4:7]
	v_mfma_f32_16x16x32_bf16 v[0:3], v[108:111], v[128:131], v[0:3]
	s_waitcnt lgkmcnt(3)
	v_mfma_f32_16x16x32_bf16 v[60:63], v[204:207], v[208:211], v[60:63]
	v_mfma_f32_16x16x32_bf16 v[56:59], v[204:207], v[212:215], v[56:59]
	v_mfma_f32_16x16x32_bf16 v[52:55], v[204:207], v[216:219], v[52:55]
	v_mfma_f32_16x16x32_bf16 v[48:51], v[204:207], v[220:223], v[48:51]
	s_waitcnt lgkmcnt(2)
	v_mfma_f32_16x16x32_bf16 v[44:47], v[224:227], v[208:211], v[44:47]
	v_mfma_f32_16x16x32_bf16 v[40:43], v[224:227], v[212:215], v[40:43]
	v_mfma_f32_16x16x32_bf16 v[36:39], v[224:227], v[216:219], v[36:39]
	v_mfma_f32_16x16x32_bf16 v[32:35], v[224:227], v[220:223], v[32:35]
	s_waitcnt lgkmcnt(1)
	v_mfma_f32_16x16x32_bf16 v[28:31], v[228:231], v[208:211], v[28:31]
	v_mfma_f32_16x16x32_bf16 v[24:27], v[228:231], v[212:215], v[24:27]
	v_mfma_f32_16x16x32_bf16 v[20:23], v[228:231], v[216:219], v[20:23]
	v_mfma_f32_16x16x32_bf16 v[16:19], v[228:231], v[220:223], v[16:19]
	s_waitcnt lgkmcnt(0)
	v_mfma_f32_16x16x32_bf16 v[12:15], v[232:235], v[208:211], v[12:15]
	v_mfma_f32_16x16x32_bf16 v[8:11], v[232:235], v[212:215], v[8:11]
	v_mfma_f32_16x16x32_bf16 v[4:7], v[232:235], v[216:219], v[4:7]
	v_mfma_f32_16x16x32_bf16 v[0:3], v[232:235], v[220:223], v[0:3]
	s_setprio 0
	s_add_u32 s6, s6, 0x80
	s_addc_u32 s7, s7, 0
	s_addk_i32 s13, 0x4000
	s_cmpk_eq_i32 s6, 0x780
	s_waitcnt vmcnt(0)
	s_barrier
	s_cbranch_scc0 .LBB0_2102
	v_add3_u32 v84, 32, v81, v85
	v_add3_u32 v85, 32, v82, v85
	v_add_u32_e32 v88, v84, v86
	v_add_u32_e32 v86, v85, v86
	ds_read_b128 v[64:67], v88 offset:32768
	ds_read_b128 v[68:71], v88 offset:34816
	ds_read_b128 v[72:75], v86 offset:49152
	ds_read_b128 v[76:79], v86 offset:51200
	ds_read_b128 v[80:83], v88 offset:36864
	ds_read_b128 v[88:91], v88 offset:38912
	ds_read_b128 v[92:95], v86 offset:53248
	ds_read_b128 v[96:99], v86 offset:55296
	s_setprio 1
	s_waitcnt lgkmcnt(0)
	v_mfma_f32_16x16x32_bf16 v[0:3], v[88:91], v[96:99], v[0:3]
	v_mfma_f32_16x16x32_bf16 v[60:63], v[64:67], v[72:75], v[60:63]
	v_mfma_f32_16x16x32_bf16 v[56:59], v[64:67], v[76:79], v[56:59]
	v_mfma_f32_16x16x32_bf16 v[52:55], v[64:67], v[92:95], v[52:55]
	v_mfma_f32_16x16x32_bf16 v[48:51], v[64:67], v[96:99], v[48:51]
	v_mfma_f32_16x16x32_bf16 v[44:47], v[68:71], v[72:75], v[44:47]
	v_mfma_f32_16x16x32_bf16 v[40:43], v[68:71], v[76:79], v[40:43]
	v_mfma_f32_16x16x32_bf16 v[36:39], v[68:71], v[92:95], v[36:39]
	v_mfma_f32_16x16x32_bf16 v[32:35], v[68:71], v[96:99], v[32:35]
	v_mfma_f32_16x16x32_bf16 v[28:31], v[80:83], v[72:75], v[28:31]
	v_mfma_f32_16x16x32_bf16 v[24:27], v[80:83], v[76:79], v[24:27]
	v_mfma_f32_16x16x32_bf16 v[20:23], v[80:83], v[92:95], v[20:23]
	v_mfma_f32_16x16x32_bf16 v[16:19], v[80:83], v[96:99], v[16:19]
	v_mfma_f32_16x16x32_bf16 v[12:15], v[88:91], v[72:75], v[12:15]
	v_mfma_f32_16x16x32_bf16 v[8:11], v[88:91], v[76:79], v[8:11]
	v_mfma_f32_16x16x32_bf16 v[4:7], v[88:91], v[92:95], v[4:7]
	s_setprio 0
	v_add_u32_e32 v84, v84, v87
	v_add_u32_e32 v92, v85, v87
	ds_read_b128 v[64:67], v84 offset:32768
	ds_read_b128 v[68:71], v84 offset:34816
	ds_read_b128 v[72:75], v92 offset:49152
	ds_read_b128 v[76:79], v92 offset:51200
	ds_read_b128 v[80:83], v84 offset:36864
	ds_read_b128 v[84:87], v84 offset:38912
	ds_read_b128 v[88:91], v92 offset:53248
	ds_read_b128 v[92:95], v92 offset:55296
	s_setprio 1
	s_waitcnt lgkmcnt(0)
	v_mfma_f32_16x16x32_bf16 v[0:3], v[84:87], v[92:95], v[0:3]
	v_mfma_f32_16x16x32_bf16 v[60:63], v[64:67], v[72:75], v[60:63]
	v_mfma_f32_16x16x32_bf16 v[56:59], v[64:67], v[76:79], v[56:59]
	v_mfma_f32_16x16x32_bf16 v[52:55], v[64:67], v[88:91], v[52:55]
	v_mfma_f32_16x16x32_bf16 v[48:51], v[64:67], v[92:95], v[48:51]
	v_mfma_f32_16x16x32_bf16 v[44:47], v[68:71], v[72:75], v[44:47]
	v_mfma_f32_16x16x32_bf16 v[40:43], v[68:71], v[76:79], v[40:43]
	v_mfma_f32_16x16x32_bf16 v[36:39], v[68:71], v[88:91], v[36:39]
	v_mfma_f32_16x16x32_bf16 v[32:35], v[68:71], v[92:95], v[32:35]
	v_mfma_f32_16x16x32_bf16 v[28:31], v[80:83], v[72:75], v[28:31]
	v_mfma_f32_16x16x32_bf16 v[24:27], v[80:83], v[76:79], v[24:27]
	v_mfma_f32_16x16x32_bf16 v[20:23], v[80:83], v[88:91], v[20:23]
	v_mfma_f32_16x16x32_bf16 v[16:19], v[80:83], v[92:95], v[16:19]
	v_mfma_f32_16x16x32_bf16 v[12:15], v[84:87], v[72:75], v[12:15]
	v_mfma_f32_16x16x32_bf16 v[8:11], v[84:87], v[76:79], v[8:11]
	v_mfma_f32_16x16x32_bf16 v[4:7], v[84:87], v[88:91], v[4:7]
	s_setprio 0
	v_lshl_or_b32 v64, v114, 2, v116
	v_mul_u32_u24_e32 v64, 0x210, v64
	v_add3_u32 v64, v115, v117, v64
	s_barrier
	ds_write2_b32 v64, v60, v56 offset1:16
	ds_write2_b32 v64, v61, v57 offset0:132 offset1:148
	v_add_u32_e32 v56, 0x400, v64
	ds_write2_b32 v56, v62, v58 offset0:8 offset1:24
	ds_write2_b32 v56, v63, v59 offset0:140 offset1:156
	ds_write2_b32 v64, v52, v48 offset0:32 offset1:48
	ds_write2_b32 v64, v53, v49 offset0:164 offset1:180
	ds_write2_b32 v56, v54, v50 offset0:40 offset1:56
	ds_write2_b32 v56, v55, v51 offset0:172 offset1:188
	v_add_u32_e32 v48, 0x2000, v64
	ds_write2_b32 v48, v44, v40 offset0:64 offset1:80
	ds_write2_b32 v48, v45, v41 offset0:196 offset1:212
	v_add_u32_e32 v40, 0x2400, v64
	ds_write2_b32 v40, v46, v42 offset0:72 offset1:88
	ds_write2_b32 v40, v47, v43 offset0:204 offset1:220
	ds_write2_b32 v48, v36, v32 offset0:96 offset1:112
	ds_write2_b32 v48, v37, v33 offset0:228 offset1:244
	ds_write2_b32 v40, v38, v34 offset0:104 offset1:120
	ds_write2_b32 v40, v39, v35 offset0:236 offset1:252
	v_add_u32_e32 v32, 0x4000, v64
	ds_write2_b32 v32, v28, v24 offset0:128 offset1:144
	v_add_u32_e32 v24, 0x4400, v64
	ds_write2_b32 v24, v29, v25 offset0:4 offset1:20
	ds_write2_b32 v24, v30, v26 offset0:136 offset1:152
	v_add_u32_e32 v25, 0x4800, v64
	ds_write2_b32 v25, v31, v27 offset0:12 offset1:28
	ds_write2_b32 v32, v20, v16 offset0:160 offset1:176
	ds_write2_b32 v24, v21, v17 offset0:36 offset1:52
	ds_write2_b32 v24, v22, v18 offset0:168 offset1:184
	ds_write2_b32 v25, v23, v19 offset0:44 offset1:60
	v_add_u32_e32 v16, 0x6000, v64
	ds_write2_b32 v16, v12, v8 offset0:192 offset1:208
	v_add_u32_e32 v8, 0x6400, v64
	ds_write2_b32 v8, v13, v9 offset0:68 offset1:84
	ds_write2_b32 v8, v14, v10 offset0:200 offset1:216
	v_add_u32_e32 v9, 0x6800, v64
	ds_write2_b32 v9, v15, v11 offset0:76 offset1:92
	ds_write2_b32 v16, v4, v0 offset0:224 offset1:240
	ds_write2_b32 v8, v5, v1 offset0:100 offset1:116
	ds_write2_b32 v8, v6, v2 offset0:232 offset1:248
	ds_write2_b32 v9, v7, v3 offset0:108 offset1:124
	v_lshlrev_b32_e32 v0, 4, v180
	v_and_b32_e32 v0, 0x70, v0
	s_lshl_b32 s7, s16, 23
	v_or_b32_e32 v0, s11, v0
	s_add_u32 s8, s14, s7
	s_addc_u32 s9, s15, 0
	v_lshlrev_b32_e32 v0, 2, v0
	v_mov_b32_e32 v1, 0
	v_lshrrev_b32_e32 v2, 3, v180
	v_and_b32_e32 v4, 7, v180
	v_lshl_add_u64 v[0:1], s[8:9], 0, v[0:1]
	s_mov_b64 s[8:9], 0x11600000
	v_mul_u32_u24_e32 v3, 0x210, v2
	v_lshlrev_b32_e32 v4, 6, v4
	s_mov_b32 s6, 0
	v_lshl_add_u64 v[0:1], v[0:1], 0, s[8:9]
	v_add3_u32 v3, v3, v4, 32
	s_mov_b32 s7, 0x38e38e39
	s_mov_b32 s8, 0x1ffffee
	s_movk_i32 s9, 0xf800
	s_waitcnt lgkmcnt(0)
	s_barrier

.LBB0_2270:
	s_and_b32 s31, s30, 0x4000
	s_xor_b32 s34, s31, 0x4000
	s_lshl_b32 s34, s34, 1
	s_add_i32 s34, s34, 32
	s_add_u32 s90, s52, s8
	s_addc_u32 s91, s53, s9
	s_add_i32 m0, s34, s82
	s_lshl_b32 s31, s31, 1
	global_load_lds_dwordx4 v184, s[90:91]
	s_add_i32 m0, s34, s83
	s_add_i32 s31, s31, 32
	global_load_lds_dwordx4 v185, s[90:91]
	s_add_i32 m0, s34, s84
	v_lshl_add_u32 v64, v114, 1, s31
	global_load_lds_dwordx4 v186, s[90:91]
	s_add_i32 m0, s34, s85
	v_lshl_add_u32 v139, v115, 1, s31
	global_load_lds_dwordx4 v187, s[90:91]
	s_add_i32 m0, s34, s86
	v_add_u32_e32 v160, v64, v136
	global_load_lds_dwordx4 v188, s[90:91]
	s_add_i32 m0, s34, s87
	v_add_u32_e32 v168, v139, v136
	global_load_lds_dwordx4 v189, s[90:91]
	s_add_i32 m0, s34, s88
	s_addk_i32 s30, 0x4000
	global_load_lds_dwordx4 v190, s[90:91]
	s_add_i32 m0, s34, s89
	s_add_u32 s8, s8, 0x80
	s_addc_u32 s9, s9, 0
	global_load_lds_dwordx4 v191, s[90:91]
	ds_read_b128 v[140:143], v160
	ds_read_b128 v[148:151], v168 offset:16384
	ds_read_b128 v[152:155], v168 offset:18432
	ds_read_b128 v[164:167], v168 offset:20480
	ds_read_b128 v[168:171], v168 offset:22528
	ds_read_b128 v[144:147], v160 offset:2048
	ds_read_b128 v[156:159], v160 offset:4096
	ds_read_b128 v[160:163], v160 offset:6144
	v_add_u32_e32 v64, v64, v137
	v_add_u32_e32 v139, v139, v137
	ds_read_b128 v[204:207], v64
	ds_read_b128 v[208:211], v139 offset:16384
	ds_read_b128 v[212:215], v139 offset:18432
	ds_read_b128 v[216:219], v139 offset:20480
	ds_read_b128 v[220:223], v139 offset:22528
	ds_read_b128 v[224:227], v64 offset:2048
	ds_read_b128 v[228:231], v64 offset:4096
	ds_read_b128 v[232:235], v64 offset:6144
	s_setprio 1
	s_waitcnt lgkmcnt(11)
	v_mfma_f32_16x16x32_bf16 v[60:63], v[140:143], v[148:151], v[60:63]
	v_mfma_f32_16x16x32_bf16 v[56:59], v[140:143], v[152:155], v[56:59]
	v_mfma_f32_16x16x32_bf16 v[52:55], v[140:143], v[164:167], v[52:55]
	v_mfma_f32_16x16x32_bf16 v[48:51], v[140:143], v[168:171], v[48:51]
	s_waitcnt lgkmcnt(10)
	v_mfma_f32_16x16x32_bf16 v[44:47], v[144:147], v[148:151], v[44:47]
	v_mfma_f32_16x16x32_bf16 v[40:43], v[144:147], v[152:155], v[40:43]
	v_mfma_f32_16x16x32_bf16 v[36:39], v[144:147], v[164:167], v[36:39]
	v_mfma_f32_16x16x32_bf16 v[32:35], v[144:147], v[168:171], v[32:35]
	s_waitcnt lgkmcnt(9)
	v_mfma_f32_16x16x32_bf16 v[28:31], v[156:159], v[148:151], v[28:31]
	v_mfma_f32_16x16x32_bf16 v[24:27], v[156:159], v[152:155], v[24:27]
	v_mfma_f32_16x16x32_bf16 v[20:23], v[156:159], v[164:167], v[20:23]
	v_mfma_f32_16x16x32_bf16 v[16:19], v[156:159], v[168:171], v[16:19]
	s_waitcnt lgkmcnt(8)
	v_mfma_f32_16x16x32_bf16 v[12:15], v[160:163], v[148:151], v[12:15]
	v_mfma_f32_16x16x32_bf16 v[8:11], v[160:163], v[152:155], v[8:11]
	v_mfma_f32_16x16x32_bf16 v[4:7], v[160:163], v[164:167], v[4:7]
	v_mfma_f32_16x16x32_bf16 v[0:3], v[160:163], v[168:171], v[0:3]
	s_waitcnt lgkmcnt(3)
	v_mfma_f32_16x16x32_bf16 v[60:63], v[204:207], v[208:211], v[60:63]
	v_mfma_f32_16x16x32_bf16 v[56:59], v[204:207], v[212:215], v[56:59]
	v_mfma_f32_16x16x32_bf16 v[52:55], v[204:207], v[216:219], v[52:55]
	v_mfma_f32_16x16x32_bf16 v[48:51], v[204:207], v[220:223], v[48:51]
	s_waitcnt lgkmcnt(2)
	v_mfma_f32_16x16x32_bf16 v[44:47], v[224:227], v[208:211], v[44:47]
	v_mfma_f32_16x16x32_bf16 v[40:43], v[224:227], v[212:215], v[40:43]
	v_mfma_f32_16x16x32_bf16 v[36:39], v[224:227], v[216:219], v[36:39]
	v_mfma_f32_16x16x32_bf16 v[32:35], v[224:227], v[220:223], v[32:35]
	s_waitcnt lgkmcnt(1)
	v_mfma_f32_16x16x32_bf16 v[28:31], v[228:231], v[208:211], v[28:31]
	v_mfma_f32_16x16x32_bf16 v[24:27], v[228:231], v[212:215], v[24:27]
	v_mfma_f32_16x16x32_bf16 v[20:23], v[228:231], v[216:219], v[20:23]
	v_mfma_f32_16x16x32_bf16 v[16:19], v[228:231], v[220:223], v[16:19]
	s_waitcnt lgkmcnt(0)
	v_mfma_f32_16x16x32_bf16 v[12:15], v[232:235], v[208:211], v[12:15]
	v_mfma_f32_16x16x32_bf16 v[8:11], v[232:235], v[212:215], v[8:11]
	v_mfma_f32_16x16x32_bf16 v[4:7], v[232:235], v[216:219], v[4:7]
	v_mfma_f32_16x16x32_bf16 v[0:3], v[232:235], v[220:223], v[0:3]
	s_setprio 0
	s_cmpk_eq_i32 s8, 0x780
	s_waitcnt vmcnt(0)
	s_barrier
	s_cbranch_scc0 .LBB0_2270
	ds_read_b128 v[90:93], v116 offset:55296
	ds_read_b128 v[94:97], v116 offset:53248
	ds_read_b128 v[98:101], v117 offset:38912
	ds_read_b128 v[102:105], v117 offset:36864
	ds_read_b128 v[140:143], v116 offset:51200
	ds_read_b128 v[144:147], v116 offset:49152
	ds_read_b128 v[148:151], v117 offset:34816
	ds_read_b128 v[152:155], v117 offset:32768
	s_setprio 1
	s_waitcnt lgkmcnt(4)
	v_mfma_f32_16x16x32_bf16 v[20:23], v[102:105], v[94:97], v[20:23]
	v_mfma_f32_16x16x32_bf16 v[16:19], v[102:105], v[90:93], v[16:19]
	s_waitcnt lgkmcnt(0)
	v_mfma_f32_16x16x32_bf16 v[60:63], v[152:155], v[144:147], v[60:63]
	v_mfma_f32_16x16x32_bf16 v[56:59], v[152:155], v[140:143], v[56:59]
	v_mfma_f32_16x16x32_bf16 v[52:55], v[152:155], v[94:97], v[52:55]
	v_mfma_f32_16x16x32_bf16 v[48:51], v[152:155], v[90:93], v[48:51]
	v_mfma_f32_16x16x32_bf16 v[44:47], v[148:151], v[144:147], v[44:47]
	v_mfma_f32_16x16x32_bf16 v[40:43], v[148:151], v[140:143], v[40:43]
	v_mfma_f32_16x16x32_bf16 v[36:39], v[148:151], v[94:97], v[36:39]
	v_mfma_f32_16x16x32_bf16 v[32:35], v[148:151], v[90:93], v[32:35]
	v_mfma_f32_16x16x32_bf16 v[28:31], v[102:105], v[144:147], v[28:31]
	v_mfma_f32_16x16x32_bf16 v[24:27], v[102:105], v[140:143], v[24:27]
	v_mfma_f32_16x16x32_bf16 v[12:15], v[98:101], v[144:147], v[12:15]
	v_mfma_f32_16x16x32_bf16 v[8:11], v[98:101], v[140:143], v[8:11]
	v_mfma_f32_16x16x32_bf16 v[4:7], v[98:101], v[94:97], v[4:7]
	v_mfma_f32_16x16x32_bf16 v[0:3], v[98:101], v[90:93], v[0:3]
	s_setprio 0
	ds_read_b128 v[90:93], v118 offset:32768
	ds_read_b128 v[94:97], v118 offset:34816
	ds_read_b128 v[98:101], v119 offset:49152
	ds_read_b128 v[102:105], v119 offset:51200
	ds_read_b128 v[140:143], v118 offset:36864
	ds_read_b128 v[144:147], v118 offset:38912
	ds_read_b128 v[148:151], v119 offset:53248
	ds_read_b128 v[152:155], v119 offset:55296
	s_setprio 1
	s_waitcnt lgkmcnt(1)
	v_mfma_f32_16x16x32_bf16 v[20:23], v[140:143], v[148:151], v[20:23]
	s_waitcnt lgkmcnt(0)
	v_mfma_f32_16x16x32_bf16 v[16:19], v[140:143], v[152:155], v[16:19]
	v_mfma_f32_16x16x32_bf16 v[60:63], v[90:93], v[98:101], v[60:63]
	v_mfma_f32_16x16x32_bf16 v[56:59], v[90:93], v[102:105], v[56:59]
	v_mfma_f32_16x16x32_bf16 v[52:55], v[90:93], v[148:151], v[52:55]
	v_mfma_f32_16x16x32_bf16 v[48:51], v[90:93], v[152:155], v[48:51]
	v_mfma_f32_16x16x32_bf16 v[44:47], v[94:97], v[98:101], v[44:47]
	v_mfma_f32_16x16x32_bf16 v[40:43], v[94:97], v[102:105], v[40:43]
	v_mfma_f32_16x16x32_bf16 v[36:39], v[94:97], v[148:151], v[36:39]
	v_mfma_f32_16x16x32_bf16 v[32:35], v[94:97], v[152:155], v[32:35]
	v_mfma_f32_16x16x32_bf16 v[28:31], v[140:143], v[98:101], v[28:31]
	v_mfma_f32_16x16x32_bf16 v[24:27], v[140:143], v[102:105], v[24:27]
	v_mfma_f32_16x16x32_bf16 v[12:15], v[144:147], v[98:101], v[12:15]
	v_mfma_f32_16x16x32_bf16 v[8:11], v[144:147], v[102:105], v[8:11]
	v_mfma_f32_16x16x32_bf16 v[4:7], v[144:147], v[148:151], v[4:7]
	v_mfma_f32_16x16x32_bf16 v[0:3], v[144:147], v[152:155], v[0:3]
	s_setprio 0
	s_barrier
	ds_write2_b32 v120, v60, v56 offset1:16
	ds_write2_b32 v120, v61, v57 offset0:132 offset1:148
	v_add_u32_e32 v56, 0x400, v120
	ds_write2_b32 v56, v62, v58 offset0:8 offset1:24
	ds_write2_b32 v56, v63, v59 offset0:140 offset1:156
	ds_write2_b32 v120, v52, v48 offset0:32 offset1:48
	ds_write2_b32 v120, v53, v49 offset0:164 offset1:180
	ds_write2_b32 v56, v54, v50 offset0:40 offset1:56
	ds_write2_b32 v56, v55, v51 offset0:172 offset1:188
	v_add_u32_e32 v48, 0x2000, v120
	ds_write2_b32 v48, v44, v40 offset0:64 offset1:80
	ds_write2_b32 v48, v45, v41 offset0:196 offset1:212
	v_add_u32_e32 v40, 0x2400, v120
	ds_write2_b32 v40, v46, v42 offset0:72 offset1:88
	ds_write2_b32 v40, v47, v43 offset0:204 offset1:220
	ds_write2_b32 v48, v36, v32 offset0:96 offset1:112
	ds_write2_b32 v48, v37, v33 offset0:228 offset1:244
	ds_write2_b32 v40, v38, v34 offset0:104 offset1:120
	ds_write2_b32 v40, v39, v35 offset0:236 offset1:252
	v_add_u32_e32 v32, 0x4000, v120
	ds_write2_b32 v32, v28, v24 offset0:128 offset1:144
	v_add_u32_e32 v24, 0x4400, v120
	ds_write2_b32 v24, v29, v25 offset0:4 offset1:20
	ds_write2_b32 v24, v30, v26 offset0:136 offset1:152
	v_add_u32_e32 v25, 0x4800, v120
	s_cmp_gt_i32 s28, 5
	ds_write2_b32 v25, v31, v27 offset0:12 offset1:28
	ds_write2_b32 v32, v20, v16 offset0:160 offset1:176
	ds_write2_b32 v24, v21, v17 offset0:36 offset1:52
	ds_write2_b32 v24, v22, v18 offset0:168 offset1:184
	ds_write2_b32 v25, v23, v19 offset0:44 offset1:60
	v_add_u32_e32 v16, 0x6000, v120
	v_or_b32_e32 v64, s29, v121
	s_cselect_b64 s[30:31], -1, 0
	s_ashr_i32 s29, s28, 31
	ds_write2_b32 v16, v12, v8 offset0:192 offset1:208
	v_add_u32_e32 v8, 0x6400, v120
	s_cmp_gt_i32 s28, 3
	ds_write2_b32 v8, v13, v9 offset0:68 offset1:84
	ds_write2_b32 v8, v14, v10 offset0:200 offset1:216
	v_add_u32_e32 v9, 0x6800, v120
	s_cselect_b64 s[34:35], -1, 0
	s_lshl_b64 s[28:29], s[28:29], 2
	ds_write2_b32 v9, v15, v11 offset0:76 offset1:92
	ds_write2_b32 v16, v4, v0 offset0:224 offset1:240
	ds_write2_b32 v8, v5, v1 offset0:100 offset1:116
	ds_write2_b32 v8, v6, v2 offset0:232 offset1:248
	ds_write2_b32 v9, v7, v3 offset0:108 offset1:124
	v_ashrrev_i32_e32 v1, 31, v64
	v_mov_b32_e32 v0, v64
	v_lshlrev_b64 v[2:3], 1, v[64:65]
	s_add_u32 s28, s40, s28
	v_cmp_gt_u32_e64 s[8:9], s44, v64
	v_lshl_add_u64 v[16:17], s[16:17], 0, v[2:3]
	s_addc_u32 s29, s41, s29
	v_lshl_add_u64 v[18:19], s[14:15], 0, v[2:3]
	v_lshl_add_u64 v[20:21], v[0:1], 1, s[12:13]
	v_add_u32_e32 v22, s36, v129
	s_mov_b32 s50, 0
	s_waitcnt lgkmcnt(0)
	s_barrier
	s_branch .LBB0_2273

.LBB0_2292:
	s_and_b32 s24, s23, 0x4000
	s_xor_b32 s25, s24, 0x4000
	s_lshl_b32 s25, s25, 1
	s_add_i32 s25, s25, 32
	s_add_u32 s90, s52, s8
	s_addc_u32 s91, s53, s9
	s_add_i32 m0, s25, s82
	s_lshl_b32 s24, s24, 1
	global_load_lds_dwordx4 v184, s[90:91]
	s_add_i32 m0, s25, s83
	s_add_i32 s24, s24, 32
	global_load_lds_dwordx4 v185, s[90:91]
	s_add_i32 m0, s25, s84
	v_lshl_add_u32 v64, v115, 1, s24
	global_load_lds_dwordx4 v186, s[90:91]
	s_add_i32 m0, s25, s85
	v_lshl_add_u32 v141, v116, 1, s24
	global_load_lds_dwordx4 v187, s[90:91]
	s_add_i32 m0, s25, s86
	v_add_u32_e32 v162, v64, v138
	global_load_lds_dwordx4 v188, s[90:91]
	s_add_i32 m0, s25, s87
	v_add_u32_e32 v170, v141, v138
	global_load_lds_dwordx4 v189, s[90:91]
	s_add_i32 m0, s25, s88
	s_addk_i32 s23, 0x4000
	global_load_lds_dwordx4 v190, s[90:91]
	s_add_i32 m0, s25, s89
	s_add_u32 s8, s8, 0x80
	s_addc_u32 s9, s9, 0
	global_load_lds_dwordx4 v191, s[90:91]
	ds_read_b128 v[142:145], v162
	ds_read_b128 v[150:153], v170 offset:16384
	ds_read_b128 v[154:157], v170 offset:18432
	ds_read_b128 v[166:169], v170 offset:20480
	ds_read_b128 v[170:173], v170 offset:22528
	ds_read_b128 v[146:149], v162 offset:2048
	ds_read_b128 v[158:161], v162 offset:4096
	ds_read_b128 v[162:165], v162 offset:6144
	v_add_u32_e32 v64, v64, v139
	v_add_u32_e32 v141, v141, v139
	ds_read_b128 v[204:207], v64
	ds_read_b128 v[208:211], v141 offset:16384
	ds_read_b128 v[212:215], v141 offset:18432
	ds_read_b128 v[216:219], v141 offset:20480
	ds_read_b128 v[220:223], v141 offset:22528
	ds_read_b128 v[224:227], v64 offset:2048
	ds_read_b128 v[228:231], v64 offset:4096
	ds_read_b128 v[232:235], v64 offset:6144
	s_setprio 1
	s_waitcnt lgkmcnt(11)
	v_mfma_f32_16x16x32_bf16 v[60:63], v[142:145], v[150:153], v[60:63]
	v_mfma_f32_16x16x32_bf16 v[56:59], v[142:145], v[154:157], v[56:59]
	v_mfma_f32_16x16x32_bf16 v[52:55], v[142:145], v[166:169], v[52:55]
	v_mfma_f32_16x16x32_bf16 v[48:51], v[142:145], v[170:173], v[48:51]
	s_waitcnt lgkmcnt(10)
	v_mfma_f32_16x16x32_bf16 v[44:47], v[146:149], v[150:153], v[44:47]
	v_mfma_f32_16x16x32_bf16 v[40:43], v[146:149], v[154:157], v[40:43]
	v_mfma_f32_16x16x32_bf16 v[36:39], v[146:149], v[166:169], v[36:39]
	v_mfma_f32_16x16x32_bf16 v[32:35], v[146:149], v[170:173], v[32:35]
	s_waitcnt lgkmcnt(9)
	v_mfma_f32_16x16x32_bf16 v[28:31], v[158:161], v[150:153], v[28:31]
	v_mfma_f32_16x16x32_bf16 v[24:27], v[158:161], v[154:157], v[24:27]
	v_mfma_f32_16x16x32_bf16 v[20:23], v[158:161], v[166:169], v[20:23]
	v_mfma_f32_16x16x32_bf16 v[16:19], v[158:161], v[170:173], v[16:19]
	s_waitcnt lgkmcnt(8)
	v_mfma_f32_16x16x32_bf16 v[12:15], v[162:165], v[150:153], v[12:15]
	v_mfma_f32_16x16x32_bf16 v[8:11], v[162:165], v[154:157], v[8:11]
	v_mfma_f32_16x16x32_bf16 v[4:7], v[162:165], v[166:169], v[4:7]
	v_mfma_f32_16x16x32_bf16 v[0:3], v[162:165], v[170:173], v[0:3]
	s_waitcnt lgkmcnt(3)
	v_mfma_f32_16x16x32_bf16 v[60:63], v[204:207], v[208:211], v[60:63]
	v_mfma_f32_16x16x32_bf16 v[56:59], v[204:207], v[212:215], v[56:59]
	v_mfma_f32_16x16x32_bf16 v[52:55], v[204:207], v[216:219], v[52:55]
	v_mfma_f32_16x16x32_bf16 v[48:51], v[204:207], v[220:223], v[48:51]
	s_waitcnt lgkmcnt(2)
	v_mfma_f32_16x16x32_bf16 v[44:47], v[224:227], v[208:211], v[44:47]
	v_mfma_f32_16x16x32_bf16 v[40:43], v[224:227], v[212:215], v[40:43]
	v_mfma_f32_16x16x32_bf16 v[36:39], v[224:227], v[216:219], v[36:39]
	v_mfma_f32_16x16x32_bf16 v[32:35], v[224:227], v[220:223], v[32:35]
	s_waitcnt lgkmcnt(1)
	v_mfma_f32_16x16x32_bf16 v[28:31], v[228:231], v[208:211], v[28:31]
	v_mfma_f32_16x16x32_bf16 v[24:27], v[228:231], v[212:215], v[24:27]
	v_mfma_f32_16x16x32_bf16 v[20:23], v[228:231], v[216:219], v[20:23]
	v_mfma_f32_16x16x32_bf16 v[16:19], v[228:231], v[220:223], v[16:19]
	s_waitcnt lgkmcnt(0)
	v_mfma_f32_16x16x32_bf16 v[12:15], v[232:235], v[208:211], v[12:15]
	v_mfma_f32_16x16x32_bf16 v[8:11], v[232:235], v[212:215], v[8:11]
	v_mfma_f32_16x16x32_bf16 v[4:7], v[232:235], v[216:219], v[4:7]
	v_mfma_f32_16x16x32_bf16 v[0:3], v[232:235], v[220:223], v[0:3]
	s_setprio 0
	s_cmpk_eq_i32 s8, 0x780
	s_waitcnt vmcnt(0)
	s_barrier
	s_cbranch_scc0 .LBB0_2292
	ds_read_b128 v[90:93], v117 offset:55296
	ds_read_b128 v[94:97], v117 offset:53248
	ds_read_b128 v[98:101], v118 offset:38912
	ds_read_b128 v[102:105], v118 offset:36864
	ds_read_b128 v[142:145], v117 offset:51200
	ds_read_b128 v[146:149], v117 offset:49152
	ds_read_b128 v[150:153], v118 offset:34816
	ds_read_b128 v[154:157], v118 offset:32768
	s_setprio 1
	s_waitcnt lgkmcnt(4)
	v_mfma_f32_16x16x32_bf16 v[20:23], v[102:105], v[94:97], v[20:23]
	v_mfma_f32_16x16x32_bf16 v[16:19], v[102:105], v[90:93], v[16:19]
	s_waitcnt lgkmcnt(0)
	v_mfma_f32_16x16x32_bf16 v[60:63], v[154:157], v[146:149], v[60:63]
	v_mfma_f32_16x16x32_bf16 v[56:59], v[154:157], v[142:145], v[56:59]
	v_mfma_f32_16x16x32_bf16 v[52:55], v[154:157], v[94:97], v[52:55]
	v_mfma_f32_16x16x32_bf16 v[48:51], v[154:157], v[90:93], v[48:51]
	v_mfma_f32_16x16x32_bf16 v[44:47], v[150:153], v[146:149], v[44:47]
	v_mfma_f32_16x16x32_bf16 v[40:43], v[150:153], v[142:145], v[40:43]
	v_mfma_f32_16x16x32_bf16 v[36:39], v[150:153], v[94:97], v[36:39]
	v_mfma_f32_16x16x32_bf16 v[32:35], v[150:153], v[90:93], v[32:35]
	v_mfma_f32_16x16x32_bf16 v[28:31], v[102:105], v[146:149], v[28:31]
	v_mfma_f32_16x16x32_bf16 v[24:27], v[102:105], v[142:145], v[24:27]
	v_mfma_f32_16x16x32_bf16 v[12:15], v[98:101], v[146:149], v[12:15]
	v_mfma_f32_16x16x32_bf16 v[8:11], v[98:101], v[142:145], v[8:11]
	v_mfma_f32_16x16x32_bf16 v[4:7], v[98:101], v[94:97], v[4:7]
	v_mfma_f32_16x16x32_bf16 v[0:3], v[98:101], v[90:93], v[0:3]
	s_setprio 0
	ds_read_b128 v[90:93], v119 offset:32768
	ds_read_b128 v[94:97], v119 offset:34816
	ds_read_b128 v[98:101], v120 offset:49152
	ds_read_b128 v[102:105], v120 offset:51200
	ds_read_b128 v[142:145], v119 offset:36864
	ds_read_b128 v[146:149], v119 offset:38912
	ds_read_b128 v[150:153], v120 offset:53248
	ds_read_b128 v[154:157], v120 offset:55296
	s_setprio 1
	s_waitcnt lgkmcnt(1)
	v_mfma_f32_16x16x32_bf16 v[20:23], v[142:145], v[150:153], v[20:23]
	s_waitcnt lgkmcnt(0)
	v_mfma_f32_16x16x32_bf16 v[16:19], v[142:145], v[154:157], v[16:19]
	v_mfma_f32_16x16x32_bf16 v[60:63], v[90:93], v[98:101], v[60:63]
	v_mfma_f32_16x16x32_bf16 v[56:59], v[90:93], v[102:105], v[56:59]
	v_mfma_f32_16x16x32_bf16 v[52:55], v[90:93], v[150:153], v[52:55]
	v_mfma_f32_16x16x32_bf16 v[48:51], v[90:93], v[154:157], v[48:51]
	v_mfma_f32_16x16x32_bf16 v[44:47], v[94:97], v[98:101], v[44:47]
	v_mfma_f32_16x16x32_bf16 v[40:43], v[94:97], v[102:105], v[40:43]
	v_mfma_f32_16x16x32_bf16 v[36:39], v[94:97], v[150:153], v[36:39]
	v_mfma_f32_16x16x32_bf16 v[32:35], v[94:97], v[154:157], v[32:35]
	v_mfma_f32_16x16x32_bf16 v[28:31], v[142:145], v[98:101], v[28:31]
	v_mfma_f32_16x16x32_bf16 v[24:27], v[142:145], v[102:105], v[24:27]
	v_mfma_f32_16x16x32_bf16 v[12:15], v[146:149], v[98:101], v[12:15]
	v_mfma_f32_16x16x32_bf16 v[8:11], v[146:149], v[102:105], v[8:11]
	v_mfma_f32_16x16x32_bf16 v[4:7], v[146:149], v[150:153], v[4:7]
	v_mfma_f32_16x16x32_bf16 v[0:3], v[146:149], v[154:157], v[0:3]
	s_setprio 0
	s_barrier
	ds_write2_b32 v121, v60, v56 offset1:16
	ds_write2_b32 v121, v61, v57 offset0:132 offset1:148
	v_add_u32_e32 v56, 0x400, v121
	ds_write2_b32 v56, v62, v58 offset0:8 offset1:24
	ds_write2_b32 v56, v63, v59 offset0:140 offset1:156
	ds_write2_b32 v121, v52, v48 offset0:32 offset1:48
	ds_write2_b32 v121, v53, v49 offset0:164 offset1:180
	ds_write2_b32 v56, v54, v50 offset0:40 offset1:56
	ds_write2_b32 v56, v55, v51 offset0:172 offset1:188
	v_add_u32_e32 v48, 0x2000, v121
	ds_write2_b32 v48, v44, v40 offset0:64 offset1:80
	ds_write2_b32 v48, v45, v41 offset0:196 offset1:212
	v_add_u32_e32 v40, 0x2400, v121
	ds_write2_b32 v40, v46, v42 offset0:72 offset1:88
	ds_write2_b32 v40, v47, v43 offset0:204 offset1:220
	ds_write2_b32 v48, v36, v32 offset0:96 offset1:112
	ds_write2_b32 v48, v37, v33 offset0:228 offset1:244
	ds_write2_b32 v40, v38, v34 offset0:104 offset1:120
	ds_write2_b32 v40, v39, v35 offset0:236 offset1:252
	v_add_u32_e32 v32, 0x4000, v121
	ds_write2_b32 v32, v28, v24 offset0:128 offset1:144
	v_add_u32_e32 v24, 0x4400, v121
	s_ashr_i32 s26, s22, 7
	ds_write2_b32 v24, v29, v25 offset0:4 offset1:20
	ds_write2_b32 v24, v30, v26 offset0:136 offset1:152
	v_add_u32_e32 v25, 0x4800, v121
	s_cmp_gt_i32 s26, 5
	ds_write2_b32 v25, v31, v27 offset0:12 offset1:28
	ds_write2_b32 v32, v20, v16 offset0:160 offset1:176
	ds_write2_b32 v24, v21, v17 offset0:36 offset1:52
	ds_write2_b32 v24, v22, v18 offset0:168 offset1:184
	ds_write2_b32 v25, v23, v19 offset0:44 offset1:60
	v_add_u32_e32 v16, 0x6000, v121
	v_or_b32_e32 v64, s22, v122
	s_cselect_b64 s[22:23], -1, 0
	s_ashr_i32 s27, s26, 31
	ds_write2_b32 v16, v12, v8 offset0:192 offset1:208
	v_add_u32_e32 v8, 0x6400, v121
	s_cmp_gt_i32 s26, 3
	ds_write2_b32 v8, v13, v9 offset0:68 offset1:84
	ds_write2_b32 v8, v14, v10 offset0:200 offset1:216
	v_add_u32_e32 v9, 0x6800, v121
	s_cselect_b64 s[24:25], -1, 0
	s_lshl_b64 s[26:27], s[26:27], 2
	ds_write2_b32 v9, v15, v11 offset0:76 offset1:92
	ds_write2_b32 v16, v4, v0 offset0:224 offset1:240
	ds_write2_b32 v8, v5, v1 offset0:100 offset1:116
	ds_write2_b32 v8, v6, v2 offset0:232 offset1:248
	ds_write2_b32 v9, v7, v3 offset0:108 offset1:124
	v_ashrrev_i32_e32 v1, 31, v64
	v_mov_b32_e32 v0, v64
	v_lshlrev_b64 v[2:3], 1, v[64:65]
	s_add_u32 s26, s40, s26
	v_cmp_gt_u32_e64 s[8:9], s38, v64
	v_lshl_add_u64 v[16:17], s[16:17], 0, v[2:3]
	s_addc_u32 s27, s41, s27
	v_lshl_add_u64 v[18:19], s[14:15], 0, v[2:3]
	v_lshl_add_u64 v[20:21], v[0:1], 1, s[12:13]
	v_add_u32_e32 v22, s28, v131
	s_mov_b32 s43, 0
	s_waitcnt lgkmcnt(0)
	s_barrier
	s_branch .LBB0_2295

.LBB0_2976:
	s_and_b32 s28, s7, 0x4000
	s_xor_b32 s29, s28, 0x4000
	s_lshl_b32 s29, s29, 1
	s_add_i32 s29, s29, 32
	s_add_u32 s90, s52, s4
	s_addc_u32 s91, s53, s5
	s_add_i32 m0, s29, s82
	s_lshl_b32 s28, s28, 1
	global_load_lds_dwordx4 v184, s[90:91]
	s_add_i32 m0, s29, s83
	s_add_i32 s28, s28, 32
	global_load_lds_dwordx4 v185, s[90:91]
	s_add_i32 m0, s29, s84
	v_lshl_add_u32 v64, v114, 1, s28
	global_load_lds_dwordx4 v186, s[90:91]
	s_add_i32 m0, s29, s85
	v_lshl_add_u32 v170, v115, 1, s28
	global_load_lds_dwordx4 v187, s[90:91]
	s_add_i32 m0, s29, s86
	v_add_u32_e32 v158, v64, v136
	global_load_lds_dwordx4 v188, s[90:91]
	s_add_i32 m0, s29, s87
	v_add_u32_e32 v166, v170, v136
	global_load_lds_dwordx4 v189, s[90:91]
	s_add_i32 m0, s29, s88
	s_addk_i32 s7, 0x4000
	global_load_lds_dwordx4 v190, s[90:91]
	s_add_i32 m0, s29, s89
	s_add_u32 s4, s4, 0x80
	s_addc_u32 s5, s5, 0
	global_load_lds_dwordx4 v191, s[90:91]
	ds_read_b128 v[138:141], v158
	ds_read_b128 v[146:149], v166 offset:16384
	ds_read_b128 v[150:153], v166 offset:18432
	ds_read_b128 v[162:165], v166 offset:20480
	ds_read_b128 v[166:169], v166 offset:22528
	ds_read_b128 v[142:145], v158 offset:2048
	ds_read_b128 v[154:157], v158 offset:4096
	ds_read_b128 v[158:161], v158 offset:6144
	v_add_u32_e32 v64, v64, v137
	v_add_u32_e32 v236, v170, v137
	ds_read_b128 v[204:207], v64
	ds_read_b128 v[208:211], v236 offset:16384
	ds_read_b128 v[212:215], v236 offset:18432
	ds_read_b128 v[216:219], v236 offset:20480
	ds_read_b128 v[220:223], v236 offset:22528
	ds_read_b128 v[224:227], v64 offset:2048
	ds_read_b128 v[228:231], v64 offset:4096
	ds_read_b128 v[232:235], v64 offset:6144
	s_setprio 1
	s_waitcnt lgkmcnt(11)
	v_mfma_f32_16x16x32_bf16 v[60:63], v[138:141], v[146:149], v[60:63]
	v_mfma_f32_16x16x32_bf16 v[56:59], v[138:141], v[150:153], v[56:59]
	v_mfma_f32_16x16x32_bf16 v[52:55], v[138:141], v[162:165], v[52:55]
	v_mfma_f32_16x16x32_bf16 v[48:51], v[138:141], v[166:169], v[48:51]
	s_waitcnt lgkmcnt(10)
	v_mfma_f32_16x16x32_bf16 v[44:47], v[142:145], v[146:149], v[44:47]
	v_mfma_f32_16x16x32_bf16 v[40:43], v[142:145], v[150:153], v[40:43]
	v_mfma_f32_16x16x32_bf16 v[36:39], v[142:145], v[162:165], v[36:39]
	v_mfma_f32_16x16x32_bf16 v[32:35], v[142:145], v[166:169], v[32:35]
	s_waitcnt lgkmcnt(9)
	v_mfma_f32_16x16x32_bf16 v[28:31], v[154:157], v[146:149], v[28:31]
	v_mfma_f32_16x16x32_bf16 v[24:27], v[154:157], v[150:153], v[24:27]
	v_mfma_f32_16x16x32_bf16 v[20:23], v[154:157], v[162:165], v[20:23]
	v_mfma_f32_16x16x32_bf16 v[16:19], v[154:157], v[166:169], v[16:19]
	s_waitcnt lgkmcnt(8)
	v_mfma_f32_16x16x32_bf16 v[12:15], v[158:161], v[146:149], v[12:15]
	v_mfma_f32_16x16x32_bf16 v[8:11], v[158:161], v[150:153], v[8:11]
	v_mfma_f32_16x16x32_bf16 v[4:7], v[158:161], v[162:165], v[4:7]
	v_mfma_f32_16x16x32_bf16 v[0:3], v[158:161], v[166:169], v[0:3]
	s_waitcnt lgkmcnt(3)
	v_mfma_f32_16x16x32_bf16 v[60:63], v[204:207], v[208:211], v[60:63]
	v_mfma_f32_16x16x32_bf16 v[56:59], v[204:207], v[212:215], v[56:59]
	v_mfma_f32_16x16x32_bf16 v[52:55], v[204:207], v[216:219], v[52:55]
	v_mfma_f32_16x16x32_bf16 v[48:51], v[204:207], v[220:223], v[48:51]
	s_waitcnt lgkmcnt(2)
	v_mfma_f32_16x16x32_bf16 v[44:47], v[224:227], v[208:211], v[44:47]
	v_mfma_f32_16x16x32_bf16 v[40:43], v[224:227], v[212:215], v[40:43]
	v_mfma_f32_16x16x32_bf16 v[36:39], v[224:227], v[216:219], v[36:39]
	v_mfma_f32_16x16x32_bf16 v[32:35], v[224:227], v[220:223], v[32:35]
	s_waitcnt lgkmcnt(1)
	v_mfma_f32_16x16x32_bf16 v[28:31], v[228:231], v[208:211], v[28:31]
	v_mfma_f32_16x16x32_bf16 v[24:27], v[228:231], v[212:215], v[24:27]
	v_mfma_f32_16x16x32_bf16 v[20:23], v[228:231], v[216:219], v[20:23]
	v_mfma_f32_16x16x32_bf16 v[16:19], v[228:231], v[220:223], v[16:19]
	s_waitcnt lgkmcnt(0)
	v_mfma_f32_16x16x32_bf16 v[12:15], v[232:235], v[208:211], v[12:15]
	v_mfma_f32_16x16x32_bf16 v[8:11], v[232:235], v[212:215], v[8:11]
	v_mfma_f32_16x16x32_bf16 v[4:7], v[232:235], v[216:219], v[4:7]
	v_mfma_f32_16x16x32_bf16 v[0:3], v[232:235], v[220:223], v[0:3]
	s_setprio 0
	s_cmpk_eq_i32 s4, 0x780
	s_waitcnt vmcnt(0)
	s_barrier
	s_cbranch_scc0 .LBB0_2976
	ds_read_b128 v[90:93], v116 offset:55296
	ds_read_b128 v[94:97], v116 offset:53248
	ds_read_b128 v[98:101], v117 offset:38912
	ds_read_b128 v[102:105], v117 offset:36864
	ds_read_b128 v[138:141], v116 offset:51200
	ds_read_b128 v[142:145], v116 offset:49152
	ds_read_b128 v[146:149], v117 offset:34816
	ds_read_b128 v[150:153], v117 offset:32768
	s_setprio 1
	s_waitcnt lgkmcnt(3)
	v_mfma_f32_16x16x32_bf16 v[24:27], v[102:105], v[138:141], v[24:27]
	v_mfma_f32_16x16x32_bf16 v[20:23], v[102:105], v[94:97], v[20:23]
	v_mfma_f32_16x16x32_bf16 v[16:19], v[102:105], v[90:93], v[16:19]
	s_waitcnt lgkmcnt(0)
	v_mfma_f32_16x16x32_bf16 v[60:63], v[150:153], v[142:145], v[60:63]
	v_mfma_f32_16x16x32_bf16 v[56:59], v[150:153], v[138:141], v[56:59]
	v_mfma_f32_16x16x32_bf16 v[52:55], v[150:153], v[94:97], v[52:55]
	v_mfma_f32_16x16x32_bf16 v[48:51], v[150:153], v[90:93], v[48:51]
	v_mfma_f32_16x16x32_bf16 v[44:47], v[146:149], v[142:145], v[44:47]
	v_mfma_f32_16x16x32_bf16 v[40:43], v[146:149], v[138:141], v[40:43]
	v_mfma_f32_16x16x32_bf16 v[36:39], v[146:149], v[94:97], v[36:39]
	v_mfma_f32_16x16x32_bf16 v[32:35], v[146:149], v[90:93], v[32:35]
	v_mfma_f32_16x16x32_bf16 v[28:31], v[102:105], v[142:145], v[28:31]
	v_mfma_f32_16x16x32_bf16 v[12:15], v[98:101], v[142:145], v[12:15]
	v_mfma_f32_16x16x32_bf16 v[8:11], v[98:101], v[138:141], v[8:11]
	v_mfma_f32_16x16x32_bf16 v[4:7], v[98:101], v[94:97], v[4:7]
	v_mfma_f32_16x16x32_bf16 v[0:3], v[98:101], v[90:93], v[0:3]
	s_setprio 0
	ds_read_b128 v[90:93], v118 offset:32768
	ds_read_b128 v[94:97], v118 offset:34816
	ds_read_b128 v[98:101], v119 offset:49152
	ds_read_b128 v[102:105], v119 offset:51200
	ds_read_b128 v[138:141], v118 offset:36864
	ds_read_b128 v[142:145], v118 offset:38912
	ds_read_b128 v[146:149], v119 offset:53248
	ds_read_b128 v[150:153], v119 offset:55296
	s_setprio 1
	s_waitcnt lgkmcnt(3)
	v_mfma_f32_16x16x32_bf16 v[24:27], v[138:141], v[102:105], v[24:27]
	s_waitcnt lgkmcnt(1)
	v_mfma_f32_16x16x32_bf16 v[20:23], v[138:141], v[146:149], v[20:23]
	s_waitcnt lgkmcnt(0)
	v_mfma_f32_16x16x32_bf16 v[16:19], v[138:141], v[150:153], v[16:19]
	v_mfma_f32_16x16x32_bf16 v[60:63], v[90:93], v[98:101], v[60:63]
	v_mfma_f32_16x16x32_bf16 v[56:59], v[90:93], v[102:105], v[56:59]
	v_mfma_f32_16x16x32_bf16 v[52:55], v[90:93], v[146:149], v[52:55]
	v_mfma_f32_16x16x32_bf16 v[48:51], v[90:93], v[150:153], v[48:51]
	v_mfma_f32_16x16x32_bf16 v[44:47], v[94:97], v[98:101], v[44:47]
	v_mfma_f32_16x16x32_bf16 v[40:43], v[94:97], v[102:105], v[40:43]
	v_mfma_f32_16x16x32_bf16 v[36:39], v[94:97], v[146:149], v[36:39]
	v_mfma_f32_16x16x32_bf16 v[32:35], v[94:97], v[150:153], v[32:35]
	v_mfma_f32_16x16x32_bf16 v[28:31], v[138:141], v[98:101], v[28:31]
	v_mfma_f32_16x16x32_bf16 v[12:15], v[142:145], v[98:101], v[12:15]
	v_mfma_f32_16x16x32_bf16 v[8:11], v[142:145], v[102:105], v[8:11]
	v_mfma_f32_16x16x32_bf16 v[4:7], v[142:145], v[146:149], v[4:7]
	v_mfma_f32_16x16x32_bf16 v[0:3], v[142:145], v[150:153], v[0:3]
	s_setprio 0
	s_barrier
	ds_write2_b32 v120, v60, v56 offset1:16
	ds_write2_b32 v120, v61, v57 offset0:132 offset1:148
	v_add_u32_e32 v56, 0x400, v120
	ds_write2_b32 v56, v62, v58 offset0:8 offset1:24
	ds_write2_b32 v56, v63, v59 offset0:140 offset1:156
	ds_write2_b32 v120, v52, v48 offset0:32 offset1:48
	ds_write2_b32 v120, v53, v49 offset0:164 offset1:180
	ds_write2_b32 v56, v54, v50 offset0:40 offset1:56
	ds_write2_b32 v56, v55, v51 offset0:172 offset1:188
	v_add_u32_e32 v48, 0x2000, v120
	ds_write2_b32 v48, v44, v40 offset0:64 offset1:80
	ds_write2_b32 v48, v45, v41 offset0:196 offset1:212
	v_add_u32_e32 v40, 0x2400, v120
	ds_write2_b32 v40, v46, v42 offset0:72 offset1:88
	ds_write2_b32 v40, v47, v43 offset0:204 offset1:220
	ds_write2_b32 v48, v36, v32 offset0:96 offset1:112
	ds_write2_b32 v48, v37, v33 offset0:228 offset1:244
	ds_write2_b32 v40, v38, v34 offset0:104 offset1:120
	ds_write2_b32 v40, v39, v35 offset0:236 offset1:252
	v_add_u32_e32 v32, 0x4000, v120
	ds_write2_b32 v32, v28, v24 offset0:128 offset1:144
	v_add_u32_e32 v24, 0x4400, v120
	ds_write2_b32 v24, v29, v25 offset0:4 offset1:20
	ds_write2_b32 v24, v30, v26 offset0:136 offset1:152
	v_add_u32_e32 v25, 0x4800, v120
	ds_write2_b32 v25, v31, v27 offset0:12 offset1:28
	ds_write2_b32 v32, v20, v16 offset0:160 offset1:176
	ds_write2_b32 v24, v21, v17 offset0:36 offset1:52
	ds_write2_b32 v24, v22, v18 offset0:168 offset1:184
	ds_write2_b32 v25, v23, v19 offset0:44 offset1:60
	v_add_u32_e32 v16, 0x6000, v120
	ds_write2_b32 v16, v12, v8 offset0:192 offset1:208
	v_add_u32_e32 v8, 0x6400, v120
	s_cmpk_gt_u32 s6, 0x3ff
	ds_write2_b32 v8, v13, v9 offset0:68 offset1:84
	ds_write2_b32 v8, v14, v10 offset0:200 offset1:216
	v_add_u32_e32 v9, 0x6800, v120
	v_or_b32_e32 v64, s6, v121
	s_cselect_b64 s[28:29], -1, 0
	s_cmpk_gt_u32 s6, 0x7ff
	ds_write2_b32 v9, v15, v11 offset0:76 offset1:92
	ds_write2_b32 v16, v4, v0 offset0:224 offset1:240
	ds_write2_b32 v8, v5, v1 offset0:100 offset1:116
	ds_write2_b32 v8, v6, v2 offset0:232 offset1:248
	ds_write2_b32 v9, v7, v3 offset0:108 offset1:124
	s_cselect_b64 s[30:31], -1, 0
	s_cmpk_gt_u32 s6, 0xbff
	v_ashrrev_i32_e32 v1, 31, v64
	v_mov_b32_e32 v0, v64
	v_lshlrev_b64 v[2:3], 1, v[64:65]
	v_cmp_lt_i32_e64 s[4:5], s41, v64
	s_cselect_b64 s[34:35], -1, 0
	v_cmp_gt_u32_e64 s[6:7], s42, v64
	v_lshl_add_u64 v[16:17], v[64:65], 2, s[18:19]
	v_lshl_add_u64 v[18:19], s[16:17], 0, v[2:3]
	v_lshl_add_u64 v[20:21], s[14:15], 0, v[2:3]
	v_lshl_add_u64 v[22:23], s[12:13], 0, v[2:3]
	v_lshl_add_u64 v[24:25], v[0:1], 1, s[10:11]
	v_add_u32_e32 v26, s36, v129
	s_mov_b32 s44, 0
	s_waitcnt lgkmcnt(0)
	s_barrier
	s_branch .LBB0_2979

.LBB0_3008:
	s_and_b32 s22, s7, 0x4000
	s_xor_b32 s23, s22, 0x4000
	s_lshl_b32 s23, s23, 1
	s_add_i32 s23, s23, 32
	s_add_u32 s90, s52, s4
	s_addc_u32 s91, s53, s5
	s_add_i32 m0, s23, s82
	s_lshl_b32 s22, s22, 1
	global_load_lds_dwordx4 v184, s[90:91]
	s_add_i32 m0, s23, s83
	s_add_i32 s22, s22, 32
	global_load_lds_dwordx4 v185, s[90:91]
	s_add_i32 m0, s23, s84
	v_lshl_add_u32 v64, v115, 1, s22
	global_load_lds_dwordx4 v186, s[90:91]
	s_add_i32 m0, s23, s85
	v_lshl_add_u32 v168, v116, 1, s22
	global_load_lds_dwordx4 v187, s[90:91]
	s_add_i32 m0, s23, s86
	v_add_u32_e32 v156, v64, v133
	global_load_lds_dwordx4 v188, s[90:91]
	s_add_i32 m0, s23, s87
	v_add_u32_e32 v164, v168, v133
	global_load_lds_dwordx4 v189, s[90:91]
	s_add_i32 m0, s23, s88
	s_addk_i32 s7, 0x4000
	global_load_lds_dwordx4 v190, s[90:91]
	s_add_i32 m0, s23, s89
	s_add_u32 s4, s4, 0x80
	s_addc_u32 s5, s5, 0
	global_load_lds_dwordx4 v191, s[90:91]
	ds_read_b128 v[136:139], v156
	ds_read_b128 v[144:147], v164 offset:16384
	ds_read_b128 v[148:151], v164 offset:18432
	ds_read_b128 v[160:163], v164 offset:20480
	ds_read_b128 v[164:167], v164 offset:22528
	ds_read_b128 v[140:143], v156 offset:2048
	ds_read_b128 v[152:155], v156 offset:4096
	ds_read_b128 v[156:159], v156 offset:6144
	v_add_u32_e32 v64, v64, v134
	v_add_u32_e32 v236, v168, v134
	ds_read_b128 v[204:207], v64
	ds_read_b128 v[208:211], v236 offset:16384
	ds_read_b128 v[212:215], v236 offset:18432
	ds_read_b128 v[216:219], v236 offset:20480
	ds_read_b128 v[220:223], v236 offset:22528
	ds_read_b128 v[224:227], v64 offset:2048
	ds_read_b128 v[228:231], v64 offset:4096
	ds_read_b128 v[232:235], v64 offset:6144
	s_setprio 1
	s_waitcnt lgkmcnt(11)
	v_mfma_f32_16x16x32_bf16 v[60:63], v[136:139], v[144:147], v[60:63]
	v_mfma_f32_16x16x32_bf16 v[56:59], v[136:139], v[148:151], v[56:59]
	v_mfma_f32_16x16x32_bf16 v[52:55], v[136:139], v[160:163], v[52:55]
	v_mfma_f32_16x16x32_bf16 v[48:51], v[136:139], v[164:167], v[48:51]
	s_waitcnt lgkmcnt(10)
	v_mfma_f32_16x16x32_bf16 v[44:47], v[140:143], v[144:147], v[44:47]
	v_mfma_f32_16x16x32_bf16 v[40:43], v[140:143], v[148:151], v[40:43]
	v_mfma_f32_16x16x32_bf16 v[36:39], v[140:143], v[160:163], v[36:39]
	v_mfma_f32_16x16x32_bf16 v[32:35], v[140:143], v[164:167], v[32:35]
	s_waitcnt lgkmcnt(9)
	v_mfma_f32_16x16x32_bf16 v[28:31], v[152:155], v[144:147], v[28:31]
	v_mfma_f32_16x16x32_bf16 v[24:27], v[152:155], v[148:151], v[24:27]
	v_mfma_f32_16x16x32_bf16 v[20:23], v[152:155], v[160:163], v[20:23]
	v_mfma_f32_16x16x32_bf16 v[16:19], v[152:155], v[164:167], v[16:19]
	s_waitcnt lgkmcnt(8)
	v_mfma_f32_16x16x32_bf16 v[12:15], v[156:159], v[144:147], v[12:15]
	v_mfma_f32_16x16x32_bf16 v[8:11], v[156:159], v[148:151], v[8:11]
	v_mfma_f32_16x16x32_bf16 v[4:7], v[156:159], v[160:163], v[4:7]
	v_mfma_f32_16x16x32_bf16 v[0:3], v[156:159], v[164:167], v[0:3]
	s_waitcnt lgkmcnt(3)
	v_mfma_f32_16x16x32_bf16 v[60:63], v[204:207], v[208:211], v[60:63]
	v_mfma_f32_16x16x32_bf16 v[56:59], v[204:207], v[212:215], v[56:59]
	v_mfma_f32_16x16x32_bf16 v[52:55], v[204:207], v[216:219], v[52:55]
	v_mfma_f32_16x16x32_bf16 v[48:51], v[204:207], v[220:223], v[48:51]
	s_waitcnt lgkmcnt(2)
	v_mfma_f32_16x16x32_bf16 v[44:47], v[224:227], v[208:211], v[44:47]
	v_mfma_f32_16x16x32_bf16 v[40:43], v[224:227], v[212:215], v[40:43]
	v_mfma_f32_16x16x32_bf16 v[36:39], v[224:227], v[216:219], v[36:39]
	v_mfma_f32_16x16x32_bf16 v[32:35], v[224:227], v[220:223], v[32:35]
	s_waitcnt lgkmcnt(1)
	v_mfma_f32_16x16x32_bf16 v[28:31], v[228:231], v[208:211], v[28:31]
	v_mfma_f32_16x16x32_bf16 v[24:27], v[228:231], v[212:215], v[24:27]
	v_mfma_f32_16x16x32_bf16 v[20:23], v[228:231], v[216:219], v[20:23]
	v_mfma_f32_16x16x32_bf16 v[16:19], v[228:231], v[220:223], v[16:19]
	s_waitcnt lgkmcnt(0)
	v_mfma_f32_16x16x32_bf16 v[12:15], v[232:235], v[208:211], v[12:15]
	v_mfma_f32_16x16x32_bf16 v[8:11], v[232:235], v[212:215], v[8:11]
	v_mfma_f32_16x16x32_bf16 v[4:7], v[232:235], v[216:219], v[4:7]
	v_mfma_f32_16x16x32_bf16 v[0:3], v[232:235], v[220:223], v[0:3]
	s_setprio 0
	s_cmpk_eq_i32 s4, 0x780
	s_waitcnt vmcnt(0)
	s_barrier
	s_cbranch_scc0 .LBB0_3008
	ds_read_b128 v[90:93], v117 offset:55296
	ds_read_b128 v[94:97], v117 offset:53248
	ds_read_b128 v[98:101], v118 offset:38912
	ds_read_b128 v[102:105], v118 offset:36864
	ds_read_b128 v[136:139], v117 offset:51200
	ds_read_b128 v[140:143], v117 offset:49152
	ds_read_b128 v[144:147], v118 offset:34816
	ds_read_b128 v[148:151], v118 offset:32768
	s_setprio 1
	s_waitcnt lgkmcnt(3)
	v_mfma_f32_16x16x32_bf16 v[24:27], v[102:105], v[136:139], v[24:27]
	v_mfma_f32_16x16x32_bf16 v[20:23], v[102:105], v[94:97], v[20:23]
	v_mfma_f32_16x16x32_bf16 v[16:19], v[102:105], v[90:93], v[16:19]
	s_waitcnt lgkmcnt(0)
	v_mfma_f32_16x16x32_bf16 v[60:63], v[148:151], v[140:143], v[60:63]
	v_mfma_f32_16x16x32_bf16 v[56:59], v[148:151], v[136:139], v[56:59]
	v_mfma_f32_16x16x32_bf16 v[52:55], v[148:151], v[94:97], v[52:55]
	v_mfma_f32_16x16x32_bf16 v[48:51], v[148:151], v[90:93], v[48:51]
	v_mfma_f32_16x16x32_bf16 v[44:47], v[144:147], v[140:143], v[44:47]
	v_mfma_f32_16x16x32_bf16 v[40:43], v[144:147], v[136:139], v[40:43]
	v_mfma_f32_16x16x32_bf16 v[36:39], v[144:147], v[94:97], v[36:39]
	v_mfma_f32_16x16x32_bf16 v[32:35], v[144:147], v[90:93], v[32:35]
	v_mfma_f32_16x16x32_bf16 v[28:31], v[102:105], v[140:143], v[28:31]
	v_mfma_f32_16x16x32_bf16 v[12:15], v[98:101], v[140:143], v[12:15]
	v_mfma_f32_16x16x32_bf16 v[8:11], v[98:101], v[136:139], v[8:11]
	v_mfma_f32_16x16x32_bf16 v[4:7], v[98:101], v[94:97], v[4:7]
	v_mfma_f32_16x16x32_bf16 v[0:3], v[98:101], v[90:93], v[0:3]
	s_setprio 0
	ds_read_b128 v[90:93], v119 offset:32768
	ds_read_b128 v[94:97], v119 offset:34816
	ds_read_b128 v[98:101], v120 offset:49152
	ds_read_b128 v[102:105], v120 offset:51200
	ds_read_b128 v[136:139], v119 offset:36864
	ds_read_b128 v[140:143], v119 offset:38912
	ds_read_b128 v[144:147], v120 offset:53248
	ds_read_b128 v[148:151], v120 offset:55296
	s_setprio 1
	s_waitcnt lgkmcnt(3)
	v_mfma_f32_16x16x32_bf16 v[24:27], v[136:139], v[102:105], v[24:27]
	s_waitcnt lgkmcnt(1)
	v_mfma_f32_16x16x32_bf16 v[20:23], v[136:139], v[144:147], v[20:23]
	s_waitcnt lgkmcnt(0)
	v_mfma_f32_16x16x32_bf16 v[16:19], v[136:139], v[148:151], v[16:19]
	v_mfma_f32_16x16x32_bf16 v[60:63], v[90:93], v[98:101], v[60:63]
	v_mfma_f32_16x16x32_bf16 v[56:59], v[90:93], v[102:105], v[56:59]
	v_mfma_f32_16x16x32_bf16 v[52:55], v[90:93], v[144:147], v[52:55]
	v_mfma_f32_16x16x32_bf16 v[48:51], v[90:93], v[148:151], v[48:51]
	v_mfma_f32_16x16x32_bf16 v[44:47], v[94:97], v[98:101], v[44:47]
	v_mfma_f32_16x16x32_bf16 v[40:43], v[94:97], v[102:105], v[40:43]
	v_mfma_f32_16x16x32_bf16 v[36:39], v[94:97], v[144:147], v[36:39]
	v_mfma_f32_16x16x32_bf16 v[32:35], v[94:97], v[148:151], v[32:35]
	v_mfma_f32_16x16x32_bf16 v[28:31], v[136:139], v[98:101], v[28:31]
	v_mfma_f32_16x16x32_bf16 v[12:15], v[140:143], v[98:101], v[12:15]
	v_mfma_f32_16x16x32_bf16 v[8:11], v[140:143], v[102:105], v[8:11]
	v_mfma_f32_16x16x32_bf16 v[4:7], v[140:143], v[144:147], v[4:7]
	v_mfma_f32_16x16x32_bf16 v[0:3], v[140:143], v[148:151], v[0:3]
	s_setprio 0
	s_barrier
	ds_write2_b32 v121, v60, v56 offset1:16
	ds_write2_b32 v121, v61, v57 offset0:132 offset1:148
	v_add_u32_e32 v56, 0x400, v121
	ds_write2_b32 v56, v62, v58 offset0:8 offset1:24
	ds_write2_b32 v56, v63, v59 offset0:140 offset1:156
	ds_write2_b32 v121, v52, v48 offset0:32 offset1:48
	ds_write2_b32 v121, v53, v49 offset0:164 offset1:180
	ds_write2_b32 v56, v54, v50 offset0:40 offset1:56
	ds_write2_b32 v56, v55, v51 offset0:172 offset1:188
	v_add_u32_e32 v48, 0x2000, v121
	ds_write2_b32 v48, v44, v40 offset0:64 offset1:80
	ds_write2_b32 v48, v45, v41 offset0:196 offset1:212
	v_add_u32_e32 v40, 0x2400, v121
	ds_write2_b32 v40, v46, v42 offset0:72 offset1:88
	ds_write2_b32 v40, v47, v43 offset0:204 offset1:220
	ds_write2_b32 v48, v36, v32 offset0:96 offset1:112
	ds_write2_b32 v48, v37, v33 offset0:228 offset1:244
	ds_write2_b32 v40, v38, v34 offset0:104 offset1:120
	ds_write2_b32 v40, v39, v35 offset0:236 offset1:252
	v_add_u32_e32 v32, 0x4000, v121
	ds_write2_b32 v32, v28, v24 offset0:128 offset1:144
	v_add_u32_e32 v24, 0x4400, v121
	ds_write2_b32 v24, v29, v25 offset0:4 offset1:20
	ds_write2_b32 v24, v30, v26 offset0:136 offset1:152
	v_add_u32_e32 v25, 0x4800, v121
	ds_write2_b32 v25, v31, v27 offset0:12 offset1:28
	ds_write2_b32 v32, v20, v16 offset0:160 offset1:176
	ds_write2_b32 v24, v21, v17 offset0:36 offset1:52
	ds_write2_b32 v24, v22, v18 offset0:168 offset1:184
	ds_write2_b32 v25, v23, v19 offset0:44 offset1:60
	v_add_u32_e32 v16, 0x6000, v121
	ds_write2_b32 v16, v12, v8 offset0:192 offset1:208
	v_add_u32_e32 v8, 0x6400, v121
	s_cmpk_gt_u32 s6, 0x3ff
	ds_write2_b32 v8, v13, v9 offset0:68 offset1:84
	ds_write2_b32 v8, v14, v10 offset0:200 offset1:216
	v_add_u32_e32 v9, 0x6800, v121
	v_or_b32_e32 v64, s6, v122
	s_cselect_b64 s[22:23], -1, 0
	s_cmpk_gt_u32 s6, 0x7ff
	ds_write2_b32 v9, v15, v11 offset0:76 offset1:92
	ds_write2_b32 v16, v4, v0 offset0:224 offset1:240
	ds_write2_b32 v8, v5, v1 offset0:100 offset1:116
	ds_write2_b32 v8, v6, v2 offset0:232 offset1:248
	ds_write2_b32 v9, v7, v3 offset0:108 offset1:124
	s_cselect_b64 s[24:25], -1, 0
	s_cmpk_gt_u32 s6, 0xbff
	v_ashrrev_i32_e32 v1, 31, v64
	v_mov_b32_e32 v0, v64
	v_lshlrev_b64 v[2:3], 1, v[64:65]
	v_cmp_lt_i32_e64 s[4:5], s36, v64
	s_cselect_b64 s[26:27], -1, 0
	v_cmp_gt_u32_e64 s[6:7], s37, v64
	v_lshl_add_u64 v[16:17], v[64:65], 2, s[18:19]
	v_lshl_add_u64 v[18:19], s[16:17], 0, v[2:3]
	v_lshl_add_u64 v[20:21], s[14:15], 0, v[2:3]
	v_lshl_add_u64 v[22:23], s[12:13], 0, v[2:3]
	v_lshl_add_u64 v[24:25], v[0:1], 1, s[10:11]
	v_add_u32_e32 v26, v126, v135
	s_mov_b32 s38, 0
	s_waitcnt lgkmcnt(0)
	s_barrier
	s_branch .LBB0_3011

.LBB0_3222:
	s_and_b32 s27, s26, 0x4000
	s_xor_b32 s28, s27, 0x4000
	s_lshl_b32 s28, s28, 1
	s_add_i32 s28, s28, 32
	s_add_u32 s90, s52, s16
	s_addc_u32 s91, s53, s17
	s_add_i32 m0, s28, s82
	s_lshl_b32 s27, s27, 1
	global_load_lds_dwordx4 v184, s[90:91]
	s_add_i32 m0, s28, s83
	s_add_i32 s27, s27, 32
	global_load_lds_dwordx4 v185, s[90:91]
	s_add_i32 m0, s28, s84
	v_add3_u32 v139, s27, v114, v136
	global_load_lds_dwordx4 v186, s[90:91]
	s_add_i32 m0, s28, s85
	v_add3_u32 v172, s27, v115, v136
	global_load_lds_dwordx4 v187, s[90:91]
	s_add_i32 m0, s28, s86
	v_add_u32_e32 v160, v139, v137
	global_load_lds_dwordx4 v188, s[90:91]
	s_add_i32 m0, s28, s87
	v_add_u32_e32 v168, v172, v137
	global_load_lds_dwordx4 v189, s[90:91]
	s_add_i32 m0, s28, s88
	s_addk_i32 s26, 0x4000
	global_load_lds_dwordx4 v190, s[90:91]
	s_add_i32 m0, s28, s89
	s_add_u32 s16, s16, 0x80
	s_addc_u32 s17, s17, 0
	global_load_lds_dwordx4 v191, s[90:91]
	ds_read_b128 v[140:143], v160
	ds_read_b128 v[148:151], v168 offset:16384
	ds_read_b128 v[152:155], v168 offset:18432
	ds_read_b128 v[164:167], v168 offset:20480
	ds_read_b128 v[168:171], v168 offset:22528
	ds_read_b128 v[144:147], v160 offset:2048
	ds_read_b128 v[156:159], v160 offset:4096
	ds_read_b128 v[160:163], v160 offset:6144
	v_add_u32_e32 v139, v139, v138
	v_add_u32_e32 v236, v172, v138
	ds_read_b128 v[204:207], v139
	ds_read_b128 v[208:211], v236 offset:16384
	ds_read_b128 v[212:215], v236 offset:18432
	ds_read_b128 v[216:219], v236 offset:20480
	ds_read_b128 v[220:223], v236 offset:22528
	ds_read_b128 v[224:227], v139 offset:2048
	ds_read_b128 v[228:231], v139 offset:4096
	ds_read_b128 v[232:235], v139 offset:6144
	s_setprio 1
	s_waitcnt lgkmcnt(11)
	v_mfma_f32_16x16x32_bf16 v[60:63], v[140:143], v[148:151], v[60:63]
	v_mfma_f32_16x16x32_bf16 v[56:59], v[140:143], v[152:155], v[56:59]
	v_mfma_f32_16x16x32_bf16 v[52:55], v[140:143], v[164:167], v[52:55]
	v_mfma_f32_16x16x32_bf16 v[48:51], v[140:143], v[168:171], v[48:51]
	s_waitcnt lgkmcnt(10)
	v_mfma_f32_16x16x32_bf16 v[44:47], v[144:147], v[148:151], v[44:47]
	v_mfma_f32_16x16x32_bf16 v[40:43], v[144:147], v[152:155], v[40:43]
	v_mfma_f32_16x16x32_bf16 v[36:39], v[144:147], v[164:167], v[36:39]
	v_mfma_f32_16x16x32_bf16 v[32:35], v[144:147], v[168:171], v[32:35]
	s_waitcnt lgkmcnt(9)
	v_mfma_f32_16x16x32_bf16 v[28:31], v[156:159], v[148:151], v[28:31]
	v_mfma_f32_16x16x32_bf16 v[24:27], v[156:159], v[152:155], v[24:27]
	v_mfma_f32_16x16x32_bf16 v[20:23], v[156:159], v[164:167], v[20:23]
	v_mfma_f32_16x16x32_bf16 v[16:19], v[156:159], v[168:171], v[16:19]
	s_waitcnt lgkmcnt(8)
	v_mfma_f32_16x16x32_bf16 v[12:15], v[160:163], v[148:151], v[12:15]
	v_mfma_f32_16x16x32_bf16 v[8:11], v[160:163], v[152:155], v[8:11]
	v_mfma_f32_16x16x32_bf16 v[4:7], v[160:163], v[164:167], v[4:7]
	v_mfma_f32_16x16x32_bf16 v[0:3], v[160:163], v[168:171], v[0:3]
	s_waitcnt lgkmcnt(3)
	v_mfma_f32_16x16x32_bf16 v[60:63], v[204:207], v[208:211], v[60:63]
	v_mfma_f32_16x16x32_bf16 v[56:59], v[204:207], v[212:215], v[56:59]
	v_mfma_f32_16x16x32_bf16 v[52:55], v[204:207], v[216:219], v[52:55]
	v_mfma_f32_16x16x32_bf16 v[48:51], v[204:207], v[220:223], v[48:51]
	s_waitcnt lgkmcnt(2)
	v_mfma_f32_16x16x32_bf16 v[44:47], v[224:227], v[208:211], v[44:47]
	v_mfma_f32_16x16x32_bf16 v[40:43], v[224:227], v[212:215], v[40:43]
	v_mfma_f32_16x16x32_bf16 v[36:39], v[224:227], v[216:219], v[36:39]
	v_mfma_f32_16x16x32_bf16 v[32:35], v[224:227], v[220:223], v[32:35]
	s_waitcnt lgkmcnt(1)
	v_mfma_f32_16x16x32_bf16 v[28:31], v[228:231], v[208:211], v[28:31]
	v_mfma_f32_16x16x32_bf16 v[24:27], v[228:231], v[212:215], v[24:27]
	v_mfma_f32_16x16x32_bf16 v[20:23], v[228:231], v[216:219], v[20:23]
	v_mfma_f32_16x16x32_bf16 v[16:19], v[228:231], v[220:223], v[16:19]
	s_waitcnt lgkmcnt(0)
	v_mfma_f32_16x16x32_bf16 v[12:15], v[232:235], v[208:211], v[12:15]
	v_mfma_f32_16x16x32_bf16 v[8:11], v[232:235], v[212:215], v[8:11]
	v_mfma_f32_16x16x32_bf16 v[4:7], v[232:235], v[216:219], v[4:7]
	v_mfma_f32_16x16x32_bf16 v[0:3], v[232:235], v[220:223], v[0:3]
	s_setprio 0
	s_cmpk_eq_i32 s16, 0x780
	s_waitcnt vmcnt(0)
	s_barrier
	s_cbranch_scc0 .LBB0_3222
	ds_read_b128 v[90:93], v118 offset:55296
	ds_read_b128 v[94:97], v118 offset:53248
	ds_read_b128 v[98:101], v119 offset:38912
	ds_read_b128 v[102:105], v119 offset:36864
	ds_read_b128 v[140:143], v118 offset:51200
	ds_read_b128 v[144:147], v118 offset:49152
	ds_read_b128 v[148:151], v119 offset:34816
	ds_read_b128 v[152:155], v119 offset:32768
	s_setprio 1
	s_waitcnt lgkmcnt(5)
	v_mfma_f32_16x16x32_bf16 v[4:7], v[98:101], v[94:97], v[4:7]
	v_mfma_f32_16x16x32_bf16 v[0:3], v[98:101], v[90:93], v[0:3]
	s_waitcnt lgkmcnt(0)
	v_mfma_f32_16x16x32_bf16 v[60:63], v[152:155], v[144:147], v[60:63]
	v_mfma_f32_16x16x32_bf16 v[56:59], v[152:155], v[140:143], v[56:59]
	v_mfma_f32_16x16x32_bf16 v[52:55], v[152:155], v[94:97], v[52:55]
	v_mfma_f32_16x16x32_bf16 v[48:51], v[152:155], v[90:93], v[48:51]
	v_mfma_f32_16x16x32_bf16 v[44:47], v[148:151], v[144:147], v[44:47]
	v_mfma_f32_16x16x32_bf16 v[40:43], v[148:151], v[140:143], v[40:43]
	v_mfma_f32_16x16x32_bf16 v[36:39], v[148:151], v[94:97], v[36:39]
	v_mfma_f32_16x16x32_bf16 v[32:35], v[148:151], v[90:93], v[32:35]
	v_mfma_f32_16x16x32_bf16 v[28:31], v[102:105], v[144:147], v[28:31]
	v_mfma_f32_16x16x32_bf16 v[24:27], v[102:105], v[140:143], v[24:27]
	v_mfma_f32_16x16x32_bf16 v[20:23], v[102:105], v[94:97], v[20:23]
	v_mfma_f32_16x16x32_bf16 v[16:19], v[102:105], v[90:93], v[16:19]
	v_mfma_f32_16x16x32_bf16 v[12:15], v[98:101], v[144:147], v[12:15]
	v_mfma_f32_16x16x32_bf16 v[8:11], v[98:101], v[140:143], v[8:11]
	s_setprio 0
	ds_read_b128 v[90:93], v120 offset:32768
	ds_read_b128 v[94:97], v120 offset:34816
	ds_read_b128 v[98:101], v121 offset:49152
	ds_read_b128 v[102:105], v121 offset:51200
	ds_read_b128 v[140:143], v120 offset:36864
	ds_read_b128 v[144:147], v120 offset:38912
	ds_read_b128 v[148:151], v121 offset:53248
	ds_read_b128 v[152:155], v121 offset:55296
	s_setprio 1
	s_waitcnt lgkmcnt(1)
	v_mfma_f32_16x16x32_bf16 v[4:7], v[144:147], v[148:151], v[4:7]
	s_waitcnt lgkmcnt(0)
	v_mfma_f32_16x16x32_bf16 v[0:3], v[144:147], v[152:155], v[0:3]
	v_mfma_f32_16x16x32_bf16 v[60:63], v[90:93], v[98:101], v[60:63]
	v_mfma_f32_16x16x32_bf16 v[56:59], v[90:93], v[102:105], v[56:59]
	v_mfma_f32_16x16x32_bf16 v[52:55], v[90:93], v[148:151], v[52:55]
	v_mfma_f32_16x16x32_bf16 v[48:51], v[90:93], v[152:155], v[48:51]
	v_mfma_f32_16x16x32_bf16 v[44:47], v[94:97], v[98:101], v[44:47]
	v_mfma_f32_16x16x32_bf16 v[40:43], v[94:97], v[102:105], v[40:43]
	v_mfma_f32_16x16x32_bf16 v[36:39], v[94:97], v[148:151], v[36:39]
	v_mfma_f32_16x16x32_bf16 v[32:35], v[94:97], v[152:155], v[32:35]
	v_mfma_f32_16x16x32_bf16 v[28:31], v[140:143], v[98:101], v[28:31]
	v_mfma_f32_16x16x32_bf16 v[24:27], v[140:143], v[102:105], v[24:27]
	v_mfma_f32_16x16x32_bf16 v[20:23], v[140:143], v[148:151], v[20:23]
	v_mfma_f32_16x16x32_bf16 v[16:19], v[140:143], v[152:155], v[16:19]
	v_mfma_f32_16x16x32_bf16 v[12:15], v[144:147], v[98:101], v[12:15]
	v_mfma_f32_16x16x32_bf16 v[8:11], v[144:147], v[102:105], v[8:11]
	s_setprio 0
	s_barrier
	ds_write2_b32 v116, v60, v56 offset1:16
	ds_write2_b32 v116, v61, v57 offset0:132 offset1:148
	v_add_u32_e32 v56, 0x400, v116
	ds_write2_b32 v56, v62, v58 offset0:8 offset1:24
	ds_write2_b32 v56, v63, v59 offset0:140 offset1:156
	ds_write2_b32 v116, v52, v48 offset0:32 offset1:48
	ds_write2_b32 v116, v53, v49 offset0:164 offset1:180
	ds_write2_b32 v56, v54, v50 offset0:40 offset1:56
	ds_write2_b32 v56, v55, v51 offset0:172 offset1:188
	v_add_u32_e32 v48, 0x2000, v116
	ds_write2_b32 v48, v44, v40 offset0:64 offset1:80
	ds_write2_b32 v48, v45, v41 offset0:196 offset1:212
	v_add_u32_e32 v40, 0x2400, v116
	ds_write2_b32 v40, v46, v42 offset0:72 offset1:88
	ds_write2_b32 v40, v47, v43 offset0:204 offset1:220
	ds_write2_b32 v48, v36, v32 offset0:96 offset1:112
	ds_write2_b32 v48, v37, v33 offset0:228 offset1:244
	ds_write2_b32 v40, v38, v34 offset0:104 offset1:120
	ds_write2_b32 v40, v39, v35 offset0:236 offset1:252
	v_add_u32_e32 v32, 0x4000, v116
	ds_write2_b32 v32, v28, v24 offset0:128 offset1:144
	v_add_u32_e32 v24, 0x4400, v116
	ds_write2_b32 v24, v29, v25 offset0:4 offset1:20
	ds_write2_b32 v24, v30, v26 offset0:136 offset1:152
	v_add_u32_e32 v25, 0x4800, v116
	ds_write2_b32 v25, v31, v27 offset0:12 offset1:28
	ds_write2_b32 v32, v20, v16 offset0:160 offset1:176
	ds_write2_b32 v24, v21, v17 offset0:36 offset1:52
	ds_write2_b32 v24, v22, v18 offset0:168 offset1:184
	ds_write2_b32 v25, v23, v19 offset0:44 offset1:60
	v_add_u32_e32 v16, 0x6000, v116
	ds_write2_b32 v16, v12, v8 offset0:192 offset1:208
	v_add_u32_e32 v8, 0x6400, v116
	ds_write2_b32 v8, v13, v9 offset0:68 offset1:84
	ds_write2_b32 v8, v14, v10 offset0:200 offset1:216
	v_add_u32_e32 v9, 0x6800, v116
	ds_write2_b32 v9, v15, v11 offset0:76 offset1:92
	ds_write2_b32 v16, v4, v0 offset0:224 offset1:240
	ds_write2_b32 v8, v5, v1 offset0:100 offset1:116
	ds_write2_b32 v8, v6, v2 offset0:232 offset1:248
	ds_write2_b32 v9, v7, v3 offset0:108 offset1:124
	v_or_b32_e32 v0, s25, v117
	v_ashrrev_i32_e32 v1, 31, v0
	v_lshlrev_b64 v[2:3], 2, v[0:1]
	v_lshl_add_u64 v[0:1], s[14:15], 0, v[2:3]
	v_lshl_add_u64 v[2:3], s[6:7], 0, v[2:3]
	v_add_u32_e32 v4, s24, v129
	s_mov_b32 s16, 0
	s_waitcnt lgkmcnt(0)
	s_barrier

.LBB0_3231:
	s_and_b32 s23, s22, 0x4000
	s_xor_b32 s24, s23, 0x4000
	s_lshl_b32 s24, s24, 1
	s_add_i32 s24, s24, 32
	s_add_u32 s90, s52, s8
	s_addc_u32 s91, s53, s9
	s_add_i32 m0, s24, s82
	s_lshl_b32 s23, s23, 1
	global_load_lds_dwordx4 v184, s[90:91]
	s_add_i32 m0, s24, s83
	s_add_i32 s23, s23, 32
	global_load_lds_dwordx4 v185, s[90:91]
	s_add_i32 m0, s24, s84
	v_add3_u32 v170, s23, v112, v135
	global_load_lds_dwordx4 v186, s[90:91]
	s_add_i32 m0, s24, s85
	v_add3_u32 v171, s23, v113, v135
	global_load_lds_dwordx4 v187, s[90:91]
	s_add_i32 m0, s24, s86
	v_add_u32_e32 v158, v170, v136
	global_load_lds_dwordx4 v188, s[90:91]
	s_add_i32 m0, s24, s87
	v_add_u32_e32 v166, v171, v136
	global_load_lds_dwordx4 v189, s[90:91]
	s_add_i32 m0, s24, s88
	s_addk_i32 s22, 0x4000
	global_load_lds_dwordx4 v190, s[90:91]
	s_add_i32 m0, s24, s89
	s_add_u32 s8, s8, 0x80
	s_addc_u32 s9, s9, 0
	global_load_lds_dwordx4 v191, s[90:91]
	ds_read_b128 v[138:141], v158
	ds_read_b128 v[146:149], v166 offset:16384
	ds_read_b128 v[150:153], v166 offset:18432
	ds_read_b128 v[162:165], v166 offset:20480
	ds_read_b128 v[166:169], v166 offset:22528
	ds_read_b128 v[142:145], v158 offset:2048
	ds_read_b128 v[154:157], v158 offset:4096
	ds_read_b128 v[158:161], v158 offset:6144
	v_add_u32_e32 v236, v170, v137
	v_add_u32_e32 v237, v171, v137
	ds_read_b128 v[204:207], v236
	ds_read_b128 v[208:211], v237 offset:16384
	ds_read_b128 v[212:215], v237 offset:18432
	ds_read_b128 v[216:219], v237 offset:20480
	ds_read_b128 v[220:223], v237 offset:22528
	ds_read_b128 v[224:227], v236 offset:2048
	ds_read_b128 v[228:231], v236 offset:4096
	ds_read_b128 v[232:235], v236 offset:6144
	s_setprio 1
	s_waitcnt lgkmcnt(11)
	v_mfma_f32_16x16x32_bf16 v[60:63], v[138:141], v[146:149], v[60:63]
	v_mfma_f32_16x16x32_bf16 v[56:59], v[138:141], v[150:153], v[56:59]
	v_mfma_f32_16x16x32_bf16 v[52:55], v[138:141], v[162:165], v[52:55]
	v_mfma_f32_16x16x32_bf16 v[48:51], v[138:141], v[166:169], v[48:51]
	s_waitcnt lgkmcnt(10)
	v_mfma_f32_16x16x32_bf16 v[44:47], v[142:145], v[146:149], v[44:47]
	v_mfma_f32_16x16x32_bf16 v[40:43], v[142:145], v[150:153], v[40:43]
	v_mfma_f32_16x16x32_bf16 v[36:39], v[142:145], v[162:165], v[36:39]
	v_mfma_f32_16x16x32_bf16 v[32:35], v[142:145], v[166:169], v[32:35]
	s_waitcnt lgkmcnt(9)
	v_mfma_f32_16x16x32_bf16 v[28:31], v[154:157], v[146:149], v[28:31]
	v_mfma_f32_16x16x32_bf16 v[24:27], v[154:157], v[150:153], v[24:27]
	v_mfma_f32_16x16x32_bf16 v[20:23], v[154:157], v[162:165], v[20:23]
	v_mfma_f32_16x16x32_bf16 v[16:19], v[154:157], v[166:169], v[16:19]
	s_waitcnt lgkmcnt(8)
	v_mfma_f32_16x16x32_bf16 v[12:15], v[158:161], v[146:149], v[12:15]
	v_mfma_f32_16x16x32_bf16 v[8:11], v[158:161], v[150:153], v[8:11]
	v_mfma_f32_16x16x32_bf16 v[4:7], v[158:161], v[162:165], v[4:7]
	v_mfma_f32_16x16x32_bf16 v[0:3], v[158:161], v[166:169], v[0:3]
	s_waitcnt lgkmcnt(3)
	v_mfma_f32_16x16x32_bf16 v[60:63], v[204:207], v[208:211], v[60:63]
	v_mfma_f32_16x16x32_bf16 v[56:59], v[204:207], v[212:215], v[56:59]
	v_mfma_f32_16x16x32_bf16 v[52:55], v[204:207], v[216:219], v[52:55]
	v_mfma_f32_16x16x32_bf16 v[48:51], v[204:207], v[220:223], v[48:51]
	s_waitcnt lgkmcnt(2)
	v_mfma_f32_16x16x32_bf16 v[44:47], v[224:227], v[208:211], v[44:47]
	v_mfma_f32_16x16x32_bf16 v[40:43], v[224:227], v[212:215], v[40:43]
	v_mfma_f32_16x16x32_bf16 v[36:39], v[224:227], v[216:219], v[36:39]
	v_mfma_f32_16x16x32_bf16 v[32:35], v[224:227], v[220:223], v[32:35]
	s_waitcnt lgkmcnt(1)
	v_mfma_f32_16x16x32_bf16 v[28:31], v[228:231], v[208:211], v[28:31]
	v_mfma_f32_16x16x32_bf16 v[24:27], v[228:231], v[212:215], v[24:27]
	v_mfma_f32_16x16x32_bf16 v[20:23], v[228:231], v[216:219], v[20:23]
	v_mfma_f32_16x16x32_bf16 v[16:19], v[228:231], v[220:223], v[16:19]
	s_waitcnt lgkmcnt(0)
	v_mfma_f32_16x16x32_bf16 v[12:15], v[232:235], v[208:211], v[12:15]
	v_mfma_f32_16x16x32_bf16 v[8:11], v[232:235], v[212:215], v[8:11]
	v_mfma_f32_16x16x32_bf16 v[4:7], v[232:235], v[216:219], v[4:7]
	v_mfma_f32_16x16x32_bf16 v[0:3], v[232:235], v[220:223], v[0:3]
	s_setprio 0
	s_cmpk_eq_i32 s8, 0x780
	s_waitcnt vmcnt(0)
	s_barrier
	s_cbranch_scc0 .LBB0_3231
	ds_read_b128 v[88:91], v116 offset:55296
	ds_read_b128 v[92:95], v116 offset:53248
	ds_read_b128 v[96:99], v117 offset:38912
	ds_read_b128 v[100:103], v117 offset:36864
	ds_read_b128 v[138:141], v116 offset:51200
	ds_read_b128 v[142:145], v116 offset:49152
	ds_read_b128 v[146:149], v117 offset:34816
	ds_read_b128 v[150:153], v117 offset:32768
	s_setprio 1
	s_waitcnt lgkmcnt(5)
	v_mfma_f32_16x16x32_bf16 v[4:7], v[96:99], v[92:95], v[4:7]
	v_mfma_f32_16x16x32_bf16 v[0:3], v[96:99], v[88:91], v[0:3]
	s_waitcnt lgkmcnt(0)
	v_mfma_f32_16x16x32_bf16 v[60:63], v[150:153], v[142:145], v[60:63]
	v_mfma_f32_16x16x32_bf16 v[56:59], v[150:153], v[138:141], v[56:59]
	v_mfma_f32_16x16x32_bf16 v[52:55], v[150:153], v[92:95], v[52:55]
	v_mfma_f32_16x16x32_bf16 v[48:51], v[150:153], v[88:91], v[48:51]
	v_mfma_f32_16x16x32_bf16 v[44:47], v[146:149], v[142:145], v[44:47]
	v_mfma_f32_16x16x32_bf16 v[40:43], v[146:149], v[138:141], v[40:43]
	v_mfma_f32_16x16x32_bf16 v[36:39], v[146:149], v[92:95], v[36:39]
	v_mfma_f32_16x16x32_bf16 v[32:35], v[146:149], v[88:91], v[32:35]
	v_mfma_f32_16x16x32_bf16 v[28:31], v[100:103], v[142:145], v[28:31]
	v_mfma_f32_16x16x32_bf16 v[24:27], v[100:103], v[138:141], v[24:27]
	v_mfma_f32_16x16x32_bf16 v[20:23], v[100:103], v[92:95], v[20:23]
	v_mfma_f32_16x16x32_bf16 v[16:19], v[100:103], v[88:91], v[16:19]
	v_mfma_f32_16x16x32_bf16 v[12:15], v[96:99], v[142:145], v[12:15]
	v_mfma_f32_16x16x32_bf16 v[8:11], v[96:99], v[138:141], v[8:11]
	s_setprio 0
	ds_read_b128 v[88:91], v118 offset:32768
	ds_read_b128 v[92:95], v118 offset:34816
	ds_read_b128 v[96:99], v119 offset:49152
	ds_read_b128 v[100:103], v119 offset:51200
	ds_read_b128 v[138:141], v118 offset:36864
	ds_read_b128 v[142:145], v118 offset:38912
	ds_read_b128 v[146:149], v119 offset:53248
	ds_read_b128 v[150:153], v119 offset:55296
	s_setprio 1
	s_waitcnt lgkmcnt(1)
	v_mfma_f32_16x16x32_bf16 v[4:7], v[142:145], v[146:149], v[4:7]
	s_waitcnt lgkmcnt(0)
	v_mfma_f32_16x16x32_bf16 v[0:3], v[142:145], v[150:153], v[0:3]
	v_mfma_f32_16x16x32_bf16 v[60:63], v[88:91], v[96:99], v[60:63]
	v_mfma_f32_16x16x32_bf16 v[56:59], v[88:91], v[100:103], v[56:59]
	v_mfma_f32_16x16x32_bf16 v[52:55], v[88:91], v[146:149], v[52:55]
	v_mfma_f32_16x16x32_bf16 v[48:51], v[88:91], v[150:153], v[48:51]
	v_mfma_f32_16x16x32_bf16 v[44:47], v[92:95], v[96:99], v[44:47]
	v_mfma_f32_16x16x32_bf16 v[40:43], v[92:95], v[100:103], v[40:43]
	v_mfma_f32_16x16x32_bf16 v[36:39], v[92:95], v[146:149], v[36:39]
	v_mfma_f32_16x16x32_bf16 v[32:35], v[92:95], v[150:153], v[32:35]
	v_mfma_f32_16x16x32_bf16 v[28:31], v[138:141], v[96:99], v[28:31]
	v_mfma_f32_16x16x32_bf16 v[24:27], v[138:141], v[100:103], v[24:27]
	v_mfma_f32_16x16x32_bf16 v[20:23], v[138:141], v[146:149], v[20:23]
	v_mfma_f32_16x16x32_bf16 v[16:19], v[138:141], v[150:153], v[16:19]
	v_mfma_f32_16x16x32_bf16 v[12:15], v[142:145], v[96:99], v[12:15]
	v_mfma_f32_16x16x32_bf16 v[8:11], v[142:145], v[100:103], v[8:11]
	s_setprio 0
	s_barrier
	ds_write2_b32 v114, v60, v56 offset1:16
	ds_write2_b32 v114, v61, v57 offset0:132 offset1:148
	v_add_u32_e32 v56, 0x400, v114
	ds_write2_b32 v56, v62, v58 offset0:8 offset1:24
	ds_write2_b32 v56, v63, v59 offset0:140 offset1:156
	ds_write2_b32 v114, v52, v48 offset0:32 offset1:48
	ds_write2_b32 v114, v53, v49 offset0:164 offset1:180
	ds_write2_b32 v56, v54, v50 offset0:40 offset1:56
	ds_write2_b32 v56, v55, v51 offset0:172 offset1:188
	v_add_u32_e32 v48, 0x2000, v114
	ds_write2_b32 v48, v44, v40 offset0:64 offset1:80
	ds_write2_b32 v48, v45, v41 offset0:196 offset1:212
	v_add_u32_e32 v40, 0x2400, v114
	ds_write2_b32 v40, v46, v42 offset0:72 offset1:88
	ds_write2_b32 v40, v47, v43 offset0:204 offset1:220
	ds_write2_b32 v48, v36, v32 offset0:96 offset1:112
	ds_write2_b32 v48, v37, v33 offset0:228 offset1:244
	ds_write2_b32 v40, v38, v34 offset0:104 offset1:120
	ds_write2_b32 v40, v39, v35 offset0:236 offset1:252
	v_add_u32_e32 v32, 0x4000, v114
	ds_write2_b32 v32, v28, v24 offset0:128 offset1:144
	v_add_u32_e32 v24, 0x4400, v114
	ds_write2_b32 v24, v29, v25 offset0:4 offset1:20
	ds_write2_b32 v24, v30, v26 offset0:136 offset1:152
	v_add_u32_e32 v25, 0x4800, v114
	ds_write2_b32 v25, v31, v27 offset0:12 offset1:28
	ds_write2_b32 v32, v20, v16 offset0:160 offset1:176
	ds_write2_b32 v24, v21, v17 offset0:36 offset1:52
	ds_write2_b32 v24, v22, v18 offset0:168 offset1:184
	ds_write2_b32 v25, v23, v19 offset0:44 offset1:60
	v_add_u32_e32 v16, 0x6000, v114
	ds_write2_b32 v16, v12, v8 offset0:192 offset1:208
	v_add_u32_e32 v8, 0x6400, v114
	ds_write2_b32 v8, v13, v9 offset0:68 offset1:84
	ds_write2_b32 v8, v14, v10 offset0:200 offset1:216
	v_add_u32_e32 v9, 0x6800, v114
	ds_write2_b32 v9, v15, v11 offset0:76 offset1:92
	ds_write2_b32 v16, v4, v0 offset0:224 offset1:240
	ds_write2_b32 v8, v5, v1 offset0:100 offset1:116
	ds_write2_b32 v8, v6, v2 offset0:232 offset1:248
	ds_write2_b32 v9, v7, v3 offset0:108 offset1:124
	v_or_b32_e32 v0, s21, v115
	v_ashrrev_i32_e32 v1, 31, v0
	v_lshlrev_b64 v[2:3], 2, v[0:1]
	v_lshl_add_u64 v[0:1], s[10:11], 0, v[2:3]
	v_lshl_add_u64 v[2:3], s[6:7], 0, v[2:3]
	v_add_u32_e32 v4, s20, v128
	s_mov_b32 s8, 0
	s_waitcnt lgkmcnt(0)
	s_barrier

.LBB0_3388:
	s_and_b32 s20, s19, 0x4000
	s_xor_b32 s21, s20, 0x4000
	s_lshl_b32 s21, s21, 1
	s_add_i32 s21, s21, 32
	s_add_u32 s90, s52, s12
	s_addc_u32 s91, s53, s13
	s_add_i32 m0, s21, s82
	s_lshl_b32 s20, s20, 1
	global_load_lds_dwordx4 v184, s[90:91]
	s_add_i32 m0, s21, s83
	s_add_i32 s20, s20, 32
	global_load_lds_dwordx4 v185, s[90:91]
	s_add_i32 m0, s21, s84
	v_lshl_add_u32 v170, v114, 1, s20
	global_load_lds_dwordx4 v186, s[90:91]
	s_add_i32 m0, s21, s85
	v_lshl_add_u32 v171, v115, 1, s20
	global_load_lds_dwordx4 v187, s[90:91]
	s_add_i32 m0, s21, s86
	v_add_u32_e32 v158, v170, v136
	global_load_lds_dwordx4 v188, s[90:91]
	s_add_i32 m0, s21, s87
	v_add_u32_e32 v166, v171, v136
	global_load_lds_dwordx4 v189, s[90:91]
	s_add_i32 m0, s21, s88
	s_addk_i32 s19, 0x4000
	global_load_lds_dwordx4 v190, s[90:91]
	s_add_i32 m0, s21, s89
	s_add_u32 s12, s12, 0x80
	s_addc_u32 s13, s13, 0
	global_load_lds_dwordx4 v191, s[90:91]
	ds_read_b128 v[138:141], v158
	ds_read_b128 v[146:149], v166 offset:16384
	ds_read_b128 v[150:153], v166 offset:18432
	ds_read_b128 v[162:165], v166 offset:20480
	ds_read_b128 v[166:169], v166 offset:22528
	ds_read_b128 v[142:145], v158 offset:2048
	ds_read_b128 v[154:157], v158 offset:4096
	ds_read_b128 v[158:161], v158 offset:6144
	v_add_u32_e32 v236, v170, v137
	v_add_u32_e32 v237, v171, v137
	ds_read_b128 v[204:207], v236
	ds_read_b128 v[208:211], v237 offset:16384
	ds_read_b128 v[212:215], v237 offset:18432
	ds_read_b128 v[216:219], v237 offset:20480
	ds_read_b128 v[220:223], v237 offset:22528
	ds_read_b128 v[224:227], v236 offset:2048
	ds_read_b128 v[228:231], v236 offset:4096
	ds_read_b128 v[232:235], v236 offset:6144
	s_setprio 1
	s_waitcnt lgkmcnt(11)
	v_mfma_f32_16x16x32_bf16 v[60:63], v[138:141], v[146:149], v[60:63]
	v_mfma_f32_16x16x32_bf16 v[56:59], v[138:141], v[150:153], v[56:59]
	v_mfma_f32_16x16x32_bf16 v[52:55], v[138:141], v[162:165], v[52:55]
	v_mfma_f32_16x16x32_bf16 v[48:51], v[138:141], v[166:169], v[48:51]
	s_waitcnt lgkmcnt(10)
	v_mfma_f32_16x16x32_bf16 v[44:47], v[142:145], v[146:149], v[44:47]
	v_mfma_f32_16x16x32_bf16 v[40:43], v[142:145], v[150:153], v[40:43]
	v_mfma_f32_16x16x32_bf16 v[36:39], v[142:145], v[162:165], v[36:39]
	v_mfma_f32_16x16x32_bf16 v[32:35], v[142:145], v[166:169], v[32:35]
	s_waitcnt lgkmcnt(9)
	v_mfma_f32_16x16x32_bf16 v[28:31], v[154:157], v[146:149], v[28:31]
	v_mfma_f32_16x16x32_bf16 v[24:27], v[154:157], v[150:153], v[24:27]
	v_mfma_f32_16x16x32_bf16 v[20:23], v[154:157], v[162:165], v[20:23]
	v_mfma_f32_16x16x32_bf16 v[16:19], v[154:157], v[166:169], v[16:19]
	s_waitcnt lgkmcnt(8)
	v_mfma_f32_16x16x32_bf16 v[12:15], v[158:161], v[146:149], v[12:15]
	v_mfma_f32_16x16x32_bf16 v[8:11], v[158:161], v[150:153], v[8:11]
	v_mfma_f32_16x16x32_bf16 v[4:7], v[158:161], v[162:165], v[4:7]
	v_mfma_f32_16x16x32_bf16 v[0:3], v[158:161], v[166:169], v[0:3]
	s_waitcnt lgkmcnt(3)
	v_mfma_f32_16x16x32_bf16 v[60:63], v[204:207], v[208:211], v[60:63]
	v_mfma_f32_16x16x32_bf16 v[56:59], v[204:207], v[212:215], v[56:59]
	v_mfma_f32_16x16x32_bf16 v[52:55], v[204:207], v[216:219], v[52:55]
	v_mfma_f32_16x16x32_bf16 v[48:51], v[204:207], v[220:223], v[48:51]
	s_waitcnt lgkmcnt(2)
	v_mfma_f32_16x16x32_bf16 v[44:47], v[224:227], v[208:211], v[44:47]
	v_mfma_f32_16x16x32_bf16 v[40:43], v[224:227], v[212:215], v[40:43]
	v_mfma_f32_16x16x32_bf16 v[36:39], v[224:227], v[216:219], v[36:39]
	v_mfma_f32_16x16x32_bf16 v[32:35], v[224:227], v[220:223], v[32:35]
	s_waitcnt lgkmcnt(1)
	v_mfma_f32_16x16x32_bf16 v[28:31], v[228:231], v[208:211], v[28:31]
	v_mfma_f32_16x16x32_bf16 v[24:27], v[228:231], v[212:215], v[24:27]
	v_mfma_f32_16x16x32_bf16 v[20:23], v[228:231], v[216:219], v[20:23]
	v_mfma_f32_16x16x32_bf16 v[16:19], v[228:231], v[220:223], v[16:19]
	s_waitcnt lgkmcnt(0)
	v_mfma_f32_16x16x32_bf16 v[12:15], v[232:235], v[208:211], v[12:15]
	v_mfma_f32_16x16x32_bf16 v[8:11], v[232:235], v[212:215], v[8:11]
	v_mfma_f32_16x16x32_bf16 v[4:7], v[232:235], v[216:219], v[4:7]
	v_mfma_f32_16x16x32_bf16 v[0:3], v[232:235], v[220:223], v[0:3]
	s_setprio 0
	s_cmpk_eq_i32 s12, 0x780
	s_waitcnt vmcnt(0)
	s_barrier
	s_cbranch_scc0 .LBB0_3388
	ds_read_b128 v[90:93], v116 offset:55296
	ds_read_b128 v[94:97], v116 offset:53248
	ds_read_b128 v[98:101], v117 offset:38912
	ds_read_b128 v[102:105], v117 offset:36864
	ds_read_b128 v[138:141], v116 offset:51200
	ds_read_b128 v[142:145], v116 offset:49152
	ds_read_b128 v[146:149], v117 offset:34816
	ds_read_b128 v[150:153], v117 offset:32768
	s_setprio 1
	s_waitcnt lgkmcnt(5)
	v_mfma_f32_16x16x32_bf16 v[0:3], v[98:101], v[90:93], v[0:3]
	s_waitcnt lgkmcnt(0)
	v_mfma_f32_16x16x32_bf16 v[60:63], v[150:153], v[142:145], v[60:63]
	v_mfma_f32_16x16x32_bf16 v[56:59], v[150:153], v[138:141], v[56:59]
	v_mfma_f32_16x16x32_bf16 v[52:55], v[150:153], v[94:97], v[52:55]
	v_mfma_f32_16x16x32_bf16 v[48:51], v[150:153], v[90:93], v[48:51]
	v_mfma_f32_16x16x32_bf16 v[44:47], v[146:149], v[142:145], v[44:47]
	v_mfma_f32_16x16x32_bf16 v[40:43], v[146:149], v[138:141], v[40:43]
	v_mfma_f32_16x16x32_bf16 v[36:39], v[146:149], v[94:97], v[36:39]
	v_mfma_f32_16x16x32_bf16 v[32:35], v[146:149], v[90:93], v[32:35]
	v_mfma_f32_16x16x32_bf16 v[28:31], v[102:105], v[142:145], v[28:31]
	v_mfma_f32_16x16x32_bf16 v[24:27], v[102:105], v[138:141], v[24:27]
	v_mfma_f32_16x16x32_bf16 v[20:23], v[102:105], v[94:97], v[20:23]
	v_mfma_f32_16x16x32_bf16 v[16:19], v[102:105], v[90:93], v[16:19]
	v_mfma_f32_16x16x32_bf16 v[12:15], v[98:101], v[142:145], v[12:15]
	v_mfma_f32_16x16x32_bf16 v[8:11], v[98:101], v[138:141], v[8:11]
	v_mfma_f32_16x16x32_bf16 v[4:7], v[98:101], v[94:97], v[4:7]
	s_setprio 0
	ds_read_b128 v[90:93], v118 offset:32768
	ds_read_b128 v[94:97], v118 offset:34816
	ds_read_b128 v[98:101], v119 offset:49152
	ds_read_b128 v[102:105], v119 offset:51200
	ds_read_b128 v[138:141], v118 offset:36864
	ds_read_b128 v[142:145], v118 offset:38912
	ds_read_b128 v[146:149], v119 offset:53248
	ds_read_b128 v[150:153], v119 offset:55296
	s_setprio 1
	s_waitcnt lgkmcnt(0)
	v_mfma_f32_16x16x32_bf16 v[0:3], v[142:145], v[150:153], v[0:3]
	v_mfma_f32_16x16x32_bf16 v[60:63], v[90:93], v[98:101], v[60:63]
	v_mfma_f32_16x16x32_bf16 v[56:59], v[90:93], v[102:105], v[56:59]
	v_mfma_f32_16x16x32_bf16 v[52:55], v[90:93], v[146:149], v[52:55]
	v_mfma_f32_16x16x32_bf16 v[48:51], v[90:93], v[150:153], v[48:51]
	v_mfma_f32_16x16x32_bf16 v[44:47], v[94:97], v[98:101], v[44:47]
	v_mfma_f32_16x16x32_bf16 v[40:43], v[94:97], v[102:105], v[40:43]
	v_mfma_f32_16x16x32_bf16 v[36:39], v[94:97], v[146:149], v[36:39]
	v_mfma_f32_16x16x32_bf16 v[32:35], v[94:97], v[150:153], v[32:35]
	v_mfma_f32_16x16x32_bf16 v[28:31], v[138:141], v[98:101], v[28:31]
	v_mfma_f32_16x16x32_bf16 v[24:27], v[138:141], v[102:105], v[24:27]
	v_mfma_f32_16x16x32_bf16 v[20:23], v[138:141], v[146:149], v[20:23]
	v_mfma_f32_16x16x32_bf16 v[16:19], v[138:141], v[150:153], v[16:19]
	v_mfma_f32_16x16x32_bf16 v[12:15], v[142:145], v[98:101], v[12:15]
	v_mfma_f32_16x16x32_bf16 v[8:11], v[142:145], v[102:105], v[8:11]
	v_mfma_f32_16x16x32_bf16 v[4:7], v[142:145], v[146:149], v[4:7]
	s_setprio 0
	s_barrier
	ds_write2_b32 v120, v60, v56 offset1:16
	ds_write2_b32 v120, v61, v57 offset0:132 offset1:148
	v_add_u32_e32 v56, 0x400, v120
	ds_write2_b32 v56, v62, v58 offset0:8 offset1:24
	ds_write2_b32 v56, v63, v59 offset0:140 offset1:156
	ds_write2_b32 v120, v52, v48 offset0:32 offset1:48
	ds_write2_b32 v120, v53, v49 offset0:164 offset1:180
	ds_write2_b32 v56, v54, v50 offset0:40 offset1:56
	ds_write2_b32 v56, v55, v51 offset0:172 offset1:188
	v_add_u32_e32 v48, 0x2000, v120
	ds_write2_b32 v48, v44, v40 offset0:64 offset1:80
	ds_write2_b32 v48, v45, v41 offset0:196 offset1:212
	v_add_u32_e32 v40, 0x2400, v120
	ds_write2_b32 v40, v46, v42 offset0:72 offset1:88
	ds_write2_b32 v40, v47, v43 offset0:204 offset1:220
	ds_write2_b32 v48, v36, v32 offset0:96 offset1:112
	ds_write2_b32 v48, v37, v33 offset0:228 offset1:244
	ds_write2_b32 v40, v38, v34 offset0:104 offset1:120
	ds_write2_b32 v40, v39, v35 offset0:236 offset1:252
	v_add_u32_e32 v32, 0x4000, v120
	ds_write2_b32 v32, v28, v24 offset0:128 offset1:144
	v_add_u32_e32 v24, 0x4400, v120
	ds_write2_b32 v24, v29, v25 offset0:4 offset1:20
	ds_write2_b32 v24, v30, v26 offset0:136 offset1:152
	v_add_u32_e32 v25, 0x4800, v120
	ds_write2_b32 v25, v31, v27 offset0:12 offset1:28
	ds_write2_b32 v32, v20, v16 offset0:160 offset1:176
	ds_write2_b32 v24, v21, v17 offset0:36 offset1:52
	ds_write2_b32 v24, v22, v18 offset0:168 offset1:184
	ds_write2_b32 v25, v23, v19 offset0:44 offset1:60
	v_add_u32_e32 v16, 0x6000, v120
	ds_write2_b32 v16, v12, v8 offset0:192 offset1:208
	v_add_u32_e32 v8, 0x6400, v120
	ds_write2_b32 v8, v13, v9 offset0:68 offset1:84
	ds_write2_b32 v8, v14, v10 offset0:200 offset1:216
	v_add_u32_e32 v9, 0x6800, v120
	ds_write2_b32 v9, v15, v11 offset0:76 offset1:92
	ds_write2_b32 v16, v4, v0 offset0:224 offset1:240
	ds_write2_b32 v8, v5, v1 offset0:100 offset1:116
	ds_write2_b32 v8, v6, v2 offset0:232 offset1:248
	ds_write2_b32 v9, v7, v3 offset0:108 offset1:124
	v_or_b32_e32 v0, s18, v121
	v_ashrrev_i32_e32 v1, 31, v0
	v_lshl_add_u64 v[0:1], v[0:1], 1, s[6:7]
	v_add_u32_e32 v2, s17, v129
	s_mov_b32 s12, 0
	s_waitcnt lgkmcnt(0)
	s_barrier

.LBB0_3399:
	s_and_b32 s18, s17, 0x4000
	s_xor_b32 s19, s18, 0x4000
	s_lshl_b32 s19, s19, 1
	s_add_i32 s19, s19, 32
	s_add_u32 s90, s52, s8
	s_addc_u32 s91, s53, s9
	s_add_i32 m0, s19, s82
	s_lshl_b32 s18, s18, 1
	global_load_lds_dwordx4 v184, s[90:91]
	s_add_i32 m0, s19, s83
	s_add_i32 s18, s18, 32
	global_load_lds_dwordx4 v185, s[90:91]
	s_add_i32 m0, s19, s84
	v_lshl_add_u32 v168, v112, 1, s18
	global_load_lds_dwordx4 v186, s[90:91]
	s_add_i32 m0, s19, s85
	v_lshl_add_u32 v169, v113, 1, s18
	global_load_lds_dwordx4 v187, s[90:91]
	s_add_i32 m0, s19, s86
	v_add_u32_e32 v156, v168, v134
	global_load_lds_dwordx4 v188, s[90:91]
	s_add_i32 m0, s19, s87
	v_add_u32_e32 v164, v169, v134
	global_load_lds_dwordx4 v189, s[90:91]
	s_add_i32 m0, s19, s88
	s_addk_i32 s17, 0x4000
	global_load_lds_dwordx4 v190, s[90:91]
	s_add_i32 m0, s19, s89
	s_add_u32 s8, s8, 0x80
	s_addc_u32 s9, s9, 0
	global_load_lds_dwordx4 v191, s[90:91]
	ds_read_b128 v[136:139], v156
	ds_read_b128 v[144:147], v164 offset:16384
	ds_read_b128 v[148:151], v164 offset:18432
	ds_read_b128 v[160:163], v164 offset:20480
	ds_read_b128 v[164:167], v164 offset:22528
	ds_read_b128 v[140:143], v156 offset:2048
	ds_read_b128 v[152:155], v156 offset:4096
	ds_read_b128 v[156:159], v156 offset:6144
	v_add_u32_e32 v236, v168, v135
	v_add_u32_e32 v237, v169, v135
	ds_read_b128 v[204:207], v236
	ds_read_b128 v[208:211], v237 offset:16384
	ds_read_b128 v[212:215], v237 offset:18432
	ds_read_b128 v[216:219], v237 offset:20480
	ds_read_b128 v[220:223], v237 offset:22528
	ds_read_b128 v[224:227], v236 offset:2048
	ds_read_b128 v[228:231], v236 offset:4096
	ds_read_b128 v[232:235], v236 offset:6144
	s_setprio 1
	s_waitcnt lgkmcnt(11)
	v_mfma_f32_16x16x32_bf16 v[60:63], v[136:139], v[144:147], v[60:63]
	v_mfma_f32_16x16x32_bf16 v[56:59], v[136:139], v[148:151], v[56:59]
	v_mfma_f32_16x16x32_bf16 v[52:55], v[136:139], v[160:163], v[52:55]
	v_mfma_f32_16x16x32_bf16 v[48:51], v[136:139], v[164:167], v[48:51]
	s_waitcnt lgkmcnt(10)
	v_mfma_f32_16x16x32_bf16 v[44:47], v[140:143], v[144:147], v[44:47]
	v_mfma_f32_16x16x32_bf16 v[40:43], v[140:143], v[148:151], v[40:43]
	v_mfma_f32_16x16x32_bf16 v[36:39], v[140:143], v[160:163], v[36:39]
	v_mfma_f32_16x16x32_bf16 v[32:35], v[140:143], v[164:167], v[32:35]
	s_waitcnt lgkmcnt(9)
	v_mfma_f32_16x16x32_bf16 v[28:31], v[152:155], v[144:147], v[28:31]
	v_mfma_f32_16x16x32_bf16 v[24:27], v[152:155], v[148:151], v[24:27]
	v_mfma_f32_16x16x32_bf16 v[20:23], v[152:155], v[160:163], v[20:23]
	v_mfma_f32_16x16x32_bf16 v[16:19], v[152:155], v[164:167], v[16:19]
	s_waitcnt lgkmcnt(8)
	v_mfma_f32_16x16x32_bf16 v[12:15], v[156:159], v[144:147], v[12:15]
	v_mfma_f32_16x16x32_bf16 v[8:11], v[156:159], v[148:151], v[8:11]
	v_mfma_f32_16x16x32_bf16 v[4:7], v[156:159], v[160:163], v[4:7]
	v_mfma_f32_16x16x32_bf16 v[0:3], v[156:159], v[164:167], v[0:3]
	s_waitcnt lgkmcnt(3)
	v_mfma_f32_16x16x32_bf16 v[60:63], v[204:207], v[208:211], v[60:63]
	v_mfma_f32_16x16x32_bf16 v[56:59], v[204:207], v[212:215], v[56:59]
	v_mfma_f32_16x16x32_bf16 v[52:55], v[204:207], v[216:219], v[52:55]
	v_mfma_f32_16x16x32_bf16 v[48:51], v[204:207], v[220:223], v[48:51]
	s_waitcnt lgkmcnt(2)
	v_mfma_f32_16x16x32_bf16 v[44:47], v[224:227], v[208:211], v[44:47]
	v_mfma_f32_16x16x32_bf16 v[40:43], v[224:227], v[212:215], v[40:43]
	v_mfma_f32_16x16x32_bf16 v[36:39], v[224:227], v[216:219], v[36:39]
	v_mfma_f32_16x16x32_bf16 v[32:35], v[224:227], v[220:223], v[32:35]
	s_waitcnt lgkmcnt(1)
	v_mfma_f32_16x16x32_bf16 v[28:31], v[228:231], v[208:211], v[28:31]
	v_mfma_f32_16x16x32_bf16 v[24:27], v[228:231], v[212:215], v[24:27]
	v_mfma_f32_16x16x32_bf16 v[20:23], v[228:231], v[216:219], v[20:23]
	v_mfma_f32_16x16x32_bf16 v[16:19], v[228:231], v[220:223], v[16:19]
	s_waitcnt lgkmcnt(0)
	v_mfma_f32_16x16x32_bf16 v[12:15], v[232:235], v[208:211], v[12:15]
	v_mfma_f32_16x16x32_bf16 v[8:11], v[232:235], v[212:215], v[8:11]
	v_mfma_f32_16x16x32_bf16 v[4:7], v[232:235], v[216:219], v[4:7]
	v_mfma_f32_16x16x32_bf16 v[0:3], v[232:235], v[220:223], v[0:3]
	s_setprio 0
	s_cmpk_eq_i32 s8, 0x780
	s_waitcnt vmcnt(0)
	s_barrier
	s_cbranch_scc0 .LBB0_3399
	ds_read_b128 v[88:91], v114 offset:55296
	ds_read_b128 v[92:95], v114 offset:53248
	ds_read_b128 v[96:99], v115 offset:38912
	ds_read_b128 v[100:103], v115 offset:36864
	ds_read_b128 v[136:139], v114 offset:51200
	ds_read_b128 v[140:143], v114 offset:49152
	ds_read_b128 v[144:147], v115 offset:34816
	ds_read_b128 v[148:151], v115 offset:32768
	s_setprio 1
	s_waitcnt lgkmcnt(5)
	v_mfma_f32_16x16x32_bf16 v[0:3], v[96:99], v[88:91], v[0:3]
	s_waitcnt lgkmcnt(0)
	v_mfma_f32_16x16x32_bf16 v[60:63], v[148:151], v[140:143], v[60:63]
	v_mfma_f32_16x16x32_bf16 v[56:59], v[148:151], v[136:139], v[56:59]
	v_mfma_f32_16x16x32_bf16 v[52:55], v[148:151], v[92:95], v[52:55]
	v_mfma_f32_16x16x32_bf16 v[48:51], v[148:151], v[88:91], v[48:51]
	v_mfma_f32_16x16x32_bf16 v[44:47], v[144:147], v[140:143], v[44:47]
	v_mfma_f32_16x16x32_bf16 v[40:43], v[144:147], v[136:139], v[40:43]
	v_mfma_f32_16x16x32_bf16 v[36:39], v[144:147], v[92:95], v[36:39]
	v_mfma_f32_16x16x32_bf16 v[32:35], v[144:147], v[88:91], v[32:35]
	v_mfma_f32_16x16x32_bf16 v[28:31], v[100:103], v[140:143], v[28:31]
	v_mfma_f32_16x16x32_bf16 v[24:27], v[100:103], v[136:139], v[24:27]
	v_mfma_f32_16x16x32_bf16 v[20:23], v[100:103], v[92:95], v[20:23]
	v_mfma_f32_16x16x32_bf16 v[16:19], v[100:103], v[88:91], v[16:19]
	v_mfma_f32_16x16x32_bf16 v[12:15], v[96:99], v[140:143], v[12:15]
	v_mfma_f32_16x16x32_bf16 v[8:11], v[96:99], v[136:139], v[8:11]
	v_mfma_f32_16x16x32_bf16 v[4:7], v[96:99], v[92:95], v[4:7]
	s_setprio 0
	ds_read_b128 v[88:91], v116 offset:32768
	ds_read_b128 v[92:95], v116 offset:34816
	ds_read_b128 v[96:99], v117 offset:49152
	ds_read_b128 v[100:103], v117 offset:51200
	ds_read_b128 v[136:139], v116 offset:36864
	ds_read_b128 v[140:143], v116 offset:38912
	ds_read_b128 v[144:147], v117 offset:53248
	ds_read_b128 v[148:151], v117 offset:55296
	s_setprio 1
	s_waitcnt lgkmcnt(0)
	v_mfma_f32_16x16x32_bf16 v[0:3], v[140:143], v[148:151], v[0:3]
	v_mfma_f32_16x16x32_bf16 v[60:63], v[88:91], v[96:99], v[60:63]
	v_mfma_f32_16x16x32_bf16 v[56:59], v[88:91], v[100:103], v[56:59]
	v_mfma_f32_16x16x32_bf16 v[52:55], v[88:91], v[144:147], v[52:55]
	v_mfma_f32_16x16x32_bf16 v[48:51], v[88:91], v[148:151], v[48:51]
	v_mfma_f32_16x16x32_bf16 v[44:47], v[92:95], v[96:99], v[44:47]
	v_mfma_f32_16x16x32_bf16 v[40:43], v[92:95], v[100:103], v[40:43]
	v_mfma_f32_16x16x32_bf16 v[36:39], v[92:95], v[144:147], v[36:39]
	v_mfma_f32_16x16x32_bf16 v[32:35], v[92:95], v[148:151], v[32:35]
	v_mfma_f32_16x16x32_bf16 v[28:31], v[136:139], v[96:99], v[28:31]
	v_mfma_f32_16x16x32_bf16 v[24:27], v[136:139], v[100:103], v[24:27]
	v_mfma_f32_16x16x32_bf16 v[20:23], v[136:139], v[144:147], v[20:23]
	v_mfma_f32_16x16x32_bf16 v[16:19], v[136:139], v[148:151], v[16:19]
	v_mfma_f32_16x16x32_bf16 v[12:15], v[140:143], v[96:99], v[12:15]
	v_mfma_f32_16x16x32_bf16 v[8:11], v[140:143], v[100:103], v[8:11]
	v_mfma_f32_16x16x32_bf16 v[4:7], v[140:143], v[144:147], v[4:7]
	s_setprio 0
	s_barrier
	ds_write2_b32 v118, v60, v56 offset1:16
	ds_write2_b32 v118, v61, v57 offset0:132 offset1:148
	v_add_u32_e32 v56, 0x400, v118
	ds_write2_b32 v56, v62, v58 offset0:8 offset1:24
	ds_write2_b32 v56, v63, v59 offset0:140 offset1:156
	ds_write2_b32 v118, v52, v48 offset0:32 offset1:48
	ds_write2_b32 v118, v53, v49 offset0:164 offset1:180
	ds_write2_b32 v56, v54, v50 offset0:40 offset1:56
	ds_write2_b32 v56, v55, v51 offset0:172 offset1:188
	v_add_u32_e32 v48, 0x2000, v118
	ds_write2_b32 v48, v44, v40 offset0:64 offset1:80
	ds_write2_b32 v48, v45, v41 offset0:196 offset1:212
	v_add_u32_e32 v40, 0x2400, v118
	ds_write2_b32 v40, v46, v42 offset0:72 offset1:88
	ds_write2_b32 v40, v47, v43 offset0:204 offset1:220
	ds_write2_b32 v48, v36, v32 offset0:96 offset1:112
	ds_write2_b32 v48, v37, v33 offset0:228 offset1:244
	ds_write2_b32 v40, v38, v34 offset0:104 offset1:120
	ds_write2_b32 v40, v39, v35 offset0:236 offset1:252
	v_add_u32_e32 v32, 0x4000, v118
	ds_write2_b32 v32, v28, v24 offset0:128 offset1:144
	v_add_u32_e32 v24, 0x4400, v118
	ds_write2_b32 v24, v29, v25 offset0:4 offset1:20
	ds_write2_b32 v24, v30, v26 offset0:136 offset1:152
	v_add_u32_e32 v25, 0x4800, v118
	ds_write2_b32 v25, v31, v27 offset0:12 offset1:28
	ds_write2_b32 v32, v20, v16 offset0:160 offset1:176
	ds_write2_b32 v24, v21, v17 offset0:36 offset1:52
	ds_write2_b32 v24, v22, v18 offset0:168 offset1:184
	ds_write2_b32 v25, v23, v19 offset0:44 offset1:60
	v_add_u32_e32 v16, 0x6000, v118
	ds_write2_b32 v16, v12, v8 offset0:192 offset1:208
	v_add_u32_e32 v8, 0x6400, v118
	ds_write2_b32 v8, v13, v9 offset0:68 offset1:84
	ds_write2_b32 v8, v14, v10 offset0:200 offset1:216
	v_add_u32_e32 v9, 0x6800, v118
	ds_write2_b32 v9, v15, v11 offset0:76 offset1:92
	ds_write2_b32 v16, v4, v0 offset0:224 offset1:240
	ds_write2_b32 v8, v5, v1 offset0:100 offset1:116
	ds_write2_b32 v8, v6, v2 offset0:232 offset1:248
	ds_write2_b32 v9, v7, v3 offset0:108 offset1:124
	v_or_b32_e32 v0, s16, v119
	v_ashrrev_i32_e32 v1, 31, v0
	v_lshl_add_u64 v[0:1], v[0:1], 1, s[6:7]
	v_add_u32_e32 v2, s15, v127
	s_mov_b32 s8, 0
	s_waitcnt lgkmcnt(0)
	s_barrier

.LBB0_3463:
	s_and_b32 s27, s26, 0x4000
	s_xor_b32 s28, s27, 0x4000
	s_lshl_b32 s28, s28, 1
	s_add_i32 s28, s28, 32
	s_add_u32 s90, s52, s16
	s_addc_u32 s91, s53, s17
	s_add_i32 m0, s28, s82
	s_lshl_b32 s27, s27, 1
	global_load_lds_dwordx4 v184, s[90:91]
	s_add_i32 m0, s28, s83
	s_add_i32 s27, s27, 32
	global_load_lds_dwordx4 v185, s[90:91]
	s_add_i32 m0, s28, s84
	v_add3_u32 v139, s27, v114, v136
	global_load_lds_dwordx4 v186, s[90:91]
	s_add_i32 m0, s28, s85
	v_add3_u32 v172, s27, v115, v136
	global_load_lds_dwordx4 v187, s[90:91]
	s_add_i32 m0, s28, s86
	v_add_u32_e32 v160, v139, v137
	global_load_lds_dwordx4 v188, s[90:91]
	s_add_i32 m0, s28, s87
	v_add_u32_e32 v168, v172, v137
	global_load_lds_dwordx4 v189, s[90:91]
	s_add_i32 m0, s28, s88
	s_addk_i32 s26, 0x4000
	global_load_lds_dwordx4 v190, s[90:91]
	s_add_i32 m0, s28, s89
	s_add_u32 s16, s16, 0x80
	s_addc_u32 s17, s17, 0
	global_load_lds_dwordx4 v191, s[90:91]
	ds_read_b128 v[140:143], v160
	ds_read_b128 v[148:151], v168 offset:16384
	ds_read_b128 v[152:155], v168 offset:18432
	ds_read_b128 v[164:167], v168 offset:20480
	ds_read_b128 v[168:171], v168 offset:22528
	ds_read_b128 v[144:147], v160 offset:2048
	ds_read_b128 v[156:159], v160 offset:4096
	ds_read_b128 v[160:163], v160 offset:6144
	v_add_u32_e32 v139, v139, v138
	v_add_u32_e32 v236, v172, v138
	ds_read_b128 v[204:207], v139
	ds_read_b128 v[208:211], v236 offset:16384
	ds_read_b128 v[212:215], v236 offset:18432
	ds_read_b128 v[216:219], v236 offset:20480
	ds_read_b128 v[220:223], v236 offset:22528
	ds_read_b128 v[224:227], v139 offset:2048
	ds_read_b128 v[228:231], v139 offset:4096
	ds_read_b128 v[232:235], v139 offset:6144
	s_setprio 1
	s_waitcnt lgkmcnt(11)
	v_mfma_f32_16x16x32_bf16 v[60:63], v[140:143], v[148:151], v[60:63]
	v_mfma_f32_16x16x32_bf16 v[56:59], v[140:143], v[152:155], v[56:59]
	v_mfma_f32_16x16x32_bf16 v[52:55], v[140:143], v[164:167], v[52:55]
	v_mfma_f32_16x16x32_bf16 v[48:51], v[140:143], v[168:171], v[48:51]
	s_waitcnt lgkmcnt(10)
	v_mfma_f32_16x16x32_bf16 v[44:47], v[144:147], v[148:151], v[44:47]
	v_mfma_f32_16x16x32_bf16 v[40:43], v[144:147], v[152:155], v[40:43]
	v_mfma_f32_16x16x32_bf16 v[36:39], v[144:147], v[164:167], v[36:39]
	v_mfma_f32_16x16x32_bf16 v[32:35], v[144:147], v[168:171], v[32:35]
	s_waitcnt lgkmcnt(9)
	v_mfma_f32_16x16x32_bf16 v[28:31], v[156:159], v[148:151], v[28:31]
	v_mfma_f32_16x16x32_bf16 v[24:27], v[156:159], v[152:155], v[24:27]
	v_mfma_f32_16x16x32_bf16 v[20:23], v[156:159], v[164:167], v[20:23]
	v_mfma_f32_16x16x32_bf16 v[16:19], v[156:159], v[168:171], v[16:19]
	s_waitcnt lgkmcnt(8)
	v_mfma_f32_16x16x32_bf16 v[12:15], v[160:163], v[148:151], v[12:15]
	v_mfma_f32_16x16x32_bf16 v[8:11], v[160:163], v[152:155], v[8:11]
	v_mfma_f32_16x16x32_bf16 v[4:7], v[160:163], v[164:167], v[4:7]
	v_mfma_f32_16x16x32_bf16 v[0:3], v[160:163], v[168:171], v[0:3]
	s_waitcnt lgkmcnt(3)
	v_mfma_f32_16x16x32_bf16 v[60:63], v[204:207], v[208:211], v[60:63]
	v_mfma_f32_16x16x32_bf16 v[56:59], v[204:207], v[212:215], v[56:59]
	v_mfma_f32_16x16x32_bf16 v[52:55], v[204:207], v[216:219], v[52:55]
	v_mfma_f32_16x16x32_bf16 v[48:51], v[204:207], v[220:223], v[48:51]
	s_waitcnt lgkmcnt(2)
	v_mfma_f32_16x16x32_bf16 v[44:47], v[224:227], v[208:211], v[44:47]
	v_mfma_f32_16x16x32_bf16 v[40:43], v[224:227], v[212:215], v[40:43]
	v_mfma_f32_16x16x32_bf16 v[36:39], v[224:227], v[216:219], v[36:39]
	v_mfma_f32_16x16x32_bf16 v[32:35], v[224:227], v[220:223], v[32:35]
	s_waitcnt lgkmcnt(1)
	v_mfma_f32_16x16x32_bf16 v[28:31], v[228:231], v[208:211], v[28:31]
	v_mfma_f32_16x16x32_bf16 v[24:27], v[228:231], v[212:215], v[24:27]
	v_mfma_f32_16x16x32_bf16 v[20:23], v[228:231], v[216:219], v[20:23]
	v_mfma_f32_16x16x32_bf16 v[16:19], v[228:231], v[220:223], v[16:19]
	s_waitcnt lgkmcnt(0)
	v_mfma_f32_16x16x32_bf16 v[12:15], v[232:235], v[208:211], v[12:15]
	v_mfma_f32_16x16x32_bf16 v[8:11], v[232:235], v[212:215], v[8:11]
	v_mfma_f32_16x16x32_bf16 v[4:7], v[232:235], v[216:219], v[4:7]
	v_mfma_f32_16x16x32_bf16 v[0:3], v[232:235], v[220:223], v[0:3]
	s_setprio 0
	s_cmpk_eq_i32 s16, 0x1f80
	s_waitcnt vmcnt(0)
	s_barrier
	s_cbranch_scc0 .LBB0_3463
	ds_read_b128 v[90:93], v118 offset:55296
	ds_read_b128 v[94:97], v118 offset:53248
	ds_read_b128 v[98:101], v119 offset:38912
	ds_read_b128 v[102:105], v119 offset:36864
	ds_read_b128 v[140:143], v118 offset:51200
	ds_read_b128 v[144:147], v118 offset:49152
	ds_read_b128 v[148:151], v119 offset:34816
	ds_read_b128 v[152:155], v119 offset:32768
	s_setprio 1
	s_waitcnt lgkmcnt(5)
	v_mfma_f32_16x16x32_bf16 v[4:7], v[98:101], v[94:97], v[4:7]
	v_mfma_f32_16x16x32_bf16 v[0:3], v[98:101], v[90:93], v[0:3]
	s_waitcnt lgkmcnt(0)
	v_mfma_f32_16x16x32_bf16 v[60:63], v[152:155], v[144:147], v[60:63]
	v_mfma_f32_16x16x32_bf16 v[56:59], v[152:155], v[140:143], v[56:59]
	v_mfma_f32_16x16x32_bf16 v[52:55], v[152:155], v[94:97], v[52:55]
	v_mfma_f32_16x16x32_bf16 v[48:51], v[152:155], v[90:93], v[48:51]
	v_mfma_f32_16x16x32_bf16 v[44:47], v[148:151], v[144:147], v[44:47]
	v_mfma_f32_16x16x32_bf16 v[40:43], v[148:151], v[140:143], v[40:43]
	v_mfma_f32_16x16x32_bf16 v[36:39], v[148:151], v[94:97], v[36:39]
	v_mfma_f32_16x16x32_bf16 v[32:35], v[148:151], v[90:93], v[32:35]
	v_mfma_f32_16x16x32_bf16 v[28:31], v[102:105], v[144:147], v[28:31]
	v_mfma_f32_16x16x32_bf16 v[24:27], v[102:105], v[140:143], v[24:27]
	v_mfma_f32_16x16x32_bf16 v[20:23], v[102:105], v[94:97], v[20:23]
	v_mfma_f32_16x16x32_bf16 v[16:19], v[102:105], v[90:93], v[16:19]
	v_mfma_f32_16x16x32_bf16 v[12:15], v[98:101], v[144:147], v[12:15]
	v_mfma_f32_16x16x32_bf16 v[8:11], v[98:101], v[140:143], v[8:11]
	s_setprio 0
	ds_read_b128 v[90:93], v120 offset:32768
	ds_read_b128 v[94:97], v120 offset:34816
	ds_read_b128 v[98:101], v121 offset:49152
	ds_read_b128 v[102:105], v121 offset:51200
	ds_read_b128 v[140:143], v120 offset:36864
	ds_read_b128 v[144:147], v120 offset:38912
	ds_read_b128 v[148:151], v121 offset:53248
	ds_read_b128 v[152:155], v121 offset:55296
	s_setprio 1
	s_waitcnt lgkmcnt(1)
	v_mfma_f32_16x16x32_bf16 v[4:7], v[144:147], v[148:151], v[4:7]
	s_waitcnt lgkmcnt(0)
	v_mfma_f32_16x16x32_bf16 v[0:3], v[144:147], v[152:155], v[0:3]
	v_mfma_f32_16x16x32_bf16 v[60:63], v[90:93], v[98:101], v[60:63]
	v_mfma_f32_16x16x32_bf16 v[56:59], v[90:93], v[102:105], v[56:59]
	v_mfma_f32_16x16x32_bf16 v[52:55], v[90:93], v[148:151], v[52:55]
	v_mfma_f32_16x16x32_bf16 v[48:51], v[90:93], v[152:155], v[48:51]
	v_mfma_f32_16x16x32_bf16 v[44:47], v[94:97], v[98:101], v[44:47]
	v_mfma_f32_16x16x32_bf16 v[40:43], v[94:97], v[102:105], v[40:43]
	v_mfma_f32_16x16x32_bf16 v[36:39], v[94:97], v[148:151], v[36:39]
	v_mfma_f32_16x16x32_bf16 v[32:35], v[94:97], v[152:155], v[32:35]
	v_mfma_f32_16x16x32_bf16 v[28:31], v[140:143], v[98:101], v[28:31]
	v_mfma_f32_16x16x32_bf16 v[24:27], v[140:143], v[102:105], v[24:27]
	v_mfma_f32_16x16x32_bf16 v[20:23], v[140:143], v[148:151], v[20:23]
	v_mfma_f32_16x16x32_bf16 v[16:19], v[140:143], v[152:155], v[16:19]
	v_mfma_f32_16x16x32_bf16 v[12:15], v[144:147], v[98:101], v[12:15]
	v_mfma_f32_16x16x32_bf16 v[8:11], v[144:147], v[102:105], v[8:11]
	s_setprio 0
	s_barrier
	ds_write2_b32 v116, v60, v56 offset1:16
	ds_write2_b32 v116, v61, v57 offset0:132 offset1:148
	v_add_u32_e32 v56, 0x400, v116
	ds_write2_b32 v56, v62, v58 offset0:8 offset1:24
	ds_write2_b32 v56, v63, v59 offset0:140 offset1:156
	ds_write2_b32 v116, v52, v48 offset0:32 offset1:48
	ds_write2_b32 v116, v53, v49 offset0:164 offset1:180
	ds_write2_b32 v56, v54, v50 offset0:40 offset1:56
	ds_write2_b32 v56, v55, v51 offset0:172 offset1:188
	v_add_u32_e32 v48, 0x2000, v116
	ds_write2_b32 v48, v44, v40 offset0:64 offset1:80
	ds_write2_b32 v48, v45, v41 offset0:196 offset1:212
	v_add_u32_e32 v40, 0x2400, v116
	ds_write2_b32 v40, v46, v42 offset0:72 offset1:88
	ds_write2_b32 v40, v47, v43 offset0:204 offset1:220
	ds_write2_b32 v48, v36, v32 offset0:96 offset1:112
	ds_write2_b32 v48, v37, v33 offset0:228 offset1:244
	ds_write2_b32 v40, v38, v34 offset0:104 offset1:120
	ds_write2_b32 v40, v39, v35 offset0:236 offset1:252
	v_add_u32_e32 v32, 0x4000, v116
	ds_write2_b32 v32, v28, v24 offset0:128 offset1:144
	v_add_u32_e32 v24, 0x4400, v116
	ds_write2_b32 v24, v29, v25 offset0:4 offset1:20
	ds_write2_b32 v24, v30, v26 offset0:136 offset1:152
	v_add_u32_e32 v25, 0x4800, v116
	ds_write2_b32 v25, v31, v27 offset0:12 offset1:28
	ds_write2_b32 v32, v20, v16 offset0:160 offset1:176
	ds_write2_b32 v24, v21, v17 offset0:36 offset1:52
	ds_write2_b32 v24, v22, v18 offset0:168 offset1:184
	ds_write2_b32 v25, v23, v19 offset0:44 offset1:60
	v_add_u32_e32 v16, 0x6000, v116
	ds_write2_b32 v16, v12, v8 offset0:192 offset1:208
	v_add_u32_e32 v8, 0x6400, v116
	ds_write2_b32 v8, v13, v9 offset0:68 offset1:84
	ds_write2_b32 v8, v14, v10 offset0:200 offset1:216
	v_add_u32_e32 v9, 0x6800, v116
	ds_write2_b32 v9, v15, v11 offset0:76 offset1:92
	ds_write2_b32 v16, v4, v0 offset0:224 offset1:240
	ds_write2_b32 v8, v5, v1 offset0:100 offset1:116
	ds_write2_b32 v8, v6, v2 offset0:232 offset1:248
	ds_write2_b32 v9, v7, v3 offset0:108 offset1:124
	v_or_b32_e32 v0, s25, v117
	v_ashrrev_i32_e32 v1, 31, v0
	v_lshlrev_b64 v[2:3], 2, v[0:1]
	v_lshl_add_u64 v[0:1], s[14:15], 0, v[2:3]
	v_lshl_add_u64 v[2:3], s[6:7], 0, v[2:3]
	v_add_u32_e32 v4, s24, v129
	s_mov_b32 s16, 0
	s_waitcnt lgkmcnt(0)
	s_barrier

.LBB0_3472:
	s_and_b32 s23, s22, 0x4000
	s_xor_b32 s24, s23, 0x4000
	s_lshl_b32 s24, s24, 1
	s_add_i32 s24, s24, 32
	s_add_u32 s90, s52, s8
	s_addc_u32 s91, s53, s9
	s_add_i32 m0, s24, s82
	s_lshl_b32 s23, s23, 1
	global_load_lds_dwordx4 v184, s[90:91]
	s_add_i32 m0, s24, s83
	s_add_i32 s23, s23, 32
	global_load_lds_dwordx4 v185, s[90:91]
	s_add_i32 m0, s24, s84
	v_add3_u32 v170, s23, v112, v135
	global_load_lds_dwordx4 v186, s[90:91]
	s_add_i32 m0, s24, s85
	v_add3_u32 v171, s23, v113, v135
	global_load_lds_dwordx4 v187, s[90:91]
	s_add_i32 m0, s24, s86
	v_add_u32_e32 v158, v170, v136
	global_load_lds_dwordx4 v188, s[90:91]
	s_add_i32 m0, s24, s87
	v_add_u32_e32 v166, v171, v136
	global_load_lds_dwordx4 v189, s[90:91]
	s_add_i32 m0, s24, s88
	s_addk_i32 s22, 0x4000
	global_load_lds_dwordx4 v190, s[90:91]
	s_add_i32 m0, s24, s89
	s_add_u32 s8, s8, 0x80
	s_addc_u32 s9, s9, 0
	global_load_lds_dwordx4 v191, s[90:91]
	ds_read_b128 v[138:141], v158
	ds_read_b128 v[146:149], v166 offset:16384
	ds_read_b128 v[150:153], v166 offset:18432
	ds_read_b128 v[162:165], v166 offset:20480
	ds_read_b128 v[166:169], v166 offset:22528
	ds_read_b128 v[142:145], v158 offset:2048
	ds_read_b128 v[154:157], v158 offset:4096
	ds_read_b128 v[158:161], v158 offset:6144
	v_add_u32_e32 v236, v170, v137
	v_add_u32_e32 v237, v171, v137
	ds_read_b128 v[204:207], v236
	ds_read_b128 v[208:211], v237 offset:16384
	ds_read_b128 v[212:215], v237 offset:18432
	ds_read_b128 v[216:219], v237 offset:20480
	ds_read_b128 v[220:223], v237 offset:22528
	ds_read_b128 v[224:227], v236 offset:2048
	ds_read_b128 v[228:231], v236 offset:4096
	ds_read_b128 v[232:235], v236 offset:6144
	s_setprio 1
	s_waitcnt lgkmcnt(11)
	v_mfma_f32_16x16x32_bf16 v[60:63], v[138:141], v[146:149], v[60:63]
	v_mfma_f32_16x16x32_bf16 v[56:59], v[138:141], v[150:153], v[56:59]
	v_mfma_f32_16x16x32_bf16 v[52:55], v[138:141], v[162:165], v[52:55]
	v_mfma_f32_16x16x32_bf16 v[48:51], v[138:141], v[166:169], v[48:51]
	s_waitcnt lgkmcnt(10)
	v_mfma_f32_16x16x32_bf16 v[44:47], v[142:145], v[146:149], v[44:47]
	v_mfma_f32_16x16x32_bf16 v[40:43], v[142:145], v[150:153], v[40:43]
	v_mfma_f32_16x16x32_bf16 v[36:39], v[142:145], v[162:165], v[36:39]
	v_mfma_f32_16x16x32_bf16 v[32:35], v[142:145], v[166:169], v[32:35]
	s_waitcnt lgkmcnt(9)
	v_mfma_f32_16x16x32_bf16 v[28:31], v[154:157], v[146:149], v[28:31]
	v_mfma_f32_16x16x32_bf16 v[24:27], v[154:157], v[150:153], v[24:27]
	v_mfma_f32_16x16x32_bf16 v[20:23], v[154:157], v[162:165], v[20:23]
	v_mfma_f32_16x16x32_bf16 v[16:19], v[154:157], v[166:169], v[16:19]
	s_waitcnt lgkmcnt(8)
	v_mfma_f32_16x16x32_bf16 v[12:15], v[158:161], v[146:149], v[12:15]
	v_mfma_f32_16x16x32_bf16 v[8:11], v[158:161], v[150:153], v[8:11]
	v_mfma_f32_16x16x32_bf16 v[4:7], v[158:161], v[162:165], v[4:7]
	v_mfma_f32_16x16x32_bf16 v[0:3], v[158:161], v[166:169], v[0:3]
	s_waitcnt lgkmcnt(3)
	v_mfma_f32_16x16x32_bf16 v[60:63], v[204:207], v[208:211], v[60:63]
	v_mfma_f32_16x16x32_bf16 v[56:59], v[204:207], v[212:215], v[56:59]
	v_mfma_f32_16x16x32_bf16 v[52:55], v[204:207], v[216:219], v[52:55]
	v_mfma_f32_16x16x32_bf16 v[48:51], v[204:207], v[220:223], v[48:51]
	s_waitcnt lgkmcnt(2)
	v_mfma_f32_16x16x32_bf16 v[44:47], v[224:227], v[208:211], v[44:47]
	v_mfma_f32_16x16x32_bf16 v[40:43], v[224:227], v[212:215], v[40:43]
	v_mfma_f32_16x16x32_bf16 v[36:39], v[224:227], v[216:219], v[36:39]
	v_mfma_f32_16x16x32_bf16 v[32:35], v[224:227], v[220:223], v[32:35]
	s_waitcnt lgkmcnt(1)
	v_mfma_f32_16x16x32_bf16 v[28:31], v[228:231], v[208:211], v[28:31]
	v_mfma_f32_16x16x32_bf16 v[24:27], v[228:231], v[212:215], v[24:27]
	v_mfma_f32_16x16x32_bf16 v[20:23], v[228:231], v[216:219], v[20:23]
	v_mfma_f32_16x16x32_bf16 v[16:19], v[228:231], v[220:223], v[16:19]
	s_waitcnt lgkmcnt(0)
	v_mfma_f32_16x16x32_bf16 v[12:15], v[232:235], v[208:211], v[12:15]
	v_mfma_f32_16x16x32_bf16 v[8:11], v[232:235], v[212:215], v[8:11]
	v_mfma_f32_16x16x32_bf16 v[4:7], v[232:235], v[216:219], v[4:7]
	v_mfma_f32_16x16x32_bf16 v[0:3], v[232:235], v[220:223], v[0:3]
	s_setprio 0
	s_cmpk_eq_i32 s8, 0x1f80
	s_waitcnt vmcnt(0)
	s_barrier
	s_cbranch_scc0 .LBB0_3472
	ds_read_b128 v[88:91], v116 offset:55296
	ds_read_b128 v[92:95], v116 offset:53248
	ds_read_b128 v[96:99], v117 offset:38912
	ds_read_b128 v[100:103], v117 offset:36864
	ds_read_b128 v[138:141], v116 offset:51200
	ds_read_b128 v[142:145], v116 offset:49152
	ds_read_b128 v[146:149], v117 offset:34816
	ds_read_b128 v[150:153], v117 offset:32768
	s_setprio 1
	s_waitcnt lgkmcnt(5)
	v_mfma_f32_16x16x32_bf16 v[4:7], v[96:99], v[92:95], v[4:7]
	v_mfma_f32_16x16x32_bf16 v[0:3], v[96:99], v[88:91], v[0:3]
	s_waitcnt lgkmcnt(0)
	v_mfma_f32_16x16x32_bf16 v[60:63], v[150:153], v[142:145], v[60:63]
	v_mfma_f32_16x16x32_bf16 v[56:59], v[150:153], v[138:141], v[56:59]
	v_mfma_f32_16x16x32_bf16 v[52:55], v[150:153], v[92:95], v[52:55]
	v_mfma_f32_16x16x32_bf16 v[48:51], v[150:153], v[88:91], v[48:51]
	v_mfma_f32_16x16x32_bf16 v[44:47], v[146:149], v[142:145], v[44:47]
	v_mfma_f32_16x16x32_bf16 v[40:43], v[146:149], v[138:141], v[40:43]
	v_mfma_f32_16x16x32_bf16 v[36:39], v[146:149], v[92:95], v[36:39]
	v_mfma_f32_16x16x32_bf16 v[32:35], v[146:149], v[88:91], v[32:35]
	v_mfma_f32_16x16x32_bf16 v[28:31], v[100:103], v[142:145], v[28:31]
	v_mfma_f32_16x16x32_bf16 v[24:27], v[100:103], v[138:141], v[24:27]
	v_mfma_f32_16x16x32_bf16 v[20:23], v[100:103], v[92:95], v[20:23]
	v_mfma_f32_16x16x32_bf16 v[16:19], v[100:103], v[88:91], v[16:19]
	v_mfma_f32_16x16x32_bf16 v[12:15], v[96:99], v[142:145], v[12:15]
	v_mfma_f32_16x16x32_bf16 v[8:11], v[96:99], v[138:141], v[8:11]
	s_setprio 0
	ds_read_b128 v[88:91], v118 offset:32768
	ds_read_b128 v[92:95], v118 offset:34816
	ds_read_b128 v[96:99], v119 offset:49152
	ds_read_b128 v[100:103], v119 offset:51200
	ds_read_b128 v[138:141], v118 offset:36864
	ds_read_b128 v[142:145], v118 offset:38912
	ds_read_b128 v[146:149], v119 offset:53248
	ds_read_b128 v[150:153], v119 offset:55296
	s_setprio 1
	s_waitcnt lgkmcnt(1)
	v_mfma_f32_16x16x32_bf16 v[4:7], v[142:145], v[146:149], v[4:7]
	s_waitcnt lgkmcnt(0)
	v_mfma_f32_16x16x32_bf16 v[0:3], v[142:145], v[150:153], v[0:3]
	v_mfma_f32_16x16x32_bf16 v[60:63], v[88:91], v[96:99], v[60:63]
	v_mfma_f32_16x16x32_bf16 v[56:59], v[88:91], v[100:103], v[56:59]
	v_mfma_f32_16x16x32_bf16 v[52:55], v[88:91], v[146:149], v[52:55]
	v_mfma_f32_16x16x32_bf16 v[48:51], v[88:91], v[150:153], v[48:51]
	v_mfma_f32_16x16x32_bf16 v[44:47], v[92:95], v[96:99], v[44:47]
	v_mfma_f32_16x16x32_bf16 v[40:43], v[92:95], v[100:103], v[40:43]
	v_mfma_f32_16x16x32_bf16 v[36:39], v[92:95], v[146:149], v[36:39]
	v_mfma_f32_16x16x32_bf16 v[32:35], v[92:95], v[150:153], v[32:35]
	v_mfma_f32_16x16x32_bf16 v[28:31], v[138:141], v[96:99], v[28:31]
	v_mfma_f32_16x16x32_bf16 v[24:27], v[138:141], v[100:103], v[24:27]
	v_mfma_f32_16x16x32_bf16 v[20:23], v[138:141], v[146:149], v[20:23]
	v_mfma_f32_16x16x32_bf16 v[16:19], v[138:141], v[150:153], v[16:19]
	v_mfma_f32_16x16x32_bf16 v[12:15], v[142:145], v[96:99], v[12:15]
	v_mfma_f32_16x16x32_bf16 v[8:11], v[142:145], v[100:103], v[8:11]
	s_setprio 0
	s_barrier
	ds_write2_b32 v114, v60, v56 offset1:16
	ds_write2_b32 v114, v61, v57 offset0:132 offset1:148
	v_add_u32_e32 v56, 0x400, v114
	ds_write2_b32 v56, v62, v58 offset0:8 offset1:24
	ds_write2_b32 v56, v63, v59 offset0:140 offset1:156
	ds_write2_b32 v114, v52, v48 offset0:32 offset1:48
	ds_write2_b32 v114, v53, v49 offset0:164 offset1:180
	ds_write2_b32 v56, v54, v50 offset0:40 offset1:56
	ds_write2_b32 v56, v55, v51 offset0:172 offset1:188
	v_add_u32_e32 v48, 0x2000, v114
	ds_write2_b32 v48, v44, v40 offset0:64 offset1:80
	ds_write2_b32 v48, v45, v41 offset0:196 offset1:212
	v_add_u32_e32 v40, 0x2400, v114
	ds_write2_b32 v40, v46, v42 offset0:72 offset1:88
	ds_write2_b32 v40, v47, v43 offset0:204 offset1:220
	ds_write2_b32 v48, v36, v32 offset0:96 offset1:112
	ds_write2_b32 v48, v37, v33 offset0:228 offset1:244
	ds_write2_b32 v40, v38, v34 offset0:104 offset1:120
	ds_write2_b32 v40, v39, v35 offset0:236 offset1:252
	v_add_u32_e32 v32, 0x4000, v114
	ds_write2_b32 v32, v28, v24 offset0:128 offset1:144
	v_add_u32_e32 v24, 0x4400, v114
	ds_write2_b32 v24, v29, v25 offset0:4 offset1:20
	ds_write2_b32 v24, v30, v26 offset0:136 offset1:152
	v_add_u32_e32 v25, 0x4800, v114
	ds_write2_b32 v25, v31, v27 offset0:12 offset1:28
	ds_write2_b32 v32, v20, v16 offset0:160 offset1:176
	ds_write2_b32 v24, v21, v17 offset0:36 offset1:52
	ds_write2_b32 v24, v22, v18 offset0:168 offset1:184
	ds_write2_b32 v25, v23, v19 offset0:44 offset1:60
	v_add_u32_e32 v16, 0x6000, v114
	ds_write2_b32 v16, v12, v8 offset0:192 offset1:208
	v_add_u32_e32 v8, 0x6400, v114
	ds_write2_b32 v8, v13, v9 offset0:68 offset1:84
	ds_write2_b32 v8, v14, v10 offset0:200 offset1:216
	v_add_u32_e32 v9, 0x6800, v114
	ds_write2_b32 v9, v15, v11 offset0:76 offset1:92
	ds_write2_b32 v16, v4, v0 offset0:224 offset1:240
	ds_write2_b32 v8, v5, v1 offset0:100 offset1:116
	ds_write2_b32 v8, v6, v2 offset0:232 offset1:248
	ds_write2_b32 v9, v7, v3 offset0:108 offset1:124
	v_or_b32_e32 v0, s21, v115
	v_ashrrev_i32_e32 v1, 31, v0
	v_lshlrev_b64 v[2:3], 2, v[0:1]
	v_lshl_add_u64 v[0:1], s[10:11], 0, v[2:3]
	v_lshl_add_u64 v[2:3], s[6:7], 0, v[2:3]
	v_add_u32_e32 v4, s20, v128
	s_mov_b32 s8, 0
	s_waitcnt lgkmcnt(0)
	s_barrier
